# v27 + attention phases: compiler-packed v_pk_mul_f32 split into scalar v_mul_f32 (packed f32 beside MFMAs)
# baseline (speedup 1.0000x reference)
.LBB0_891:
	ds_bpermute_b32 v4, v206, v2
	s_lshl_b32 s14, s34, 7
	s_lshl_b32 s15, s35, 11
	s_add_i32 s33, s33, s90
	s_waitcnt lgkmcnt(0)
	v_add_f32_e32 v2, v2, v4
	v_div_scale_f32 v4, s[12:13], v2, v2, 1.0
	v_rcp_f32_e32 v5, v4
	v_div_scale_f32 v6, vcc, 1.0, v2, 1.0
	s_or_b32 s12, s15, s14
	v_fma_f32 v7, -v4, v5, 1.0
	v_fmac_f32_e32 v5, v7, v5
	v_mul_f32_e32 v7, v6, v5
	v_fma_f32 v8, -v4, v7, v6
	v_fmac_f32_e32 v7, v8, v5
	v_fma_f32 v4, -v4, v7, v6
	v_div_fmas_f32 v4, v4, v5, v7
	v_div_fixup_f32 v8, v4, v2, 1.0
	v_mov_b32_e32 v2, v1
	v_mul_f32 v4, v66, v8
	v_mul_f32 v5, v67, v8
	v_mul_f32 v6, v68, v8
	v_mul_f32 v7, v69, v8
	v_cvt_pk_bf16_f32 v4, v4, v5
	v_cvt_pk_bf16_f32 v5, v6, v7
	v_mul_f32 v6, v70, v8
	v_mul_f32 v7, v71, v8
	v_mul_f32 v12, v72, v8
	v_mul_f32 v13, v73, v8
	v_lshl_add_u32 v2, v2, 11, s12
	v_cvt_pk_bf16_f32 v6, v6, v7
	v_cvt_pk_bf16_f32 v7, v12, v13
	v_lshl_add_u64 v[10:11], v[2:3], 1, v[198:199]
	v_permlane32_swap_b32_e32 v4, v6
	v_permlane32_swap_b32_e32 v5, v7
	global_store_dwordx4 v[10:11], v[4:7], off
	v_mul_f32 v12, v80, v8
	v_mul_f32 v13, v81, v8
	s_cmpk_gt_i32 s33, 0xff
	v_mul_f32 v4, v74, v8
	v_mul_f32 v5, v75, v8
	v_mul_f32 v6, v76, v8
	v_mul_f32 v7, v77, v8
	v_cvt_pk_bf16_f32 v4, v4, v5
	v_cvt_pk_bf16_f32 v5, v6, v7
	v_mul_f32 v6, v78, v8
	v_mul_f32 v7, v79, v8
	s_nop 0
	v_cvt_pk_bf16_f32 v6, v6, v7
	v_cvt_pk_bf16_f32 v7, v12, v13
	s_nop 0
	v_permlane32_swap_b32_e32 v4, v6
	v_permlane32_swap_b32_e32 v5, v7
	global_store_dwordx4 v[10:11], v[4:7], off offset:32
	v_mul_f32 v12, v56, v8
	v_mul_f32 v13, v57, v8
	s_nop 0
	v_mul_f32 v4, v50, v8
	v_mul_f32 v5, v51, v8
	v_mul_f32 v6, v52, v8
	v_mul_f32 v7, v53, v8
	v_cvt_pk_bf16_f32 v4, v4, v5
	v_cvt_pk_bf16_f32 v5, v6, v7
	v_mul_f32 v6, v54, v8
	v_mul_f32 v7, v55, v8
	s_nop 0
	v_cvt_pk_bf16_f32 v6, v6, v7
	v_cvt_pk_bf16_f32 v7, v12, v13
	s_nop 0
	v_permlane32_swap_b32_e32 v4, v6
	v_permlane32_swap_b32_e32 v5, v7
	global_store_dwordx4 v[10:11], v[4:7], off offset:64
	v_mul_f32 v12, v64, v8
	v_mul_f32 v13, v65, v8
	s_nop 0
	v_mul_f32 v4, v58, v8
	v_mul_f32 v5, v59, v8
	v_mul_f32 v6, v60, v8
	v_mul_f32 v7, v61, v8
	v_cvt_pk_bf16_f32 v4, v4, v5
	v_cvt_pk_bf16_f32 v5, v6, v7
	v_mul_f32 v6, v62, v8
	v_mul_f32 v7, v63, v8
	s_nop 0
	v_cvt_pk_bf16_f32 v6, v6, v7
	v_cvt_pk_bf16_f32 v7, v12, v13
	s_nop 0
	v_permlane32_swap_b32_e32 v4, v6
	v_permlane32_swap_b32_e32 v5, v7
	global_store_dwordx4 v[10:11], v[4:7], off offset:96
	v_mul_f32 v12, v40, v8
	v_mul_f32 v13, v41, v8
	s_nop 0
	v_mul_f32 v4, v34, v8
	v_mul_f32 v5, v35, v8
	v_mul_f32 v6, v36, v8
	v_mul_f32 v7, v37, v8
	v_cvt_pk_bf16_f32 v4, v4, v5
	v_cvt_pk_bf16_f32 v5, v6, v7
	v_mul_f32 v6, v38, v8
	v_mul_f32 v7, v39, v8
	s_nop 0
	v_cvt_pk_bf16_f32 v6, v6, v7
	v_cvt_pk_bf16_f32 v7, v12, v13
	s_nop 0
	v_permlane32_swap_b32_e32 v4, v6
	v_permlane32_swap_b32_e32 v5, v7
	global_store_dwordx4 v[10:11], v[4:7], off offset:128
	v_mul_f32 v12, v48, v8
	v_mul_f32 v13, v49, v8
	s_nop 0
	v_mul_f32 v4, v42, v8
	v_mul_f32 v5, v43, v8
	v_mul_f32 v6, v44, v8
	v_mul_f32 v7, v45, v8
	v_cvt_pk_bf16_f32 v4, v4, v5
	v_cvt_pk_bf16_f32 v5, v6, v7
	v_mul_f32 v6, v46, v8
	v_mul_f32 v7, v47, v8
	s_nop 0
	v_cvt_pk_bf16_f32 v6, v6, v7
	v_cvt_pk_bf16_f32 v7, v12, v13
	s_nop 0
	v_permlane32_swap_b32_e32 v4, v6
	v_permlane32_swap_b32_e32 v5, v7
	global_store_dwordx4 v[10:11], v[4:7], off offset:160
	v_mul_f32 v12, v24, v8
	v_mul_f32 v13, v25, v8
	s_nop 0
	v_mul_f32 v4, v18, v8
	v_mul_f32 v5, v19, v8
	v_mul_f32 v6, v20, v8
	v_mul_f32 v7, v21, v8
	v_cvt_pk_bf16_f32 v4, v4, v5
	v_cvt_pk_bf16_f32 v5, v6, v7
	v_mul_f32 v6, v22, v8
	v_mul_f32 v7, v23, v8
	s_nop 0
	v_cvt_pk_bf16_f32 v6, v6, v7
	v_cvt_pk_bf16_f32 v7, v12, v13
	s_nop 0
	v_permlane32_swap_b32_e32 v4, v6
	v_permlane32_swap_b32_e32 v5, v7
	global_store_dwordx4 v[10:11], v[4:7], off offset:192
	s_nop 1
	v_mul_f32 v4, v26, v8
	v_mul_f32 v5, v27, v8
	v_mul_f32 v6, v28, v8
	v_mul_f32 v7, v29, v8
	v_cvt_pk_bf16_f32 v4, v4, v5
	v_cvt_pk_bf16_f32 v5, v6, v7
	v_mul_f32 v6, v30, v8
	v_mul_f32 v7, v31, v8
	v_mul_f32 v9, v33, v8
	v_mul_f32 v8, v32, v8
	v_cvt_pk_bf16_f32 v6, v6, v7
	v_cvt_pk_bf16_f32 v7, v8, v9
	s_nop 0
	v_permlane32_swap_b32_e32 v4, v6
	v_permlane32_swap_b32_e32 v5, v7
	global_store_dwordx4 v[10:11], v[4:7], off offset:224
	s_cbranch_scc1 .LBB0_917

.LBB0_893:
	v_max_f32_e32 v162, v162, v162
	v_max_f32_e32 v163, v184, v184
	v_max_f32_e32 v163, v163, v162
	v_sub_f32_e32 v162, v184, v163
	v_exp_f32_e32 v162, v162
	v_mov_b32_e32 v184, v163
	v_mul_f32_e32 v2, v2, v162
	v_mul_f32 v80, v80, v162
	v_mul_f32 v81, v81, v162
	v_mul_f32 v78, v78, v162
	v_mul_f32 v79, v79, v162
	v_mul_f32 v76, v76, v162
	v_mul_f32 v77, v77, v162
	v_mul_f32 v74, v74, v162
	v_mul_f32 v75, v75, v162
	v_mul_f32 v72, v72, v162
	v_mul_f32 v73, v73, v162
	v_mul_f32 v70, v70, v162
	v_mul_f32 v71, v71, v162
	v_mul_f32 v68, v68, v162
	v_mul_f32 v69, v69, v162
	v_mul_f32 v66, v66, v162
	v_mul_f32 v67, v67, v162
	v_mul_f32 v64, v64, v162
	v_mul_f32 v65, v65, v162
	v_mul_f32 v62, v62, v162
	v_mul_f32 v63, v63, v162
	v_mul_f32 v60, v60, v162
	v_mul_f32 v61, v61, v162
	v_mul_f32 v58, v58, v162
	v_mul_f32 v59, v59, v162
	v_mul_f32 v56, v56, v162
	v_mul_f32 v57, v57, v162
	v_mul_f32 v54, v54, v162
	v_mul_f32 v55, v55, v162
	v_mul_f32 v52, v52, v162
	v_mul_f32 v53, v53, v162
	v_mul_f32 v50, v50, v162
	v_mul_f32 v51, v51, v162
	v_mul_f32 v48, v48, v162
	v_mul_f32 v49, v49, v162
	v_mul_f32 v46, v46, v162
	v_mul_f32 v47, v47, v162
	v_mul_f32 v44, v44, v162
	v_mul_f32 v45, v45, v162
	v_mul_f32 v42, v42, v162
	v_mul_f32 v43, v43, v162
	v_mul_f32 v40, v40, v162
	v_mul_f32 v41, v41, v162
	v_mul_f32 v38, v38, v162
	v_mul_f32 v39, v39, v162
	v_mul_f32 v36, v36, v162
	v_mul_f32 v37, v37, v162
	v_mul_f32 v34, v34, v162
	v_mul_f32 v35, v35, v162
	v_mul_f32 v32, v32, v162
	v_mul_f32 v33, v33, v162
	v_mul_f32 v30, v30, v162
	v_mul_f32 v31, v31, v162
	v_mul_f32 v28, v28, v162
	v_mul_f32 v29, v29, v162
	v_mul_f32 v26, v26, v162
	v_mul_f32 v27, v27, v162
	v_mul_f32 v24, v24, v162
	v_mul_f32 v25, v25, v162
	v_mul_f32 v22, v22, v162
	v_mul_f32 v23, v23, v162
	v_mul_f32 v20, v20, v162
	v_mul_f32 v21, v21, v162
	v_mul_f32 v18, v18, v162
	v_mul_f32 v19, v19, v162
	v_xor_b32_e32 v162, 0x80000000, v163

.LBB0_895:
	s_cmp_lt_u32 s40, 6
	s_cselect_b64 s[16:17], -1, 0
	s_and_b64 s[18:19], s[16:17], exec
	s_cselect_b32 s18, 2, -6
	s_add_i32 s18, s18, s40
	s_and_b64 s[42:43], s[16:17], exec
	s_cselect_b32 s41, s13, s37
	s_cselect_b32 s42, s12, s36
	s_ashr_i32 s19, s18, 31
	s_mul_i32 s44, s18, 0x6000
	s_mul_hi_i32 s43, s18, 0x6000
	s_add_u32 s42, s42, s44
	s_addc_u32 s43, s41, s43
	s_waitcnt vmcnt(5)
	s_and_b64 s[16:17], s[16:17], exec
	s_mov_b32 m0, s64
	s_waitcnt lgkmcnt(0)
	s_barrier
	v_lshl_add_u64 v[4:5], s[42:43], 0, v[192:193]
	s_cselect_b32 s41, s15, s39
	s_cselect_b32 s42, s14, s38
	s_lshl_b64 s[16:17], s[18:19], 14
	s_add_u32 s16, s42, s16
	global_load_lds_dwordx4 v[4:5], off
	v_lshl_add_u64 v[6:7], v[4:5], 0, s[0:1]
	s_mov_b32 m0, s65
	s_addc_u32 s17, s41, s17
	global_load_lds_dwordx4 v[6:7], off
	v_lshl_add_u64 v[4:5], v[4:5], 0, s[4:5]
	s_mov_b32 m0, s47
	s_nop 0
	global_load_lds_dwordx4 v[4:5], off
	v_lshl_add_u64 v[4:5], s[16:17], 0, v[192:193]
	s_mov_b32 m0, s48
	s_nop 0
	global_load_lds_dwordx4 v[4:5], off
	v_lshl_add_u64 v[4:5], v[4:5], 0, s[0:1]
	s_mov_b32 m0, s49
	s_nop 0
	global_load_lds_dwordx4 v[4:5], off
	ds_read_b128 v[4:7], v195 offset:0
	ds_read_b128 v[8:11], v195 offset:0x400
	ds_read_b128 v[12:15], v195 offset:0x800
	ds_read_b128 v[82:85], v195 offset:0xc00
	ds_read_b128 v[86:89], v195 offset:0x1000
	ds_read_b128 v[90:93], v195 offset:0x1400
	ds_read_b128 v[94:97], v195 offset:0x1800
	ds_read_b128 v[162:165], v195 offset:0x1c00
	s_nop 0
	s_waitcnt lgkmcnt(4)
	s_nop 0
	v_mfma_f32_32x32x16_bf16 v[98:113], v[4:7], v[114:117], 0
	v_mfma_f32_32x32x16_bf16 v[98:113], v[8:11], v[118:121], v[98:113]
	ds_read_b128 v[8:11], v195 offset:0x2000
	ds_read_b128 v[166:169], v195 offset:0x2400
	ds_read_b128 v[170:173], v195 offset:0x2800
	ds_read_b128 v[188:191], v195 offset:0x2c00
	s_waitcnt lgkmcnt(4)
	v_mfma_f32_32x32x16_bf16 v[98:113], v[12:15], v[122:125], v[98:113]
	v_mfma_f32_32x32x16_bf16 v[98:113], v[82:85], v[126:129], v[98:113]
	ds_read_b128 v[82:85], v195 offset:0x3000
	ds_read_b128 v[200:203], v195 offset:0x3400
	ds_read_b128 v[210:213], v195 offset:0x3800
	ds_read_b128 v[214:217], v195 offset:0x3c00
	s_waitcnt lgkmcnt(4)
	ds_read_b128 v[178:181], v195 offset:0x4000
	ds_read_b128 v[174:177], v195 offset:0x4400
	v_mfma_f32_32x32x16_bf16 v[98:113], v[86:89], v[130:133], v[98:113]
	ds_read_b128 v[12:15], v195 offset:0x4800
	ds_read_b128 v[4:7], v195 offset:0x4c00
	s_waitcnt lgkmcnt(4)
	v_mfma_f32_32x32x16_bf16 v[98:113], v[90:93], v[134:137], v[98:113]
	v_mfma_f32_32x32x16_bf16 v[98:113], v[94:97], v[138:141], v[98:113]
	v_mfma_f32_32x32x16_bf16 v[98:113], v[162:165], v[142:145], v[98:113]
	v_mfma_f32_32x32x16_bf16 v[98:113], v[8:11], v[146:149], v[98:113]
	v_and_b32_e32 v9, 64, v183
	v_xor_b32_e32 v8, 32, v183
	v_add_u32_e32 v9, 64, v9
	v_cmp_lt_i32_e32 vcc, v8, v9
	s_nop 1
	v_cndmask_b32_e32 v8, v183, v8, vcc
	v_mfma_f32_32x32x16_bf16 v[98:113], v[166:169], v[150:153], v[98:113]
	v_lshlrev_b32_e32 v206, 2, v8
	ds_read_b128 v[166:169], v195 offset:0x5000
	v_mfma_f32_32x32x16_bf16 v[98:113], v[170:173], v[154:157], v[98:113]
	ds_read_b128 v[170:173], v195 offset:0x5400
	ds_read_b128 v[162:165], v195 offset:0x5800
	v_mfma_f32_32x32x16_bf16 v[82:97], v[82:85], v[114:117], 0
	v_mfma_f32_32x32x16_bf16 v[98:113], v[188:191], v[158:161], v[98:113]
	v_mfma_f32_32x32x16_bf16 v[82:97], v[200:203], v[118:121], v[82:97]
	s_nop 10
	v_max3_f32 v8, v98, s29, v99
	v_max3_f32 v8, v8, v100, v101
	v_max3_f32 v8, v8, v102, v103
	v_max3_f32 v8, v8, v104, v105
	v_max3_f32 v8, v8, v106, v107
	v_max3_f32 v8, v8, v108, v109
	v_max3_f32 v8, v8, v110, v111
	v_mfma_f32_32x32x16_bf16 v[82:97], v[210:213], v[122:125], v[82:97]
	v_max3_f32 v8, v8, v112, v113
	v_mul_f32_e32 v16, 0x3dd53b94, v8
	ds_bpermute_b32 v17, v206, v16
	ds_read_b128 v[8:11], v195 offset:0x5c00
	s_waitcnt lgkmcnt(0)
	v_max_f32_e32 v17, v17, v17
	v_mfma_f32_32x32x16_bf16 v[82:97], v[214:217], v[126:129], v[82:97]
	v_max_f32_e32 v16, v16, v17
	v_sub_f32_e32 v17, v16, v184
	v_cmp_ge_f32_e32 vcc, s31, v17
	s_cmp_eq_u64 vcc, exec
	s_cbranch_scc1 .LBB0_897
	v_max_f32_e32 v16, v16, v16
	v_max_f32_e32 v17, v184, v184
	v_max_f32_e32 v17, v17, v16
	v_sub_f32_e32 v16, v184, v17
	v_exp_f32_e32 v16, v16
	v_mov_b32_e32 v184, v17
	v_mul_f32_e32 v2, v2, v16
	v_mul_f32 v80, v80, v16
	v_mul_f32 v81, v81, v16
	v_mul_f32 v78, v78, v16
	v_mul_f32 v79, v79, v16
	v_mul_f32 v76, v76, v16
	v_mul_f32 v77, v77, v16
	v_mul_f32 v74, v74, v16
	v_mul_f32 v75, v75, v16
	v_mul_f32 v72, v72, v16
	v_mul_f32 v73, v73, v16
	v_mul_f32 v70, v70, v16
	v_mul_f32 v71, v71, v16
	v_mul_f32 v68, v68, v16
	v_mul_f32 v69, v69, v16
	v_mul_f32 v66, v66, v16
	v_mul_f32 v67, v67, v16
	v_mul_f32 v64, v64, v16
	v_mul_f32 v65, v65, v16
	v_mul_f32 v62, v62, v16
	v_mul_f32 v63, v63, v16
	v_mul_f32 v60, v60, v16
	v_mul_f32 v61, v61, v16
	v_mul_f32 v58, v58, v16
	v_mul_f32 v59, v59, v16
	v_mul_f32 v56, v56, v16
	v_mul_f32 v57, v57, v16
	v_mul_f32 v54, v54, v16
	v_mul_f32 v55, v55, v16
	v_mul_f32 v52, v52, v16
	v_mul_f32 v53, v53, v16
	v_mul_f32 v50, v50, v16
	v_mul_f32 v51, v51, v16
	v_mul_f32 v48, v48, v16
	v_mul_f32 v49, v49, v16
	v_mul_f32 v46, v46, v16
	v_mul_f32 v47, v47, v16
	v_mul_f32 v44, v44, v16
	v_mul_f32 v45, v45, v16
	v_mul_f32 v42, v42, v16
	v_mul_f32 v43, v43, v16
	v_mul_f32 v40, v40, v16
	v_mul_f32 v41, v41, v16
	v_mul_f32 v38, v38, v16
	v_mul_f32 v39, v39, v16
	v_mul_f32 v36, v36, v16
	v_mul_f32 v37, v37, v16
	v_mul_f32 v34, v34, v16
	v_mul_f32 v35, v35, v16
	v_mul_f32 v32, v32, v16
	v_mul_f32 v33, v33, v16
	v_mul_f32 v30, v30, v16
	v_mul_f32 v31, v31, v16
	v_mul_f32 v28, v28, v16
	v_mul_f32 v29, v29, v16
	v_mul_f32 v26, v26, v16
	v_mul_f32 v27, v27, v16
	v_mul_f32 v24, v24, v16
	v_mul_f32 v25, v25, v16
	v_mul_f32 v22, v22, v16
	v_mul_f32 v23, v23, v16
	v_mul_f32 v20, v20, v16
	v_mul_f32 v21, v21, v16
	v_mul_f32 v18, v18, v16
	v_mul_f32 v19, v19, v16
.LBB0_897:
	s_waitcnt lgkmcnt(4)
	ds_read_b128 v[188:191], v195 offset:0x6000
	ds_read_b128 v[200:203], v195 offset:0x6400
	ds_read_b128 v[210:213], v195 offset:0x6800
	ds_read_b128 v[214:217], v195 offset:0x6c00
	s_waitcnt lgkmcnt(4)
	s_nop 0
	v_mfma_f32_32x32x16_bf16 v[82:97], v[178:181], v[130:133], v[82:97]
	v_fma_f32 v16, v98, s30, -v184
	v_exp_f32_e32 v16, v16
	v_fma_f32 v17, v99, s30, -v184
	v_exp_f32_e32 v17, v17
	ds_read_b128 v[178:181], v195 offset:0x7000
	v_add_f32_e32 v98, 0, v16
	v_add_f32_e32 v185, v17, v98
	v_mfma_f32_32x32x16_bf16 v[82:97], v[174:177], v[134:137], v[82:97]
	v_fma_f32 v98, v100, s30, -v184
	v_exp_f32_e32 v187, v98
	v_fma_f32 v98, v101, s30, -v184
	v_exp_f32_e32 v207, v98
	v_fma_f32 v98, v102, s30, -v184
	v_exp_f32_e32 v208, v98
	v_fma_f32 v98, v103, s30, -v184
	v_mfma_f32_32x32x16_bf16 v[82:97], v[12:15], v[138:141], v[82:97]
	v_exp_f32_e32 v222, v98
	v_fma_f32 v12, v104, s30, -v184
	v_exp_f32_e32 v12, v12
	v_fma_f32 v13, v105, s30, -v184
	v_exp_f32_e32 v13, v13
	v_cvt_pk_bf16_f32 v218, v16, v17
	v_cvt_pk_bf16_f32 v219, v187, v207
	v_mfma_f32_32x32x16_bf16 v[82:97], v[4:7], v[142:145], v[82:97]
	v_add_f32_e32 v4, v187, v185
	v_add_f32_e32 v4, v207, v4
	v_fma_f32 v5, v106, s30, -v184
	v_add_f32_e32 v4, v208, v4
	v_exp_f32_e32 v16, v5
	v_fma_f32 v5, v107, s30, -v184
	v_add_f32_e32 v4, v222, v4
	v_mfma_f32_32x32x16_bf16 v[82:97], v[166:169], v[146:149], v[82:97]
	v_exp_f32_e32 v17, v5
	v_fma_f32 v5, v108, s30, -v184
	v_add_f32_e32 v4, v12, v4
	v_exp_f32_e32 v166, v5
	v_fma_f32 v5, v109, s30, -v184
	v_add_f32_e32 v4, v13, v4
	v_exp_f32_e32 v167, v5
	v_mfma_f32_32x32x16_bf16 v[82:97], v[170:173], v[150:153], v[82:97]
	v_fma_f32 v5, v110, s30, -v184
	v_add_f32_e32 v4, v16, v4
	v_exp_f32_e32 v110, v5
	v_fma_f32 v5, v111, s30, -v184
	v_add_f32_e32 v4, v17, v4
	v_exp_f32_e32 v111, v5
	v_fma_f32 v5, v112, s30, -v184
	v_mfma_f32_32x32x16_bf16 v[82:97], v[162:165], v[154:157], v[82:97]
	v_add_f32_e32 v4, v166, v4
	v_exp_f32_e32 v112, v5
	v_fma_f32 v5, v113, s30, -v184
	v_add_f32_e32 v4, v167, v4
	v_exp_f32_e32 v113, v5
	v_add_f32_e32 v4, v110, v4
	v_add_f32_e32 v4, v111, v4
	v_mfma_f32_32x32x16_bf16 v[82:97], v[8:11], v[158:161], v[82:97]
	v_add_f32_e32 v4, v112, v4
	v_add_f32_e32 v4, v113, v4
	v_add_f32_e32 v2, v2, v4
	v_cvt_pk_bf16_f32 v220, v208, v222
	v_cvt_pk_bf16_f32 v221, v12, v13
	ds_read_b128 v[174:177], v195 offset:0x7400
	ds_read_b128 v[102:105], v195 offset:0x7800
	s_nop 6
	v_max3_f32 v4, v82, s29, v83
	v_max3_f32 v4, v4, v84, v85
	v_max3_f32 v4, v4, v86, v87
	v_max3_f32 v4, v4, v88, v89
	v_max3_f32 v4, v4, v90, v91
	v_max3_f32 v4, v4, v92, v93
	v_max3_f32 v4, v4, v94, v95
	v_max3_f32 v4, v4, v96, v97
	v_mul_f32_e32 v162, 0x3dd53b94, v4
	ds_bpermute_b32 v163, v206, v162
	ds_read_b128 v[98:101], v195 offset:0x7c00
	s_waitcnt lgkmcnt(4)
	ds_read_b128 v[8:11], v195 offset:0x8000
	ds_read_b128 v[106:109], v195 offset:0x8400
	s_waitcnt lgkmcnt(0)
	v_max_f32_e32 v163, v163, v163
	v_mfma_f32_32x32x16_bf16 v[66:81], v[188:191], v[218:221], v[66:81]
	v_max_f32_e32 v162, v162, v163
	ds_read_b128 v[12:15], v195 offset:0x8800
	ds_read_b128 v[4:7], v195 offset:0x8c00
	v_sub_f32_e32 v163, v162, v184
	v_cmp_ge_f32_e32 vcc, s31, v163
	s_cmp_eq_u64 vcc, exec
	v_mfma_f32_32x32x16_bf16 v[50:65], v[200:203], v[218:221], v[50:65]
	v_mfma_f32_32x32x16_bf16 v[34:49], v[210:213], v[218:221], v[34:49]
	v_mfma_f32_32x32x16_bf16 v[18:33], v[214:217], v[218:221], v[18:33]
	s_cbranch_scc1 .LBB0_899
	v_max_f32_e32 v162, v162, v162
	v_max_f32_e32 v163, v184, v184
	v_max_f32_e32 v163, v163, v162
	v_sub_f32_e32 v162, v184, v163
	v_exp_f32_e32 v162, v162
	v_mov_b32_e32 v184, v163
	v_mul_f32_e32 v2, v2, v162
	v_mul_f32 v80, v80, v162
	v_mul_f32 v81, v81, v162
	v_mul_f32 v78, v78, v162
	v_mul_f32 v79, v79, v162
	v_mul_f32 v76, v76, v162
	v_mul_f32 v77, v77, v162
	v_mul_f32 v74, v74, v162
	v_mul_f32 v75, v75, v162
	v_mul_f32 v72, v72, v162
	v_mul_f32 v73, v73, v162
	v_mul_f32 v70, v70, v162
	v_mul_f32 v71, v71, v162
	v_mul_f32 v68, v68, v162
	v_mul_f32 v69, v69, v162
	v_mul_f32 v66, v66, v162
	v_mul_f32 v67, v67, v162
	v_mul_f32 v64, v64, v162
	v_mul_f32 v65, v65, v162
	v_mul_f32 v62, v62, v162
	v_mul_f32 v63, v63, v162
	v_mul_f32 v60, v60, v162
	v_mul_f32 v61, v61, v162
	v_mul_f32 v58, v58, v162
	v_mul_f32 v59, v59, v162
	v_mul_f32 v56, v56, v162
	v_mul_f32 v57, v57, v162
	v_mul_f32 v54, v54, v162
	v_mul_f32 v55, v55, v162
	v_mul_f32 v52, v52, v162
	v_mul_f32 v53, v53, v162
	v_mul_f32 v50, v50, v162
	v_mul_f32 v51, v51, v162
	v_mul_f32 v48, v48, v162
	v_mul_f32 v49, v49, v162
	v_mul_f32 v46, v46, v162
	v_mul_f32 v47, v47, v162
	v_mul_f32 v44, v44, v162
	v_mul_f32 v45, v45, v162
	v_mul_f32 v42, v42, v162
	v_mul_f32 v43, v43, v162
	v_mul_f32 v40, v40, v162
	v_mul_f32 v41, v41, v162
	v_mul_f32 v38, v38, v162
	v_mul_f32 v39, v39, v162
	v_mul_f32 v36, v36, v162
	v_mul_f32 v37, v37, v162
	v_mul_f32 v34, v34, v162
	v_mul_f32 v35, v35, v162
	v_mul_f32 v32, v32, v162
	v_mul_f32 v33, v33, v162
	v_mul_f32 v30, v30, v162
	v_mul_f32 v31, v31, v162
	v_mul_f32 v28, v28, v162
	v_mul_f32 v29, v29, v162
	v_mul_f32 v26, v26, v162
	v_mul_f32 v27, v27, v162
	v_mul_f32 v24, v24, v162
	v_mul_f32 v25, v25, v162
	v_mul_f32 v22, v22, v162
	v_mul_f32 v23, v23, v162
	v_mul_f32 v20, v20, v162
	v_mul_f32 v21, v21, v162
	v_mul_f32 v18, v18, v162
	v_mul_f32 v19, v19, v162
	v_xor_b32_e32 v162, 0x80000000, v163
	s_branch .LBB0_900

.LBB0_902:
	ds_read_b128 v[90:93], v197 offset:0
	ds_read_b128 v[94:97], v197 offset:0x400
	ds_read_b128 v[162:165], v197 offset:0x800
	ds_read_b128 v[166:169], v197 offset:0xc00
	ds_read_b128 v[170:173], v197 offset:0x1000
	ds_read_b128 v[174:177], v197 offset:0x1400
	ds_read_b128 v[178:181], v197 offset:0x1800
	ds_read_b128 v[188:191], v197 offset:0x1c00
	v_add_f32_e32 v5, 0, v16
	s_waitcnt lgkmcnt(4)
	v_add_f32_e32 v5, v17, v5
	v_mfma_f32_32x32x16_bf16 v[98:113], v[90:93], v[114:117], 0
	ds_read_b128 v[90:93], v197 offset:0x2000
	v_add_f32_e32 v5, v82, v5
	v_add_f32_e32 v5, v83, v5
	v_add_f32_e32 v5, v84, v5
	v_add_f32_e32 v5, v86, v5
	v_add_f32_e32 v5, v85, v5
	v_add_f32_e32 v5, v87, v5
	v_mfma_f32_32x32x16_bf16 v[98:113], v[94:97], v[118:121], v[98:113]
	ds_read_b128 v[94:97], v197 offset:0x2400
	v_add_f32_e32 v5, v8, v5
	v_add_f32_e32 v5, v10, v5
	v_add_f32_e32 v5, v88, v5
	v_add_f32_e32 v5, v12, v5
	v_add_f32_e32 v5, v13, v5
	v_add_f32_e32 v5, v9, v5
	v_mfma_f32_32x32x16_bf16 v[98:113], v[162:165], v[122:125], v[98:113]
	ds_read_b128 v[162:165], v197 offset:0x2800
	v_add_f32_e32 v5, v11, v5
	v_add_f32_e32 v8, v4, v5
	v_add_f32_e32 v2, v2, v8
	v_mfma_f32_32x32x16_bf16 v[98:113], v[166:169], v[126:129], v[98:113]
	ds_read_b128 v[166:169], v197 offset:0x2c00
	s_waitcnt lgkmcnt(4)
	s_nop 0
	v_mfma_f32_32x32x16_bf16 v[98:113], v[170:173], v[130:133], v[98:113]
	v_mfma_f32_32x32x16_bf16 v[98:113], v[174:177], v[134:137], v[98:113]
	v_mfma_f32_32x32x16_bf16 v[98:113], v[178:181], v[138:141], v[98:113]
	v_mfma_f32_32x32x16_bf16 v[98:113], v[188:191], v[142:145], v[98:113]
	ds_read_b128 v[188:191], v197 offset:0x3000
	ds_read_b128 v[200:203], v197 offset:0x3400
	ds_read_b128 v[210:213], v197 offset:0x3800
	ds_read_b128 v[214:217], v197 offset:0x3c00
	s_waitcnt lgkmcnt(4)
	ds_read_b128 v[178:181], v197 offset:0x4000
	ds_read_b128 v[174:177], v197 offset:0x4400
	ds_read_b128 v[170:173], v197 offset:0x4800
	s_nop 0
	v_mfma_f32_32x32x16_bf16 v[98:113], v[90:93], v[146:149], v[98:113]
	v_mfma_f32_32x32x16_bf16 v[98:113], v[94:97], v[150:153], v[98:113]
	v_mfma_f32_32x32x16_bf16 v[98:113], v[162:165], v[154:157], v[98:113]
	v_mfma_f32_32x32x16_bf16 v[98:113], v[166:169], v[158:161], v[98:113]
	ds_read_b128 v[166:169], v197 offset:0x4c00
	s_waitcnt lgkmcnt(4)
	ds_read_b128 v[12:15], v197 offset:0x5000
	ds_read_b128 v[4:7], v197 offset:0x5400
	ds_read_b128 v[162:165], v197 offset:0x5800
	s_nop 11
	v_max3_f32 v9, v98, s29, v99
	v_mfma_f32_32x32x16_bf16 v[82:97], v[188:191], v[114:117], 0
	v_max3_f32 v9, v9, v100, v101
	v_max3_f32 v9, v9, v102, v103
	v_max3_f32 v9, v9, v104, v105
	v_max3_f32 v9, v9, v106, v107
	v_max3_f32 v9, v9, v108, v109
	v_max3_f32 v9, v9, v110, v111
	v_max3_f32 v9, v9, v112, v113
	v_mfma_f32_32x32x16_bf16 v[82:97], v[200:203], v[118:121], v[82:97]
	v_mul_f32_e32 v16, 0x3dd53b94, v9
	ds_bpermute_b32 v17, v206, v16
	ds_read_b128 v[8:11], v197 offset:0x5c00
	s_waitcnt lgkmcnt(0)
	v_max_f32_e32 v17, v17, v17
	v_mfma_f32_32x32x16_bf16 v[82:97], v[210:213], v[122:125], v[82:97]
	v_max_f32_e32 v16, v16, v17
	v_sub_f32_e32 v17, v16, v184
	v_cmp_ge_f32_e32 vcc, s31, v17
	s_cmp_eq_u64 vcc, exec
	v_mfma_f32_32x32x16_bf16 v[82:97], v[214:217], v[126:129], v[82:97]
	s_cbranch_scc1 .LBB0_904
	v_max_f32_e32 v16, v16, v16
	v_max_f32_e32 v17, v184, v184
	v_max_f32_e32 v17, v17, v16
	v_sub_f32_e32 v16, v184, v17
	v_exp_f32_e32 v16, v16
	v_mov_b32_e32 v184, v17
	v_mul_f32_e32 v2, v2, v16
	v_mul_f32 v80, v80, v16
	v_mul_f32 v81, v81, v16
	v_mul_f32 v78, v78, v16
	v_mul_f32 v79, v79, v16
	v_mul_f32 v76, v76, v16
	v_mul_f32 v77, v77, v16
	v_mul_f32 v74, v74, v16
	v_mul_f32 v75, v75, v16
	v_mul_f32 v72, v72, v16
	v_mul_f32 v73, v73, v16
	v_mul_f32 v70, v70, v16
	v_mul_f32 v71, v71, v16
	v_mul_f32 v68, v68, v16
	v_mul_f32 v69, v69, v16
	v_mul_f32 v66, v66, v16
	v_mul_f32 v67, v67, v16
	v_mul_f32 v64, v64, v16
	v_mul_f32 v65, v65, v16
	v_mul_f32 v62, v62, v16
	v_mul_f32 v63, v63, v16
	v_mul_f32 v60, v60, v16
	v_mul_f32 v61, v61, v16
	v_mul_f32 v58, v58, v16
	v_mul_f32 v59, v59, v16
	v_mul_f32 v56, v56, v16
	v_mul_f32 v57, v57, v16
	v_mul_f32 v54, v54, v16
	v_mul_f32 v55, v55, v16
	v_mul_f32 v52, v52, v16
	v_mul_f32 v53, v53, v16
	v_mul_f32 v50, v50, v16
	v_mul_f32 v51, v51, v16
	v_mul_f32 v48, v48, v16
	v_mul_f32 v49, v49, v16
	v_mul_f32 v46, v46, v16
	v_mul_f32 v47, v47, v16
	v_mul_f32 v44, v44, v16
	v_mul_f32 v45, v45, v16
	v_mul_f32 v42, v42, v16
	v_mul_f32 v43, v43, v16
	v_mul_f32 v40, v40, v16
	v_mul_f32 v41, v41, v16
	v_mul_f32 v38, v38, v16
	v_mul_f32 v39, v39, v16
	v_mul_f32 v36, v36, v16
	v_mul_f32 v37, v37, v16
	v_mul_f32 v34, v34, v16
	v_mul_f32 v35, v35, v16
	v_mul_f32 v32, v32, v16
	v_mul_f32 v33, v33, v16
	v_mul_f32 v30, v30, v16
	v_mul_f32 v31, v31, v16
	v_mul_f32 v28, v28, v16
	v_mul_f32 v29, v29, v16
	v_mul_f32 v26, v26, v16
	v_mul_f32 v27, v27, v16
	v_mul_f32 v24, v24, v16
	v_mul_f32 v25, v25, v16
	v_mul_f32 v22, v22, v16
	v_mul_f32 v23, v23, v16
	v_mul_f32 v20, v20, v16
	v_mul_f32 v21, v21, v16
	v_mul_f32 v18, v18, v16
	v_mul_f32 v19, v19, v16
.LBB0_904:
	s_waitcnt lgkmcnt(4)
	ds_read_b128 v[188:191], v197 offset:0x6000
	ds_read_b128 v[200:203], v197 offset:0x6400
	v_fma_f32 v16, v98, s30, -v184
	v_mfma_f32_32x32x16_bf16 v[82:97], v[178:181], v[130:133], v[82:97]
	ds_read_b128 v[178:181], v197 offset:0x6800
	ds_read_b128 v[210:213], v197 offset:0x6c00
	s_waitcnt lgkmcnt(4)
	v_exp_f32_e32 v16, v16
	v_fma_f32 v17, v99, s30, -v184
	v_exp_f32_e32 v17, v17
	v_add_f32_e32 v98, 0, v16
	v_mfma_f32_32x32x16_bf16 v[82:97], v[174:177], v[134:137], v[82:97]
	v_add_f32_e32 v185, v17, v98
	v_fma_f32 v98, v100, s30, -v184
	v_exp_f32_e32 v174, v98
	v_fma_f32 v98, v101, s30, -v184
	v_exp_f32_e32 v175, v98
	v_fma_f32 v98, v102, s30, -v184
	v_exp_f32_e32 v176, v98
	v_mfma_f32_32x32x16_bf16 v[82:97], v[170:173], v[138:141], v[82:97]
	v_fma_f32 v98, v103, s30, -v184
	v_exp_f32_e32 v177, v98
	v_fma_f32 v98, v104, s30, -v184
	v_exp_f32_e32 v187, v98
	v_fma_f32 v98, v105, s30, -v184
	v_cvt_pk_bf16_f32 v214, v16, v17
	v_add_f32_e32 v16, v174, v185
	v_mfma_f32_32x32x16_bf16 v[82:97], v[166:169], v[142:145], v[82:97]
	v_exp_f32_e32 v207, v98
	v_add_f32_e32 v16, v175, v16
	v_add_f32_e32 v16, v176, v16
	v_add_f32_e32 v16, v177, v16
	v_add_f32_e32 v16, v187, v16
	v_cvt_pk_bf16_f32 v215, v174, v175
	v_add_f32_e32 v175, v207, v16
	v_mfma_f32_32x32x16_bf16 v[82:97], v[12:15], v[146:149], v[82:97]
	v_fma_f32 v16, v106, s30, -v184
	v_exp_f32_e32 v16, v16
	v_fma_f32 v12, v107, s30, -v184
	v_exp_f32_e32 v17, v12
	v_fma_f32 v12, v108, s30, -v184
	v_exp_f32_e32 v174, v12
	v_add_f32_e32 v12, v16, v175
	v_mfma_f32_32x32x16_bf16 v[82:97], v[4:7], v[150:153], v[82:97]
	v_fma_f32 v5, v109, s30, -v184
	v_exp_f32_e32 v175, v5
	v_fma_f32 v5, v110, s30, -v184
	v_exp_f32_e32 v110, v5
	v_fma_f32 v5, v111, s30, -v184
	v_add_f32_e32 v12, v17, v12
	v_exp_f32_e32 v111, v5
	v_mfma_f32_32x32x16_bf16 v[82:97], v[162:165], v[154:157], v[82:97]
	v_fma_f32 v5, v112, s30, -v184
	v_add_f32_e32 v4, v174, v12
	v_exp_f32_e32 v112, v5
	v_fma_f32 v5, v113, s30, -v184
	v_add_f32_e32 v4, v175, v4
	v_exp_f32_e32 v113, v5
	v_add_f32_e32 v4, v110, v4
	v_mfma_f32_32x32x16_bf16 v[82:97], v[8:11], v[158:161], v[82:97]
	v_add_f32_e32 v4, v111, v4
	v_add_f32_e32 v4, v112, v4
	v_add_f32_e32 v4, v113, v4
	v_add_f32_e32 v2, v2, v4
	v_cvt_pk_bf16_f32 v216, v176, v177
	v_cvt_pk_bf16_f32 v217, v187, v207
	ds_read_b128 v[170:173], v197 offset:0x7000
	s_nop 5
	v_max3_f32 v4, v82, s29, v83
	v_max3_f32 v4, v4, v84, v85
	v_max3_f32 v4, v4, v86, v87
	v_max3_f32 v4, v4, v88, v89
	v_max3_f32 v4, v4, v90, v91
	v_max3_f32 v4, v4, v92, v93
	v_max3_f32 v4, v4, v94, v95
	v_max3_f32 v4, v4, v96, v97
	v_mul_f32_e32 v162, 0x3dd53b94, v4
	ds_bpermute_b32 v163, v206, v162
	ds_read_b128 v[166:169], v197 offset:0x7400
	ds_read_b128 v[102:105], v197 offset:0x7800
	ds_read_b128 v[98:101], v197 offset:0x7c00
	s_waitcnt lgkmcnt(4)
	s_waitcnt lgkmcnt(0)
	v_max_f32_e32 v163, v163, v163
	v_mfma_f32_32x32x16_bf16 v[66:81], v[188:191], v[214:217], v[66:81]
	v_max_f32_e32 v162, v162, v163
	ds_read_b128 v[8:11], v197 offset:0x8000
	ds_read_b128 v[106:109], v197 offset:0x8400
	ds_read_b128 v[12:15], v197 offset:0x8800
	ds_read_b128 v[4:7], v197 offset:0x8c00
	v_sub_f32_e32 v163, v162, v184
	v_cmp_ge_f32_e32 vcc, s31, v163
	v_mfma_f32_32x32x16_bf16 v[50:65], v[200:203], v[214:217], v[50:65]
	s_cmp_eq_u64 vcc, exec
	v_mfma_f32_32x32x16_bf16 v[34:49], v[178:181], v[214:217], v[34:49]
	v_mfma_f32_32x32x16_bf16 v[18:33], v[210:213], v[214:217], v[18:33]
	s_cbranch_scc1 .LBB0_906
	v_max_f32_e32 v162, v162, v162
	v_max_f32_e32 v163, v184, v184
	v_max_f32_e32 v163, v163, v162
	v_sub_f32_e32 v162, v184, v163
	v_exp_f32_e32 v162, v162
	v_mov_b32_e32 v184, v163
	v_mul_f32_e32 v2, v2, v162
	v_mul_f32 v80, v80, v162
	v_mul_f32 v81, v81, v162
	v_mul_f32 v78, v78, v162
	v_mul_f32 v79, v79, v162
	v_mul_f32 v76, v76, v162
	v_mul_f32 v77, v77, v162
	v_mul_f32 v74, v74, v162
	v_mul_f32 v75, v75, v162
	v_mul_f32 v72, v72, v162
	v_mul_f32 v73, v73, v162
	v_mul_f32 v70, v70, v162
	v_mul_f32 v71, v71, v162
	v_mul_f32 v68, v68, v162
	v_mul_f32 v69, v69, v162
	v_mul_f32 v66, v66, v162
	v_mul_f32 v67, v67, v162
	v_mul_f32 v64, v64, v162
	v_mul_f32 v65, v65, v162
	v_mul_f32 v62, v62, v162
	v_mul_f32 v63, v63, v162
	v_mul_f32 v60, v60, v162
	v_mul_f32 v61, v61, v162
	v_mul_f32 v58, v58, v162
	v_mul_f32 v59, v59, v162
	v_mul_f32 v56, v56, v162
	v_mul_f32 v57, v57, v162
	v_mul_f32 v54, v54, v162
	v_mul_f32 v55, v55, v162
	v_mul_f32 v52, v52, v162
	v_mul_f32 v53, v53, v162
	v_mul_f32 v50, v50, v162
	v_mul_f32 v51, v51, v162
	v_mul_f32 v48, v48, v162
	v_mul_f32 v49, v49, v162
	v_mul_f32 v46, v46, v162
	v_mul_f32 v47, v47, v162
	v_mul_f32 v44, v44, v162
	v_mul_f32 v45, v45, v162
	v_mul_f32 v42, v42, v162
	v_mul_f32 v43, v43, v162
	v_mul_f32 v40, v40, v162
	v_mul_f32 v41, v41, v162
	v_mul_f32 v38, v38, v162
	v_mul_f32 v39, v39, v162
	v_mul_f32 v36, v36, v162
	v_mul_f32 v37, v37, v162
	v_mul_f32 v34, v34, v162
	v_mul_f32 v35, v35, v162
	v_mul_f32 v32, v32, v162
	v_mul_f32 v33, v33, v162
	v_mul_f32 v30, v30, v162
	v_mul_f32 v31, v31, v162
	v_mul_f32 v28, v28, v162
	v_mul_f32 v29, v29, v162
	v_mul_f32 v26, v26, v162
	v_mul_f32 v27, v27, v162
	v_mul_f32 v24, v24, v162
	v_mul_f32 v25, v25, v162
	v_mul_f32 v22, v22, v162
	v_mul_f32 v23, v23, v162
	v_mul_f32 v20, v20, v162
	v_mul_f32 v21, v21, v162
	v_mul_f32 v18, v18, v162
	v_mul_f32 v19, v19, v162
	v_xor_b32_e32 v162, 0x80000000, v163
	s_branch .LBB0_907

.LBB0_913:
	ds_read_b128 v[90:93], v204 offset:0
	ds_read_b128 v[94:97], v204 offset:0x400
	ds_read_b128 v[162:165], v204 offset:0x800
	ds_read_b128 v[166:169], v204 offset:0xc00
	ds_read_b128 v[170:173], v204 offset:0x1000
	ds_read_b128 v[174:177], v204 offset:0x1400
	ds_read_b128 v[178:181], v204 offset:0x1800
	ds_read_b128 v[188:191], v204 offset:0x1c00
	v_add_f32_e32 v5, 0, v16
	s_waitcnt lgkmcnt(4)
	v_add_f32_e32 v5, v17, v5
	v_mfma_f32_32x32x16_bf16 v[98:113], v[90:93], v[114:117], 0
	ds_read_b128 v[90:93], v204 offset:0x2000
	v_add_f32_e32 v5, v82, v5
	v_add_f32_e32 v5, v83, v5
	v_add_f32_e32 v5, v84, v5
	v_add_f32_e32 v5, v86, v5
	v_add_f32_e32 v5, v85, v5
	v_add_f32_e32 v5, v87, v5
	v_mfma_f32_32x32x16_bf16 v[98:113], v[94:97], v[118:121], v[98:113]
	ds_read_b128 v[94:97], v204 offset:0x2400
	v_add_f32_e32 v5, v8, v5
	v_add_f32_e32 v5, v10, v5
	v_add_f32_e32 v5, v88, v5
	v_add_f32_e32 v5, v12, v5
	v_add_f32_e32 v5, v13, v5
	v_add_f32_e32 v5, v9, v5
	v_mfma_f32_32x32x16_bf16 v[98:113], v[162:165], v[122:125], v[98:113]
	ds_read_b128 v[162:165], v204 offset:0x2800
	v_add_f32_e32 v5, v11, v5
	v_add_f32_e32 v8, v4, v5
	v_add_f32_e32 v2, v2, v8
	v_mfma_f32_32x32x16_bf16 v[98:113], v[166:169], v[126:129], v[98:113]
	ds_read_b128 v[166:169], v204 offset:0x2c00
	s_waitcnt lgkmcnt(4)
	s_nop 0
	v_mfma_f32_32x32x16_bf16 v[98:113], v[170:173], v[130:133], v[98:113]
	v_mfma_f32_32x32x16_bf16 v[98:113], v[174:177], v[134:137], v[98:113]
	v_mfma_f32_32x32x16_bf16 v[98:113], v[178:181], v[138:141], v[98:113]
	v_mfma_f32_32x32x16_bf16 v[98:113], v[188:191], v[142:145], v[98:113]
	ds_read_b128 v[188:191], v204 offset:0x3000
	ds_read_b128 v[200:203], v204 offset:0x3400
	ds_read_b128 v[210:213], v204 offset:0x3800
	ds_read_b128 v[214:217], v204 offset:0x3c00
	s_waitcnt lgkmcnt(4)
	ds_read_b128 v[178:181], v204 offset:0x4000
	ds_read_b128 v[174:177], v204 offset:0x4400
	ds_read_b128 v[170:173], v204 offset:0x4800
	s_nop 0
	v_mfma_f32_32x32x16_bf16 v[98:113], v[90:93], v[146:149], v[98:113]
	v_mfma_f32_32x32x16_bf16 v[98:113], v[94:97], v[150:153], v[98:113]
	v_mfma_f32_32x32x16_bf16 v[98:113], v[162:165], v[154:157], v[98:113]
	v_mfma_f32_32x32x16_bf16 v[98:113], v[166:169], v[158:161], v[98:113]
	ds_read_b128 v[166:169], v204 offset:0x4c00
	s_waitcnt lgkmcnt(4)
	ds_read_b128 v[12:15], v204 offset:0x5000
	ds_read_b128 v[4:7], v204 offset:0x5400
	ds_read_b128 v[162:165], v204 offset:0x5800
	s_nop 11
	v_max3_f32 v9, v98, s29, v99
	v_mfma_f32_32x32x16_bf16 v[82:97], v[188:191], v[114:117], 0
	v_max3_f32 v9, v9, v100, v101
	v_max3_f32 v9, v9, v102, v103
	v_max3_f32 v9, v9, v104, v105
	v_max3_f32 v9, v9, v106, v107
	v_max3_f32 v9, v9, v108, v109
	v_max3_f32 v9, v9, v110, v111
	v_max3_f32 v9, v9, v112, v113
	v_mfma_f32_32x32x16_bf16 v[82:97], v[200:203], v[118:121], v[82:97]
	v_mul_f32_e32 v16, 0x3dd53b94, v9
	ds_bpermute_b32 v17, v206, v16
	ds_read_b128 v[8:11], v204 offset:0x5c00
	s_waitcnt lgkmcnt(0)
	v_max_f32_e32 v17, v17, v17
	v_mfma_f32_32x32x16_bf16 v[82:97], v[210:213], v[122:125], v[82:97]
	v_max_f32_e32 v16, v16, v17
	v_sub_f32_e32 v17, v16, v184
	v_cmp_ge_f32_e32 vcc, s31, v17
	s_cmp_eq_u64 vcc, exec
	v_mfma_f32_32x32x16_bf16 v[82:97], v[214:217], v[126:129], v[82:97]
	s_cbranch_scc1 .LBB0_915
	v_max_f32_e32 v16, v16, v16
	v_max_f32_e32 v17, v184, v184
	v_max_f32_e32 v17, v17, v16
	v_sub_f32_e32 v16, v184, v17
	v_exp_f32_e32 v16, v16
	v_mov_b32_e32 v184, v17
	v_mul_f32_e32 v2, v2, v16
	v_mul_f32 v80, v80, v16
	v_mul_f32 v81, v81, v16
	v_mul_f32 v78, v78, v16
	v_mul_f32 v79, v79, v16
	v_mul_f32 v76, v76, v16
	v_mul_f32 v77, v77, v16
	v_mul_f32 v74, v74, v16
	v_mul_f32 v75, v75, v16
	v_mul_f32 v72, v72, v16
	v_mul_f32 v73, v73, v16
	v_mul_f32 v70, v70, v16
	v_mul_f32 v71, v71, v16
	v_mul_f32 v68, v68, v16
	v_mul_f32 v69, v69, v16
	v_mul_f32 v66, v66, v16
	v_mul_f32 v67, v67, v16
	v_mul_f32 v64, v64, v16
	v_mul_f32 v65, v65, v16
	v_mul_f32 v62, v62, v16
	v_mul_f32 v63, v63, v16
	v_mul_f32 v60, v60, v16
	v_mul_f32 v61, v61, v16
	v_mul_f32 v58, v58, v16
	v_mul_f32 v59, v59, v16
	v_mul_f32 v56, v56, v16
	v_mul_f32 v57, v57, v16
	v_mul_f32 v54, v54, v16
	v_mul_f32 v55, v55, v16
	v_mul_f32 v52, v52, v16
	v_mul_f32 v53, v53, v16
	v_mul_f32 v50, v50, v16
	v_mul_f32 v51, v51, v16
	v_mul_f32 v48, v48, v16
	v_mul_f32 v49, v49, v16
	v_mul_f32 v46, v46, v16
	v_mul_f32 v47, v47, v16
	v_mul_f32 v44, v44, v16
	v_mul_f32 v45, v45, v16
	v_mul_f32 v42, v42, v16
	v_mul_f32 v43, v43, v16
	v_mul_f32 v40, v40, v16
	v_mul_f32 v41, v41, v16
	v_mul_f32 v38, v38, v16
	v_mul_f32 v39, v39, v16
	v_mul_f32 v36, v36, v16
	v_mul_f32 v37, v37, v16
	v_mul_f32 v34, v34, v16
	v_mul_f32 v35, v35, v16
	v_mul_f32 v32, v32, v16
	v_mul_f32 v33, v33, v16
	v_mul_f32 v30, v30, v16
	v_mul_f32 v31, v31, v16
	v_mul_f32 v28, v28, v16
	v_mul_f32 v29, v29, v16
	v_mul_f32 v26, v26, v16
	v_mul_f32 v27, v27, v16
	v_mul_f32 v24, v24, v16
	v_mul_f32 v25, v25, v16
	v_mul_f32 v22, v22, v16
	v_mul_f32 v23, v23, v16
	v_mul_f32 v20, v20, v16
	v_mul_f32 v21, v21, v16
	v_mul_f32 v18, v18, v16
	v_mul_f32 v19, v19, v16

.LBB0_918:
	ds_bpermute_b32 v2, v206, v150
	v_readlane_b32 s0, v248, 44
	s_lshl_b32 s2, s0, 11
	v_readlane_b32 s90, v248, 42
	v_readlane_b32 s3, v248, 43
	s_waitcnt lgkmcnt(0)
	v_add_f32_e32 v2, v150, v2
	v_div_scale_f32 v4, s[0:1], v2, v2, 1.0
	v_rcp_f32_e32 v5, v4
	v_readlane_b32 s0, v248, 45
	s_or_b32 s0, s0, s2
	s_add_i32 s3, s3, s90
	v_fma_f32 v6, -v4, v5, 1.0
	v_fmac_f32_e32 v5, v6, v5
	v_div_scale_f32 v6, vcc, 1.0, v2, 1.0
	v_mul_f32_e32 v7, v6, v5
	v_fma_f32 v8, -v4, v7, v6
	v_fmac_f32_e32 v7, v8, v5
	v_fma_f32 v4, -v4, v7, v6
	v_div_fmas_f32 v4, v4, v5, v7
	v_div_fixup_f32 v4, v4, v2, 1.0
	v_mov_b32_e32 v2, v1
	v_mul_f32 v6, v66, v4
	v_mul_f32 v7, v67, v4
	v_mul_f32 v8, v68, v4
	v_mul_f32 v9, v69, v4
	v_lshl_add_u32 v2, v2, 11, s0
	v_cvt_pk_bf16_f32 v6, v6, v7
	v_cvt_pk_bf16_f32 v7, v8, v9
	v_mul_f32 v8, v70, v4
	v_mul_f32 v9, v71, v4
	v_mul_f32 v12, v72, v4
	v_mul_f32 v13, v73, v4
	v_or_b32_e32 v2, 0x400, v2
	v_cvt_pk_bf16_f32 v8, v8, v9
	v_cvt_pk_bf16_f32 v9, v12, v13
	v_lshl_add_u64 v[10:11], v[2:3], 1, v[198:199]
	v_permlane32_swap_b32_e32 v6, v8
	v_permlane32_swap_b32_e32 v7, v9
	global_store_dwordx4 v[10:11], v[6:9], off
	v_mul_f32 v12, v80, v4
	v_mul_f32 v13, v81, v4
	s_cmpk_gt_i32 s3, 0xff
	v_mul_f32 v6, v74, v4
	v_mul_f32 v7, v75, v4
	v_mul_f32 v8, v76, v4
	v_mul_f32 v9, v77, v4
	v_cvt_pk_bf16_f32 v6, v6, v7
	v_cvt_pk_bf16_f32 v7, v8, v9
	v_mul_f32 v8, v78, v4
	v_mul_f32 v9, v79, v4
	s_nop 0
	v_cvt_pk_bf16_f32 v8, v8, v9
	v_cvt_pk_bf16_f32 v9, v12, v13
	s_nop 0
	v_permlane32_swap_b32_e32 v6, v8
	v_permlane32_swap_b32_e32 v7, v9
	global_store_dwordx4 v[10:11], v[6:9], off offset:32
	v_mul_f32 v12, v56, v4
	v_mul_f32 v13, v57, v4
	s_nop 0
	v_mul_f32 v6, v50, v4
	v_mul_f32 v7, v51, v4
	v_mul_f32 v8, v52, v4
	v_mul_f32 v9, v53, v4
	v_cvt_pk_bf16_f32 v6, v6, v7
	v_cvt_pk_bf16_f32 v7, v8, v9
	v_mul_f32 v8, v54, v4
	v_mul_f32 v9, v55, v4
	s_nop 0
	v_cvt_pk_bf16_f32 v8, v8, v9
	v_cvt_pk_bf16_f32 v9, v12, v13
	s_nop 0
	v_permlane32_swap_b32_e32 v6, v8
	v_permlane32_swap_b32_e32 v7, v9
	global_store_dwordx4 v[10:11], v[6:9], off offset:64
	v_mul_f32 v12, v64, v4
	v_mul_f32 v13, v65, v4
	s_nop 0
	v_mul_f32 v6, v58, v4
	v_mul_f32 v7, v59, v4
	v_mul_f32 v8, v60, v4
	v_mul_f32 v9, v61, v4
	v_cvt_pk_bf16_f32 v6, v6, v7
	v_cvt_pk_bf16_f32 v7, v8, v9
	v_mul_f32 v8, v62, v4
	v_mul_f32 v9, v63, v4
	s_nop 0
	v_cvt_pk_bf16_f32 v8, v8, v9
	v_cvt_pk_bf16_f32 v9, v12, v13
	s_nop 0
	v_permlane32_swap_b32_e32 v6, v8
	v_permlane32_swap_b32_e32 v7, v9
	global_store_dwordx4 v[10:11], v[6:9], off offset:96
	v_mul_f32 v12, v40, v4
	v_mul_f32 v13, v41, v4
	s_nop 0
	v_mul_f32 v6, v34, v4
	v_mul_f32 v7, v35, v4
	v_mul_f32 v8, v36, v4
	v_mul_f32 v9, v37, v4
	v_cvt_pk_bf16_f32 v6, v6, v7
	v_cvt_pk_bf16_f32 v7, v8, v9
	v_mul_f32 v8, v38, v4
	v_mul_f32 v9, v39, v4
	s_nop 0
	v_cvt_pk_bf16_f32 v8, v8, v9
	v_cvt_pk_bf16_f32 v9, v12, v13
	s_nop 0
	v_permlane32_swap_b32_e32 v6, v8
	v_permlane32_swap_b32_e32 v7, v9
	global_store_dwordx4 v[10:11], v[6:9], off offset:128
	v_mul_f32 v12, v48, v4
	v_mul_f32 v13, v49, v4
	s_nop 0
	v_mul_f32 v6, v42, v4
	v_mul_f32 v7, v43, v4
	v_mul_f32 v8, v44, v4
	v_mul_f32 v9, v45, v4
	v_cvt_pk_bf16_f32 v6, v6, v7
	v_cvt_pk_bf16_f32 v7, v8, v9
	v_mul_f32 v8, v46, v4
	v_mul_f32 v9, v47, v4
	s_nop 0
	v_cvt_pk_bf16_f32 v8, v8, v9
	v_cvt_pk_bf16_f32 v9, v12, v13
	s_nop 0
	v_permlane32_swap_b32_e32 v6, v8
	v_permlane32_swap_b32_e32 v7, v9
	global_store_dwordx4 v[10:11], v[6:9], off offset:160
	v_mul_f32 v12, v24, v4
	v_mul_f32 v13, v25, v4
	s_nop 0
	v_mul_f32 v6, v18, v4
	v_mul_f32 v7, v19, v4
	v_mul_f32 v8, v20, v4
	v_mul_f32 v9, v21, v4
	v_cvt_pk_bf16_f32 v6, v6, v7
	v_cvt_pk_bf16_f32 v7, v8, v9
	v_mul_f32 v8, v22, v4
	v_mul_f32 v9, v23, v4
	s_nop 0
	v_cvt_pk_bf16_f32 v8, v8, v9
	v_cvt_pk_bf16_f32 v9, v12, v13
	s_nop 0
	v_permlane32_swap_b32_e32 v6, v8
	v_permlane32_swap_b32_e32 v7, v9
	global_store_dwordx4 v[10:11], v[6:9], off offset:192
	s_nop 1
	v_mul_f32 v6, v26, v4
	v_mul_f32 v7, v27, v4
	v_mul_f32 v8, v28, v4
	v_mul_f32 v9, v29, v4
	v_cvt_pk_bf16_f32 v6, v6, v7
	v_cvt_pk_bf16_f32 v7, v8, v9
	v_mul_f32 v8, v30, v4
	v_mul_f32 v9, v31, v4
	v_mul_f32 v5, v33, v4
	v_mul_f32 v4, v32, v4
	v_cvt_pk_bf16_f32 v8, v8, v9
	v_cvt_pk_bf16_f32 v9, v4, v5
	s_nop 0
	v_permlane32_swap_b32_e32 v6, v8
	v_permlane32_swap_b32_e32 v7, v9
	global_store_dwordx4 v[10:11], v[6:9], off offset:224
	s_cbranch_scc1 .LBB0_1001

.LBB0_939:
	ds_read_b128 v[82:85], v195 offset:0
	ds_read_b128 v[86:89], v195 offset:0x400
	ds_read_b128 v[146:149], v195 offset:0x800
	ds_read_b128 v[152:155], v195 offset:0xc00
	ds_read_b128 v[156:159], v195 offset:0x1000
	ds_read_b128 v[160:163], v195 offset:0x1400
	ds_read_b128 v[164:167], v195 offset:0x1800
	ds_read_b128 v[168:171], v195 offset:0x1c00
	ds_read_b128 v[172:175], v195 offset:0x2000
	ds_read_b128 v[176:179], v195 offset:0x2400
	ds_read_b128 v[180:183], v195 offset:0x2800
	ds_read_b128 v[142:145], v195 offset:0x2c00
	ds_read_b128 v[138:141], v195 offset:0x3000
	ds_read_b128 v[12:15], v195 offset:0x3400
	ds_read_b128 v[8:11], v195 offset:0x3800
	ds_read_b128 v[4:7], v195 offset:0x3c00
	s_nop 0
	s_waitcnt lgkmcnt(8)
	s_and_b64 s[74:75], exec, s[72:73]
	v_mfma_f32_32x32x16_bf16 v[90:105], v[82:85], v[106:109], 0
	s_cselect_b32 s5, 0, s67
	s_sub_i32 s5, s5, s94
	v_med3_i32 v2, s5, -7, 7
	s_movk_i32 s5, 0x7c
	v_mul_lo_u32 v2, v2, s5
	v_add_u32_e32 v2, 0, v2
	v_add_u32_e32 v2, 0x20200, v2
	v_mfma_f32_32x32x16_bf16 v[90:105], v[86:89], v[110:113], v[90:105]
	s_waitcnt lgkmcnt(0)
	v_readlane_b32 s74, v248, 10
	v_readlane_b32 s75, v248, 11
	v_mfma_f32_32x32x16_bf16 v[90:105], v[146:149], v[114:117], v[90:105]
	v_lshl_add_u32 v147, v187, 2, v2
	v_lshl_add_u32 v149, v213, 2, v2
	ds_read_b32 v149, v149 offset:1000
	v_mfma_f32_32x32x16_bf16 v[90:105], v[152:155], v[118:121], v[90:105]
	ds_read_b32 v154, v147 offset:928
	v_lshl_add_u32 v147, v188, 2, v2
	ds_read_b32 v155, v147 offset:932
	v_mfma_f32_32x32x16_bf16 v[90:105], v[156:159], v[122:125], v[90:105]
	v_lshl_add_u32 v159, v214, 2, v2
	v_mfma_f32_32x32x16_bf16 v[90:105], v[160:163], v[126:129], v[90:105]
	ds_read_b32 v163, v159 offset:1004
	v_lshl_add_u32 v147, v189, 2, v2
	v_lshl_add_u32 v159, v215, 2, v2
	ds_read_b32 v156, v147 offset:936
	v_mfma_f32_32x32x16_bf16 v[90:105], v[164:167], v[130:133], v[90:105]
	ds_read_b32 v165, v159 offset:1024
	v_lshl_add_u32 v147, v190, 2, v2
	v_lshl_add_u32 v159, v216, 2, v2
	ds_read_b32 v158, v147 offset:940
	ds_read_b32 v167, v159 offset:1028
	v_lshl_add_u32 v147, v191, 2, v2
	v_lshl_add_u32 v159, v217, 2, v2
	v_mfma_f32_32x32x16_bf16 v[90:105], v[168:171], v[134:137], v[90:105]
	ds_read_b32 v160, v147 offset:960
	ds_read_b32 v169, v159 offset:1032
	v_lshl_add_u32 v147, v200, 2, v2
	v_lshl_add_u32 v159, v218, 2, v2
	ds_read_b32 v162, v147 offset:964
	ds_read_b32 v171, v159 offset:1036
	v_lshl_add_u32 v147, v201, 2, v2
	s_nop 4
	v_mul_f32_e32 v16, 0x3e0293ee, v90
	s_waitcnt lgkmcnt(0)
	v_fmamk_f32 v154, v154, 0x3fb8aa3b, v16
	v_mul_f32_e32 v17, 0x3e0293ee, v91
	v_cndmask_b32_e64 v154, v235, v154, s[74:75]
	v_readlane_b32 s74, v248, 12
	v_cndmask_b32_e64 v159, v154, v16, s[72:73]
	v_fmamk_f32 v16, v155, 0x3fb8aa3b, v17
	v_readlane_b32 s75, v248, 13
	v_mul_f32_e32 v146, 0x3e0293ee, v92
	v_mul_f32_e32 v148, 0x3e0293ee, v93
	v_cndmask_b32_e64 v16, v235, v16, s[74:75]
	v_readlane_b32 s74, v248, 14
	v_cndmask_b32_e64 v161, v16, v17, s[72:73]
	v_fmamk_f32 v16, v156, 0x3fb8aa3b, v146
	v_readlane_b32 s75, v248, 15
	v_mul_f32_e32 v151, 0x3e0293ee, v94
	ds_read_b32 v164, v147 offset:968
	v_cndmask_b32_e64 v16, v235, v16, s[74:75]
	v_readlane_b32 s74, v248, 16
	v_cndmask_b32_e64 v154, v16, v146, s[72:73]
	v_fmamk_f32 v16, v158, 0x3fb8aa3b, v148
	v_readlane_b32 s75, v248, 17
	v_lshl_add_u32 v147, v202, 2, v2
	v_mul_f32_e32 v152, 0x3e0293ee, v95
	v_cndmask_b32_e64 v16, v235, v16, s[74:75]
	v_readlane_b32 s74, v248, 18
	v_cndmask_b32_e64 v156, v16, v148, s[72:73]
	v_fmamk_f32 v16, v160, 0x3fb8aa3b, v151
	v_readlane_b32 s75, v248, 19
	ds_read_b32 v166, v147 offset:972
	v_lshl_add_u32 v147, v203, 2, v2
	v_cndmask_b32_e64 v16, v235, v16, s[74:75]
	v_readlane_b32 s74, v248, 20
	v_cndmask_b32_e64 v155, v16, v151, s[72:73]
	v_fmamk_f32 v16, v162, 0x3fb8aa3b, v152
	v_readlane_b32 s75, v248, 21
	v_mul_f32_e32 v153, 0x3e0293ee, v96
	ds_read_b32 v168, v147 offset:992
	v_cndmask_b32_e64 v16, v235, v16, s[74:75]
	v_readlane_b32 s74, v248, 22
	v_cndmask_b32_e64 v152, v16, v152, s[72:73]
	s_waitcnt lgkmcnt(0)
	v_fmamk_f32 v16, v164, 0x3fb8aa3b, v153
	v_readlane_b32 s75, v248, 23
	v_mul_f32_e32 v157, 0x3e0293ee, v97
	v_lshl_add_u32 v147, v212, 2, v2
	v_cndmask_b32_e64 v16, v235, v16, s[74:75]
	v_readlane_b32 s74, v248, 24
	ds_read_b32 v147, v147 offset:996
	v_fmamk_f32 v17, v166, 0x3fb8aa3b, v157
	v_readlane_b32 s75, v248, 25
	v_mul_f32_e32 v98, 0x3e0293ee, v98
	v_fmamk_f32 v146, v168, 0x3fb8aa3b, v98
	v_cndmask_b32_e64 v17, v235, v17, s[74:75]
	v_readlane_b32 s74, v248, 26
	v_readlane_b32 s75, v248, 27
	v_mov_b32_e32 v148, v100
	v_cndmask_b32_e64 v16, v16, v153, s[72:73]
	v_cndmask_b32_e64 v146, v235, v146, s[74:75]
	v_cndmask_b32_e64 v151, v146, v98, s[72:73]
	v_mov_b32_e32 v146, v99
	s_waitcnt lgkmcnt(0)
	v_mul_f32 v98, s68, v146
	v_mul_f32 v99, s69, v147
	v_readlane_b32 s74, v248, 28
	v_add_f32_e32 v99, v98, v99
	v_readlane_b32 s75, v248, 29
	v_mov_b32_e32 v162, v101
	v_cndmask_b32_e64 v17, v17, v157, s[72:73]
	v_cndmask_b32_e64 v99, v235, v99, s[74:75]
	v_cndmask_b32_e64 v153, v99, v98, s[72:73]
	v_mul_f32 v98, s68, v148
	v_mul_f32 v99, s69, v149
	v_mfma_f32_32x32x16_bf16 v[82:97], v[172:175], v[106:109], 0
	v_add_f32_e32 v99, v98, v99
	v_cndmask_b32_e64 v99, v235, v99, s[20:21]
	v_cndmask_b32_e64 v157, v99, v98, s[72:73]
	v_mul_f32_e64 v98, v162, s68
	v_mul_f32_e64 v99, v163, s69
	v_mov_b32_e32 v164, v102
	v_add_f32_e32 v99, v98, v99
	v_cndmask_b32_e64 v99, v235, v99, s[22:23]
	v_cndmask_b32_e64 v158, v99, v98, s[72:73]
	v_mul_f32 v98, s68, v164
	v_mul_f32 v99, s69, v165
	v_mov_b32_e32 v166, v103
	v_add_f32_e32 v99, v98, v99
	v_cndmask_b32_e64 v99, v235, v99, s[24:25]
	v_cndmask_b32_e64 v160, v99, v98, s[72:73]
	v_mul_f32 v98, s68, v166
	v_mul_f32 v99, s69, v167
	v_mov_b32_e32 v168, v104
	v_add_f32_e32 v99, v98, v99
	v_cndmask_b32_e64 v99, v235, v99, s[26:27]
	v_mfma_f32_32x32x16_bf16 v[82:97], v[176:179], v[110:113], v[82:97]
	v_cndmask_b32_e64 v162, v99, v98, s[72:73]
	v_mul_f32_e64 v98, v168, s68
	v_mul_f32_e64 v99, v169, s69
	v_mov_b32_e32 v170, v105
	v_add_f32_e32 v99, v98, v99
	v_cndmask_b32_e64 v99, v235, v99, s[28:29]
	v_cndmask_b32_e64 v163, v99, v98, s[72:73]
	v_mul_f32 v98, s68, v170
	v_mul_f32 v99, s69, v171
	v_mfma_f32_32x32x16_bf16 v[82:97], v[180:183], v[114:117], v[82:97]
	v_add_f32_e32 v99, v98, v99
	v_cndmask_b32_e64 v99, v235, v99, s[30:31]
	v_cndmask_b32_e64 v164, v99, v98, s[72:73]
	v_max3_f32 v98, v159, s92, v161
	v_max3_f32 v98, v98, v154, v156
	v_max3_f32 v98, v98, v155, v152
	v_max3_f32 v98, v98, v16, v17
	v_max3_f32 v98, v98, v151, v153
	v_max3_f32 v98, v98, v157, v158
	v_max3_f32 v98, v98, v160, v162
	v_max3_f32 v98, v98, v163, v164
	ds_bpermute_b32 v99, v206, v98
	v_mfma_f32_32x32x16_bf16 v[82:97], v[142:145], v[118:121], v[82:97]
	s_waitcnt lgkmcnt(0)
	v_max_f32_e32 v99, v99, v99
	v_max_f32_e32 v98, v98, v99
	v_sub_f32_e32 v99, v98, v236
	v_cmp_ge_f32_e32 vcc, s93, v99
	s_cmp_eq_u64 vcc, exec
	s_cbranch_scc1 .LBB0_941
	v_max_f32_e32 v98, v98, v98
	v_max_f32_e32 v99, v236, v236
	v_max_f32_e32 v99, v99, v98
	v_sub_f32_e32 v98, v236, v99
	v_exp_f32_e32 v98, v98
	v_mov_b32_e32 v236, v99
	v_mul_f32_e32 v150, v150, v98
	v_mul_f32 v80, v80, v98
	v_mul_f32 v81, v81, v98
	v_mul_f32 v78, v78, v98
	v_mul_f32 v79, v79, v98
	v_mul_f32 v76, v76, v98
	v_mul_f32 v77, v77, v98
	v_mul_f32 v74, v74, v98
	v_mul_f32 v75, v75, v98
	v_mul_f32 v72, v72, v98
	v_mul_f32 v73, v73, v98
	v_mul_f32 v70, v70, v98
	v_mul_f32 v71, v71, v98
	v_mul_f32 v68, v68, v98
	v_mul_f32 v69, v69, v98
	v_mul_f32 v66, v66, v98
	v_mul_f32 v67, v67, v98
	v_mul_f32 v64, v64, v98
	v_mul_f32 v65, v65, v98
	v_mul_f32 v62, v62, v98
	v_mul_f32 v63, v63, v98
	v_mul_f32 v60, v60, v98
	v_mul_f32 v61, v61, v98
	v_mul_f32 v58, v58, v98
	v_mul_f32 v59, v59, v98
	v_mul_f32 v56, v56, v98
	v_mul_f32 v57, v57, v98
	v_mul_f32 v54, v54, v98
	v_mul_f32 v55, v55, v98
	v_mul_f32 v52, v52, v98
	v_mul_f32 v53, v53, v98
	v_mul_f32 v50, v50, v98
	v_mul_f32 v51, v51, v98
	v_mul_f32 v48, v48, v98
	v_mul_f32 v49, v49, v98
	v_mul_f32 v46, v46, v98
	v_mul_f32 v47, v47, v98
	v_mul_f32 v44, v44, v98
	v_mul_f32 v45, v45, v98
	v_mul_f32 v42, v42, v98
	v_mul_f32 v43, v43, v98
	v_mul_f32 v40, v40, v98
	v_mul_f32 v41, v41, v98
	v_mul_f32 v38, v38, v98
	v_mul_f32 v39, v39, v98
	v_mul_f32 v36, v36, v98
	v_mul_f32 v37, v37, v98
	v_mul_f32 v34, v34, v98
	v_mul_f32 v35, v35, v98
	v_mul_f32 v32, v32, v98
	v_mul_f32 v33, v33, v98
	v_mul_f32 v30, v30, v98
	v_mul_f32 v31, v31, v98
	v_mul_f32 v28, v28, v98
	v_mul_f32 v29, v29, v98
	v_mul_f32 v26, v26, v98
	v_mul_f32 v27, v27, v98
	v_mul_f32 v24, v24, v98
	v_mul_f32 v25, v25, v98
	v_mul_f32 v22, v22, v98
	v_mul_f32 v23, v23, v98
	v_mul_f32 v20, v20, v98
	v_mul_f32 v21, v21, v98
	v_mul_f32 v18, v18, v98
	v_mul_f32 v19, v19, v98
.LBB0_941:
	v_sub_f32_e32 v159, v159, v236
	v_mfma_f32_32x32x16_bf16 v[82:97], v[138:141], v[122:125], v[82:97]
	v_exp_f32_e32 v159, v159
	v_sub_f32_e32 v161, v161, v236
	v_exp_f32_e32 v161, v161
	v_sub_f32_e32 v154, v154, v236
	v_exp_f32_e32 v154, v154
	v_sub_f32_e32 v156, v156, v236
	v_exp_f32_e32 v156, v156
	v_sub_f32_e32 v155, v155, v236
	v_add_f32_e32 v165, 0, v159
	v_exp_f32_e32 v155, v155
	v_sub_f32_e32 v152, v152, v236
	v_add_f32_e32 v165, v161, v165
	v_exp_f32_e32 v152, v152
	v_sub_f32_e32 v16, v16, v236
	v_add_f32_e32 v165, v154, v165
	v_exp_f32_e32 v166, v16
	v_add_f32_e32 v165, v156, v165
	v_mfma_f32_32x32x16_bf16 v[82:97], v[12:15], v[126:129], v[82:97]
	v_add_f32_e32 v165, v155, v165
	v_add_f32_e32 v165, v152, v165
	v_sub_f32_e32 v17, v17, v236
	v_add_f32_e32 v16, v166, v165
	v_exp_f32_e32 v165, v17
	ds_read_b128 v[182:185], v195 offset:0x4000
	ds_read_b128 v[170:173], v195 offset:0x4400
	v_mfma_f32_32x32x16_bf16 v[82:97], v[8:11], v[130:133], v[82:97]
	v_add_f32_e32 v17, v165, v16
	v_sub_f32_e32 v16, v151, v236
	v_exp_f32_e32 v16, v16
	ds_read_b128 v[174:177], v195 offset:0x4800
	ds_read_b128 v[178:181], v195 offset:0x4c00
	ds_read_b128 v[146:149], v195 offset:0x5000
	ds_read_b128 v[142:145], v195 offset:0x5400
	v_mfma_f32_32x32x16_bf16 v[82:97], v[4:7], v[134:137], v[82:97]
	v_add_f32_e32 v151, v16, v17
	v_sub_f32_e32 v17, v153, v236
	v_exp_f32_e32 v17, v17
	v_sub_f32_e32 v153, v157, v236
	v_exp_f32_e32 v237, v153
	v_sub_f32_e32 v153, v158, v236
	v_exp_f32_e32 v238, v153
	v_sub_f32_e32 v153, v160, v236
	v_exp_f32_e32 v239, v153
	v_sub_f32_e32 v153, v162, v236
	v_add_f32_e32 v151, v17, v151
	v_exp_f32_e32 v240, v153
	v_sub_f32_e32 v153, v163, v236
	v_add_f32_e32 v151, v237, v151
	v_exp_f32_e32 v241, v153
	v_sub_f32_e32 v153, v164, v236
	v_add_f32_e32 v151, v238, v151
	v_exp_f32_e32 v242, v153
	v_add_f32_e32 v151, v239, v151
	v_add_f32_e32 v151, v240, v151
	v_add_f32_e32 v151, v241, v151
	ds_read_b128 v[102:105], v195 offset:0x5800
	ds_read_b128 v[98:101], v195 offset:0x5c00
	v_add_f32_e32 v151, v242, v151
	v_lshl_add_u32 v5, v219, 2, v2
	v_lshl_add_u32 v7, v229, 2, v2
	v_add_f32_e32 v243, v150, v151
	v_cvt_pk_bf16_f32 v244, v159, v161
	v_cvt_pk_bf16_f32 v245, v154, v156
	v_cvt_pk_bf16_f32 v246, v155, v152
	v_cvt_pk_bf16_f32 v247, v166, v165
	ds_read_b128 v[166:169], v195 offset:0x6000
	ds_read_b128 v[162:165], v195 offset:0x6400
	ds_read_b128 v[158:161], v195 offset:0x6800
	ds_read_b128 v[154:157], v195 offset:0x6c00
	ds_read_b128 v[150:153], v195 offset:0x7000
	ds_read_b128 v[138:141], v195 offset:0x7400
	ds_read_b128 v[12:15], v195 offset:0x7800
	ds_read_b128 v[8:11], v195 offset:0x7c00
	s_waitcnt lgkmcnt(8)
	v_mul_f32_e32 v4, 0x3e0293ee, v82
	v_mul_f32_e32 v6, 0x3e0293ee, v83
	v_mul_f32_e32 v82, 0x3e0293ee, v84
	v_mul_f32_e32 v84, 0x3e0293ee, v85
	ds_read_b32 v85, v5 offset:928
	ds_read_b32 v7, v7 offset:1000
	v_lshl_add_u32 v5, v220, 2, v2
	v_lshl_add_u32 v83, v230, 2, v2
	v_mfma_f32_32x32x16_bf16 v[50:65], v[170:173], v[244:247], v[50:65]
	v_mul_f32_e32 v170, 0x3e0293ee, v86
	ds_read_b32 v86, v5 offset:932
	ds_read_b32 v83, v83 offset:1004
	v_lshl_add_u32 v5, v221, 2, v2
	v_lshl_add_u32 v171, v231, 2, v2
	v_mul_f32_e32 v172, 0x3e0293ee, v87
	ds_read_b32 v87, v5 offset:936
	ds_read_b32 v173, v171 offset:1024
	v_lshl_add_u32 v5, v222, 2, v2
	v_lshl_add_u32 v171, v232, 2, v2
	v_mfma_f32_32x32x16_bf16 v[34:49], v[174:177], v[244:247], v[34:49]
	v_mul_f32_e32 v174, 0x3e0293ee, v88
	ds_read_b32 v88, v5 offset:940
	ds_read_b32 v175, v171 offset:1028
	v_lshl_add_u32 v5, v223, 2, v2
	v_lshl_add_u32 v171, v233, 2, v2
	v_mul_f32_e32 v176, 0x3e0293ee, v89
	ds_read_b32 v89, v5 offset:960
	ds_read_b32 v177, v171 offset:1032
	v_lshl_add_u32 v5, v224, 2, v2
	v_mfma_f32_32x32x16_bf16 v[18:33], v[178:181], v[244:247], v[18:33]
	v_mul_f32_e32 v178, 0x3e0293ee, v90
	ds_read_b32 v90, v5 offset:964
	v_lshl_add_u32 v5, v225, 2, v2
	ds_read_b32 v180, v5 offset:968
	v_lshl_add_u32 v5, v226, 2, v2
	ds_read_b32 v181, v5 offset:972
	v_lshl_add_u32 v5, v227, 2, v2
	v_mfma_f32_32x32x16_bf16 v[66:81], v[182:185], v[244:247], v[66:81]
	ds_read_b32 v182, v5 offset:992
	v_lshl_add_u32 v5, v228, 2, v2
	v_lshl_add_u32 v2, v234, 2, v2
	ds_read_b32 v5, v5 offset:996
	ds_read_b32 v179, v2 offset:1036
	s_waitcnt lgkmcnt(0)
	v_fmamk_f32 v2, v85, 0x3fb8aa3b, v4
	v_cndmask_b32_e64 v2, v235, v2, s[34:35]
	v_cndmask_b32_e64 v171, v2, v4, s[72:73]
	v_fmamk_f32 v2, v86, 0x3fb8aa3b, v6
	v_cndmask_b32_e64 v2, v235, v2, s[36:37]
	v_cndmask_b32_e64 v85, v2, v6, s[72:73]
	v_fmamk_f32 v2, v87, 0x3fb8aa3b, v82
	v_cndmask_b32_e64 v2, v235, v2, s[38:39]
	v_mov_b32_e32 v4, v91
	v_cndmask_b32_e64 v86, v2, v82, s[72:73]
	v_fmamk_f32 v2, v88, 0x3fb8aa3b, v84
	v_mul_f32 v4, s68, v4
	v_mul_f32 v5, s69, v5
	v_cndmask_b32_e64 v2, v235, v2, s[40:41]
	v_add_f32_e32 v5, v4, v5
	v_mov_b32_e32 v6, v92
	v_cndmask_b32_e64 v87, v2, v84, s[72:73]
	v_fmamk_f32 v2, v89, 0x3fb8aa3b, v170
	v_cndmask_b32_e64 v5, v235, v5, s[6:7]
	v_mul_f32 v6, s68, v6
	v_mul_f32 v7, s69, v7
	v_cndmask_b32_e64 v2, v235, v2, s[42:43]
	v_cndmask_b32_e64 v4, v5, v4, s[72:73]
	v_add_f32_e32 v5, v6, v7
	v_cndmask_b32_e64 v88, v2, v170, s[72:73]
	v_fmamk_f32 v2, v90, 0x3fb8aa3b, v172
	v_cndmask_b32_e64 v5, v235, v5, s[8:9]
	v_mov_b32_e32 v82, v93
	v_cndmask_b32_e64 v2, v235, v2, s[44:45]
	v_cndmask_b32_e64 v5, v5, v6, s[72:73]
	v_mul_f32 v6, s68, v82
	v_mul_f32 v7, s69, v83
	v_cndmask_b32_e64 v89, v2, v172, s[72:73]
	v_add_f32_e32 v7, v6, v7
	v_mov_b32_e32 v172, v94
	v_fmamk_f32 v2, v180, 0x3fb8aa3b, v174
	v_cndmask_b32_e64 v7, v235, v7, s[10:11]
	v_mul_f32 v82, s68, v172
	v_mul_f32 v83, s69, v173
	v_cndmask_b32_e64 v2, v235, v2, s[46:47]
	v_cndmask_b32_e64 v6, v7, v6, s[72:73]
	v_add_f32_e32 v7, v82, v83
	v_cndmask_b32_e64 v90, v2, v174, s[72:73]
	v_fmamk_f32 v2, v181, 0x3fb8aa3b, v176
	v_cndmask_b32_e64 v7, v235, v7, s[12:13]
	v_mov_b32_e32 v174, v95
	v_cndmask_b32_e64 v2, v235, v2, s[48:49]
	v_cndmask_b32_e64 v7, v7, v82, s[72:73]
	v_mul_f32 v82, s68, v174
	v_mul_f32 v83, s69, v175
	v_cndmask_b32_e64 v170, v2, v176, s[72:73]
	v_add_f32_e32 v83, v82, v83
	v_mov_b32_e32 v176, v96
	v_fmamk_f32 v2, v182, 0x3fb8aa3b, v178
	v_cndmask_b32_e64 v83, v235, v83, s[14:15]
	v_mul_f32 v92, s68, v176
	v_mul_f32 v93, s69, v177
	v_max3_f32 v91, v171, s92, v85
	v_cndmask_b32_e64 v2, v235, v2, s[50:51]
	v_cndmask_b32_e64 v82, v83, v82, s[72:73]
	v_add_f32_e32 v83, v92, v93
	v_max3_f32 v91, v91, v86, v87
	v_cndmask_b32_e64 v2, v2, v178, s[72:73]
	v_cndmask_b32_e64 v83, v235, v83, s[16:17]
	v_mov_b32_e32 v178, v97
	v_max3_f32 v91, v91, v88, v89
	v_cndmask_b32_e64 v83, v83, v92, s[72:73]
	v_mul_f32 v92, s68, v178
	v_mul_f32 v93, s69, v179
	v_max3_f32 v91, v91, v90, v170
	v_add_f32_e32 v84, v92, v93
	v_max3_f32 v91, v91, v2, v4
	v_cndmask_b32_e64 v84, v235, v84, s[18:19]
	v_max3_f32 v91, v91, v5, v6
	v_cndmask_b32_e64 v84, v84, v92, s[72:73]
	v_max3_f32 v91, v91, v7, v82
	v_max3_f32 v91, v91, v83, v84
	ds_bpermute_b32 v92, v206, v91
	s_waitcnt lgkmcnt(0)
	v_max_f32_e32 v92, v92, v92
	v_max_f32_e32 v91, v91, v92
	v_sub_f32_e32 v92, v91, v236
	v_cmp_ge_f32_e32 vcc, s93, v92
	s_cmp_eq_u64 vcc, exec
	s_cbranch_scc1 .LBB0_943
	v_max_f32_e32 v91, v91, v91
	v_max_f32_e32 v92, v236, v236
	v_max_f32_e32 v91, v92, v91
	v_sub_f32_e32 v92, v236, v91
	v_exp_f32_e32 v92, v92
	v_mov_b32_e32 v236, v91
	v_mul_f32_e32 v243, v243, v92
	v_mul_f32 v80, v80, v92
	v_mul_f32 v81, v81, v92
	v_mul_f32 v78, v78, v92
	v_mul_f32 v79, v79, v92
	v_mul_f32 v76, v76, v92
	v_mul_f32 v77, v77, v92
	v_mul_f32 v74, v74, v92
	v_mul_f32 v75, v75, v92
	v_mul_f32 v72, v72, v92
	v_mul_f32 v73, v73, v92
	v_mul_f32 v70, v70, v92
	v_mul_f32 v71, v71, v92
	v_mul_f32 v68, v68, v92
	v_mul_f32 v69, v69, v92
	v_mul_f32 v66, v66, v92
	v_mul_f32 v67, v67, v92
	v_mul_f32 v64, v64, v92
	v_mul_f32 v65, v65, v92
	v_mul_f32 v62, v62, v92
	v_mul_f32 v63, v63, v92
	v_mul_f32 v60, v60, v92
	v_mul_f32 v61, v61, v92
	v_mul_f32 v58, v58, v92
	v_mul_f32 v59, v59, v92
	v_mul_f32 v56, v56, v92
	v_mul_f32 v57, v57, v92
	v_mul_f32 v54, v54, v92
	v_mul_f32 v55, v55, v92
	v_mul_f32 v52, v52, v92
	v_mul_f32 v53, v53, v92
	v_mul_f32 v50, v50, v92
	v_mul_f32 v51, v51, v92
	v_mul_f32 v48, v48, v92
	v_mul_f32 v49, v49, v92
	v_mul_f32 v46, v46, v92
	v_mul_f32 v47, v47, v92
	v_mul_f32 v44, v44, v92
	v_mul_f32 v45, v45, v92
	v_mul_f32 v42, v42, v92
	v_mul_f32 v43, v43, v92
	v_mul_f32 v40, v40, v92
	v_mul_f32 v41, v41, v92
	v_mul_f32 v38, v38, v92
	v_mul_f32 v39, v39, v92
	v_mul_f32 v36, v36, v92
	v_mul_f32 v37, v37, v92
	v_mul_f32 v34, v34, v92
	v_mul_f32 v35, v35, v92
	v_mul_f32 v32, v32, v92
	v_mul_f32 v33, v33, v92
	v_mul_f32 v30, v30, v92
	v_mul_f32 v31, v31, v92
	v_mul_f32 v28, v28, v92
	v_mul_f32 v29, v29, v92
	v_mul_f32 v26, v26, v92
	v_mul_f32 v27, v27, v92
	v_mul_f32 v24, v24, v92
	v_mul_f32 v25, v25, v92
	v_mul_f32 v22, v22, v92
	v_mul_f32 v23, v23, v92
	v_mul_f32 v20, v20, v92
	v_mul_f32 v21, v21, v92
	v_mul_f32 v18, v18, v92
	v_mul_f32 v19, v19, v92

.LBB0_971:
	ds_read_b128 v[82:85], v208 offset:0
	ds_read_b128 v[86:89], v208 offset:0x400
	ds_read_b128 v[146:149], v208 offset:0x800
	ds_read_b128 v[152:155], v208 offset:0xc00
	ds_read_b128 v[156:159], v208 offset:0x1000
	ds_read_b128 v[160:163], v208 offset:0x1400
	ds_read_b128 v[164:167], v208 offset:0x1800
	ds_read_b128 v[168:171], v208 offset:0x1c00
	ds_read_b128 v[172:175], v208 offset:0x2000
	ds_read_b128 v[176:179], v208 offset:0x2400
	ds_read_b128 v[180:183], v208 offset:0x2800
	ds_read_b128 v[142:145], v208 offset:0x2c00
	ds_read_b128 v[138:141], v208 offset:0x3000
	ds_read_b128 v[12:15], v208 offset:0x3400
	ds_read_b128 v[8:11], v208 offset:0x3800
	ds_read_b128 v[4:7], v208 offset:0x3c00
	s_nop 0
	s_waitcnt lgkmcnt(8)
	s_and_b64 s[74:75], exec, s[72:73]
	v_mfma_f32_32x32x16_bf16 v[90:105], v[82:85], v[106:109], 0
	s_cselect_b32 s5, 0, s5
	s_sub_i32 s5, s5, s94
	v_med3_i32 v2, s5, -7, 7
	s_movk_i32 s5, 0x7c
	v_mul_lo_u32 v2, v2, s5
	v_add_u32_e32 v2, 0, v2
	v_add_u32_e32 v2, 0x20200, v2
	v_mfma_f32_32x32x16_bf16 v[90:105], v[86:89], v[110:113], v[90:105]
	s_waitcnt lgkmcnt(0)
	v_readlane_b32 s74, v248, 10
	v_readlane_b32 s75, v248, 11
	v_mfma_f32_32x32x16_bf16 v[90:105], v[146:149], v[114:117], v[90:105]
	v_lshl_add_u32 v147, v187, 2, v2
	v_lshl_add_u32 v149, v213, 2, v2
	ds_read_b32 v149, v149 offset:1000
	v_mfma_f32_32x32x16_bf16 v[90:105], v[152:155], v[118:121], v[90:105]
	ds_read_b32 v154, v147 offset:928
	v_lshl_add_u32 v147, v188, 2, v2
	ds_read_b32 v155, v147 offset:932
	v_mfma_f32_32x32x16_bf16 v[90:105], v[156:159], v[122:125], v[90:105]
	v_lshl_add_u32 v159, v214, 2, v2
	v_mfma_f32_32x32x16_bf16 v[90:105], v[160:163], v[126:129], v[90:105]
	ds_read_b32 v163, v159 offset:1004
	v_lshl_add_u32 v147, v189, 2, v2
	v_lshl_add_u32 v159, v215, 2, v2
	ds_read_b32 v156, v147 offset:936
	v_mfma_f32_32x32x16_bf16 v[90:105], v[164:167], v[130:133], v[90:105]
	ds_read_b32 v165, v159 offset:1024
	v_lshl_add_u32 v147, v190, 2, v2
	v_lshl_add_u32 v159, v216, 2, v2
	ds_read_b32 v158, v147 offset:940
	ds_read_b32 v167, v159 offset:1028
	v_lshl_add_u32 v147, v191, 2, v2
	v_lshl_add_u32 v159, v217, 2, v2
	v_mfma_f32_32x32x16_bf16 v[90:105], v[168:171], v[134:137], v[90:105]
	ds_read_b32 v160, v147 offset:960
	ds_read_b32 v169, v159 offset:1032
	v_lshl_add_u32 v147, v200, 2, v2
	v_lshl_add_u32 v159, v218, 2, v2
	ds_read_b32 v162, v147 offset:964
	ds_read_b32 v171, v159 offset:1036
	v_lshl_add_u32 v147, v201, 2, v2
	s_nop 4
	v_mul_f32_e32 v16, 0x3e0293ee, v90
	s_waitcnt lgkmcnt(0)
	v_fmamk_f32 v154, v154, 0x3fb8aa3b, v16
	v_mul_f32_e32 v17, 0x3e0293ee, v91
	v_cndmask_b32_e64 v154, v235, v154, s[74:75]
	v_readlane_b32 s74, v248, 12
	v_cndmask_b32_e64 v159, v154, v16, s[72:73]
	v_fmamk_f32 v16, v155, 0x3fb8aa3b, v17
	v_readlane_b32 s75, v248, 13
	v_mul_f32_e32 v146, 0x3e0293ee, v92
	v_mul_f32_e32 v148, 0x3e0293ee, v93
	v_cndmask_b32_e64 v16, v235, v16, s[74:75]
	v_readlane_b32 s74, v248, 14
	v_cndmask_b32_e64 v161, v16, v17, s[72:73]
	v_fmamk_f32 v16, v156, 0x3fb8aa3b, v146
	v_readlane_b32 s75, v248, 15
	v_mul_f32_e32 v151, 0x3e0293ee, v94
	ds_read_b32 v164, v147 offset:968
	v_cndmask_b32_e64 v16, v235, v16, s[74:75]
	v_readlane_b32 s74, v248, 16
	v_cndmask_b32_e64 v154, v16, v146, s[72:73]
	v_fmamk_f32 v16, v158, 0x3fb8aa3b, v148
	v_readlane_b32 s75, v248, 17
	v_lshl_add_u32 v147, v202, 2, v2
	v_mul_f32_e32 v152, 0x3e0293ee, v95
	v_cndmask_b32_e64 v16, v235, v16, s[74:75]
	v_readlane_b32 s74, v248, 18
	v_cndmask_b32_e64 v156, v16, v148, s[72:73]
	v_fmamk_f32 v16, v160, 0x3fb8aa3b, v151
	v_readlane_b32 s75, v248, 19
	ds_read_b32 v166, v147 offset:972
	v_lshl_add_u32 v147, v203, 2, v2
	v_cndmask_b32_e64 v16, v235, v16, s[74:75]
	v_readlane_b32 s74, v248, 20
	v_cndmask_b32_e64 v155, v16, v151, s[72:73]
	v_fmamk_f32 v16, v162, 0x3fb8aa3b, v152
	v_readlane_b32 s75, v248, 21
	v_mul_f32_e32 v153, 0x3e0293ee, v96
	ds_read_b32 v168, v147 offset:992
	v_cndmask_b32_e64 v16, v235, v16, s[74:75]
	v_readlane_b32 s74, v248, 22
	v_cndmask_b32_e64 v152, v16, v152, s[72:73]
	s_waitcnt lgkmcnt(0)
	v_fmamk_f32 v16, v164, 0x3fb8aa3b, v153
	v_readlane_b32 s75, v248, 23
	v_mul_f32_e32 v157, 0x3e0293ee, v97
	v_lshl_add_u32 v147, v212, 2, v2
	v_cndmask_b32_e64 v16, v235, v16, s[74:75]
	v_readlane_b32 s74, v248, 24
	ds_read_b32 v147, v147 offset:996
	v_fmamk_f32 v17, v166, 0x3fb8aa3b, v157
	v_readlane_b32 s75, v248, 25
	v_mul_f32_e32 v98, 0x3e0293ee, v98
	v_fmamk_f32 v146, v168, 0x3fb8aa3b, v98
	v_cndmask_b32_e64 v17, v235, v17, s[74:75]
	v_readlane_b32 s74, v248, 26
	v_readlane_b32 s75, v248, 27
	v_mov_b32_e32 v148, v100
	v_cndmask_b32_e64 v16, v16, v153, s[72:73]
	v_cndmask_b32_e64 v146, v235, v146, s[74:75]
	v_cndmask_b32_e64 v151, v146, v98, s[72:73]
	v_mov_b32_e32 v146, v99
	s_waitcnt lgkmcnt(0)
	v_mul_f32 v98, s68, v146
	v_mul_f32 v99, s69, v147
	v_readlane_b32 s74, v248, 28
	v_add_f32_e32 v99, v98, v99
	v_readlane_b32 s75, v248, 29
	v_mov_b32_e32 v162, v101
	v_cndmask_b32_e64 v17, v17, v157, s[72:73]
	v_cndmask_b32_e64 v99, v235, v99, s[74:75]
	v_cndmask_b32_e64 v153, v99, v98, s[72:73]
	v_mul_f32 v98, s68, v148
	v_mul_f32 v99, s69, v149
	v_mfma_f32_32x32x16_bf16 v[82:97], v[172:175], v[106:109], 0
	v_add_f32_e32 v99, v98, v99
	v_cndmask_b32_e64 v99, v235, v99, s[20:21]
	v_cndmask_b32_e64 v157, v99, v98, s[72:73]
	v_mul_f32_e64 v98, v162, s68
	v_mul_f32_e64 v99, v163, s69
	v_mov_b32_e32 v164, v102
	v_add_f32_e32 v99, v98, v99
	v_cndmask_b32_e64 v99, v235, v99, s[22:23]
	v_cndmask_b32_e64 v158, v99, v98, s[72:73]
	v_mul_f32 v98, s68, v164
	v_mul_f32 v99, s69, v165
	v_mov_b32_e32 v166, v103
	v_add_f32_e32 v99, v98, v99
	v_cndmask_b32_e64 v99, v235, v99, s[24:25]
	v_cndmask_b32_e64 v160, v99, v98, s[72:73]
	v_mul_f32 v98, s68, v166
	v_mul_f32 v99, s69, v167
	v_mov_b32_e32 v168, v104
	v_add_f32_e32 v99, v98, v99
	v_cndmask_b32_e64 v99, v235, v99, s[26:27]
	v_mfma_f32_32x32x16_bf16 v[82:97], v[176:179], v[110:113], v[82:97]
	v_cndmask_b32_e64 v162, v99, v98, s[72:73]
	v_mul_f32_e64 v98, v168, s68
	v_mul_f32_e64 v99, v169, s69
	v_mov_b32_e32 v170, v105
	v_add_f32_e32 v99, v98, v99
	v_cndmask_b32_e64 v99, v235, v99, s[28:29]
	v_cndmask_b32_e64 v163, v99, v98, s[72:73]
	v_mul_f32 v98, s68, v170
	v_mul_f32 v99, s69, v171
	v_mfma_f32_32x32x16_bf16 v[82:97], v[180:183], v[114:117], v[82:97]
	v_add_f32_e32 v99, v98, v99
	v_cndmask_b32_e64 v99, v235, v99, s[30:31]
	v_cndmask_b32_e64 v164, v99, v98, s[72:73]
	v_max3_f32 v98, v159, s92, v161
	v_max3_f32 v98, v98, v154, v156
	v_max3_f32 v98, v98, v155, v152
	v_max3_f32 v98, v98, v16, v17
	v_max3_f32 v98, v98, v151, v153
	v_max3_f32 v98, v98, v157, v158
	v_max3_f32 v98, v98, v160, v162
	v_max3_f32 v98, v98, v163, v164
	ds_bpermute_b32 v99, v206, v98
	v_mfma_f32_32x32x16_bf16 v[82:97], v[142:145], v[118:121], v[82:97]
	s_waitcnt lgkmcnt(0)
	v_max_f32_e32 v99, v99, v99
	v_max_f32_e32 v98, v98, v99
	v_sub_f32_e32 v99, v98, v236
	v_cmp_ge_f32_e32 vcc, s93, v99
	s_cmp_eq_u64 vcc, exec
	s_cbranch_scc1 .LBB0_973
	v_max_f32_e32 v98, v98, v98
	v_max_f32_e32 v99, v236, v236
	v_max_f32_e32 v99, v99, v98
	v_sub_f32_e32 v98, v236, v99
	v_exp_f32_e32 v98, v98
	v_mov_b32_e32 v236, v99
	v_mul_f32_e32 v150, v150, v98
	v_mul_f32 v80, v80, v98
	v_mul_f32 v81, v81, v98
	v_mul_f32 v78, v78, v98
	v_mul_f32 v79, v79, v98
	v_mul_f32 v76, v76, v98
	v_mul_f32 v77, v77, v98
	v_mul_f32 v74, v74, v98
	v_mul_f32 v75, v75, v98
	v_mul_f32 v72, v72, v98
	v_mul_f32 v73, v73, v98
	v_mul_f32 v70, v70, v98
	v_mul_f32 v71, v71, v98
	v_mul_f32 v68, v68, v98
	v_mul_f32 v69, v69, v98
	v_mul_f32 v66, v66, v98
	v_mul_f32 v67, v67, v98
	v_mul_f32 v64, v64, v98
	v_mul_f32 v65, v65, v98
	v_mul_f32 v62, v62, v98
	v_mul_f32 v63, v63, v98
	v_mul_f32 v60, v60, v98
	v_mul_f32 v61, v61, v98
	v_mul_f32 v58, v58, v98
	v_mul_f32 v59, v59, v98
	v_mul_f32 v56, v56, v98
	v_mul_f32 v57, v57, v98
	v_mul_f32 v54, v54, v98
	v_mul_f32 v55, v55, v98
	v_mul_f32 v52, v52, v98
	v_mul_f32 v53, v53, v98
	v_mul_f32 v50, v50, v98
	v_mul_f32 v51, v51, v98
	v_mul_f32 v48, v48, v98
	v_mul_f32 v49, v49, v98
	v_mul_f32 v46, v46, v98
	v_mul_f32 v47, v47, v98
	v_mul_f32 v44, v44, v98
	v_mul_f32 v45, v45, v98
	v_mul_f32 v42, v42, v98
	v_mul_f32 v43, v43, v98
	v_mul_f32 v40, v40, v98
	v_mul_f32 v41, v41, v98
	v_mul_f32 v38, v38, v98
	v_mul_f32 v39, v39, v98
	v_mul_f32 v36, v36, v98
	v_mul_f32 v37, v37, v98
	v_mul_f32 v34, v34, v98
	v_mul_f32 v35, v35, v98
	v_mul_f32 v32, v32, v98
	v_mul_f32 v33, v33, v98
	v_mul_f32 v30, v30, v98
	v_mul_f32 v31, v31, v98
	v_mul_f32 v28, v28, v98
	v_mul_f32 v29, v29, v98
	v_mul_f32 v26, v26, v98
	v_mul_f32 v27, v27, v98
	v_mul_f32 v24, v24, v98
	v_mul_f32 v25, v25, v98
	v_mul_f32 v22, v22, v98
	v_mul_f32 v23, v23, v98
	v_mul_f32 v20, v20, v98
	v_mul_f32 v21, v21, v98
	v_mul_f32 v18, v18, v98
	v_mul_f32 v19, v19, v98
.LBB0_973:
	v_sub_f32_e32 v159, v159, v236
	v_mfma_f32_32x32x16_bf16 v[82:97], v[138:141], v[122:125], v[82:97]
	v_exp_f32_e32 v159, v159
	v_sub_f32_e32 v161, v161, v236
	v_exp_f32_e32 v161, v161
	v_sub_f32_e32 v154, v154, v236
	v_exp_f32_e32 v154, v154
	v_sub_f32_e32 v156, v156, v236
	v_exp_f32_e32 v156, v156
	v_sub_f32_e32 v155, v155, v236
	v_add_f32_e32 v165, 0, v159
	v_exp_f32_e32 v155, v155
	v_sub_f32_e32 v152, v152, v236
	v_add_f32_e32 v165, v161, v165
	v_exp_f32_e32 v152, v152
	v_sub_f32_e32 v16, v16, v236
	v_add_f32_e32 v165, v154, v165
	v_exp_f32_e32 v166, v16
	v_add_f32_e32 v165, v156, v165
	v_mfma_f32_32x32x16_bf16 v[82:97], v[12:15], v[126:129], v[82:97]
	v_add_f32_e32 v165, v155, v165
	v_add_f32_e32 v165, v152, v165
	v_sub_f32_e32 v17, v17, v236
	v_add_f32_e32 v16, v166, v165
	v_exp_f32_e32 v165, v17
	ds_read_b128 v[182:185], v208 offset:0x4000
	ds_read_b128 v[170:173], v208 offset:0x4400
	v_mfma_f32_32x32x16_bf16 v[82:97], v[8:11], v[130:133], v[82:97]
	v_add_f32_e32 v17, v165, v16
	v_sub_f32_e32 v16, v151, v236
	v_exp_f32_e32 v16, v16
	ds_read_b128 v[174:177], v208 offset:0x4800
	ds_read_b128 v[178:181], v208 offset:0x4c00
	ds_read_b128 v[146:149], v208 offset:0x5000
	ds_read_b128 v[142:145], v208 offset:0x5400
	v_mfma_f32_32x32x16_bf16 v[82:97], v[4:7], v[134:137], v[82:97]
	v_add_f32_e32 v151, v16, v17
	v_sub_f32_e32 v17, v153, v236
	v_exp_f32_e32 v17, v17
	v_sub_f32_e32 v153, v157, v236
	v_exp_f32_e32 v237, v153
	v_sub_f32_e32 v153, v158, v236
	v_exp_f32_e32 v238, v153
	v_sub_f32_e32 v153, v160, v236
	v_exp_f32_e32 v239, v153
	v_sub_f32_e32 v153, v162, v236
	v_add_f32_e32 v151, v17, v151
	v_exp_f32_e32 v240, v153
	v_sub_f32_e32 v153, v163, v236
	v_add_f32_e32 v151, v237, v151
	v_exp_f32_e32 v241, v153
	v_sub_f32_e32 v153, v164, v236
	v_add_f32_e32 v151, v238, v151
	v_exp_f32_e32 v242, v153
	v_add_f32_e32 v151, v239, v151
	v_add_f32_e32 v151, v240, v151
	v_add_f32_e32 v151, v241, v151
	ds_read_b128 v[102:105], v208 offset:0x5800
	ds_read_b128 v[98:101], v208 offset:0x5c00
	v_add_f32_e32 v151, v242, v151
	v_lshl_add_u32 v5, v219, 2, v2
	v_lshl_add_u32 v7, v229, 2, v2
	v_add_f32_e32 v243, v150, v151
	v_cvt_pk_bf16_f32 v244, v159, v161
	v_cvt_pk_bf16_f32 v245, v154, v156
	v_cvt_pk_bf16_f32 v246, v155, v152
	v_cvt_pk_bf16_f32 v247, v166, v165
	ds_read_b128 v[166:169], v208 offset:0x6000
	ds_read_b128 v[162:165], v208 offset:0x6400
	ds_read_b128 v[158:161], v208 offset:0x6800
	ds_read_b128 v[154:157], v208 offset:0x6c00
	ds_read_b128 v[150:153], v208 offset:0x7000
	ds_read_b128 v[138:141], v208 offset:0x7400
	ds_read_b128 v[12:15], v208 offset:0x7800
	ds_read_b128 v[8:11], v208 offset:0x7c00
	s_waitcnt lgkmcnt(8)
	v_mul_f32_e32 v4, 0x3e0293ee, v82
	v_mul_f32_e32 v6, 0x3e0293ee, v83
	v_mul_f32_e32 v82, 0x3e0293ee, v84
	v_mul_f32_e32 v84, 0x3e0293ee, v85
	ds_read_b32 v85, v5 offset:928
	ds_read_b32 v7, v7 offset:1000
	v_lshl_add_u32 v5, v220, 2, v2
	v_lshl_add_u32 v83, v230, 2, v2
	v_mfma_f32_32x32x16_bf16 v[50:65], v[170:173], v[244:247], v[50:65]
	v_mul_f32_e32 v170, 0x3e0293ee, v86
	ds_read_b32 v86, v5 offset:932
	ds_read_b32 v83, v83 offset:1004
	v_lshl_add_u32 v5, v221, 2, v2
	v_lshl_add_u32 v171, v231, 2, v2
	v_mul_f32_e32 v172, 0x3e0293ee, v87
	ds_read_b32 v87, v5 offset:936
	ds_read_b32 v173, v171 offset:1024
	v_lshl_add_u32 v5, v222, 2, v2
	v_lshl_add_u32 v171, v232, 2, v2
	v_mfma_f32_32x32x16_bf16 v[34:49], v[174:177], v[244:247], v[34:49]
	v_mul_f32_e32 v174, 0x3e0293ee, v88
	ds_read_b32 v88, v5 offset:940
	ds_read_b32 v175, v171 offset:1028
	v_lshl_add_u32 v5, v223, 2, v2
	v_lshl_add_u32 v171, v233, 2, v2
	v_mul_f32_e32 v176, 0x3e0293ee, v89
	ds_read_b32 v89, v5 offset:960
	ds_read_b32 v177, v171 offset:1032
	v_lshl_add_u32 v5, v224, 2, v2
	v_mfma_f32_32x32x16_bf16 v[18:33], v[178:181], v[244:247], v[18:33]
	v_mul_f32_e32 v178, 0x3e0293ee, v90
	ds_read_b32 v90, v5 offset:964
	v_lshl_add_u32 v5, v225, 2, v2
	ds_read_b32 v180, v5 offset:968
	v_lshl_add_u32 v5, v226, 2, v2
	ds_read_b32 v181, v5 offset:972
	v_lshl_add_u32 v5, v227, 2, v2
	v_mfma_f32_32x32x16_bf16 v[66:81], v[182:185], v[244:247], v[66:81]
	ds_read_b32 v182, v5 offset:992
	v_lshl_add_u32 v5, v228, 2, v2
	v_lshl_add_u32 v2, v234, 2, v2
	ds_read_b32 v5, v5 offset:996
	ds_read_b32 v179, v2 offset:1036
	s_waitcnt lgkmcnt(0)
	v_fmamk_f32 v2, v85, 0x3fb8aa3b, v4
	v_cndmask_b32_e64 v2, v235, v2, s[34:35]
	v_cndmask_b32_e64 v171, v2, v4, s[72:73]
	v_fmamk_f32 v2, v86, 0x3fb8aa3b, v6
	v_cndmask_b32_e64 v2, v235, v2, s[36:37]
	v_cndmask_b32_e64 v85, v2, v6, s[72:73]
	v_fmamk_f32 v2, v87, 0x3fb8aa3b, v82
	v_cndmask_b32_e64 v2, v235, v2, s[38:39]
	v_mov_b32_e32 v4, v91
	v_cndmask_b32_e64 v86, v2, v82, s[72:73]
	v_fmamk_f32 v2, v88, 0x3fb8aa3b, v84
	v_mul_f32 v4, s68, v4
	v_mul_f32 v5, s69, v5
	v_cndmask_b32_e64 v2, v235, v2, s[40:41]
	v_add_f32_e32 v5, v4, v5
	v_mov_b32_e32 v6, v92
	v_cndmask_b32_e64 v87, v2, v84, s[72:73]
	v_fmamk_f32 v2, v89, 0x3fb8aa3b, v170
	v_cndmask_b32_e64 v5, v235, v5, s[6:7]
	v_mul_f32 v6, s68, v6
	v_mul_f32 v7, s69, v7
	v_cndmask_b32_e64 v2, v235, v2, s[42:43]
	v_cndmask_b32_e64 v4, v5, v4, s[72:73]
	v_add_f32_e32 v5, v6, v7
	v_cndmask_b32_e64 v88, v2, v170, s[72:73]
	v_fmamk_f32 v2, v90, 0x3fb8aa3b, v172
	v_cndmask_b32_e64 v5, v235, v5, s[8:9]
	v_mov_b32_e32 v82, v93
	v_cndmask_b32_e64 v2, v235, v2, s[44:45]
	v_cndmask_b32_e64 v5, v5, v6, s[72:73]
	v_mul_f32 v6, s68, v82
	v_mul_f32 v7, s69, v83
	v_cndmask_b32_e64 v89, v2, v172, s[72:73]
	v_add_f32_e32 v7, v6, v7
	v_mov_b32_e32 v172, v94
	v_fmamk_f32 v2, v180, 0x3fb8aa3b, v174
	v_cndmask_b32_e64 v7, v235, v7, s[10:11]
	v_mul_f32 v82, s68, v172
	v_mul_f32 v83, s69, v173
	v_cndmask_b32_e64 v2, v235, v2, s[46:47]
	v_cndmask_b32_e64 v6, v7, v6, s[72:73]
	v_add_f32_e32 v7, v82, v83
	v_cndmask_b32_e64 v90, v2, v174, s[72:73]
	v_fmamk_f32 v2, v181, 0x3fb8aa3b, v176
	v_cndmask_b32_e64 v7, v235, v7, s[12:13]
	v_mov_b32_e32 v174, v95
	v_cndmask_b32_e64 v2, v235, v2, s[48:49]
	v_cndmask_b32_e64 v7, v7, v82, s[72:73]
	v_mul_f32 v82, s68, v174
	v_mul_f32 v83, s69, v175
	v_cndmask_b32_e64 v170, v2, v176, s[72:73]
	v_add_f32_e32 v83, v82, v83
	v_mov_b32_e32 v176, v96
	v_fmamk_f32 v2, v182, 0x3fb8aa3b, v178
	v_cndmask_b32_e64 v83, v235, v83, s[14:15]
	v_mul_f32 v92, s68, v176
	v_mul_f32 v93, s69, v177
	v_max3_f32 v91, v171, s92, v85
	v_cndmask_b32_e64 v2, v235, v2, s[50:51]
	v_cndmask_b32_e64 v82, v83, v82, s[72:73]
	v_add_f32_e32 v83, v92, v93
	v_max3_f32 v91, v91, v86, v87
	v_cndmask_b32_e64 v2, v2, v178, s[72:73]
	v_cndmask_b32_e64 v83, v235, v83, s[16:17]
	v_mov_b32_e32 v178, v97
	v_max3_f32 v91, v91, v88, v89
	v_cndmask_b32_e64 v83, v83, v92, s[72:73]
	v_mul_f32 v92, s68, v178
	v_mul_f32 v93, s69, v179
	v_max3_f32 v91, v91, v90, v170
	v_add_f32_e32 v84, v92, v93
	v_max3_f32 v91, v91, v2, v4
	v_cndmask_b32_e64 v84, v235, v84, s[18:19]
	v_max3_f32 v91, v91, v5, v6
	v_cndmask_b32_e64 v84, v84, v92, s[72:73]
	v_max3_f32 v91, v91, v7, v82
	v_max3_f32 v91, v91, v83, v84
	ds_bpermute_b32 v92, v206, v91
	s_waitcnt lgkmcnt(0)
	v_max_f32_e32 v92, v92, v92
	v_max_f32_e32 v91, v91, v92
	v_sub_f32_e32 v92, v91, v236
	v_cmp_ge_f32_e32 vcc, s93, v92
	s_cmp_eq_u64 vcc, exec
	s_cbranch_scc1 .LBB0_975
	v_max_f32_e32 v91, v91, v91
	v_max_f32_e32 v92, v236, v236
	v_max_f32_e32 v91, v92, v91
	v_sub_f32_e32 v92, v236, v91
	v_exp_f32_e32 v92, v92
	v_mov_b32_e32 v236, v91
	v_mul_f32_e32 v243, v243, v92
	v_mul_f32 v80, v80, v92
	v_mul_f32 v81, v81, v92
	v_mul_f32 v78, v78, v92
	v_mul_f32 v79, v79, v92
	v_mul_f32 v76, v76, v92
	v_mul_f32 v77, v77, v92
	v_mul_f32 v74, v74, v92
	v_mul_f32 v75, v75, v92
	v_mul_f32 v72, v72, v92
	v_mul_f32 v73, v73, v92
	v_mul_f32 v70, v70, v92
	v_mul_f32 v71, v71, v92
	v_mul_f32 v68, v68, v92
	v_mul_f32 v69, v69, v92
	v_mul_f32 v66, v66, v92
	v_mul_f32 v67, v67, v92
	v_mul_f32 v64, v64, v92
	v_mul_f32 v65, v65, v92
	v_mul_f32 v62, v62, v92
	v_mul_f32 v63, v63, v92
	v_mul_f32 v60, v60, v92
	v_mul_f32 v61, v61, v92
	v_mul_f32 v58, v58, v92
	v_mul_f32 v59, v59, v92
	v_mul_f32 v56, v56, v92
	v_mul_f32 v57, v57, v92
	v_mul_f32 v54, v54, v92
	v_mul_f32 v55, v55, v92
	v_mul_f32 v52, v52, v92
	v_mul_f32 v53, v53, v92
	v_mul_f32 v50, v50, v92
	v_mul_f32 v51, v51, v92
	v_mul_f32 v48, v48, v92
	v_mul_f32 v49, v49, v92
	v_mul_f32 v46, v46, v92
	v_mul_f32 v47, v47, v92
	v_mul_f32 v44, v44, v92
	v_mul_f32 v45, v45, v92
	v_mul_f32 v42, v42, v92
	v_mul_f32 v43, v43, v92
	v_mul_f32 v40, v40, v92
	v_mul_f32 v41, v41, v92
	v_mul_f32 v38, v38, v92
	v_mul_f32 v39, v39, v92
	v_mul_f32 v36, v36, v92
	v_mul_f32 v37, v37, v92
	v_mul_f32 v34, v34, v92
	v_mul_f32 v35, v35, v92
	v_mul_f32 v32, v32, v92
	v_mul_f32 v33, v33, v92
	v_mul_f32 v30, v30, v92
	v_mul_f32 v31, v31, v92
	v_mul_f32 v28, v28, v92
	v_mul_f32 v29, v29, v92
	v_mul_f32 v26, v26, v92
	v_mul_f32 v27, v27, v92
	v_mul_f32 v24, v24, v92
	v_mul_f32 v25, v25, v92
	v_mul_f32 v22, v22, v92
	v_mul_f32 v23, v23, v92
	v_mul_f32 v20, v20, v92
	v_mul_f32 v21, v21, v92
	v_mul_f32 v18, v18, v92
	v_mul_f32 v19, v19, v92

.LBB0_978:
	ds_read_b128 v[82:85], v210 offset:0
	ds_read_b128 v[86:89], v210 offset:0x400
	ds_read_b128 v[146:149], v210 offset:0x800
	ds_read_b128 v[152:155], v210 offset:0xc00
	ds_read_b128 v[156:159], v210 offset:0x1000
	ds_read_b128 v[160:163], v210 offset:0x1400
	ds_read_b128 v[164:167], v210 offset:0x1800
	ds_read_b128 v[168:171], v210 offset:0x1c00
	ds_read_b128 v[172:175], v210 offset:0x2000
	ds_read_b128 v[176:179], v210 offset:0x2400
	ds_read_b128 v[180:183], v210 offset:0x2800
	ds_read_b128 v[142:145], v210 offset:0x2c00
	ds_read_b128 v[138:141], v210 offset:0x3000
	ds_read_b128 v[12:15], v210 offset:0x3400
	ds_read_b128 v[8:11], v210 offset:0x3800
	ds_read_b128 v[4:7], v210 offset:0x3c00
	s_nop 0
	s_waitcnt lgkmcnt(8)
	s_and_b64 s[74:75], exec, s[72:73]
	v_mfma_f32_32x32x16_bf16 v[90:105], v[82:85], v[106:109], 0
	s_cselect_b32 s5, 0, s5
	s_sub_i32 s5, s5, s94
	v_med3_i32 v2, s5, -7, 7
	s_movk_i32 s5, 0x7c
	v_mul_lo_u32 v2, v2, s5
	v_add_u32_e32 v2, 0, v2
	v_add_u32_e32 v2, 0x20200, v2
	v_mfma_f32_32x32x16_bf16 v[90:105], v[86:89], v[110:113], v[90:105]
	s_waitcnt lgkmcnt(0)
	v_readlane_b32 s74, v248, 10
	v_readlane_b32 s75, v248, 11
	v_mfma_f32_32x32x16_bf16 v[90:105], v[146:149], v[114:117], v[90:105]
	v_lshl_add_u32 v147, v187, 2, v2
	v_lshl_add_u32 v149, v213, 2, v2
	ds_read_b32 v149, v149 offset:1000
	v_mfma_f32_32x32x16_bf16 v[90:105], v[152:155], v[118:121], v[90:105]
	ds_read_b32 v154, v147 offset:928
	v_lshl_add_u32 v147, v188, 2, v2
	ds_read_b32 v155, v147 offset:932
	v_mfma_f32_32x32x16_bf16 v[90:105], v[156:159], v[122:125], v[90:105]
	v_lshl_add_u32 v159, v214, 2, v2
	v_mfma_f32_32x32x16_bf16 v[90:105], v[160:163], v[126:129], v[90:105]
	ds_read_b32 v163, v159 offset:1004
	v_lshl_add_u32 v147, v189, 2, v2
	v_lshl_add_u32 v159, v215, 2, v2
	ds_read_b32 v156, v147 offset:936
	v_mfma_f32_32x32x16_bf16 v[90:105], v[164:167], v[130:133], v[90:105]
	ds_read_b32 v165, v159 offset:1024
	v_lshl_add_u32 v147, v190, 2, v2
	v_lshl_add_u32 v159, v216, 2, v2
	ds_read_b32 v158, v147 offset:940
	ds_read_b32 v167, v159 offset:1028
	v_lshl_add_u32 v147, v191, 2, v2
	v_lshl_add_u32 v159, v217, 2, v2
	v_mfma_f32_32x32x16_bf16 v[90:105], v[168:171], v[134:137], v[90:105]
	ds_read_b32 v160, v147 offset:960
	ds_read_b32 v169, v159 offset:1032
	v_lshl_add_u32 v147, v200, 2, v2
	v_lshl_add_u32 v159, v218, 2, v2
	ds_read_b32 v162, v147 offset:964
	ds_read_b32 v171, v159 offset:1036
	v_lshl_add_u32 v147, v201, 2, v2
	s_nop 4
	v_mul_f32_e32 v16, 0x3e0293ee, v90
	s_waitcnt lgkmcnt(0)
	v_fmamk_f32 v154, v154, 0x3fb8aa3b, v16
	v_mul_f32_e32 v17, 0x3e0293ee, v91
	v_cndmask_b32_e64 v154, v235, v154, s[74:75]
	v_readlane_b32 s74, v248, 12
	v_cndmask_b32_e64 v159, v154, v16, s[72:73]
	v_fmamk_f32 v16, v155, 0x3fb8aa3b, v17
	v_readlane_b32 s75, v248, 13
	v_mul_f32_e32 v146, 0x3e0293ee, v92
	v_mul_f32_e32 v148, 0x3e0293ee, v93
	v_cndmask_b32_e64 v16, v235, v16, s[74:75]
	v_readlane_b32 s74, v248, 14
	v_cndmask_b32_e64 v161, v16, v17, s[72:73]
	v_fmamk_f32 v16, v156, 0x3fb8aa3b, v146
	v_readlane_b32 s75, v248, 15
	v_mul_f32_e32 v151, 0x3e0293ee, v94
	ds_read_b32 v164, v147 offset:968
	v_cndmask_b32_e64 v16, v235, v16, s[74:75]
	v_readlane_b32 s74, v248, 16
	v_cndmask_b32_e64 v154, v16, v146, s[72:73]
	v_fmamk_f32 v16, v158, 0x3fb8aa3b, v148
	v_readlane_b32 s75, v248, 17
	v_lshl_add_u32 v147, v202, 2, v2
	v_mul_f32_e32 v152, 0x3e0293ee, v95
	v_cndmask_b32_e64 v16, v235, v16, s[74:75]
	v_readlane_b32 s74, v248, 18
	v_cndmask_b32_e64 v156, v16, v148, s[72:73]
	v_fmamk_f32 v16, v160, 0x3fb8aa3b, v151
	v_readlane_b32 s75, v248, 19
	ds_read_b32 v166, v147 offset:972
	v_lshl_add_u32 v147, v203, 2, v2
	v_cndmask_b32_e64 v16, v235, v16, s[74:75]
	v_readlane_b32 s74, v248, 20
	v_cndmask_b32_e64 v155, v16, v151, s[72:73]
	v_fmamk_f32 v16, v162, 0x3fb8aa3b, v152
	v_readlane_b32 s75, v248, 21
	v_mul_f32_e32 v153, 0x3e0293ee, v96
	ds_read_b32 v168, v147 offset:992
	v_cndmask_b32_e64 v16, v235, v16, s[74:75]
	v_readlane_b32 s74, v248, 22
	v_cndmask_b32_e64 v152, v16, v152, s[72:73]
	s_waitcnt lgkmcnt(0)
	v_fmamk_f32 v16, v164, 0x3fb8aa3b, v153
	v_readlane_b32 s75, v248, 23
	v_mul_f32_e32 v157, 0x3e0293ee, v97
	v_lshl_add_u32 v147, v212, 2, v2
	v_cndmask_b32_e64 v16, v235, v16, s[74:75]
	v_readlane_b32 s74, v248, 24
	ds_read_b32 v147, v147 offset:996
	v_fmamk_f32 v17, v166, 0x3fb8aa3b, v157
	v_readlane_b32 s75, v248, 25
	v_mul_f32_e32 v98, 0x3e0293ee, v98
	v_fmamk_f32 v146, v168, 0x3fb8aa3b, v98
	v_cndmask_b32_e64 v17, v235, v17, s[74:75]
	v_readlane_b32 s74, v248, 26
	v_readlane_b32 s75, v248, 27
	v_mov_b32_e32 v148, v100
	v_cndmask_b32_e64 v16, v16, v153, s[72:73]
	v_cndmask_b32_e64 v146, v235, v146, s[74:75]
	v_cndmask_b32_e64 v151, v146, v98, s[72:73]
	v_mov_b32_e32 v146, v99
	s_waitcnt lgkmcnt(0)
	v_mul_f32 v98, s68, v146
	v_mul_f32 v99, s69, v147
	v_readlane_b32 s74, v248, 28
	v_add_f32_e32 v99, v98, v99
	v_readlane_b32 s75, v248, 29
	v_mov_b32_e32 v162, v101
	v_cndmask_b32_e64 v17, v17, v157, s[72:73]
	v_cndmask_b32_e64 v99, v235, v99, s[74:75]
	v_cndmask_b32_e64 v153, v99, v98, s[72:73]
	v_mul_f32 v98, s68, v148
	v_mul_f32 v99, s69, v149
	v_mfma_f32_32x32x16_bf16 v[82:97], v[172:175], v[106:109], 0
	v_add_f32_e32 v99, v98, v99
	v_cndmask_b32_e64 v99, v235, v99, s[20:21]
	v_cndmask_b32_e64 v157, v99, v98, s[72:73]
	v_mul_f32_e64 v98, v162, s68
	v_mul_f32_e64 v99, v163, s69
	v_mov_b32_e32 v164, v102
	v_add_f32_e32 v99, v98, v99
	v_cndmask_b32_e64 v99, v235, v99, s[22:23]
	v_cndmask_b32_e64 v158, v99, v98, s[72:73]
	v_mul_f32 v98, s68, v164
	v_mul_f32 v99, s69, v165
	v_mov_b32_e32 v166, v103
	v_add_f32_e32 v99, v98, v99
	v_cndmask_b32_e64 v99, v235, v99, s[24:25]
	v_cndmask_b32_e64 v160, v99, v98, s[72:73]
	v_mul_f32 v98, s68, v166
	v_mul_f32 v99, s69, v167
	v_mov_b32_e32 v168, v104
	v_add_f32_e32 v99, v98, v99
	v_cndmask_b32_e64 v99, v235, v99, s[26:27]
	v_mfma_f32_32x32x16_bf16 v[82:97], v[176:179], v[110:113], v[82:97]
	v_cndmask_b32_e64 v162, v99, v98, s[72:73]
	v_mul_f32_e64 v98, v168, s68
	v_mul_f32_e64 v99, v169, s69
	v_mov_b32_e32 v170, v105
	v_add_f32_e32 v99, v98, v99
	v_cndmask_b32_e64 v99, v235, v99, s[28:29]
	v_cndmask_b32_e64 v163, v99, v98, s[72:73]
	v_mul_f32 v98, s68, v170
	v_mul_f32 v99, s69, v171
	v_mfma_f32_32x32x16_bf16 v[82:97], v[180:183], v[114:117], v[82:97]
	v_add_f32_e32 v99, v98, v99
	v_cndmask_b32_e64 v99, v235, v99, s[30:31]
	v_cndmask_b32_e64 v164, v99, v98, s[72:73]
	v_max3_f32 v98, v159, s92, v161
	v_max3_f32 v98, v98, v154, v156
	v_max3_f32 v98, v98, v155, v152
	v_max3_f32 v98, v98, v16, v17
	v_max3_f32 v98, v98, v151, v153
	v_max3_f32 v98, v98, v157, v158
	v_max3_f32 v98, v98, v160, v162
	v_max3_f32 v98, v98, v163, v164
	ds_bpermute_b32 v99, v206, v98
	v_mfma_f32_32x32x16_bf16 v[82:97], v[142:145], v[118:121], v[82:97]
	s_waitcnt lgkmcnt(0)
	v_max_f32_e32 v99, v99, v99
	v_max_f32_e32 v98, v98, v99
	v_sub_f32_e32 v99, v98, v236
	v_cmp_ge_f32_e32 vcc, s93, v99
	s_cmp_eq_u64 vcc, exec
	s_cbranch_scc1 .LBB0_980
	v_max_f32_e32 v98, v98, v98
	v_max_f32_e32 v99, v236, v236
	v_max_f32_e32 v99, v99, v98
	v_sub_f32_e32 v98, v236, v99
	v_exp_f32_e32 v98, v98
	v_mov_b32_e32 v236, v99
	v_mul_f32_e32 v150, v150, v98
	v_mul_f32 v80, v80, v98
	v_mul_f32 v81, v81, v98
	v_mul_f32 v78, v78, v98
	v_mul_f32 v79, v79, v98
	v_mul_f32 v76, v76, v98
	v_mul_f32 v77, v77, v98
	v_mul_f32 v74, v74, v98
	v_mul_f32 v75, v75, v98
	v_mul_f32 v72, v72, v98
	v_mul_f32 v73, v73, v98
	v_mul_f32 v70, v70, v98
	v_mul_f32 v71, v71, v98
	v_mul_f32 v68, v68, v98
	v_mul_f32 v69, v69, v98
	v_mul_f32 v66, v66, v98
	v_mul_f32 v67, v67, v98
	v_mul_f32 v64, v64, v98
	v_mul_f32 v65, v65, v98
	v_mul_f32 v62, v62, v98
	v_mul_f32 v63, v63, v98
	v_mul_f32 v60, v60, v98
	v_mul_f32 v61, v61, v98
	v_mul_f32 v58, v58, v98
	v_mul_f32 v59, v59, v98
	v_mul_f32 v56, v56, v98
	v_mul_f32 v57, v57, v98
	v_mul_f32 v54, v54, v98
	v_mul_f32 v55, v55, v98
	v_mul_f32 v52, v52, v98
	v_mul_f32 v53, v53, v98
	v_mul_f32 v50, v50, v98
	v_mul_f32 v51, v51, v98
	v_mul_f32 v48, v48, v98
	v_mul_f32 v49, v49, v98
	v_mul_f32 v46, v46, v98
	v_mul_f32 v47, v47, v98
	v_mul_f32 v44, v44, v98
	v_mul_f32 v45, v45, v98
	v_mul_f32 v42, v42, v98
	v_mul_f32 v43, v43, v98
	v_mul_f32 v40, v40, v98
	v_mul_f32 v41, v41, v98
	v_mul_f32 v38, v38, v98
	v_mul_f32 v39, v39, v98
	v_mul_f32 v36, v36, v98
	v_mul_f32 v37, v37, v98
	v_mul_f32 v34, v34, v98
	v_mul_f32 v35, v35, v98
	v_mul_f32 v32, v32, v98
	v_mul_f32 v33, v33, v98
	v_mul_f32 v30, v30, v98
	v_mul_f32 v31, v31, v98
	v_mul_f32 v28, v28, v98
	v_mul_f32 v29, v29, v98
	v_mul_f32 v26, v26, v98
	v_mul_f32 v27, v27, v98
	v_mul_f32 v24, v24, v98
	v_mul_f32 v25, v25, v98
	v_mul_f32 v22, v22, v98
	v_mul_f32 v23, v23, v98
	v_mul_f32 v20, v20, v98
	v_mul_f32 v21, v21, v98
	v_mul_f32 v18, v18, v98
	v_mul_f32 v19, v19, v98
.LBB0_980:
	v_sub_f32_e32 v159, v159, v236
	v_mfma_f32_32x32x16_bf16 v[82:97], v[138:141], v[122:125], v[82:97]
	v_exp_f32_e32 v159, v159
	v_sub_f32_e32 v161, v161, v236
	v_exp_f32_e32 v161, v161
	v_sub_f32_e32 v154, v154, v236
	v_exp_f32_e32 v154, v154
	v_sub_f32_e32 v156, v156, v236
	v_exp_f32_e32 v156, v156
	v_sub_f32_e32 v155, v155, v236
	v_add_f32_e32 v165, 0, v159
	v_exp_f32_e32 v155, v155
	v_sub_f32_e32 v152, v152, v236
	v_add_f32_e32 v165, v161, v165
	v_exp_f32_e32 v152, v152
	v_sub_f32_e32 v16, v16, v236
	v_add_f32_e32 v165, v154, v165
	v_exp_f32_e32 v166, v16
	v_add_f32_e32 v165, v156, v165
	v_mfma_f32_32x32x16_bf16 v[82:97], v[12:15], v[126:129], v[82:97]
	v_add_f32_e32 v165, v155, v165
	v_add_f32_e32 v165, v152, v165
	v_sub_f32_e32 v17, v17, v236
	v_add_f32_e32 v16, v166, v165
	v_exp_f32_e32 v165, v17
	ds_read_b128 v[182:185], v210 offset:0x4000
	ds_read_b128 v[170:173], v210 offset:0x4400
	v_mfma_f32_32x32x16_bf16 v[82:97], v[8:11], v[130:133], v[82:97]
	v_add_f32_e32 v17, v165, v16
	v_sub_f32_e32 v16, v151, v236
	v_exp_f32_e32 v16, v16
	ds_read_b128 v[174:177], v210 offset:0x4800
	ds_read_b128 v[178:181], v210 offset:0x4c00
	ds_read_b128 v[146:149], v210 offset:0x5000
	ds_read_b128 v[142:145], v210 offset:0x5400
	v_mfma_f32_32x32x16_bf16 v[82:97], v[4:7], v[134:137], v[82:97]
	v_add_f32_e32 v151, v16, v17
	v_sub_f32_e32 v17, v153, v236
	v_exp_f32_e32 v17, v17
	v_sub_f32_e32 v153, v157, v236
	v_exp_f32_e32 v237, v153
	v_sub_f32_e32 v153, v158, v236
	v_exp_f32_e32 v238, v153
	v_sub_f32_e32 v153, v160, v236
	v_exp_f32_e32 v239, v153
	v_sub_f32_e32 v153, v162, v236
	v_add_f32_e32 v151, v17, v151
	v_exp_f32_e32 v240, v153
	v_sub_f32_e32 v153, v163, v236
	v_add_f32_e32 v151, v237, v151
	v_exp_f32_e32 v241, v153
	v_sub_f32_e32 v153, v164, v236
	v_add_f32_e32 v151, v238, v151
	v_exp_f32_e32 v242, v153
	v_add_f32_e32 v151, v239, v151
	v_add_f32_e32 v151, v240, v151
	v_add_f32_e32 v151, v241, v151
	ds_read_b128 v[102:105], v210 offset:0x5800
	ds_read_b128 v[98:101], v210 offset:0x5c00
	v_add_f32_e32 v151, v242, v151
	v_lshl_add_u32 v5, v219, 2, v2
	v_lshl_add_u32 v7, v229, 2, v2
	v_add_f32_e32 v243, v150, v151
	v_cvt_pk_bf16_f32 v244, v159, v161
	v_cvt_pk_bf16_f32 v245, v154, v156
	v_cvt_pk_bf16_f32 v246, v155, v152
	v_cvt_pk_bf16_f32 v247, v166, v165
	ds_read_b128 v[166:169], v210 offset:0x6000
	ds_read_b128 v[162:165], v210 offset:0x6400
	ds_read_b128 v[158:161], v210 offset:0x6800
	ds_read_b128 v[154:157], v210 offset:0x6c00
	ds_read_b128 v[150:153], v210 offset:0x7000
	ds_read_b128 v[138:141], v210 offset:0x7400
	ds_read_b128 v[12:15], v210 offset:0x7800
	ds_read_b128 v[8:11], v210 offset:0x7c00
	s_waitcnt lgkmcnt(8)
	v_mul_f32_e32 v4, 0x3e0293ee, v82
	v_mul_f32_e32 v6, 0x3e0293ee, v83
	v_mul_f32_e32 v82, 0x3e0293ee, v84
	v_mul_f32_e32 v84, 0x3e0293ee, v85
	ds_read_b32 v85, v5 offset:928
	ds_read_b32 v7, v7 offset:1000
	v_lshl_add_u32 v5, v220, 2, v2
	v_lshl_add_u32 v83, v230, 2, v2
	v_mfma_f32_32x32x16_bf16 v[50:65], v[170:173], v[244:247], v[50:65]
	v_mul_f32_e32 v170, 0x3e0293ee, v86
	ds_read_b32 v86, v5 offset:932
	ds_read_b32 v83, v83 offset:1004
	v_lshl_add_u32 v5, v221, 2, v2
	v_lshl_add_u32 v171, v231, 2, v2
	v_mul_f32_e32 v172, 0x3e0293ee, v87
	ds_read_b32 v87, v5 offset:936
	ds_read_b32 v173, v171 offset:1024
	v_lshl_add_u32 v5, v222, 2, v2
	v_lshl_add_u32 v171, v232, 2, v2
	v_mfma_f32_32x32x16_bf16 v[34:49], v[174:177], v[244:247], v[34:49]
	v_mul_f32_e32 v174, 0x3e0293ee, v88
	ds_read_b32 v88, v5 offset:940
	ds_read_b32 v175, v171 offset:1028
	v_lshl_add_u32 v5, v223, 2, v2
	v_lshl_add_u32 v171, v233, 2, v2
	v_mul_f32_e32 v176, 0x3e0293ee, v89
	ds_read_b32 v89, v5 offset:960
	ds_read_b32 v177, v171 offset:1032
	v_lshl_add_u32 v5, v224, 2, v2
	v_mfma_f32_32x32x16_bf16 v[18:33], v[178:181], v[244:247], v[18:33]
	v_mul_f32_e32 v178, 0x3e0293ee, v90
	ds_read_b32 v90, v5 offset:964
	v_lshl_add_u32 v5, v225, 2, v2
	ds_read_b32 v180, v5 offset:968
	v_lshl_add_u32 v5, v226, 2, v2
	ds_read_b32 v181, v5 offset:972
	v_lshl_add_u32 v5, v227, 2, v2
	v_mfma_f32_32x32x16_bf16 v[66:81], v[182:185], v[244:247], v[66:81]
	ds_read_b32 v182, v5 offset:992
	v_lshl_add_u32 v5, v228, 2, v2
	v_lshl_add_u32 v2, v234, 2, v2
	ds_read_b32 v5, v5 offset:996
	ds_read_b32 v179, v2 offset:1036
	s_waitcnt lgkmcnt(0)
	v_fmamk_f32 v2, v85, 0x3fb8aa3b, v4
	v_cndmask_b32_e64 v2, v235, v2, s[34:35]
	v_cndmask_b32_e64 v171, v2, v4, s[72:73]
	v_fmamk_f32 v2, v86, 0x3fb8aa3b, v6
	v_cndmask_b32_e64 v2, v235, v2, s[36:37]
	v_cndmask_b32_e64 v85, v2, v6, s[72:73]
	v_fmamk_f32 v2, v87, 0x3fb8aa3b, v82
	v_cndmask_b32_e64 v2, v235, v2, s[38:39]
	v_mov_b32_e32 v4, v91
	v_cndmask_b32_e64 v86, v2, v82, s[72:73]
	v_fmamk_f32 v2, v88, 0x3fb8aa3b, v84
	v_mul_f32 v4, s68, v4
	v_mul_f32 v5, s69, v5
	v_cndmask_b32_e64 v2, v235, v2, s[40:41]
	v_add_f32_e32 v5, v4, v5
	v_mov_b32_e32 v6, v92
	v_cndmask_b32_e64 v87, v2, v84, s[72:73]
	v_fmamk_f32 v2, v89, 0x3fb8aa3b, v170
	v_cndmask_b32_e64 v5, v235, v5, s[6:7]
	v_mul_f32 v6, s68, v6
	v_mul_f32 v7, s69, v7
	v_cndmask_b32_e64 v2, v235, v2, s[42:43]
	v_cndmask_b32_e64 v4, v5, v4, s[72:73]
	v_add_f32_e32 v5, v6, v7
	v_cndmask_b32_e64 v88, v2, v170, s[72:73]
	v_fmamk_f32 v2, v90, 0x3fb8aa3b, v172
	v_cndmask_b32_e64 v5, v235, v5, s[8:9]
	v_mov_b32_e32 v82, v93
	v_cndmask_b32_e64 v2, v235, v2, s[44:45]
	v_cndmask_b32_e64 v5, v5, v6, s[72:73]
	v_mul_f32 v6, s68, v82
	v_mul_f32 v7, s69, v83
	v_cndmask_b32_e64 v89, v2, v172, s[72:73]
	v_add_f32_e32 v7, v6, v7
	v_mov_b32_e32 v172, v94
	v_fmamk_f32 v2, v180, 0x3fb8aa3b, v174
	v_cndmask_b32_e64 v7, v235, v7, s[10:11]
	v_mul_f32 v82, s68, v172
	v_mul_f32 v83, s69, v173
	v_cndmask_b32_e64 v2, v235, v2, s[46:47]
	v_cndmask_b32_e64 v6, v7, v6, s[72:73]
	v_add_f32_e32 v7, v82, v83
	v_cndmask_b32_e64 v90, v2, v174, s[72:73]
	v_fmamk_f32 v2, v181, 0x3fb8aa3b, v176
	v_cndmask_b32_e64 v7, v235, v7, s[12:13]
	v_mov_b32_e32 v174, v95
	v_cndmask_b32_e64 v2, v235, v2, s[48:49]
	v_cndmask_b32_e64 v7, v7, v82, s[72:73]
	v_mul_f32 v82, s68, v174
	v_mul_f32 v83, s69, v175
	v_cndmask_b32_e64 v170, v2, v176, s[72:73]
	v_add_f32_e32 v83, v82, v83
	v_mov_b32_e32 v176, v96
	v_fmamk_f32 v2, v182, 0x3fb8aa3b, v178
	v_cndmask_b32_e64 v83, v235, v83, s[14:15]
	v_mul_f32 v92, s68, v176
	v_mul_f32 v93, s69, v177
	v_max3_f32 v91, v171, s92, v85
	v_cndmask_b32_e64 v2, v235, v2, s[50:51]
	v_cndmask_b32_e64 v82, v83, v82, s[72:73]
	v_add_f32_e32 v83, v92, v93
	v_max3_f32 v91, v91, v86, v87
	v_cndmask_b32_e64 v2, v2, v178, s[72:73]
	v_cndmask_b32_e64 v83, v235, v83, s[16:17]
	v_mov_b32_e32 v178, v97
	v_max3_f32 v91, v91, v88, v89
	v_cndmask_b32_e64 v83, v83, v92, s[72:73]
	v_mul_f32 v92, s68, v178
	v_mul_f32 v93, s69, v179
	v_max3_f32 v91, v91, v90, v170
	v_add_f32_e32 v84, v92, v93
	v_max3_f32 v91, v91, v2, v4
	v_cndmask_b32_e64 v84, v235, v84, s[18:19]
	v_max3_f32 v91, v91, v5, v6
	v_cndmask_b32_e64 v84, v84, v92, s[72:73]
	v_max3_f32 v91, v91, v7, v82
	v_max3_f32 v91, v91, v83, v84
	ds_bpermute_b32 v92, v206, v91
	s_waitcnt lgkmcnt(0)
	v_max_f32_e32 v92, v92, v92
	v_max_f32_e32 v91, v91, v92
	v_sub_f32_e32 v92, v91, v236
	v_cmp_ge_f32_e32 vcc, s93, v92
	s_cmp_eq_u64 vcc, exec
	s_cbranch_scc1 .LBB0_982
	v_max_f32_e32 v91, v91, v91
	v_max_f32_e32 v92, v236, v236
	v_max_f32_e32 v91, v92, v91
	v_sub_f32_e32 v92, v236, v91
	v_exp_f32_e32 v92, v92
	v_mov_b32_e32 v236, v91
	v_mul_f32_e32 v243, v243, v92
	v_mul_f32 v80, v80, v92
	v_mul_f32 v81, v81, v92
	v_mul_f32 v78, v78, v92
	v_mul_f32 v79, v79, v92
	v_mul_f32 v76, v76, v92
	v_mul_f32 v77, v77, v92
	v_mul_f32 v74, v74, v92
	v_mul_f32 v75, v75, v92
	v_mul_f32 v72, v72, v92
	v_mul_f32 v73, v73, v92
	v_mul_f32 v70, v70, v92
	v_mul_f32 v71, v71, v92
	v_mul_f32 v68, v68, v92
	v_mul_f32 v69, v69, v92
	v_mul_f32 v66, v66, v92
	v_mul_f32 v67, v67, v92
	v_mul_f32 v64, v64, v92
	v_mul_f32 v65, v65, v92
	v_mul_f32 v62, v62, v92
	v_mul_f32 v63, v63, v92
	v_mul_f32 v60, v60, v92
	v_mul_f32 v61, v61, v92
	v_mul_f32 v58, v58, v92
	v_mul_f32 v59, v59, v92
	v_mul_f32 v56, v56, v92
	v_mul_f32 v57, v57, v92
	v_mul_f32 v54, v54, v92
	v_mul_f32 v55, v55, v92
	v_mul_f32 v52, v52, v92
	v_mul_f32 v53, v53, v92
	v_mul_f32 v50, v50, v92
	v_mul_f32 v51, v51, v92
	v_mul_f32 v48, v48, v92
	v_mul_f32 v49, v49, v92
	v_mul_f32 v46, v46, v92
	v_mul_f32 v47, v47, v92
	v_mul_f32 v44, v44, v92
	v_mul_f32 v45, v45, v92
	v_mul_f32 v42, v42, v92
	v_mul_f32 v43, v43, v92
	v_mul_f32 v40, v40, v92
	v_mul_f32 v41, v41, v92
	v_mul_f32 v38, v38, v92
	v_mul_f32 v39, v39, v92
	v_mul_f32 v36, v36, v92
	v_mul_f32 v37, v37, v92
	v_mul_f32 v34, v34, v92
	v_mul_f32 v35, v35, v92
	v_mul_f32 v32, v32, v92
	v_mul_f32 v33, v33, v92
	v_mul_f32 v30, v30, v92
	v_mul_f32 v31, v31, v92
	v_mul_f32 v28, v28, v92
	v_mul_f32 v29, v29, v92
	v_mul_f32 v26, v26, v92
	v_mul_f32 v27, v27, v92
	v_mul_f32 v24, v24, v92
	v_mul_f32 v25, v25, v92
	v_mul_f32 v22, v22, v92
	v_mul_f32 v23, v23, v92
	v_mul_f32 v20, v20, v92
	v_mul_f32 v21, v21, v92
	v_mul_f32 v18, v18, v92
	v_mul_f32 v19, v19, v92

.LBB0_996:
	ds_read_b128 v[82:85], v211 offset:0
	ds_read_b128 v[86:89], v211 offset:0x400
	ds_read_b128 v[146:149], v211 offset:0x800
	ds_read_b128 v[152:155], v211 offset:0xc00
	ds_read_b128 v[156:159], v211 offset:0x1000
	ds_read_b128 v[160:163], v211 offset:0x1400
	ds_read_b128 v[164:167], v211 offset:0x1800
	ds_read_b128 v[168:171], v211 offset:0x1c00
	ds_read_b128 v[172:175], v211 offset:0x2000
	ds_read_b128 v[176:179], v211 offset:0x2400
	ds_read_b128 v[180:183], v211 offset:0x2800
	ds_read_b128 v[142:145], v211 offset:0x2c00
	ds_read_b128 v[138:141], v211 offset:0x3000
	ds_read_b128 v[12:15], v211 offset:0x3400
	ds_read_b128 v[8:11], v211 offset:0x3800
	ds_read_b128 v[4:7], v211 offset:0x3c00
	s_nop 0
	s_waitcnt lgkmcnt(8)
	s_and_b64 s[74:75], exec, s[72:73]
	v_mfma_f32_32x32x16_bf16 v[90:105], v[82:85], v[106:109], 0
	s_cselect_b32 s4, 0, s4
	s_sub_i32 s4, s4, s94
	v_med3_i32 v2, s4, -7, 7
	s_movk_i32 s4, 0x7c
	v_mul_lo_u32 v2, v2, s4
	v_add_u32_e32 v2, 0, v2
	v_add_u32_e32 v2, 0x20200, v2
	v_mfma_f32_32x32x16_bf16 v[90:105], v[86:89], v[110:113], v[90:105]
	s_waitcnt lgkmcnt(0)
	v_readlane_b32 s4, v248, 10
	v_readlane_b32 s5, v248, 11
	v_mfma_f32_32x32x16_bf16 v[90:105], v[146:149], v[114:117], v[90:105]
	v_lshl_add_u32 v147, v187, 2, v2
	v_lshl_add_u32 v149, v213, 2, v2
	ds_read_b32 v149, v149 offset:1000
	v_mfma_f32_32x32x16_bf16 v[90:105], v[152:155], v[118:121], v[90:105]
	ds_read_b32 v154, v147 offset:928
	v_lshl_add_u32 v147, v188, 2, v2
	ds_read_b32 v155, v147 offset:932
	v_mfma_f32_32x32x16_bf16 v[90:105], v[156:159], v[122:125], v[90:105]
	v_lshl_add_u32 v159, v214, 2, v2
	v_mfma_f32_32x32x16_bf16 v[90:105], v[160:163], v[126:129], v[90:105]
	ds_read_b32 v163, v159 offset:1004
	v_lshl_add_u32 v147, v189, 2, v2
	v_lshl_add_u32 v159, v215, 2, v2
	ds_read_b32 v156, v147 offset:936
	v_mfma_f32_32x32x16_bf16 v[90:105], v[164:167], v[130:133], v[90:105]
	ds_read_b32 v165, v159 offset:1024
	v_lshl_add_u32 v147, v190, 2, v2
	v_lshl_add_u32 v159, v216, 2, v2
	ds_read_b32 v158, v147 offset:940
	ds_read_b32 v167, v159 offset:1028
	v_lshl_add_u32 v147, v191, 2, v2
	v_lshl_add_u32 v159, v217, 2, v2
	v_mfma_f32_32x32x16_bf16 v[90:105], v[168:171], v[134:137], v[90:105]
	ds_read_b32 v160, v147 offset:960
	ds_read_b32 v169, v159 offset:1032
	v_lshl_add_u32 v147, v200, 2, v2
	v_lshl_add_u32 v159, v218, 2, v2
	ds_read_b32 v162, v147 offset:964
	ds_read_b32 v171, v159 offset:1036
	v_lshl_add_u32 v147, v201, 2, v2
	s_nop 4
	v_mul_f32_e32 v16, 0x3e0293ee, v90
	s_waitcnt lgkmcnt(0)
	v_fmamk_f32 v154, v154, 0x3fb8aa3b, v16
	v_mul_f32_e32 v17, 0x3e0293ee, v91
	v_cndmask_b32_e64 v154, v235, v154, s[4:5]
	v_readlane_b32 s4, v248, 12
	v_cndmask_b32_e64 v159, v154, v16, s[72:73]
	v_fmamk_f32 v16, v155, 0x3fb8aa3b, v17
	v_readlane_b32 s5, v248, 13
	v_mul_f32_e32 v146, 0x3e0293ee, v92
	v_mul_f32_e32 v148, 0x3e0293ee, v93
	v_cndmask_b32_e64 v16, v235, v16, s[4:5]
	v_readlane_b32 s4, v248, 14
	v_cndmask_b32_e64 v161, v16, v17, s[72:73]
	v_fmamk_f32 v16, v156, 0x3fb8aa3b, v146
	v_readlane_b32 s5, v248, 15
	v_mul_f32_e32 v151, 0x3e0293ee, v94
	ds_read_b32 v164, v147 offset:968
	v_cndmask_b32_e64 v16, v235, v16, s[4:5]
	v_readlane_b32 s4, v248, 16
	v_cndmask_b32_e64 v154, v16, v146, s[72:73]
	v_fmamk_f32 v16, v158, 0x3fb8aa3b, v148
	v_readlane_b32 s5, v248, 17
	v_lshl_add_u32 v147, v202, 2, v2
	v_mul_f32_e32 v152, 0x3e0293ee, v95
	v_cndmask_b32_e64 v16, v235, v16, s[4:5]
	v_readlane_b32 s4, v248, 18
	v_cndmask_b32_e64 v156, v16, v148, s[72:73]
	v_fmamk_f32 v16, v160, 0x3fb8aa3b, v151
	v_readlane_b32 s5, v248, 19
	ds_read_b32 v166, v147 offset:972
	v_lshl_add_u32 v147, v203, 2, v2
	v_cndmask_b32_e64 v16, v235, v16, s[4:5]
	v_readlane_b32 s4, v248, 20
	v_cndmask_b32_e64 v155, v16, v151, s[72:73]
	v_fmamk_f32 v16, v162, 0x3fb8aa3b, v152
	v_readlane_b32 s5, v248, 21
	v_mul_f32_e32 v153, 0x3e0293ee, v96
	ds_read_b32 v168, v147 offset:992
	v_cndmask_b32_e64 v16, v235, v16, s[4:5]
	v_readlane_b32 s4, v248, 22
	v_cndmask_b32_e64 v152, v16, v152, s[72:73]
	s_waitcnt lgkmcnt(0)
	v_fmamk_f32 v16, v164, 0x3fb8aa3b, v153
	v_readlane_b32 s5, v248, 23
	v_mul_f32_e32 v157, 0x3e0293ee, v97
	v_lshl_add_u32 v147, v212, 2, v2
	v_cndmask_b32_e64 v16, v235, v16, s[4:5]
	v_readlane_b32 s4, v248, 24
	ds_read_b32 v147, v147 offset:996
	v_fmamk_f32 v17, v166, 0x3fb8aa3b, v157
	v_readlane_b32 s5, v248, 25
	v_mul_f32_e32 v98, 0x3e0293ee, v98
	v_fmamk_f32 v146, v168, 0x3fb8aa3b, v98
	v_cndmask_b32_e64 v17, v235, v17, s[4:5]
	v_readlane_b32 s4, v248, 26
	v_readlane_b32 s5, v248, 27
	v_mov_b32_e32 v148, v100
	v_cndmask_b32_e64 v16, v16, v153, s[72:73]
	v_cndmask_b32_e64 v146, v235, v146, s[4:5]
	v_cndmask_b32_e64 v151, v146, v98, s[72:73]
	v_mov_b32_e32 v146, v99
	s_waitcnt lgkmcnt(0)
	v_mul_f32 v98, s68, v146
	v_mul_f32 v99, s69, v147
	v_readlane_b32 s4, v248, 28
	v_add_f32_e32 v99, v98, v99
	v_readlane_b32 s5, v248, 29
	v_mov_b32_e32 v162, v101
	v_cndmask_b32_e64 v17, v17, v157, s[72:73]
	v_cndmask_b32_e64 v99, v235, v99, s[4:5]
	v_cndmask_b32_e64 v153, v99, v98, s[72:73]
	v_mul_f32 v98, s68, v148
	v_mul_f32 v99, s69, v149
	v_mfma_f32_32x32x16_bf16 v[82:97], v[172:175], v[106:109], 0
	v_add_f32_e32 v99, v98, v99
	v_cndmask_b32_e64 v99, v235, v99, s[20:21]
	v_cndmask_b32_e64 v157, v99, v98, s[72:73]
	v_mul_f32_e64 v98, v162, s68
	v_mul_f32_e64 v99, v163, s69
	v_mov_b32_e32 v164, v102
	v_add_f32_e32 v99, v98, v99
	v_cndmask_b32_e64 v99, v235, v99, s[22:23]
	v_cndmask_b32_e64 v158, v99, v98, s[72:73]
	v_mul_f32 v98, s68, v164
	v_mul_f32 v99, s69, v165
	v_mov_b32_e32 v166, v103
	v_add_f32_e32 v99, v98, v99
	v_cndmask_b32_e64 v99, v235, v99, s[24:25]
	v_cndmask_b32_e64 v160, v99, v98, s[72:73]
	v_mul_f32 v98, s68, v166
	v_mul_f32 v99, s69, v167
	v_mov_b32_e32 v168, v104
	v_add_f32_e32 v99, v98, v99
	v_cndmask_b32_e64 v99, v235, v99, s[26:27]
	v_mfma_f32_32x32x16_bf16 v[82:97], v[176:179], v[110:113], v[82:97]
	v_cndmask_b32_e64 v162, v99, v98, s[72:73]
	v_mul_f32_e64 v98, v168, s68
	v_mul_f32_e64 v99, v169, s69
	v_mov_b32_e32 v170, v105
	v_add_f32_e32 v99, v98, v99
	v_cndmask_b32_e64 v99, v235, v99, s[28:29]
	v_cndmask_b32_e64 v163, v99, v98, s[72:73]
	v_mul_f32 v98, s68, v170
	v_mul_f32 v99, s69, v171
	v_mfma_f32_32x32x16_bf16 v[82:97], v[180:183], v[114:117], v[82:97]
	v_add_f32_e32 v99, v98, v99
	v_cndmask_b32_e64 v99, v235, v99, s[30:31]
	v_cndmask_b32_e64 v164, v99, v98, s[72:73]
	v_max3_f32 v98, v159, s92, v161
	v_max3_f32 v98, v98, v154, v156
	v_max3_f32 v98, v98, v155, v152
	v_max3_f32 v98, v98, v16, v17
	v_max3_f32 v98, v98, v151, v153
	v_max3_f32 v98, v98, v157, v158
	v_max3_f32 v98, v98, v160, v162
	v_max3_f32 v98, v98, v163, v164
	ds_bpermute_b32 v99, v206, v98
	v_mfma_f32_32x32x16_bf16 v[82:97], v[142:145], v[118:121], v[82:97]
	s_waitcnt lgkmcnt(0)
	v_max_f32_e32 v99, v99, v99
	v_max_f32_e32 v98, v98, v99
	v_sub_f32_e32 v99, v98, v236
	v_cmp_ge_f32_e32 vcc, s93, v99
	s_cmp_eq_u64 vcc, exec
	s_cbranch_scc1 .LBB0_998
	v_max_f32_e32 v98, v98, v98
	v_max_f32_e32 v99, v236, v236
	v_max_f32_e32 v99, v99, v98
	v_sub_f32_e32 v98, v236, v99
	v_exp_f32_e32 v98, v98
	v_mov_b32_e32 v236, v99
	v_mul_f32_e32 v150, v150, v98
	v_mul_f32 v80, v80, v98
	v_mul_f32 v81, v81, v98
	v_mul_f32 v78, v78, v98
	v_mul_f32 v79, v79, v98
	v_mul_f32 v76, v76, v98
	v_mul_f32 v77, v77, v98
	v_mul_f32 v74, v74, v98
	v_mul_f32 v75, v75, v98
	v_mul_f32 v72, v72, v98
	v_mul_f32 v73, v73, v98
	v_mul_f32 v70, v70, v98
	v_mul_f32 v71, v71, v98
	v_mul_f32 v68, v68, v98
	v_mul_f32 v69, v69, v98
	v_mul_f32 v66, v66, v98
	v_mul_f32 v67, v67, v98
	v_mul_f32 v64, v64, v98
	v_mul_f32 v65, v65, v98
	v_mul_f32 v62, v62, v98
	v_mul_f32 v63, v63, v98
	v_mul_f32 v60, v60, v98
	v_mul_f32 v61, v61, v98
	v_mul_f32 v58, v58, v98
	v_mul_f32 v59, v59, v98
	v_mul_f32 v56, v56, v98
	v_mul_f32 v57, v57, v98
	v_mul_f32 v54, v54, v98
	v_mul_f32 v55, v55, v98
	v_mul_f32 v52, v52, v98
	v_mul_f32 v53, v53, v98
	v_mul_f32 v50, v50, v98
	v_mul_f32 v51, v51, v98
	v_mul_f32 v48, v48, v98
	v_mul_f32 v49, v49, v98
	v_mul_f32 v46, v46, v98
	v_mul_f32 v47, v47, v98
	v_mul_f32 v44, v44, v98
	v_mul_f32 v45, v45, v98
	v_mul_f32 v42, v42, v98
	v_mul_f32 v43, v43, v98
	v_mul_f32 v40, v40, v98
	v_mul_f32 v41, v41, v98
	v_mul_f32 v38, v38, v98
	v_mul_f32 v39, v39, v98
	v_mul_f32 v36, v36, v98
	v_mul_f32 v37, v37, v98
	v_mul_f32 v34, v34, v98
	v_mul_f32 v35, v35, v98
	v_mul_f32 v32, v32, v98
	v_mul_f32 v33, v33, v98
	v_mul_f32 v30, v30, v98
	v_mul_f32 v31, v31, v98
	v_mul_f32 v28, v28, v98
	v_mul_f32 v29, v29, v98
	v_mul_f32 v26, v26, v98
	v_mul_f32 v27, v27, v98
	v_mul_f32 v24, v24, v98
	v_mul_f32 v25, v25, v98
	v_mul_f32 v22, v22, v98
	v_mul_f32 v23, v23, v98
	v_mul_f32 v20, v20, v98
	v_mul_f32 v21, v21, v98
	v_mul_f32 v18, v18, v98
	v_mul_f32 v19, v19, v98
.LBB0_998:
	v_sub_f32_e32 v159, v159, v236
	v_mfma_f32_32x32x16_bf16 v[82:97], v[138:141], v[122:125], v[82:97]
	v_exp_f32_e32 v159, v159
	v_sub_f32_e32 v161, v161, v236
	v_exp_f32_e32 v161, v161
	v_sub_f32_e32 v154, v154, v236
	v_exp_f32_e32 v154, v154
	v_sub_f32_e32 v156, v156, v236
	v_exp_f32_e32 v156, v156
	v_sub_f32_e32 v155, v155, v236
	v_add_f32_e32 v165, 0, v159
	v_exp_f32_e32 v155, v155
	v_sub_f32_e32 v152, v152, v236
	v_add_f32_e32 v165, v161, v165
	v_exp_f32_e32 v152, v152
	v_sub_f32_e32 v16, v16, v236
	v_add_f32_e32 v165, v154, v165
	v_exp_f32_e32 v166, v16
	v_add_f32_e32 v165, v156, v165
	v_mfma_f32_32x32x16_bf16 v[82:97], v[12:15], v[126:129], v[82:97]
	v_add_f32_e32 v165, v155, v165
	v_add_f32_e32 v165, v152, v165
	v_sub_f32_e32 v17, v17, v236
	v_add_f32_e32 v16, v166, v165
	v_exp_f32_e32 v165, v17
	ds_read_b128 v[182:185], v211 offset:0x4000
	ds_read_b128 v[170:173], v211 offset:0x4400
	v_mfma_f32_32x32x16_bf16 v[82:97], v[8:11], v[130:133], v[82:97]
	v_add_f32_e32 v17, v165, v16
	v_sub_f32_e32 v16, v151, v236
	v_exp_f32_e32 v16, v16
	ds_read_b128 v[174:177], v211 offset:0x4800
	ds_read_b128 v[178:181], v211 offset:0x4c00
	ds_read_b128 v[146:149], v211 offset:0x5000
	ds_read_b128 v[142:145], v211 offset:0x5400
	v_mfma_f32_32x32x16_bf16 v[82:97], v[4:7], v[134:137], v[82:97]
	v_add_f32_e32 v151, v16, v17
	v_sub_f32_e32 v17, v153, v236
	v_exp_f32_e32 v17, v17
	v_sub_f32_e32 v153, v157, v236
	v_exp_f32_e32 v237, v153
	v_sub_f32_e32 v153, v158, v236
	v_exp_f32_e32 v238, v153
	v_sub_f32_e32 v153, v160, v236
	v_exp_f32_e32 v239, v153
	v_sub_f32_e32 v153, v162, v236
	v_add_f32_e32 v151, v17, v151
	v_exp_f32_e32 v240, v153
	v_sub_f32_e32 v153, v163, v236
	v_add_f32_e32 v151, v237, v151
	v_exp_f32_e32 v241, v153
	v_sub_f32_e32 v153, v164, v236
	v_add_f32_e32 v151, v238, v151
	v_exp_f32_e32 v242, v153
	v_add_f32_e32 v151, v239, v151
	v_add_f32_e32 v151, v240, v151
	v_add_f32_e32 v151, v241, v151
	ds_read_b128 v[102:105], v211 offset:0x5800
	ds_read_b128 v[98:101], v211 offset:0x5c00
	v_add_f32_e32 v151, v242, v151
	v_lshl_add_u32 v5, v219, 2, v2
	v_lshl_add_u32 v7, v229, 2, v2
	v_add_f32_e32 v243, v150, v151
	v_cvt_pk_bf16_f32 v244, v159, v161
	v_cvt_pk_bf16_f32 v245, v154, v156
	v_cvt_pk_bf16_f32 v246, v155, v152
	v_cvt_pk_bf16_f32 v247, v166, v165
	ds_read_b128 v[166:169], v211 offset:0x6000
	ds_read_b128 v[162:165], v211 offset:0x6400
	ds_read_b128 v[158:161], v211 offset:0x6800
	ds_read_b128 v[154:157], v211 offset:0x6c00
	ds_read_b128 v[150:153], v211 offset:0x7000
	ds_read_b128 v[138:141], v211 offset:0x7400
	ds_read_b128 v[12:15], v211 offset:0x7800
	ds_read_b128 v[8:11], v211 offset:0x7c00
	s_waitcnt lgkmcnt(8)
	v_mul_f32_e32 v4, 0x3e0293ee, v82
	v_mul_f32_e32 v6, 0x3e0293ee, v83
	v_mul_f32_e32 v82, 0x3e0293ee, v84
	v_mul_f32_e32 v84, 0x3e0293ee, v85
	ds_read_b32 v85, v5 offset:928
	ds_read_b32 v7, v7 offset:1000
	v_lshl_add_u32 v5, v220, 2, v2
	v_lshl_add_u32 v83, v230, 2, v2
	v_mfma_f32_32x32x16_bf16 v[50:65], v[170:173], v[244:247], v[50:65]
	v_mul_f32_e32 v170, 0x3e0293ee, v86
	ds_read_b32 v86, v5 offset:932
	ds_read_b32 v83, v83 offset:1004
	v_lshl_add_u32 v5, v221, 2, v2
	v_lshl_add_u32 v171, v231, 2, v2
	v_mul_f32_e32 v172, 0x3e0293ee, v87
	ds_read_b32 v87, v5 offset:936
	ds_read_b32 v173, v171 offset:1024
	v_lshl_add_u32 v5, v222, 2, v2
	v_lshl_add_u32 v171, v232, 2, v2
	v_mfma_f32_32x32x16_bf16 v[34:49], v[174:177], v[244:247], v[34:49]
	v_mul_f32_e32 v174, 0x3e0293ee, v88
	ds_read_b32 v88, v5 offset:940
	ds_read_b32 v175, v171 offset:1028
	v_lshl_add_u32 v5, v223, 2, v2
	v_lshl_add_u32 v171, v233, 2, v2
	v_mul_f32_e32 v176, 0x3e0293ee, v89
	ds_read_b32 v89, v5 offset:960
	ds_read_b32 v177, v171 offset:1032
	v_lshl_add_u32 v5, v224, 2, v2
	v_mfma_f32_32x32x16_bf16 v[18:33], v[178:181], v[244:247], v[18:33]
	v_mul_f32_e32 v178, 0x3e0293ee, v90
	ds_read_b32 v90, v5 offset:964
	v_lshl_add_u32 v5, v225, 2, v2
	ds_read_b32 v180, v5 offset:968
	v_lshl_add_u32 v5, v226, 2, v2
	ds_read_b32 v181, v5 offset:972
	v_lshl_add_u32 v5, v227, 2, v2
	v_mfma_f32_32x32x16_bf16 v[66:81], v[182:185], v[244:247], v[66:81]
	ds_read_b32 v182, v5 offset:992
	v_lshl_add_u32 v5, v228, 2, v2
	v_lshl_add_u32 v2, v234, 2, v2
	ds_read_b32 v5, v5 offset:996
	ds_read_b32 v179, v2 offset:1036
	s_waitcnt lgkmcnt(0)
	v_fmamk_f32 v2, v85, 0x3fb8aa3b, v4
	v_cndmask_b32_e64 v2, v235, v2, s[34:35]
	v_cndmask_b32_e64 v171, v2, v4, s[72:73]
	v_fmamk_f32 v2, v86, 0x3fb8aa3b, v6
	v_cndmask_b32_e64 v2, v235, v2, s[36:37]
	v_cndmask_b32_e64 v85, v2, v6, s[72:73]
	v_fmamk_f32 v2, v87, 0x3fb8aa3b, v82
	v_cndmask_b32_e64 v2, v235, v2, s[38:39]
	v_mov_b32_e32 v4, v91
	v_cndmask_b32_e64 v86, v2, v82, s[72:73]
	v_fmamk_f32 v2, v88, 0x3fb8aa3b, v84
	v_mul_f32 v4, s68, v4
	v_mul_f32 v5, s69, v5
	v_cndmask_b32_e64 v2, v235, v2, s[40:41]
	v_add_f32_e32 v5, v4, v5
	v_mov_b32_e32 v6, v92
	v_cndmask_b32_e64 v87, v2, v84, s[72:73]
	v_fmamk_f32 v2, v89, 0x3fb8aa3b, v170
	v_cndmask_b32_e64 v5, v235, v5, s[6:7]
	v_mul_f32 v6, s68, v6
	v_mul_f32 v7, s69, v7
	v_cndmask_b32_e64 v2, v235, v2, s[42:43]
	v_cndmask_b32_e64 v4, v5, v4, s[72:73]
	v_add_f32_e32 v5, v6, v7
	v_cndmask_b32_e64 v88, v2, v170, s[72:73]
	v_fmamk_f32 v2, v90, 0x3fb8aa3b, v172
	v_cndmask_b32_e64 v5, v235, v5, s[8:9]
	v_mov_b32_e32 v82, v93
	v_cndmask_b32_e64 v2, v235, v2, s[44:45]
	v_cndmask_b32_e64 v5, v5, v6, s[72:73]
	v_mul_f32 v6, s68, v82
	v_mul_f32 v7, s69, v83
	v_cndmask_b32_e64 v89, v2, v172, s[72:73]
	v_add_f32_e32 v7, v6, v7
	v_mov_b32_e32 v172, v94
	v_fmamk_f32 v2, v180, 0x3fb8aa3b, v174
	v_cndmask_b32_e64 v7, v235, v7, s[10:11]
	v_mul_f32 v82, s68, v172
	v_mul_f32 v83, s69, v173
	v_cndmask_b32_e64 v2, v235, v2, s[46:47]
	v_cndmask_b32_e64 v6, v7, v6, s[72:73]
	v_add_f32_e32 v7, v82, v83
	v_cndmask_b32_e64 v90, v2, v174, s[72:73]
	v_fmamk_f32 v2, v181, 0x3fb8aa3b, v176
	v_cndmask_b32_e64 v7, v235, v7, s[12:13]
	v_mov_b32_e32 v174, v95
	v_cndmask_b32_e64 v2, v235, v2, s[48:49]
	v_cndmask_b32_e64 v7, v7, v82, s[72:73]
	v_mul_f32 v82, s68, v174
	v_mul_f32 v83, s69, v175
	v_cndmask_b32_e64 v170, v2, v176, s[72:73]
	v_add_f32_e32 v83, v82, v83
	v_mov_b32_e32 v176, v96
	v_fmamk_f32 v2, v182, 0x3fb8aa3b, v178
	v_cndmask_b32_e64 v83, v235, v83, s[14:15]
	v_mul_f32 v92, s68, v176
	v_mul_f32 v93, s69, v177
	v_max3_f32 v91, v171, s92, v85
	v_cndmask_b32_e64 v2, v235, v2, s[50:51]
	v_cndmask_b32_e64 v82, v83, v82, s[72:73]
	v_add_f32_e32 v83, v92, v93
	v_max3_f32 v91, v91, v86, v87
	v_cndmask_b32_e64 v2, v2, v178, s[72:73]
	v_cndmask_b32_e64 v83, v235, v83, s[16:17]
	v_mov_b32_e32 v178, v97
	v_max3_f32 v91, v91, v88, v89
	v_cndmask_b32_e64 v83, v83, v92, s[72:73]
	v_mul_f32 v92, s68, v178
	v_mul_f32 v93, s69, v179
	v_max3_f32 v91, v91, v90, v170
	v_add_f32_e32 v84, v92, v93
	v_max3_f32 v91, v91, v2, v4
	v_cndmask_b32_e64 v84, v235, v84, s[18:19]
	v_max3_f32 v91, v91, v5, v6
	v_cndmask_b32_e64 v84, v84, v92, s[72:73]
	v_max3_f32 v91, v91, v7, v82
	v_max3_f32 v91, v91, v83, v84
	ds_bpermute_b32 v92, v206, v91
	s_waitcnt lgkmcnt(0)
	v_max_f32_e32 v92, v92, v92
	v_max_f32_e32 v91, v91, v92
	v_sub_f32_e32 v92, v91, v236
	v_cmp_ge_f32_e32 vcc, s93, v92
	s_cmp_eq_u64 vcc, exec
	s_cbranch_scc1 .LBB0_1000
	v_max_f32_e32 v91, v91, v91
	v_max_f32_e32 v92, v236, v236
	v_max_f32_e32 v91, v92, v91
	v_sub_f32_e32 v92, v236, v91
	v_exp_f32_e32 v92, v92
	v_mov_b32_e32 v236, v91
	v_mul_f32_e32 v243, v243, v92
	v_mul_f32 v80, v80, v92
	v_mul_f32 v81, v81, v92
	v_mul_f32 v78, v78, v92
	v_mul_f32 v79, v79, v92
	v_mul_f32 v76, v76, v92
	v_mul_f32 v77, v77, v92
	v_mul_f32 v74, v74, v92
	v_mul_f32 v75, v75, v92
	v_mul_f32 v72, v72, v92
	v_mul_f32 v73, v73, v92
	v_mul_f32 v70, v70, v92
	v_mul_f32 v71, v71, v92
	v_mul_f32 v68, v68, v92
	v_mul_f32 v69, v69, v92
	v_mul_f32 v66, v66, v92
	v_mul_f32 v67, v67, v92
	v_mul_f32 v64, v64, v92
	v_mul_f32 v65, v65, v92
	v_mul_f32 v62, v62, v92
	v_mul_f32 v63, v63, v92
	v_mul_f32 v60, v60, v92
	v_mul_f32 v61, v61, v92
	v_mul_f32 v58, v58, v92
	v_mul_f32 v59, v59, v92
	v_mul_f32 v56, v56, v92
	v_mul_f32 v57, v57, v92
	v_mul_f32 v54, v54, v92
	v_mul_f32 v55, v55, v92
	v_mul_f32 v52, v52, v92
	v_mul_f32 v53, v53, v92
	v_mul_f32 v50, v50, v92
	v_mul_f32 v51, v51, v92
	v_mul_f32 v48, v48, v92
	v_mul_f32 v49, v49, v92
	v_mul_f32 v46, v46, v92
	v_mul_f32 v47, v47, v92
	v_mul_f32 v44, v44, v92
	v_mul_f32 v45, v45, v92
	v_mul_f32 v42, v42, v92
	v_mul_f32 v43, v43, v92
	v_mul_f32 v40, v40, v92
	v_mul_f32 v41, v41, v92
	v_mul_f32 v38, v38, v92
	v_mul_f32 v39, v39, v92
	v_mul_f32 v36, v36, v92
	v_mul_f32 v37, v37, v92
	v_mul_f32 v34, v34, v92
	v_mul_f32 v35, v35, v92
	v_mul_f32 v32, v32, v92
	v_mul_f32 v33, v33, v92
	v_mul_f32 v30, v30, v92
	v_mul_f32 v31, v31, v92
	v_mul_f32 v28, v28, v92
	v_mul_f32 v29, v29, v92
	v_mul_f32 v26, v26, v92
	v_mul_f32 v27, v27, v92
	v_mul_f32 v24, v24, v92
	v_mul_f32 v25, v25, v92
	v_mul_f32 v22, v22, v92
	v_mul_f32 v23, v23, v92
	v_mul_f32 v20, v20, v92
	v_mul_f32 v21, v21, v92
	v_mul_f32 v18, v18, v92
	v_mul_f32 v19, v19, v92

.LBB0_1002:
	ds_bpermute_b32 v2, v206, v215
	s_lshl_b32 s4, s44, 7
	s_lshl_b32 s26, s45, 16
	s_waitcnt lgkmcnt(0)
	v_add_f32_e32 v2, v215, v2
	v_div_scale_f32 v4, s[0:1], v2, v2, 1.0
	v_rcp_f32_e32 v5, v4
	v_div_scale_f32 v6, vcc, 1.0, v2, 1.0
	s_or_b32 s0, s26, s4
	v_fma_f32 v7, -v4, v5, 1.0
	v_fmac_f32_e32 v5, v7, v5
	v_mul_f32_e32 v7, v6, v5
	v_fma_f32 v8, -v4, v7, v6
	v_fmac_f32_e32 v7, v8, v5
	v_fma_f32 v4, -v4, v7, v6
	v_div_fmas_f32 v4, v4, v5, v7
	v_div_fixup_f32 v8, v4, v2, 1.0
	v_mov_b32_e32 v2, v1
	v_mul_f32 v4, v66, v8
	v_mul_f32 v5, v67, v8
	v_mul_f32 v6, v68, v8
	v_mul_f32 v7, v69, v8
	v_cvt_pk_bf16_f32 v4, v4, v5
	v_cvt_pk_bf16_f32 v5, v6, v7
	v_mul_f32 v6, v70, v8
	v_mul_f32 v7, v71, v8
	v_mul_f32 v12, v72, v8
	v_mul_f32 v13, v73, v8
	v_lshl_add_u32 v2, v2, 11, s0
	v_cvt_pk_bf16_f32 v6, v6, v7
	v_cvt_pk_bf16_f32 v7, v12, v13
	v_lshl_add_u64 v[10:11], v[2:3], 1, v[198:199]
	v_permlane32_swap_b32_e32 v4, v6
	v_permlane32_swap_b32_e32 v5, v7
	global_store_dwordx4 v[10:11], v[4:7], off
	v_mul_f32 v12, v80, v8
	v_mul_f32 v13, v81, v8
	s_nop 0
	v_mul_f32 v4, v74, v8
	v_mul_f32 v5, v75, v8
	v_mul_f32 v6, v76, v8
	v_mul_f32 v7, v77, v8
	v_cvt_pk_bf16_f32 v4, v4, v5
	v_cvt_pk_bf16_f32 v5, v6, v7
	v_mul_f32 v6, v78, v8
	v_mul_f32 v7, v79, v8
	s_nop 0
	v_cvt_pk_bf16_f32 v6, v6, v7
	v_cvt_pk_bf16_f32 v7, v12, v13
	s_nop 0
	v_permlane32_swap_b32_e32 v4, v6
	v_permlane32_swap_b32_e32 v5, v7
	global_store_dwordx4 v[10:11], v[4:7], off offset:32
	v_mul_f32 v12, v56, v8
	v_mul_f32 v13, v57, v8
	s_nop 0
	v_mul_f32 v4, v50, v8
	v_mul_f32 v5, v51, v8
	v_mul_f32 v6, v52, v8
	v_mul_f32 v7, v53, v8
	v_cvt_pk_bf16_f32 v4, v4, v5
	v_cvt_pk_bf16_f32 v5, v6, v7
	v_mul_f32 v6, v54, v8
	v_mul_f32 v7, v55, v8
	s_nop 0
	v_cvt_pk_bf16_f32 v6, v6, v7
	v_cvt_pk_bf16_f32 v7, v12, v13
	s_nop 0
	v_permlane32_swap_b32_e32 v4, v6
	v_permlane32_swap_b32_e32 v5, v7
	global_store_dwordx4 v[10:11], v[4:7], off offset:64
	v_mul_f32 v12, v64, v8
	v_mul_f32 v13, v65, v8
	s_nop 0
	v_mul_f32 v4, v58, v8
	v_mul_f32 v5, v59, v8
	v_mul_f32 v6, v60, v8
	v_mul_f32 v7, v61, v8
	v_cvt_pk_bf16_f32 v4, v4, v5
	v_cvt_pk_bf16_f32 v5, v6, v7
	v_mul_f32 v6, v62, v8
	v_mul_f32 v7, v63, v8
	s_nop 0
	v_cvt_pk_bf16_f32 v6, v6, v7
	v_cvt_pk_bf16_f32 v7, v12, v13
	s_nop 0
	v_permlane32_swap_b32_e32 v4, v6
	v_permlane32_swap_b32_e32 v5, v7
	global_store_dwordx4 v[10:11], v[4:7], off offset:96
	v_mul_f32 v12, v40, v8
	v_mul_f32 v13, v41, v8
	s_nop 0
	v_mul_f32 v4, v34, v8
	v_mul_f32 v5, v35, v8
	v_mul_f32 v6, v36, v8
	v_mul_f32 v7, v37, v8
	v_cvt_pk_bf16_f32 v4, v4, v5
	v_cvt_pk_bf16_f32 v5, v6, v7
	v_mul_f32 v6, v38, v8
	v_mul_f32 v7, v39, v8
	s_nop 0
	v_cvt_pk_bf16_f32 v6, v6, v7
	v_cvt_pk_bf16_f32 v7, v12, v13
	s_nop 0
	v_permlane32_swap_b32_e32 v4, v6
	v_permlane32_swap_b32_e32 v5, v7
	global_store_dwordx4 v[10:11], v[4:7], off offset:128
	v_mul_f32 v12, v48, v8
	v_mul_f32 v13, v49, v8
	s_nop 0
	v_mul_f32 v4, v42, v8
	v_mul_f32 v5, v43, v8
	v_mul_f32 v6, v44, v8
	v_mul_f32 v7, v45, v8
	v_cvt_pk_bf16_f32 v4, v4, v5
	v_cvt_pk_bf16_f32 v5, v6, v7
	v_mul_f32 v6, v46, v8
	v_mul_f32 v7, v47, v8
	s_nop 0
	v_cvt_pk_bf16_f32 v6, v6, v7
	v_cvt_pk_bf16_f32 v7, v12, v13
	s_nop 0
	v_permlane32_swap_b32_e32 v4, v6
	v_permlane32_swap_b32_e32 v5, v7
	global_store_dwordx4 v[10:11], v[4:7], off offset:160
	v_mul_f32 v12, v24, v8
	v_mul_f32 v13, v25, v8
	s_nop 0
	v_mul_f32 v4, v18, v8
	v_mul_f32 v5, v19, v8
	v_mul_f32 v6, v20, v8
	v_mul_f32 v7, v21, v8
	v_cvt_pk_bf16_f32 v4, v4, v5
	v_cvt_pk_bf16_f32 v5, v6, v7
	v_mul_f32 v6, v22, v8
	v_mul_f32 v7, v23, v8
	s_nop 0
	v_cvt_pk_bf16_f32 v6, v6, v7
	v_cvt_pk_bf16_f32 v7, v12, v13
	s_nop 0
	v_permlane32_swap_b32_e32 v4, v6
	v_permlane32_swap_b32_e32 v5, v7
	global_store_dwordx4 v[10:11], v[4:7], off offset:192
	s_nop 1
	v_mul_f32 v4, v26, v8
	v_mul_f32 v5, v27, v8
	v_mul_f32 v6, v28, v8
	v_mul_f32 v7, v29, v8
	v_cvt_pk_bf16_f32 v4, v4, v5
	v_cvt_pk_bf16_f32 v5, v6, v7
	v_mul_f32 v6, v30, v8
	v_mul_f32 v7, v31, v8
	v_mul_f32 v9, v33, v8
	v_mul_f32 v8, v32, v8
	v_cvt_pk_bf16_f32 v6, v6, v7
	v_cvt_pk_bf16_f32 v7, v8, v9
	s_nop 0
	v_permlane32_swap_b32_e32 v4, v6
	v_permlane32_swap_b32_e32 v5, v7

.LBB0_1004:
	s_and_b32 s45, s46, 0x78
	v_readlane_b32 s0, v249, 45
	s_and_b32 s4, s46, 0x7f
	s_and_b32 s44, s46, 7
	s_add_i32 s45, s45, s0
	s_cmpk_gt_i32 s46, 0x7f
	s_mov_b64 s[0:1], -1
	s_cbranch_scc0 .LBB0_1024
	s_lshl_b32 s1, s45, 15
	s_lshl_b32 s0, s44, 7
	s_lshl_b32 s28, s4, 16
	s_add_u32 s26, s2, s28
	s_addc_u32 s27, s3, 0
	s_add_u32 s28, s33, s28
	s_addc_u32 s29, s34, 0
	s_or_b32 s1, s1, s0
	v_readlane_b32 s30, v248, 5
	v_or_b32_e32 v2, s1, v207
	v_readlane_b32 s31, v248, 6
	s_waitcnt lgkmcnt(0)
	s_barrier
	v_or_b32_e32 v6, 16, v2
	v_lshl_add_u64 v[4:5], v[2:3], 1, s[30:31]
	v_mov_b32_e32 v7, v3
	v_lshl_add_u64 v[6:7], v[6:7], 1, s[30:31]
	global_load_dwordx4 v[128:131], v[4:5], off
	global_load_dwordx4 v[124:127], v[6:7], off
	v_or_b32_e32 v4, 32, v2
	v_mov_b32_e32 v5, v3
	v_lshl_add_u64 v[4:5], v[4:5], 1, s[30:31]
	v_or_b32_e32 v6, 48, v2
	v_mov_b32_e32 v7, v3
	v_lshl_add_u64 v[6:7], v[6:7], 1, s[30:31]
	global_load_dwordx4 v[120:123], v[4:5], off
	global_load_dwordx4 v[116:119], v[6:7], off
	v_or_b32_e32 v4, 64, v2
	v_mov_b32_e32 v5, v3
	v_lshl_add_u64 v[4:5], v[4:5], 1, s[30:31]
	v_or_b32_e32 v6, 0x50, v2
	v_mov_b32_e32 v7, v3
	v_lshl_add_u64 v[6:7], v[6:7], 1, s[30:31]
	global_load_dwordx4 v[112:115], v[4:5], off
	global_load_dwordx4 v[104:107], v[6:7], off
	v_or_b32_e32 v4, 0x60, v2
	v_mov_b32_e32 v5, v3
	v_lshl_add_u64 v[4:5], v[4:5], 1, s[30:31]
	v_or_b32_e32 v2, 0x70, v2
	v_lshl_add_u64 v[6:7], v[2:3], 1, s[30:31]
	global_load_dwordx4 v[108:111], v[4:5], off
	global_load_dwordx4 v[100:103], v[6:7], off
	s_mov_b32 m0, s54
	v_lshl_add_u64 v[4:5], s[26:27], 0, v[192:193]
	global_load_lds_dwordx4 v[4:5], off
	v_lshl_add_u64 v[6:7], v[4:5], 0, s[6:7]
	s_mov_b32 m0, s56
	v_readlane_b32 s1, v248, 46
	global_load_lds_dwordx4 v[6:7], off
	v_lshl_add_u64 v[6:7], s[28:29], 0, v[192:193]
	s_mov_b32 m0, s57
	v_lshl_add_u64 v[8:9], v[6:7], 0, s[6:7]
	global_load_lds_dwordx4 v[6:7], off
	s_mov_b32 m0, s58
	s_nop 0
	global_load_lds_dwordx4 v[8:9], off
	v_lshl_add_u64 v[8:9], v[4:5], 0, s[8:9]
	s_mov_b32 m0, s59
	s_nop 0
	global_load_lds_dwordx4 v[8:9], off
	v_lshl_add_u64 v[8:9], v[4:5], 0, s[10:11]
	s_mov_b32 m0, s55
	s_nop 0
	global_load_lds_dwordx4 v[8:9], off
	v_lshl_add_u64 v[8:9], v[6:7], 0, s[8:9]
	s_mov_b32 m0, s60
	s_nop 0
	global_load_lds_dwordx4 v[8:9], off
	v_lshl_add_u64 v[8:9], v[6:7], 0, s[10:11]
	s_mov_b32 m0, s61
	s_nop 0
	global_load_lds_dwordx4 v[8:9], off
	v_lshl_add_u64 v[8:9], v[4:5], 0, s[12:13]
	s_mov_b32 m0, s1
	v_readlane_b32 s1, v248, 47
	global_load_lds_dwordx4 v[8:9], off
	v_lshl_add_u64 v[8:9], v[4:5], 0, s[14:15]
	s_mov_b32 m0, s1
	v_readlane_b32 s1, v248, 0
	global_load_lds_dwordx4 v[8:9], off
	v_lshl_add_u64 v[8:9], v[6:7], 0, s[12:13]
	s_mov_b32 m0, s64
	s_nop 0
	global_load_lds_dwordx4 v[8:9], off
	v_lshl_add_u64 v[8:9], v[6:7], 0, s[14:15]
	s_mov_b32 m0, s65
	s_nop 0
	global_load_lds_dwordx4 v[8:9], off
	s_waitcnt vmcnt(8)
	s_waitcnt lgkmcnt(0)
	s_barrier
	v_lshl_add_u64 v[8:9], v[4:5], 0, s[16:17]
	s_mov_b32 m0, s1
	v_readlane_b32 s1, v249, 63
	global_load_lds_dwordx4 v[8:9], off
	v_lshl_add_u64 v[4:5], v[4:5], 0, s[18:19]
	s_mov_b32 m0, s1
	v_readlane_b32 s1, v249, 62
	global_load_lds_dwordx4 v[4:5], off
	v_lshl_add_u64 v[4:5], v[6:7], 0, s[16:17]
	s_mov_b32 m0, s1
	s_nop 0
	global_load_lds_dwordx4 v[4:5], off
	v_lshl_add_u64 v[4:5], v[6:7], 0, s[18:19]
	s_mov_b32 m0, s39
	s_nop 0
	global_load_lds_dwordx4 v[4:5], off
	ds_read_b128 v[4:7], v195 offset:0
	ds_read_b128 v[8:11], v195 offset:0x400
	ds_read_b128 v[12:15], v195 offset:0x800
	ds_read_b128 v[16:19], v195 offset:0xc00
	ds_read_b128 v[36:39], v195 offset:0x1000
	ds_read_b128 v[40:43], v195 offset:0x1400
	ds_read_b128 v[44:47], v195 offset:0x1800
	ds_read_b128 v[48:51], v195 offset:0x1c00
	ds_read_b128 v[52:55], v195 offset:0x2000
	ds_read_b128 v[56:59], v195 offset:0x2400
	ds_read_b128 v[60:63], v195 offset:0x2800
	ds_read_b128 v[64:67], v195 offset:0x2c00
	ds_read_b128 v[132:135], v195 offset:0x3000
	ds_read_b128 v[136:139], v195 offset:0x3400
	ds_read_b128 v[140:143], v195 offset:0x3800
	ds_read_b128 v[172:175], v195 offset:0x3c00
	s_nop 0
	s_waitcnt lgkmcnt(8)
	s_waitcnt vmcnt(0)
	v_mfma_f32_32x32x16_bf16 v[20:35], v[4:7], v[128:131], 0
	v_mfma_f32_32x32x16_bf16 v[20:35], v[8:11], v[124:127], v[20:35]
	v_mfma_f32_32x32x16_bf16 v[20:35], v[12:15], v[120:123], v[20:35]
	v_mfma_f32_32x32x16_bf16 v[20:35], v[16:19], v[116:119], v[20:35]
	v_mfma_f32_32x32x16_bf16 v[20:35], v[36:39], v[112:115], v[20:35]
	ds_read_b128 v[36:39], v195 offset:0x4000
	ds_read_b128 v[176:179], v195 offset:0x4400
	ds_read_b128 v[180:183], v195 offset:0x4800
	ds_read_b128 v[184:187], v195 offset:0x4c00
	ds_read_b128 v[96:99], v195 offset:0x5000
	ds_read_b128 v[92:95], v195 offset:0x5400
	ds_read_b128 v[88:91], v195 offset:0x5800
	ds_read_b128 v[84:87], v195 offset:0x5c00
	s_waitcnt lgkmcnt(8)
	v_mfma_f32_32x32x16_bf16 v[20:35], v[40:43], v[104:107], v[20:35]
	ds_read_b128 v[160:163], v195 offset:0x6000
	ds_read_b128 v[156:159], v195 offset:0x6400
	ds_read_b128 v[152:155], v195 offset:0x6800
	ds_read_b128 v[148:151], v195 offset:0x6c00
	ds_read_b128 v[144:147], v195 offset:0x7000
	v_mfma_f32_32x32x16_bf16 v[68:83], v[52:55], v[128:131], 0
	v_mfma_f32_32x32x16_bf16 v[68:83], v[56:59], v[124:127], v[68:83]
	v_mfma_f32_32x32x16_bf16 v[20:35], v[44:47], v[108:111], v[20:35]
	v_mfma_f32_32x32x16_bf16 v[68:83], v[60:63], v[120:123], v[68:83]
	v_mfma_f32_32x32x16_bf16 v[20:35], v[48:51], v[100:103], v[20:35]
	v_mfma_f32_32x32x16_bf16 v[68:83], v[64:67], v[116:119], v[68:83]
	s_nop 10
	v_max3_f32 v2, v20, s40, v21
	v_max3_f32 v2, v2, v22, v23
	v_max3_f32 v2, v2, v24, v25
	v_max3_f32 v2, v2, v26, v27
	v_max3_f32 v2, v2, v28, v29
	v_max3_f32 v2, v2, v30, v31
	v_max3_f32 v2, v2, v32, v33
	v_mfma_f32_32x32x16_bf16 v[68:83], v[132:135], v[112:115], v[68:83]
	v_max3_f32 v2, v2, v34, v35
	v_mul_f32_e32 v2, 0x3e0293ee, v2
	ds_bpermute_b32 v4, v206, v2
	s_waitcnt lgkmcnt(0)
	v_max_f32_e32 v4, v4, v4
	v_mfma_f32_32x32x16_bf16 v[68:83], v[136:139], v[104:107], v[68:83]
	v_max_f32_e32 v2, v2, v4
	v_max_f32_e32 v19, 0xf149f2ca, v2
	v_sub_f32_e32 v4, 0xf149f2ca, v19
	v_exp_f32_e32 v4, v4
	v_add_f32_e32 v2, 0x7149f2ca, v2
	v_cmp_ge_f32_e32 vcc, s42, v2
	s_cmp_eq_u64 vcc, exec
	v_mfma_f32_32x32x16_bf16 v[68:83], v[140:143], v[108:111], v[68:83]
	v_mul_f32_e32 v2, 0, v4
	s_cselect_b64 vcc, -1, 0
	v_cndmask_b32_e64 v4, v2, 0, vcc
	v_cndmask_b32_e32 v2, v19, v213, vcc
	v_fma_f32 v19, v20, s41, -v2
	v_exp_f32_e32 v20, v19
	v_fma_f32 v19, v21, s41, -v2
	v_exp_f32_e32 v21, v19
	v_fma_f32 v19, v22, s41, -v2
	v_mfma_f32_32x32x16_bf16 v[68:83], v[172:175], v[100:103], v[68:83]
	v_exp_f32_e32 v22, v19
	v_fma_f32 v23, v23, s41, -v2
	v_add_f32_e32 v40, 0, v20
	v_exp_f32_e32 v23, v23
	v_fma_f32 v24, v24, s41, -v2
	v_add_f32_e32 v40, v21, v40
	v_exp_f32_e32 v24, v24
	v_fma_f32 v25, v25, s41, -v2
	v_cvt_pk_bf16_f32 v188, v20, v21
	v_fma_f32 v21, v31, s41, -v2
	v_exp_f32_e32 v25, v25
	v_fma_f32 v26, v26, s41, -v2
	v_exp_f32_e32 v167, v21
	v_fma_f32 v21, v32, s41, -v2
	v_add_f32_e32 v40, v22, v40
	v_exp_f32_e32 v26, v26
	v_fma_f32 v27, v27, s41, -v2
	v_exp_f32_e32 v168, v21
	v_fma_f32 v21, v33, s41, -v2
	v_add_f32_e32 v40, v23, v40
	v_exp_f32_e32 v27, v27
	v_fma_f32 v28, v28, s41, -v2
	v_exp_f32_e32 v169, v21
	v_fma_f32 v21, v34, s41, -v2
	v_add_f32_e32 v40, v24, v40
	v_exp_f32_e32 v164, v28
	v_fma_f32 v28, v29, s41, -v2
	v_exp_f32_e32 v170, v21
	v_fma_f32 v21, v35, s41, -v2
	v_add_f32_e32 v40, v25, v40
	v_exp_f32_e32 v165, v28
	v_fma_f32 v29, v30, s41, -v2
	v_exp_f32_e32 v171, v21
	v_max3_f32 v21, v68, s40, v69
	v_add_f32_e32 v40, v26, v40
	v_exp_f32_e32 v166, v29
	v_max3_f32 v21, v21, v70, v71
	v_add_f32_e32 v28, v27, v40
	v_max3_f32 v21, v21, v72, v73
	v_add_f32_e32 v28, v164, v28
	v_max3_f32 v21, v21, v74, v75
	v_add_f32_e32 v28, v165, v28
	v_max3_f32 v21, v21, v76, v77
	v_add_f32_e32 v20, v166, v28
	v_max3_f32 v21, v21, v78, v79
	v_add_f32_e32 v20, v167, v20
	v_max3_f32 v21, v21, v80, v81
	v_add_f32_e32 v20, v168, v20
	v_max3_f32 v21, v21, v82, v83
	v_add_f32_e32 v20, v169, v20
	v_mul_f32_e32 v173, 0x3e0293ee, v21
	ds_bpermute_b32 v174, v206, v173
	v_add_f32_e32 v172, v170, v20
	v_mov_b32_e32 v5, v4
	v_mov_b32_e32 v6, v4
	v_mov_b32_e32 v7, v4
	v_mov_b32_e32 v8, v4
	v_mov_b32_e32 v9, v4
	v_mov_b32_e32 v10, v4
	v_mov_b32_e32 v11, v4
	v_mov_b32_e32 v12, v4
	v_mov_b32_e32 v13, v4
	v_mov_b32_e32 v14, v4
	v_mov_b32_e32 v15, v4
	v_mov_b32_e32 v16, v4
	v_mov_b32_e32 v17, v4
	v_mov_b32_e32 v18, v4
	v_mov_b32_e32 v19, v4
	v_cvt_pk_bf16_f32 v189, v22, v23
	v_cvt_pk_bf16_f32 v190, v24, v25
	v_cvt_pk_bf16_f32 v191, v26, v27
	ds_read_b128 v[140:143], v195 offset:0x7400
	ds_read_b128 v[136:139], v195 offset:0x7800
	ds_read_b128 v[132:135], v195 offset:0x7c00
	s_waitcnt lgkmcnt(8)
	v_add_f32_e32 v172, v171, v172
	s_nop 0
	v_mfma_f32_32x32x16_bf16 v[52:67], v[36:39], v[188:191], v[4:19]
	v_add_f32_e32 v172, v4, v172
	s_waitcnt lgkmcnt(0)
	v_max_f32_e32 v174, v174, v174
	v_max_f32_e32 v173, v173, v174
	v_sub_f32_e32 v174, v173, v2
	v_cmp_ge_f32_e32 vcc, s42, v174
	s_cmp_eq_u64 vcc, exec
	v_mfma_f32_32x32x16_bf16 v[36:51], v[176:179], v[188:191], v[4:19]
	v_mfma_f32_32x32x16_bf16 v[20:35], v[180:183], v[188:191], v[4:19]
	v_mfma_f32_32x32x16_bf16 v[4:19], v[184:187], v[188:191], v[4:19]
	s_cbranch_scc1 .LBB0_1007
	v_max_f32_e32 v173, v173, v173
	v_max_f32_e32 v174, v2, v2
	v_max_f32_e32 v174, v174, v173
	v_sub_f32_e32 v2, v2, v174
	v_exp_f32_e32 v2, v2
	v_xor_b32_e32 v173, 0x80000000, v174
	v_mul_f32_e32 v172, v172, v2
	v_mul_f32 v66, v66, v2
	v_mul_f32 v67, v67, v2
	v_mul_f32 v64, v64, v2
	v_mul_f32 v65, v65, v2
	v_mul_f32 v62, v62, v2
	v_mul_f32 v63, v63, v2
	v_mul_f32 v60, v60, v2
	v_mul_f32 v61, v61, v2
	v_mul_f32 v58, v58, v2
	v_mul_f32 v59, v59, v2
	v_mul_f32 v56, v56, v2
	v_mul_f32 v57, v57, v2
	v_mul_f32 v54, v54, v2
	v_mul_f32 v55, v55, v2
	v_mul_f32 v52, v52, v2
	v_mul_f32 v53, v53, v2
	v_mul_f32 v50, v50, v2
	v_mul_f32 v51, v51, v2
	v_mul_f32 v48, v48, v2
	v_mul_f32 v49, v49, v2
	v_mul_f32 v46, v46, v2
	v_mul_f32 v47, v47, v2
	v_mul_f32 v44, v44, v2
	v_mul_f32 v45, v45, v2
	v_mul_f32 v42, v42, v2
	v_mul_f32 v43, v43, v2
	v_mul_f32 v40, v40, v2
	v_mul_f32 v41, v41, v2
	v_mul_f32 v38, v38, v2
	v_mul_f32 v39, v39, v2
	v_mul_f32 v36, v36, v2
	v_mul_f32 v37, v37, v2
	v_mul_f32 v34, v34, v2
	v_mul_f32 v35, v35, v2
	v_mul_f32 v32, v32, v2
	v_mul_f32 v33, v33, v2
	v_mul_f32 v30, v30, v2
	v_mul_f32 v31, v31, v2
	v_mul_f32 v28, v28, v2
	v_mul_f32 v29, v29, v2
	v_mul_f32 v26, v26, v2
	v_mul_f32 v27, v27, v2
	v_mul_f32 v24, v24, v2
	v_mul_f32 v25, v25, v2
	v_mul_f32 v22, v22, v2
	v_mul_f32 v23, v23, v2
	v_mul_f32 v20, v20, v2
	v_mul_f32 v21, v21, v2
	v_mul_f32 v18, v18, v2
	v_mul_f32 v19, v19, v2
	v_mul_f32 v16, v16, v2
	v_mul_f32 v17, v17, v2
	v_mul_f32 v14, v14, v2
	v_mul_f32 v15, v15, v2
	v_mul_f32 v12, v12, v2
	v_mul_f32 v13, v13, v2
	v_mul_f32 v10, v10, v2
	v_mul_f32 v11, v11, v2
	v_mul_f32 v8, v8, v2
	v_mul_f32 v9, v9, v2
	v_mul_f32 v6, v6, v2
	v_mul_f32 v7, v7, v2
	v_mul_f32 v4, v4, v2
	v_mul_f32 v5, v5, v2
	v_mov_b32_e32 v2, v174
	s_branch .LBB0_1008

.LBB0_1008:
	v_cvt_pk_bf16_f32 v164, v164, v165
	v_cvt_pk_bf16_f32 v165, v166, v167
	v_cvt_pk_bf16_f32 v166, v168, v169
	v_cvt_pk_bf16_f32 v167, v170, v171
	v_fmamk_f32 v68, v68, 0x3e0293ee, v173
	s_waitcnt lgkmcnt(0)
	s_waitcnt vmcnt(8)
	s_waitcnt lgkmcnt(0)
	s_barrier
	v_mfma_f32_32x32x16_bf16 v[52:67], v[96:99], v[164:167], v[52:67]
	v_mfma_f32_32x32x16_bf16 v[36:51], v[92:95], v[164:167], v[36:51]
	v_mfma_f32_32x32x16_bf16 v[20:35], v[88:91], v[164:167], v[20:35]
	v_mfma_f32_32x32x16_bf16 v[4:19], v[84:87], v[164:167], v[4:19]
	v_exp_f32_e32 v164, v68
	v_fmamk_f32 v68, v69, 0x3e0293ee, v173
	v_exp_f32_e32 v165, v68
	v_fmamk_f32 v68, v70, 0x3e0293ee, v173
	v_exp_f32_e32 v166, v68
	v_fmamk_f32 v68, v71, 0x3e0293ee, v173
	v_exp_f32_e32 v167, v68
	v_fmamk_f32 v68, v72, 0x3e0293ee, v173
	v_exp_f32_e32 v178, v68
	v_fmamk_f32 v68, v73, 0x3e0293ee, v173
	v_exp_f32_e32 v179, v68
	v_fmamk_f32 v68, v74, 0x3e0293ee, v173
	v_exp_f32_e32 v180, v68
	v_fmamk_f32 v68, v75, 0x3e0293ee, v173
	v_exp_f32_e32 v181, v68
	v_fmamk_f32 v72, v76, 0x3e0293ee, v173
	v_exp_f32_e32 v182, v72
	v_fmamk_f32 v72, v77, 0x3e0293ee, v173
	v_exp_f32_e32 v183, v72
	v_fmamk_f32 v72, v78, 0x3e0293ee, v173
	v_cvt_pk_bf16_f32 v68, v164, v165
	v_cvt_pk_bf16_f32 v69, v166, v167
	v_cvt_pk_bf16_f32 v70, v178, v179
	v_cvt_pk_bf16_f32 v71, v180, v181
	v_exp_f32_e32 v188, v72
	v_fmamk_f32 v72, v79, 0x3e0293ee, v173
	v_mfma_f32_32x32x16_bf16 v[52:67], v[160:163], v[68:71], v[52:67]
	v_exp_f32_e32 v218, v72
	v_fmamk_f32 v72, v80, 0x3e0293ee, v173
	v_exp_f32_e32 v219, v72
	v_fmamk_f32 v72, v81, 0x3e0293ee, v173
	v_exp_f32_e32 v220, v72
	v_fmamk_f32 v72, v82, 0x3e0293ee, v173
	v_fmac_f32_e32 v173, 0x3e0293ee, v83
	v_mfma_f32_32x32x16_bf16 v[36:51], v[156:159], v[68:71], v[36:51]
	v_exp_f32_e32 v221, v72
	v_exp_f32_e32 v173, v173
	v_mfma_f32_32x32x16_bf16 v[20:35], v[152:155], v[68:71], v[20:35]
	v_mfma_f32_32x32x16_bf16 v[4:19], v[148:151], v[68:71], v[4:19]
	v_cvt_pk_bf16_f32 v68, v182, v183
	v_cvt_pk_bf16_f32 v69, v188, v218
	v_cvt_pk_bf16_f32 v70, v219, v220
	v_cvt_pk_bf16_f32 v71, v221, v173
	s_nop 1
	v_mfma_f32_32x32x16_bf16 v[52:67], v[144:147], v[68:71], v[52:67]
	v_mfma_f32_32x32x16_bf16 v[36:51], v[140:143], v[68:71], v[36:51]
	v_mfma_f32_32x32x16_bf16 v[20:35], v[136:139], v[68:71], v[20:35]
	v_mfma_f32_32x32x16_bf16 v[4:19], v[132:135], v[68:71], v[4:19]
	ds_read_b128 v[68:71], v208 offset:0
	ds_read_b128 v[72:75], v208 offset:0x400
	ds_read_b128 v[76:79], v208 offset:0x800
	ds_read_b128 v[80:83], v208 offset:0xc00
	ds_read_b128 v[132:135], v208 offset:0x1000
	ds_read_b128 v[136:139], v208 offset:0x1400
	ds_read_b128 v[140:143], v208 offset:0x1800
	ds_read_b128 v[144:147], v208 offset:0x1c00
	ds_read_b128 v[174:177], v208 offset:0x2000
	ds_read_b128 v[184:187], v208 offset:0x2400
	ds_read_b128 v[200:203], v208 offset:0x2800
	ds_read_b128 v[214:217], v208 offset:0x2c00
	ds_read_b128 v[168:171], v208 offset:0x3000
	ds_read_b128 v[160:163], v208 offset:0x3400
	ds_read_b128 v[156:159], v208 offset:0x3800
	ds_read_b128 v[148:151], v208 offset:0x3c00
	s_nop 0
	s_waitcnt lgkmcnt(8)
	s_nop 0
	v_mfma_f32_32x32x16_bf16 v[84:99], v[68:71], v[128:131], 0
	v_add_f32_e32 v68, 0, v164
	v_add_f32_e32 v68, v165, v68
	v_add_f32_e32 v68, v166, v68
	v_add_f32_e32 v68, v167, v68
	v_add_f32_e32 v68, v178, v68
	v_add_f32_e32 v68, v179, v68
	v_add_f32_e32 v68, v180, v68
	v_mfma_f32_32x32x16_bf16 v[84:99], v[72:75], v[124:127], v[84:99]
	v_add_f32_e32 v68, v181, v68
	v_add_f32_e32 v68, v182, v68
	v_add_f32_e32 v68, v183, v68
	v_add_f32_e32 v178, v188, v68
	ds_read_b128 v[188:191], v208 offset:0x4000
	ds_read_b128 v[180:183], v208 offset:0x4400
	ds_read_b128 v[164:167], v208 offset:0x4800
	v_mfma_f32_32x32x16_bf16 v[84:99], v[76:79], v[120:123], v[84:99]
	ds_read_b128 v[152:155], v208 offset:0x4c00
	v_mfma_f32_32x32x16_bf16 v[84:99], v[80:83], v[116:119], v[84:99]
	v_mfma_f32_32x32x16_bf16 v[84:99], v[132:135], v[112:115], v[84:99]
	v_mfma_f32_32x32x16_bf16 v[84:99], v[136:139], v[104:107], v[84:99]
	v_mfma_f32_32x32x16_bf16 v[84:99], v[140:143], v[108:111], v[84:99]
	v_mfma_f32_32x32x16_bf16 v[84:99], v[144:147], v[100:103], v[84:99]
	ds_read_b128 v[144:147], v208 offset:0x5000
	ds_read_b128 v[140:143], v208 offset:0x5400
	ds_read_b128 v[136:139], v208 offset:0x5800
	ds_read_b128 v[132:135], v208 offset:0x5c00
	s_waitcnt lgkmcnt(8)
	s_nop 0
	v_mfma_f32_32x32x16_bf16 v[68:83], v[174:177], v[128:131], 0
	s_nop 9
	v_max3_f32 v175, v84, s40, v85
	v_max3_f32 v175, v175, v86, v87
	v_max3_f32 v175, v175, v88, v89
	v_max3_f32 v175, v175, v90, v91
	v_max3_f32 v175, v175, v92, v93
	v_max3_f32 v175, v175, v94, v95
	v_max3_f32 v175, v175, v96, v97
	v_mfma_f32_32x32x16_bf16 v[68:83], v[184:187], v[124:127], v[68:83]
	v_max3_f32 v175, v175, v98, v99
	v_mul_f32_e32 v175, 0x3e0293ee, v175
	v_add_f32_e32 v174, v218, v178
	ds_bpermute_b32 v176, v206, v175
	v_add_f32_e32 v174, v219, v174
	v_add_f32_e32 v174, v220, v174
	v_add_f32_e32 v174, v221, v174
	v_mfma_f32_32x32x16_bf16 v[68:83], v[200:203], v[120:123], v[68:83]
	v_add_f32_e32 v173, v173, v174
	v_add_f32_e32 v200, v172, v173
	s_waitcnt lgkmcnt(0)
	v_max_f32_e32 v172, v176, v176
	v_max_f32_e32 v172, v175, v172
	v_sub_f32_e32 v173, v172, v2
	v_cmp_ge_f32_e32 vcc, s42, v173
	s_cmp_eq_u64 vcc, exec
	v_mfma_f32_32x32x16_bf16 v[68:83], v[214:217], v[116:119], v[68:83]
	s_cbranch_scc1 .LBB0_1010
	v_max_f32_e32 v172, v172, v172
	v_max_f32_e32 v173, v2, v2
	v_max_f32_e32 v172, v173, v172
	v_sub_f32_e32 v2, v2, v172
	v_exp_f32_e32 v2, v2
	s_nop 0
	v_mul_f32_e32 v200, v200, v2
	v_mul_f32 v66, v66, v2
	v_mul_f32 v67, v67, v2
	v_mul_f32 v64, v64, v2
	v_mul_f32 v65, v65, v2
	v_mul_f32 v62, v62, v2
	v_mul_f32 v63, v63, v2
	v_mul_f32 v60, v60, v2
	v_mul_f32 v61, v61, v2
	v_mul_f32 v58, v58, v2
	v_mul_f32 v59, v59, v2
	v_mul_f32 v56, v56, v2
	v_mul_f32 v57, v57, v2
	v_mul_f32 v54, v54, v2
	v_mul_f32 v55, v55, v2
	v_mul_f32 v52, v52, v2
	v_mul_f32 v53, v53, v2
	v_mul_f32 v50, v50, v2
	v_mul_f32 v51, v51, v2
	v_mul_f32 v48, v48, v2
	v_mul_f32 v49, v49, v2
	v_mul_f32 v46, v46, v2
	v_mul_f32 v47, v47, v2
	v_mul_f32 v44, v44, v2
	v_mul_f32 v45, v45, v2
	v_mul_f32 v42, v42, v2
	v_mul_f32 v43, v43, v2
	v_mul_f32 v40, v40, v2
	v_mul_f32 v41, v41, v2
	v_mul_f32 v38, v38, v2
	v_mul_f32 v39, v39, v2
	v_mul_f32 v36, v36, v2
	v_mul_f32 v37, v37, v2
	v_mul_f32 v34, v34, v2
	v_mul_f32 v35, v35, v2
	v_mul_f32 v32, v32, v2
	v_mul_f32 v33, v33, v2
	v_mul_f32 v30, v30, v2
	v_mul_f32 v31, v31, v2
	v_mul_f32 v28, v28, v2
	v_mul_f32 v29, v29, v2
	v_mul_f32 v26, v26, v2
	v_mul_f32 v27, v27, v2
	v_mul_f32 v24, v24, v2
	v_mul_f32 v25, v25, v2
	v_mul_f32 v22, v22, v2
	v_mul_f32 v23, v23, v2
	v_mul_f32 v20, v20, v2
	v_mul_f32 v21, v21, v2
	v_mul_f32 v18, v18, v2
	v_mul_f32 v19, v19, v2
	v_mul_f32 v16, v16, v2
	v_mul_f32 v17, v17, v2
	v_mul_f32 v14, v14, v2
	v_mul_f32 v15, v15, v2
	v_mul_f32 v12, v12, v2
	v_mul_f32 v13, v13, v2
	v_mul_f32 v10, v10, v2
	v_mul_f32 v11, v11, v2
	v_mul_f32 v8, v8, v2
	v_mul_f32 v9, v9, v2
	v_mul_f32 v6, v6, v2
	v_mul_f32 v7, v7, v2
	v_mul_f32 v4, v4, v2
	v_mul_f32 v5, v5, v2
	v_mov_b32_e32 v2, v172
.LBB0_1010:
	v_mfma_f32_32x32x16_bf16 v[68:83], v[168:171], v[112:115], v[68:83]
	v_fma_f32 v84, v84, s41, -v2
	v_exp_f32_e32 v84, v84
	v_fma_f32 v85, v85, s41, -v2
	v_exp_f32_e32 v85, v85
	v_fma_f32 v86, v86, s41, -v2
	v_exp_f32_e32 v86, v86
	v_fma_f32 v87, v87, s41, -v2
	v_mfma_f32_32x32x16_bf16 v[68:83], v[160:163], v[104:107], v[68:83]
	v_exp_f32_e32 v87, v87
	v_fma_f32 v88, v88, s41, -v2
	v_add_f32_e32 v172, 0, v84
	v_exp_f32_e32 v88, v88
	v_fma_f32 v89, v89, s41, -v2
	v_add_f32_e32 v172, v85, v172
	v_exp_f32_e32 v89, v89
	v_mfma_f32_32x32x16_bf16 v[68:83], v[156:159], v[108:111], v[68:83]
	v_fma_f32 v90, v90, s41, -v2
	v_add_f32_e32 v172, v86, v172
	v_exp_f32_e32 v90, v90
	v_fma_f32 v91, v91, s41, -v2
	v_add_f32_e32 v172, v87, v172
	v_exp_f32_e32 v91, v91
	v_fma_f32 v92, v92, s41, -v2
	v_mfma_f32_32x32x16_bf16 v[68:83], v[148:151], v[100:103], v[68:83]
	v_add_f32_e32 v172, v88, v172
	v_exp_f32_e32 v92, v92
	v_fma_f32 v93, v93, s41, -v2
	v_add_f32_e32 v172, v89, v172
	v_exp_f32_e32 v93, v93
	v_fma_f32 v94, v94, s41, -v2
	v_add_f32_e32 v172, v90, v172
	s_nop 4
	v_max3_f32 v148, v68, s40, v69
	v_max3_f32 v148, v148, v70, v71
	v_max3_f32 v148, v148, v72, v73
	v_max3_f32 v148, v148, v74, v75
	v_max3_f32 v148, v148, v76, v77
	v_max3_f32 v148, v148, v78, v79
	v_max3_f32 v148, v148, v80, v81
	v_max3_f32 v148, v148, v82, v83
	v_exp_f32_e32 v94, v94
	v_fma_f32 v95, v95, s41, -v2
	v_mul_f32_e32 v148, 0x3e0293ee, v148
	v_add_f32_e32 v168, v91, v172
	v_exp_f32_e32 v95, v95
	v_fma_f32 v96, v96, s41, -v2
	ds_bpermute_b32 v149, v206, v148
	v_add_f32_e32 v168, v92, v168
	v_cvt_pk_bf16_f32 v214, v84, v85
	v_cvt_pk_bf16_f32 v215, v86, v87
	v_cvt_pk_bf16_f32 v216, v88, v89
	v_cvt_pk_bf16_f32 v217, v90, v91
	v_exp_f32_e32 v96, v96
	v_fma_f32 v97, v97, s41, -v2
	v_add_f32_e32 v201, v93, v168
	ds_read_b128 v[184:187], v208 offset:0x6000
	ds_read_b128 v[176:179], v208 offset:0x6400
	ds_read_b128 v[172:175], v208 offset:0x6800
	ds_read_b128 v[168:171], v208 offset:0x6c00
	ds_read_b128 v[160:163], v208 offset:0x7000
	ds_read_b128 v[156:159], v208 offset:0x7400
	ds_read_b128 v[88:91], v208 offset:0x7800
	ds_read_b128 v[84:87], v208 offset:0x7c00
	s_waitcnt lgkmcnt(8)
	v_exp_f32_e32 v97, v97
	v_mfma_f32_32x32x16_bf16 v[52:67], v[188:191], v[214:217], v[52:67]
	v_fma_f32 v98, v98, s41, -v2
	v_add_f32_e32 v188, v94, v201
	v_exp_f32_e32 v98, v98
	v_fma_f32 v99, v99, s41, -v2
	v_exp_f32_e32 v99, v99
	s_waitcnt lgkmcnt(0)
	v_max_f32_e32 v149, v149, v149
	v_max_f32_e32 v148, v148, v149
	v_mfma_f32_32x32x16_bf16 v[36:51], v[180:183], v[214:217], v[36:51]
	v_add_f32_e32 v180, v95, v188
	v_add_f32_e32 v180, v96, v180
	v_add_f32_e32 v180, v97, v180
	v_add_f32_e32 v150, v98, v180
	v_sub_f32_e32 v149, v148, v2
	v_add_f32_e32 v150, v99, v150
	v_cmp_ge_f32_e32 vcc, s42, v149
	v_mfma_f32_32x32x16_bf16 v[20:35], v[164:167], v[214:217], v[20:35]
	v_add_f32_e32 v200, v200, v150
	s_cmp_eq_u64 vcc, exec
	v_mfma_f32_32x32x16_bf16 v[4:19], v[152:155], v[214:217], v[4:19]
	s_cbranch_scc1 .LBB0_1012
	v_max_f32_e32 v148, v148, v148
	v_max_f32_e32 v149, v2, v2
	v_max_f32_e32 v149, v149, v148
	v_sub_f32_e32 v2, v2, v149
	v_exp_f32_e32 v2, v2
	v_xor_b32_e32 v148, 0x80000000, v149
	v_mul_f32_e32 v200, v200, v2
	v_mul_f32 v66, v66, v2
	v_mul_f32 v67, v67, v2
	v_mul_f32 v64, v64, v2
	v_mul_f32 v65, v65, v2
	v_mul_f32 v62, v62, v2
	v_mul_f32 v63, v63, v2
	v_mul_f32 v60, v60, v2
	v_mul_f32 v61, v61, v2
	v_mul_f32 v58, v58, v2
	v_mul_f32 v59, v59, v2
	v_mul_f32 v56, v56, v2
	v_mul_f32 v57, v57, v2
	v_mul_f32 v54, v54, v2
	v_mul_f32 v55, v55, v2
	v_mul_f32 v52, v52, v2
	v_mul_f32 v53, v53, v2
	v_mul_f32 v50, v50, v2
	v_mul_f32 v51, v51, v2
	v_mul_f32 v48, v48, v2
	v_mul_f32 v49, v49, v2
	v_mul_f32 v46, v46, v2
	v_mul_f32 v47, v47, v2
	v_mul_f32 v44, v44, v2
	v_mul_f32 v45, v45, v2
	v_mul_f32 v42, v42, v2
	v_mul_f32 v43, v43, v2
	v_mul_f32 v40, v40, v2
	v_mul_f32 v41, v41, v2
	v_mul_f32 v38, v38, v2
	v_mul_f32 v39, v39, v2
	v_mul_f32 v36, v36, v2
	v_mul_f32 v37, v37, v2
	v_mul_f32 v34, v34, v2
	v_mul_f32 v35, v35, v2
	v_mul_f32 v32, v32, v2
	v_mul_f32 v33, v33, v2
	v_mul_f32 v30, v30, v2
	v_mul_f32 v31, v31, v2
	v_mul_f32 v28, v28, v2
	v_mul_f32 v29, v29, v2
	v_mul_f32 v26, v26, v2
	v_mul_f32 v27, v27, v2
	v_mul_f32 v24, v24, v2
	v_mul_f32 v25, v25, v2
	v_mul_f32 v22, v22, v2
	v_mul_f32 v23, v23, v2
	v_mul_f32 v20, v20, v2
	v_mul_f32 v21, v21, v2
	v_mul_f32 v18, v18, v2
	v_mul_f32 v19, v19, v2
	v_mul_f32 v16, v16, v2
	v_mul_f32 v17, v17, v2
	v_mul_f32 v14, v14, v2
	v_mul_f32 v15, v15, v2
	v_mul_f32 v12, v12, v2
	v_mul_f32 v13, v13, v2
	v_mul_f32 v10, v10, v2
	v_mul_f32 v11, v11, v2
	v_mul_f32 v8, v8, v2
	v_mul_f32 v9, v9, v2
	v_mul_f32 v6, v6, v2
	v_mul_f32 v7, v7, v2
	v_mul_f32 v4, v4, v2
	v_mul_f32 v5, v5, v2
	v_mov_b32_e32 v2, v149
	s_branch .LBB0_1013

.LBB0_1013:
	v_fmamk_f32 v68, v68, 0x3e0293ee, v148
	v_exp_f32_e32 v152, v68
	v_fmamk_f32 v68, v69, 0x3e0293ee, v148
	v_exp_f32_e32 v153, v68
	v_fmamk_f32 v68, v70, 0x3e0293ee, v148
	v_exp_f32_e32 v154, v68
	v_fmamk_f32 v68, v71, 0x3e0293ee, v148
	v_cvt_pk_bf16_f32 v92, v92, v93
	v_cvt_pk_bf16_f32 v93, v94, v95
	v_cvt_pk_bf16_f32 v94, v96, v97
	v_cvt_pk_bf16_f32 v95, v98, v99
	v_exp_f32_e32 v155, v68
	v_fmamk_f32 v68, v72, 0x3e0293ee, v148
	v_mfma_f32_32x32x16_bf16 v[52:67], v[144:147], v[92:95], v[52:67]
	v_exp_f32_e32 v164, v68
	v_fmamk_f32 v68, v73, 0x3e0293ee, v148
	v_exp_f32_e32 v165, v68
	v_fmamk_f32 v68, v74, 0x3e0293ee, v148
	v_exp_f32_e32 v166, v68
	v_fmamk_f32 v68, v75, 0x3e0293ee, v148
	v_exp_f32_e32 v167, v68
	v_mfma_f32_32x32x16_bf16 v[36:51], v[140:143], v[92:95], v[36:51]
	v_fmamk_f32 v72, v76, 0x3e0293ee, v148
	v_exp_f32_e32 v180, v72
	v_fmamk_f32 v72, v77, 0x3e0293ee, v148
	v_exp_f32_e32 v181, v72
	v_fmamk_f32 v72, v78, 0x3e0293ee, v148
	v_cvt_pk_bf16_f32 v68, v152, v153
	v_cvt_pk_bf16_f32 v69, v154, v155
	v_mfma_f32_32x32x16_bf16 v[20:35], v[136:139], v[92:95], v[20:35]
	v_cvt_pk_bf16_f32 v70, v164, v165
	v_cvt_pk_bf16_f32 v71, v166, v167
	v_exp_f32_e32 v182, v72
	v_fmamk_f32 v72, v79, 0x3e0293ee, v148
	s_waitcnt lgkmcnt(0)
	v_exp_f32_e32 v201, v72
	v_fmamk_f32 v72, v80, 0x3e0293ee, v148
	v_mfma_f32_32x32x16_bf16 v[4:19], v[132:135], v[92:95], v[4:19]
	v_exp_f32_e32 v202, v72
	v_fmamk_f32 v72, v81, 0x3e0293ee, v148
	v_exp_f32_e32 v203, v72
	v_fmamk_f32 v72, v82, 0x3e0293ee, v148
	v_fmac_f32_e32 v148, 0x3e0293ee, v83
	v_exp_f32_e32 v218, v72
	v_exp_f32_e32 v219, v148
	v_mfma_f32_32x32x16_bf16 v[52:67], v[184:187], v[68:71], v[52:67]
	s_waitcnt vmcnt(4)
	s_waitcnt lgkmcnt(0)
	s_barrier
	v_mfma_f32_32x32x16_bf16 v[36:51], v[176:179], v[68:71], v[36:51]
	v_mfma_f32_32x32x16_bf16 v[20:35], v[172:175], v[68:71], v[20:35]
	v_mfma_f32_32x32x16_bf16 v[4:19], v[168:171], v[68:71], v[4:19]
	v_cvt_pk_bf16_f32 v68, v180, v181
	v_cvt_pk_bf16_f32 v69, v182, v201
	v_cvt_pk_bf16_f32 v70, v202, v203
	v_cvt_pk_bf16_f32 v71, v218, v219
	s_nop 1
	v_mfma_f32_32x32x16_bf16 v[52:67], v[160:163], v[68:71], v[52:67]
	v_mfma_f32_32x32x16_bf16 v[36:51], v[156:159], v[68:71], v[36:51]
	v_mfma_f32_32x32x16_bf16 v[20:35], v[88:91], v[68:71], v[20:35]
	v_mfma_f32_32x32x16_bf16 v[4:19], v[84:87], v[68:71], v[4:19]
	ds_read_b128 v[68:71], v210 offset:0
	ds_read_b128 v[72:75], v210 offset:0x400
	ds_read_b128 v[76:79], v210 offset:0x800
	ds_read_b128 v[80:83], v210 offset:0xc00
	ds_read_b128 v[132:135], v210 offset:0x1000
	ds_read_b128 v[136:139], v210 offset:0x1400
	ds_read_b128 v[140:143], v210 offset:0x1800
	ds_read_b128 v[144:147], v210 offset:0x1c00
	ds_read_b128 v[172:175], v210 offset:0x2000
	ds_read_b128 v[176:179], v210 offset:0x2400
	ds_read_b128 v[184:187], v210 offset:0x2800
	ds_read_b128 v[214:217], v210 offset:0x2c00
	ds_read_b128 v[168:171], v210 offset:0x3000
	ds_read_b128 v[160:163], v210 offset:0x3400
	ds_read_b128 v[156:159], v210 offset:0x3800
	ds_read_b128 v[148:151], v210 offset:0x3c00
	s_nop 0
	s_waitcnt lgkmcnt(8)
	ds_read_b128 v[188:191], v210 offset:0x4000
	s_nop 0
	v_mfma_f32_32x32x16_bf16 v[84:99], v[68:71], v[128:131], 0
	v_add_f32_e32 v68, 0, v152
	v_add_f32_e32 v68, v153, v68
	v_add_f32_e32 v68, v154, v68
	v_add_f32_e32 v68, v155, v68
	v_add_f32_e32 v68, v164, v68
	v_add_f32_e32 v68, v165, v68
	v_add_f32_e32 v68, v166, v68
	v_mfma_f32_32x32x16_bf16 v[84:99], v[72:75], v[124:127], v[84:99]
	v_add_f32_e32 v68, v167, v68
	v_add_f32_e32 v68, v180, v68
	v_add_f32_e32 v68, v181, v68
	v_add_f32_e32 v220, v182, v68
	ds_read_b128 v[180:183], v210 offset:0x4400
	ds_read_b128 v[164:167], v210 offset:0x4800
	ds_read_b128 v[152:155], v210 offset:0x4c00
	v_mfma_f32_32x32x16_bf16 v[84:99], v[76:79], v[120:123], v[84:99]
	v_mfma_f32_32x32x16_bf16 v[84:99], v[80:83], v[116:119], v[84:99]
	v_mfma_f32_32x32x16_bf16 v[84:99], v[132:135], v[112:115], v[84:99]
	v_mfma_f32_32x32x16_bf16 v[84:99], v[136:139], v[104:107], v[84:99]
	v_mfma_f32_32x32x16_bf16 v[84:99], v[140:143], v[108:111], v[84:99]
	v_mfma_f32_32x32x16_bf16 v[84:99], v[144:147], v[100:103], v[84:99]
	ds_read_b128 v[144:147], v210 offset:0x5000
	ds_read_b128 v[140:143], v210 offset:0x5400
	ds_read_b128 v[136:139], v210 offset:0x5800
	ds_read_b128 v[132:135], v210 offset:0x5c00
	s_waitcnt lgkmcnt(8)
	s_nop 0
	v_mfma_f32_32x32x16_bf16 v[68:83], v[172:175], v[128:131], 0
	s_nop 9
	v_max3_f32 v173, v84, s40, v85
	v_max3_f32 v173, v173, v86, v87
	v_max3_f32 v173, v173, v88, v89
	v_max3_f32 v173, v173, v90, v91
	v_max3_f32 v173, v173, v92, v93
	v_max3_f32 v173, v173, v94, v95
	v_max3_f32 v173, v173, v96, v97
	v_mfma_f32_32x32x16_bf16 v[68:83], v[176:179], v[124:127], v[68:83]
	v_max3_f32 v173, v173, v98, v99
	v_mul_f32_e32 v173, 0x3e0293ee, v173
	v_add_f32_e32 v172, v201, v220
	ds_bpermute_b32 v174, v206, v173
	v_add_f32_e32 v172, v202, v172
	v_add_f32_e32 v172, v203, v172
	v_add_f32_e32 v172, v218, v172
	v_mfma_f32_32x32x16_bf16 v[68:83], v[184:187], v[120:123], v[68:83]
	v_add_f32_e32 v172, v219, v172
	v_add_f32_e32 v200, v200, v172
	s_waitcnt lgkmcnt(0)
	v_max_f32_e32 v172, v174, v174
	v_max_f32_e32 v172, v173, v172
	v_sub_f32_e32 v173, v172, v2
	v_cmp_ge_f32_e32 vcc, s42, v173
	s_cmp_eq_u64 vcc, exec
	v_mfma_f32_32x32x16_bf16 v[68:83], v[214:217], v[116:119], v[68:83]
	s_cbranch_scc1 .LBB0_1015
	v_max_f32_e32 v172, v172, v172
	v_max_f32_e32 v173, v2, v2
	v_max_f32_e32 v172, v173, v172
	v_sub_f32_e32 v2, v2, v172
	v_exp_f32_e32 v2, v2
	s_nop 0
	v_mul_f32_e32 v200, v200, v2
	v_mul_f32 v66, v66, v2
	v_mul_f32 v67, v67, v2
	v_mul_f32 v64, v64, v2
	v_mul_f32 v65, v65, v2
	v_mul_f32 v62, v62, v2
	v_mul_f32 v63, v63, v2
	v_mul_f32 v60, v60, v2
	v_mul_f32 v61, v61, v2
	v_mul_f32 v58, v58, v2
	v_mul_f32 v59, v59, v2
	v_mul_f32 v56, v56, v2
	v_mul_f32 v57, v57, v2
	v_mul_f32 v54, v54, v2
	v_mul_f32 v55, v55, v2
	v_mul_f32 v52, v52, v2
	v_mul_f32 v53, v53, v2
	v_mul_f32 v50, v50, v2
	v_mul_f32 v51, v51, v2
	v_mul_f32 v48, v48, v2
	v_mul_f32 v49, v49, v2
	v_mul_f32 v46, v46, v2
	v_mul_f32 v47, v47, v2
	v_mul_f32 v44, v44, v2
	v_mul_f32 v45, v45, v2
	v_mul_f32 v42, v42, v2
	v_mul_f32 v43, v43, v2
	v_mul_f32 v40, v40, v2
	v_mul_f32 v41, v41, v2
	v_mul_f32 v38, v38, v2
	v_mul_f32 v39, v39, v2
	v_mul_f32 v36, v36, v2
	v_mul_f32 v37, v37, v2
	v_mul_f32 v34, v34, v2
	v_mul_f32 v35, v35, v2
	v_mul_f32 v32, v32, v2
	v_mul_f32 v33, v33, v2
	v_mul_f32 v30, v30, v2
	v_mul_f32 v31, v31, v2
	v_mul_f32 v28, v28, v2
	v_mul_f32 v29, v29, v2
	v_mul_f32 v26, v26, v2
	v_mul_f32 v27, v27, v2
	v_mul_f32 v24, v24, v2
	v_mul_f32 v25, v25, v2
	v_mul_f32 v22, v22, v2
	v_mul_f32 v23, v23, v2
	v_mul_f32 v20, v20, v2
	v_mul_f32 v21, v21, v2
	v_mul_f32 v18, v18, v2
	v_mul_f32 v19, v19, v2
	v_mul_f32 v16, v16, v2
	v_mul_f32 v17, v17, v2
	v_mul_f32 v14, v14, v2
	v_mul_f32 v15, v15, v2
	v_mul_f32 v12, v12, v2
	v_mul_f32 v13, v13, v2
	v_mul_f32 v10, v10, v2
	v_mul_f32 v11, v11, v2
	v_mul_f32 v8, v8, v2
	v_mul_f32 v9, v9, v2
	v_mul_f32 v6, v6, v2
	v_mul_f32 v7, v7, v2
	v_mul_f32 v4, v4, v2
	v_mul_f32 v5, v5, v2
	v_mov_b32_e32 v2, v172
.LBB0_1015:
	v_mfma_f32_32x32x16_bf16 v[68:83], v[168:171], v[112:115], v[68:83]
	v_fma_f32 v84, v84, s41, -v2
	v_exp_f32_e32 v84, v84
	v_fma_f32 v85, v85, s41, -v2
	v_exp_f32_e32 v85, v85
	v_fma_f32 v86, v86, s41, -v2
	v_exp_f32_e32 v86, v86
	v_fma_f32 v87, v87, s41, -v2
	v_mfma_f32_32x32x16_bf16 v[68:83], v[160:163], v[104:107], v[68:83]
	v_exp_f32_e32 v87, v87
	v_fma_f32 v88, v88, s41, -v2
	v_add_f32_e32 v172, 0, v84
	v_exp_f32_e32 v88, v88
	v_fma_f32 v89, v89, s41, -v2
	v_add_f32_e32 v172, v85, v172
	v_exp_f32_e32 v89, v89
	v_mfma_f32_32x32x16_bf16 v[68:83], v[156:159], v[108:111], v[68:83]
	v_fma_f32 v90, v90, s41, -v2
	v_add_f32_e32 v172, v86, v172
	v_exp_f32_e32 v90, v90
	v_fma_f32 v91, v91, s41, -v2
	v_add_f32_e32 v172, v87, v172
	v_exp_f32_e32 v91, v91
	v_fma_f32 v92, v92, s41, -v2
	v_mfma_f32_32x32x16_bf16 v[68:83], v[148:151], v[100:103], v[68:83]
	v_add_f32_e32 v172, v88, v172
	v_exp_f32_e32 v92, v92
	v_fma_f32 v93, v93, s41, -v2
	v_add_f32_e32 v172, v89, v172
	v_exp_f32_e32 v93, v93
	v_fma_f32 v94, v94, s41, -v2
	v_add_f32_e32 v172, v90, v172
	s_nop 4
	v_max3_f32 v148, v68, s40, v69
	v_max3_f32 v148, v148, v70, v71
	v_max3_f32 v148, v148, v72, v73
	v_max3_f32 v148, v148, v74, v75
	v_max3_f32 v148, v148, v76, v77
	v_max3_f32 v148, v148, v78, v79
	v_max3_f32 v148, v148, v80, v81
	v_max3_f32 v148, v148, v82, v83
	v_exp_f32_e32 v94, v94
	v_fma_f32 v95, v95, s41, -v2
	v_mul_f32_e32 v148, 0x3e0293ee, v148
	v_add_f32_e32 v168, v91, v172
	v_exp_f32_e32 v95, v95
	v_fma_f32 v96, v96, s41, -v2
	ds_bpermute_b32 v149, v206, v148
	v_add_f32_e32 v168, v92, v168
	v_cvt_pk_bf16_f32 v214, v84, v85
	v_cvt_pk_bf16_f32 v215, v86, v87
	v_cvt_pk_bf16_f32 v216, v88, v89
	v_cvt_pk_bf16_f32 v217, v90, v91
	v_exp_f32_e32 v96, v96
	v_fma_f32 v97, v97, s41, -v2
	v_add_f32_e32 v201, v93, v168
	ds_read_b128 v[184:187], v210 offset:0x6000
	ds_read_b128 v[176:179], v210 offset:0x6400
	ds_read_b128 v[172:175], v210 offset:0x6800
	ds_read_b128 v[168:171], v210 offset:0x6c00
	ds_read_b128 v[160:163], v210 offset:0x7000
	ds_read_b128 v[156:159], v210 offset:0x7400
	ds_read_b128 v[88:91], v210 offset:0x7800
	ds_read_b128 v[84:87], v210 offset:0x7c00
	s_waitcnt lgkmcnt(8)
	v_exp_f32_e32 v97, v97
	v_mfma_f32_32x32x16_bf16 v[52:67], v[188:191], v[214:217], v[52:67]
	v_fma_f32 v98, v98, s41, -v2
	v_add_f32_e32 v188, v94, v201
	v_exp_f32_e32 v98, v98
	v_fma_f32 v99, v99, s41, -v2
	v_exp_f32_e32 v99, v99
	s_waitcnt lgkmcnt(0)
	v_max_f32_e32 v149, v149, v149
	v_max_f32_e32 v148, v148, v149
	v_mfma_f32_32x32x16_bf16 v[36:51], v[180:183], v[214:217], v[36:51]
	v_add_f32_e32 v180, v95, v188
	v_add_f32_e32 v180, v96, v180
	v_add_f32_e32 v180, v97, v180
	v_add_f32_e32 v150, v98, v180
	v_sub_f32_e32 v149, v148, v2
	v_add_f32_e32 v150, v99, v150
	v_cmp_ge_f32_e32 vcc, s42, v149
	v_mfma_f32_32x32x16_bf16 v[20:35], v[164:167], v[214:217], v[20:35]
	v_add_f32_e32 v180, v200, v150
	s_cmp_eq_u64 vcc, exec
	v_mfma_f32_32x32x16_bf16 v[4:19], v[152:155], v[214:217], v[4:19]
	s_cbranch_scc1 .LBB0_1017
	v_max_f32_e32 v148, v148, v148
	v_max_f32_e32 v149, v2, v2
	v_max_f32_e32 v149, v149, v148
	v_sub_f32_e32 v2, v2, v149
	v_exp_f32_e32 v2, v2
	v_xor_b32_e32 v148, 0x80000000, v149
	v_mul_f32_e32 v180, v180, v2
	v_mul_f32 v66, v66, v2
	v_mul_f32 v67, v67, v2
	v_mul_f32 v64, v64, v2
	v_mul_f32 v65, v65, v2
	v_mul_f32 v62, v62, v2
	v_mul_f32 v63, v63, v2
	v_mul_f32 v60, v60, v2
	v_mul_f32 v61, v61, v2
	v_mul_f32 v58, v58, v2
	v_mul_f32 v59, v59, v2
	v_mul_f32 v56, v56, v2
	v_mul_f32 v57, v57, v2
	v_mul_f32 v54, v54, v2
	v_mul_f32 v55, v55, v2
	v_mul_f32 v52, v52, v2
	v_mul_f32 v53, v53, v2
	v_mul_f32 v50, v50, v2
	v_mul_f32 v51, v51, v2
	v_mul_f32 v48, v48, v2
	v_mul_f32 v49, v49, v2
	v_mul_f32 v46, v46, v2
	v_mul_f32 v47, v47, v2
	v_mul_f32 v44, v44, v2
	v_mul_f32 v45, v45, v2
	v_mul_f32 v42, v42, v2
	v_mul_f32 v43, v43, v2
	v_mul_f32 v40, v40, v2
	v_mul_f32 v41, v41, v2
	v_mul_f32 v38, v38, v2
	v_mul_f32 v39, v39, v2
	v_mul_f32 v36, v36, v2
	v_mul_f32 v37, v37, v2
	v_mul_f32 v34, v34, v2
	v_mul_f32 v35, v35, v2
	v_mul_f32 v32, v32, v2
	v_mul_f32 v33, v33, v2
	v_mul_f32 v30, v30, v2
	v_mul_f32 v31, v31, v2
	v_mul_f32 v28, v28, v2
	v_mul_f32 v29, v29, v2
	v_mul_f32 v26, v26, v2
	v_mul_f32 v27, v27, v2
	v_mul_f32 v24, v24, v2
	v_mul_f32 v25, v25, v2
	v_mul_f32 v22, v22, v2
	v_mul_f32 v23, v23, v2
	v_mul_f32 v20, v20, v2
	v_mul_f32 v21, v21, v2
	v_mul_f32 v18, v18, v2
	v_mul_f32 v19, v19, v2
	v_mul_f32 v16, v16, v2
	v_mul_f32 v17, v17, v2
	v_mul_f32 v14, v14, v2
	v_mul_f32 v15, v15, v2
	v_mul_f32 v12, v12, v2
	v_mul_f32 v13, v13, v2
	v_mul_f32 v10, v10, v2
	v_mul_f32 v11, v11, v2
	v_mul_f32 v8, v8, v2
	v_mul_f32 v9, v9, v2
	v_mul_f32 v6, v6, v2
	v_mul_f32 v7, v7, v2
	v_mul_f32 v4, v4, v2
	v_mul_f32 v5, v5, v2
	v_mov_b32_e32 v2, v149
	s_branch .LBB0_1018

.LBB0_1018:
	v_fmamk_f32 v68, v68, 0x3e0293ee, v148
	v_exp_f32_e32 v152, v68
	v_fmamk_f32 v68, v69, 0x3e0293ee, v148
	v_exp_f32_e32 v153, v68
	v_fmamk_f32 v68, v70, 0x3e0293ee, v148
	v_exp_f32_e32 v154, v68
	v_fmamk_f32 v68, v71, 0x3e0293ee, v148
	v_cvt_pk_bf16_f32 v92, v92, v93
	v_cvt_pk_bf16_f32 v93, v94, v95
	v_cvt_pk_bf16_f32 v94, v96, v97
	v_cvt_pk_bf16_f32 v95, v98, v99
	v_exp_f32_e32 v155, v68
	v_fmamk_f32 v68, v72, 0x3e0293ee, v148
	v_mfma_f32_32x32x16_bf16 v[36:51], v[140:143], v[92:95], v[36:51]
	v_exp_f32_e32 v181, v68
	v_fmamk_f32 v68, v73, 0x3e0293ee, v148
	v_exp_f32_e32 v190, v68
	v_fmamk_f32 v68, v74, 0x3e0293ee, v148
	v_exp_f32_e32 v191, v68
	v_fmamk_f32 v68, v75, 0x3e0293ee, v148
	v_exp_f32_e32 v218, v68
	v_mfma_f32_32x32x16_bf16 v[52:67], v[144:147], v[92:95], v[52:67]
	v_cvt_pk_bf16_f32 v68, v152, v153
	v_cvt_pk_bf16_f32 v69, v154, v155
	v_cvt_pk_bf16_f32 v70, v181, v190
	v_cvt_pk_bf16_f32 v71, v191, v218
	s_waitcnt lgkmcnt(0)
	v_fmamk_f32 v72, v76, 0x3e0293ee, v148
	s_waitcnt vmcnt(0)
	v_mfma_f32_32x32x16_bf16 v[20:35], v[136:139], v[92:95], v[20:35]
	s_waitcnt lgkmcnt(0)
	s_barrier
	v_mfma_f32_32x32x16_bf16 v[4:19], v[132:135], v[92:95], v[4:19]
	v_mfma_f32_32x32x16_bf16 v[36:51], v[176:179], v[68:71], v[36:51]
	v_exp_f32_e32 v176, v72
	v_fmamk_f32 v72, v77, 0x3e0293ee, v148
	v_exp_f32_e32 v177, v72
	v_fmamk_f32 v72, v78, 0x3e0293ee, v148
	v_exp_f32_e32 v178, v72
	v_fmamk_f32 v72, v79, 0x3e0293ee, v148
	v_exp_f32_e32 v219, v72
	v_mfma_f32_32x32x16_bf16 v[52:67], v[184:187], v[68:71], v[52:67]
	v_fmamk_f32 v72, v80, 0x3e0293ee, v148
	v_exp_f32_e32 v220, v72
	v_fmamk_f32 v72, v81, 0x3e0293ee, v148
	v_exp_f32_e32 v221, v72
	v_fmamk_f32 v72, v82, 0x3e0293ee, v148
	v_fmac_f32_e32 v148, 0x3e0293ee, v83
	v_exp_f32_e32 v222, v72
	v_mfma_f32_32x32x16_bf16 v[20:35], v[172:175], v[68:71], v[20:35]
	v_exp_f32_e32 v223, v148
	v_mfma_f32_32x32x16_bf16 v[4:19], v[168:171], v[68:71], v[4:19]
	v_cvt_pk_bf16_f32 v68, v176, v177
	v_cvt_pk_bf16_f32 v69, v178, v219
	v_cvt_pk_bf16_f32 v70, v220, v221
	v_cvt_pk_bf16_f32 v71, v222, v223
	s_nop 1
	v_mfma_f32_32x32x16_bf16 v[52:67], v[160:163], v[68:71], v[52:67]
	v_mfma_f32_32x32x16_bf16 v[36:51], v[156:159], v[68:71], v[36:51]
	v_mfma_f32_32x32x16_bf16 v[20:35], v[88:91], v[68:71], v[20:35]
	v_mfma_f32_32x32x16_bf16 v[4:19], v[84:87], v[68:71], v[4:19]
	ds_read_b128 v[68:71], v211 offset:0
	ds_read_b128 v[72:75], v211 offset:0x400
	ds_read_b128 v[76:79], v211 offset:0x800
	ds_read_b128 v[80:83], v211 offset:0xc00
	ds_read_b128 v[132:135], v211 offset:0x1000
	ds_read_b128 v[136:139], v211 offset:0x1400
	ds_read_b128 v[140:143], v211 offset:0x1800
	ds_read_b128 v[144:147], v211 offset:0x1c00
	ds_read_b128 v[182:185], v211 offset:0x2000
	ds_read_b128 v[186:189], v211 offset:0x2400
	ds_read_b128 v[200:203], v211 offset:0x2800
	ds_read_b128 v[214:217], v211 offset:0x2c00
	ds_read_b128 v[168:171], v211 offset:0x3000
	ds_read_b128 v[164:167], v211 offset:0x3400
	ds_read_b128 v[156:159], v211 offset:0x3800
	ds_read_b128 v[148:151], v211 offset:0x3c00
	s_nop 0
	s_waitcnt lgkmcnt(8)
	s_nop 0
	v_mfma_f32_32x32x16_bf16 v[84:99], v[68:71], v[128:131], 0
	v_add_f32_e32 v68, 0, v152
	v_add_f32_e32 v68, v153, v68
	v_add_f32_e32 v68, v154, v68
	v_add_f32_e32 v68, v155, v68
	v_add_f32_e32 v68, v181, v68
	v_add_f32_e32 v68, v190, v68
	v_add_f32_e32 v68, v191, v68
	v_mfma_f32_32x32x16_bf16 v[84:99], v[72:75], v[124:127], v[84:99]
	v_add_f32_e32 v68, v218, v68
	v_add_f32_e32 v68, v176, v68
	v_add_f32_e32 v68, v177, v68
	v_add_f32_e32 v181, v178, v68
	ds_read_b128 v[176:179], v211 offset:0x4000
	ds_read_b128 v[172:175], v211 offset:0x4400
	ds_read_b128 v[160:163], v211 offset:0x4800
	v_mfma_f32_32x32x16_bf16 v[84:99], v[76:79], v[120:123], v[84:99]
	ds_read_b128 v[152:155], v211 offset:0x4c00
	v_mfma_f32_32x32x16_bf16 v[84:99], v[80:83], v[116:119], v[84:99]
	v_mfma_f32_32x32x16_bf16 v[84:99], v[132:135], v[112:115], v[84:99]
	v_mfma_f32_32x32x16_bf16 v[84:99], v[136:139], v[104:107], v[84:99]
	v_mfma_f32_32x32x16_bf16 v[84:99], v[140:143], v[108:111], v[84:99]
	v_mfma_f32_32x32x16_bf16 v[84:99], v[144:147], v[100:103], v[84:99]
	ds_read_b128 v[144:147], v211 offset:0x5000
	ds_read_b128 v[140:143], v211 offset:0x5400
	ds_read_b128 v[136:139], v211 offset:0x5800
	ds_read_b128 v[132:135], v211 offset:0x5c00
	s_waitcnt lgkmcnt(8)
	s_nop 0
	v_mfma_f32_32x32x16_bf16 v[68:83], v[182:185], v[128:131], 0
	s_nop 9
	v_max3_f32 v129, v84, s40, v85
	v_max3_f32 v129, v129, v86, v87
	v_max3_f32 v129, v129, v88, v89
	v_max3_f32 v129, v129, v90, v91
	v_add_f32_e32 v128, v219, v181
	v_add_f32_e32 v128, v220, v128
	v_add_f32_e32 v128, v221, v128
	v_mfma_f32_32x32x16_bf16 v[68:83], v[186:189], v[124:127], v[68:83]
	v_max3_f32 v124, v129, v92, v93
	v_max3_f32 v124, v124, v94, v95
	v_max3_f32 v124, v124, v96, v97
	v_max3_f32 v124, v124, v98, v99
	v_mul_f32_e32 v124, 0x3e0293ee, v124
	ds_bpermute_b32 v125, v206, v124
	v_add_f32_e32 v126, v222, v128
	v_mfma_f32_32x32x16_bf16 v[68:83], v[200:203], v[120:123], v[68:83]
	v_add_f32_e32 v120, v223, v126
	v_add_f32_e32 v128, v180, v120
	s_waitcnt lgkmcnt(0)
	v_max_f32_e32 v120, v125, v125
	v_max_f32_e32 v120, v124, v120
	v_sub_f32_e32 v121, v120, v2
	v_cmp_ge_f32_e32 vcc, s42, v121
	s_cmp_eq_u64 vcc, exec
	v_mfma_f32_32x32x16_bf16 v[68:83], v[214:217], v[116:119], v[68:83]
	s_cbranch_scc1 .LBB0_1020
	v_max_f32_e32 v116, v120, v120
	v_max_f32_e32 v117, v2, v2
	v_max_f32_e32 v116, v117, v116
	v_sub_f32_e32 v2, v2, v116
	v_exp_f32_e32 v2, v2
	s_nop 0
	v_mul_f32_e32 v128, v128, v2
	v_mul_f32 v66, v66, v2
	v_mul_f32 v67, v67, v2
	v_mul_f32 v64, v64, v2
	v_mul_f32 v65, v65, v2
	v_mul_f32 v62, v62, v2
	v_mul_f32 v63, v63, v2
	v_mul_f32 v60, v60, v2
	v_mul_f32 v61, v61, v2
	v_mul_f32 v58, v58, v2
	v_mul_f32 v59, v59, v2
	v_mul_f32 v56, v56, v2
	v_mul_f32 v57, v57, v2
	v_mul_f32 v54, v54, v2
	v_mul_f32 v55, v55, v2
	v_mul_f32 v52, v52, v2
	v_mul_f32 v53, v53, v2
	v_mul_f32 v50, v50, v2
	v_mul_f32 v51, v51, v2
	v_mul_f32 v48, v48, v2
	v_mul_f32 v49, v49, v2
	v_mul_f32 v46, v46, v2
	v_mul_f32 v47, v47, v2
	v_mul_f32 v44, v44, v2
	v_mul_f32 v45, v45, v2
	v_mul_f32 v42, v42, v2
	v_mul_f32 v43, v43, v2
	v_mul_f32 v40, v40, v2
	v_mul_f32 v41, v41, v2
	v_mul_f32 v38, v38, v2
	v_mul_f32 v39, v39, v2
	v_mul_f32 v36, v36, v2
	v_mul_f32 v37, v37, v2
	v_mul_f32 v34, v34, v2
	v_mul_f32 v35, v35, v2
	v_mul_f32 v32, v32, v2
	v_mul_f32 v33, v33, v2
	v_mul_f32 v30, v30, v2
	v_mul_f32 v31, v31, v2
	v_mul_f32 v28, v28, v2
	v_mul_f32 v29, v29, v2
	v_mul_f32 v26, v26, v2
	v_mul_f32 v27, v27, v2
	v_mul_f32 v24, v24, v2
	v_mul_f32 v25, v25, v2
	v_mul_f32 v22, v22, v2
	v_mul_f32 v23, v23, v2
	v_mul_f32 v20, v20, v2
	v_mul_f32 v21, v21, v2
	v_mul_f32 v18, v18, v2
	v_mul_f32 v19, v19, v2
	v_mul_f32 v16, v16, v2
	v_mul_f32 v17, v17, v2
	v_mul_f32 v14, v14, v2
	v_mul_f32 v15, v15, v2
	v_mul_f32 v12, v12, v2
	v_mul_f32 v13, v13, v2
	v_mul_f32 v10, v10, v2
	v_mul_f32 v11, v11, v2
	v_mul_f32 v8, v8, v2
	v_mul_f32 v9, v9, v2
	v_mul_f32 v6, v6, v2
	v_mul_f32 v7, v7, v2
	v_mul_f32 v4, v4, v2
	v_mul_f32 v5, v5, v2
	v_mov_b32_e32 v2, v116
.LBB0_1020:
	v_mfma_f32_32x32x16_bf16 v[68:83], v[168:171], v[112:115], v[68:83]
	v_fma_f32 v92, v92, s41, -v2
	v_exp_f32_e32 v129, v92
	v_fma_f32 v92, v93, s41, -v2
	v_fma_f32 v93, v94, s41, -v2
	v_exp_f32_e32 v94, v93
	v_fma_f32 v93, v95, s41, -v2
	v_exp_f32_e32 v131, v93
	v_mfma_f32_32x32x16_bf16 v[68:83], v[164:167], v[104:107], v[68:83]
	v_fma_f32 v93, v96, s41, -v2
	v_fma_f32 v84, v84, s41, -v2
	v_exp_f32_e32 v95, v93
	v_fma_f32 v93, v97, s41, -v2
	v_exp_f32_e32 v84, v84
	v_fma_f32 v85, v85, s41, -v2
	v_exp_f32_e32 v96, v93
	v_mfma_f32_32x32x16_bf16 v[68:83], v[156:159], v[108:111], v[68:83]
	v_fma_f32 v93, v98, s41, -v2
	v_exp_f32_e32 v85, v85
	v_fma_f32 v86, v86, s41, -v2
	v_exp_f32_e32 v97, v93
	v_fma_f32 v93, v99, s41, -v2
	v_exp_f32_e32 v86, v86
	v_fma_f32 v87, v87, s41, -v2
	v_mfma_f32_32x32x16_bf16 v[68:83], v[148:151], v[100:103], v[68:83]
	v_exp_f32_e32 v98, v93
	v_exp_f32_e32 v87, v87
	v_fma_f32 v88, v88, s41, -v2
	v_add_f32_e32 v116, 0, v84
	v_exp_f32_e32 v88, v88
	v_fma_f32 v89, v89, s41, -v2
	v_add_f32_e32 v116, v85, v116
	s_nop 4
	v_max3_f32 v93, v68, s40, v69
	v_max3_f32 v93, v93, v70, v71
	v_max3_f32 v93, v93, v72, v73
	v_exp_f32_e32 v89, v89
	v_fma_f32 v90, v90, s41, -v2
	v_max3_f32 v93, v93, v74, v75
	v_add_f32_e32 v116, v86, v116
	v_exp_f32_e32 v90, v90
	v_fma_f32 v91, v91, s41, -v2
	v_max3_f32 v93, v93, v76, v77
	v_add_f32_e32 v116, v87, v116
	v_exp_f32_e32 v91, v91
	v_max3_f32 v93, v93, v78, v79
	v_add_f32_e32 v116, v88, v116
	v_max3_f32 v93, v93, v80, v81
	v_add_f32_e32 v116, v89, v116
	v_exp_f32_e32 v130, v92
	v_max3_f32 v93, v93, v82, v83
	v_add_f32_e32 v116, v90, v116
	v_mul_f32_e32 v93, 0x3e0293ee, v93
	v_add_f32_e32 v92, v91, v116
	ds_bpermute_b32 v99, v206, v93
	v_add_f32_e32 v92, v129, v92
	v_cvt_pk_bf16_f32 v164, v84, v85
	v_cvt_pk_bf16_f32 v165, v86, v87
	v_cvt_pk_bf16_f32 v166, v88, v89
	v_cvt_pk_bf16_f32 v167, v90, v91
	v_add_f32_e32 v92, v130, v92
	ds_read_b128 v[124:127], v211 offset:0x6000
	ds_read_b128 v[120:123], v211 offset:0x6400
	ds_read_b128 v[116:119], v211 offset:0x6800
	ds_read_b128 v[112:115], v211 offset:0x6c00
	ds_read_b128 v[108:111], v211 offset:0x7000
	ds_read_b128 v[104:107], v211 offset:0x7400
	ds_read_b128 v[88:91], v211 offset:0x7800
	ds_read_b128 v[84:87], v211 offset:0x7c00
	s_waitcnt lgkmcnt(8)
	v_add_f32_e32 v92, v94, v92
	v_mfma_f32_32x32x16_bf16 v[52:67], v[176:179], v[164:167], v[52:67]
	v_add_f32_e32 v92, v131, v92
	v_add_f32_e32 v92, v95, v92
	s_waitcnt lgkmcnt(0)
	v_max_f32_e32 v99, v99, v99
	v_add_f32_e32 v92, v96, v92
	v_max_f32_e32 v93, v93, v99
	v_add_f32_e32 v92, v97, v92
	v_sub_f32_e32 v99, v93, v2
	v_mfma_f32_32x32x16_bf16 v[36:51], v[172:175], v[164:167], v[36:51]
	v_add_f32_e32 v92, v98, v92
	v_cmp_ge_f32_e32 vcc, s42, v99
	v_add_f32_e32 v92, v128, v92
	s_cmp_eq_u64 vcc, exec
	v_mfma_f32_32x32x16_bf16 v[20:35], v[160:163], v[164:167], v[20:35]
	v_mfma_f32_32x32x16_bf16 v[4:19], v[152:155], v[164:167], v[4:19]
	s_cbranch_scc1 .LBB0_1022
	v_max_f32_e64 v93, -v93, -v93
	v_max_f32_e64 v99, -v2, -v2
	v_min_f32_e32 v93, v99, v93
	v_add_f32_e32 v2, v2, v93
	v_exp_f32_e32 v2, v2
	s_nop 0
	v_mul_f32_e32 v92, v92, v2
	v_mul_f32 v66, v66, v2
	v_mul_f32 v67, v67, v2
	v_mul_f32 v64, v64, v2
	v_mul_f32 v65, v65, v2
	v_mul_f32 v62, v62, v2
	v_mul_f32 v63, v63, v2
	v_mul_f32 v60, v60, v2
	v_mul_f32 v61, v61, v2
	v_mul_f32 v58, v58, v2
	v_mul_f32 v59, v59, v2
	v_mul_f32 v56, v56, v2
	v_mul_f32 v57, v57, v2
	v_mul_f32 v54, v54, v2
	v_mul_f32 v55, v55, v2
	v_mul_f32 v52, v52, v2
	v_mul_f32 v53, v53, v2
	v_mul_f32 v50, v50, v2
	v_mul_f32 v51, v51, v2
	v_mul_f32 v48, v48, v2
	v_mul_f32 v49, v49, v2
	v_mul_f32 v46, v46, v2
	v_mul_f32 v47, v47, v2
	v_mul_f32 v44, v44, v2
	v_mul_f32 v45, v45, v2
	v_mul_f32 v42, v42, v2
	v_mul_f32 v43, v43, v2
	v_mul_f32 v40, v40, v2
	v_mul_f32 v41, v41, v2
	v_mul_f32 v38, v38, v2
	v_mul_f32 v39, v39, v2
	v_mul_f32 v36, v36, v2
	v_mul_f32 v37, v37, v2
	v_mul_f32 v34, v34, v2
	v_mul_f32 v35, v35, v2
	v_mul_f32 v32, v32, v2
	v_mul_f32 v33, v33, v2
	v_mul_f32 v30, v30, v2
	v_mul_f32 v31, v31, v2
	v_mul_f32 v28, v28, v2
	v_mul_f32 v29, v29, v2
	v_mul_f32 v26, v26, v2
	v_mul_f32 v27, v27, v2
	v_mul_f32 v24, v24, v2
	v_mul_f32 v25, v25, v2
	v_mul_f32 v22, v22, v2
	v_mul_f32 v23, v23, v2
	v_mul_f32 v20, v20, v2
	v_mul_f32 v21, v21, v2
	v_mul_f32 v18, v18, v2
	v_mul_f32 v19, v19, v2
	v_mul_f32 v16, v16, v2
	v_mul_f32 v17, v17, v2
	v_mul_f32 v14, v14, v2
	v_mul_f32 v15, v15, v2
	v_mul_f32 v12, v12, v2
	v_mul_f32 v13, v13, v2
	v_mul_f32 v10, v10, v2
	v_mul_f32 v11, v11, v2
	v_mul_f32 v8, v8, v2
	v_mul_f32 v9, v9, v2
	v_mul_f32 v6, v6, v2
	v_mul_f32 v7, v7, v2
	v_mul_f32 v4, v4, v2
	v_mul_f32 v5, v5, v2
	s_branch .LBB0_1023

.LBB0_1023:
	v_fmamk_f32 v2, v68, 0x3e0293ee, v93
	v_exp_f32_e32 v2, v2
	v_fmamk_f32 v69, v69, 0x3e0293ee, v93
	v_exp_f32_e32 v69, v69
	v_fmamk_f32 v70, v70, 0x3e0293ee, v93
	v_exp_f32_e32 v70, v70
	v_fmamk_f32 v71, v71, 0x3e0293ee, v93
	v_exp_f32_e32 v71, v71
	v_fmamk_f32 v72, v72, 0x3e0293ee, v93
	v_add_f32_e32 v68, 0, v2
	v_exp_f32_e32 v72, v72
	v_fmamk_f32 v73, v73, 0x3e0293ee, v93
	v_add_f32_e32 v68, v69, v68
	v_exp_f32_e32 v73, v73
	v_fmamk_f32 v74, v74, 0x3e0293ee, v93
	v_add_f32_e32 v68, v70, v68
	v_exp_f32_e32 v74, v74
	v_fmamk_f32 v75, v75, 0x3e0293ee, v93
	v_add_f32_e32 v68, v71, v68
	v_exp_f32_e32 v75, v75
	v_add_f32_e32 v68, v72, v68
	v_add_f32_e32 v68, v73, v68
	v_add_f32_e32 v68, v74, v68
	v_cvt_pk_bf16_f32 v101, v94, v131
	v_add_f32_e32 v94, v75, v68
	v_fmamk_f32 v68, v76, 0x3e0293ee, v93
	v_exp_f32_e32 v76, v68
	v_cvt_pk_bf16_f32 v68, v2, v69
	v_cvt_pk_bf16_f32 v69, v70, v71
	v_cvt_pk_bf16_f32 v70, v72, v73
	v_fmamk_f32 v72, v77, 0x3e0293ee, v93
	v_exp_f32_e32 v72, v72
	v_fmamk_f32 v73, v78, 0x3e0293ee, v93
	v_cvt_pk_bf16_f32 v71, v74, v75
	v_exp_f32_e32 v73, v73
	v_fmamk_f32 v74, v79, 0x3e0293ee, v93
	v_exp_f32_e32 v74, v74
	v_fmamk_f32 v75, v80, 0x3e0293ee, v93
	v_cvt_pk_bf16_f32 v100, v129, v130
	v_cvt_pk_bf16_f32 v102, v95, v96
	v_cvt_pk_bf16_f32 v103, v97, v98
	v_add_f32_e32 v2, v76, v94
	v_exp_f32_e32 v75, v75
	v_fmamk_f32 v77, v81, 0x3e0293ee, v93
	v_mfma_f32_32x32x16_bf16 v[52:67], v[144:147], v[100:103], v[52:67]
	v_add_f32_e32 v2, v72, v2
	v_exp_f32_e32 v77, v77
	v_fmamk_f32 v78, v82, 0x3e0293ee, v93
	v_add_f32_e32 v2, v73, v2
	v_exp_f32_e32 v78, v78
	v_fmac_f32_e32 v93, 0x3e0293ee, v83
	v_add_f32_e32 v2, v74, v2
	v_mfma_f32_32x32x16_bf16 v[36:51], v[140:143], v[100:103], v[36:51]
	v_exp_f32_e32 v79, v93
	v_add_f32_e32 v2, v75, v2
	v_add_f32_e32 v2, v77, v2
	v_add_f32_e32 v2, v78, v2
	v_add_f32_e32 v2, v79, v2
	v_add_f32_e32 v2, v92, v2
	s_waitcnt lgkmcnt(0)
	v_mfma_f32_32x32x16_bf16 v[20:35], v[136:139], v[100:103], v[20:35]
	s_lshl_b32 s1, s45, 16
	s_or_b32 s0, s0, s1
	v_mfma_f32_32x32x16_bf16 v[4:19], v[132:135], v[100:103], v[4:19]
	v_mfma_f32_32x32x16_bf16 v[52:67], v[124:127], v[68:71], v[52:67]
	v_mfma_f32_32x32x16_bf16 v[36:51], v[120:123], v[68:71], v[36:51]
	v_mfma_f32_32x32x16_bf16 v[20:35], v[116:119], v[68:71], v[20:35]
	v_mfma_f32_32x32x16_bf16 v[4:19], v[112:115], v[68:71], v[4:19]
	v_cvt_pk_bf16_f32 v68, v76, v72
	ds_bpermute_b32 v72, v206, v2
	v_cvt_pk_bf16_f32 v69, v73, v74
	v_cvt_pk_bf16_f32 v70, v75, v77
	v_cvt_pk_bf16_f32 v71, v78, v79
	s_waitcnt lgkmcnt(0)
	v_add_f32_e32 v2, v2, v72
	v_div_scale_f32 v72, s[26:27], v2, v2, 1.0
	v_rcp_f32_e32 v73, v72
	v_mfma_f32_32x32x16_bf16 v[52:67], v[108:111], v[68:71], v[52:67]
	v_fma_f32 v74, -v72, v73, 1.0
	v_fmac_f32_e32 v73, v74, v73
	v_div_scale_f32 v74, vcc, 1.0, v2, 1.0
	v_mul_f32_e32 v75, v74, v73
	v_mfma_f32_32x32x16_bf16 v[36:51], v[104:107], v[68:71], v[36:51]
	v_fma_f32 v76, -v72, v75, v74
	v_fmac_f32_e32 v75, v76, v73
	v_fma_f32 v72, -v72, v75, v74
	v_div_fmas_f32 v72, v72, v73, v75
	v_div_fixup_f32 v72, v72, v2, 1.0
	v_mov_b32_e32 v2, v1
	v_mfma_f32_32x32x16_bf16 v[20:35], v[88:91], v[68:71], v[20:35]
	v_mul_f32_e64 v52, v52, v72
	v_mul_f32_e64 v53, v53, v72
	v_mul_f32_e64 v54, v54, v72
	v_mul_f32_e64 v55, v55, v72
	s_nop 0
	v_mul_f32_e64 v36, v36, v72
	v_mul_f32_e64 v37, v37, v72
	v_mul_f32 v38, v38, v72
	v_mul_f32 v39, v39, v72
	v_lshl_add_u32 v2, v2, 11, s0
	v_cvt_pk_bf16_f32 v52, v52, v53
	v_cvt_pk_bf16_f32 v53, v54, v55
	v_mfma_f32_32x32x16_bf16 v[4:19], v[84:87], v[68:71], v[4:19]
	v_mul_f32_e64 v20, v20, v72
	v_mul_f32_e64 v21, v21, v72
	v_mul_f32_e64 v22, v22, v72
	v_mul_f32_e64 v23, v23, v72
	v_mul_f32_e64 v54, v56, v72
	v_mul_f32_e64 v55, v57, v72
	v_mul_f32 v56, v58, v72
	v_mul_f32 v57, v59, v72
	v_cvt_pk_bf16_f32 v36, v36, v37
	v_cvt_pk_bf16_f32 v37, v38, v39
	v_mul_f32 v38, v40, v72
	v_mul_f32 v39, v41, v72
	v_mul_f32 v40, v42, v72
	v_mul_f32 v41, v43, v72
	v_cvt_pk_bf16_f32 v20, v20, v21
	v_cvt_pk_bf16_f32 v21, v22, v23
	v_mul_f32 v22, v24, v72
	v_mul_f32 v23, v25, v72
	v_mul_f32 v24, v26, v72
	v_mul_f32 v25, v27, v72
	v_mul_f32 v4, v4, v72
	v_mul_f32 v5, v5, v72
	v_mul_f32 v6, v6, v72
	v_mul_f32 v7, v7, v72
	v_or_b32_e32 v2, 0x400, v2
	v_cvt_pk_bf16_f32 v54, v54, v55
	v_cvt_pk_bf16_f32 v55, v56, v57
	v_cvt_pk_bf16_f32 v38, v38, v39
	v_cvt_pk_bf16_f32 v39, v40, v41
	v_cvt_pk_bf16_f32 v22, v22, v23
	v_cvt_pk_bf16_f32 v23, v24, v25
	v_cvt_pk_bf16_f32 v4, v4, v5
	v_cvt_pk_bf16_f32 v5, v6, v7
	v_mul_f32 v6, v8, v72
	v_mul_f32 v7, v9, v72
	v_mul_f32 v8, v10, v72
	v_mul_f32 v9, v11, v72
	v_lshl_add_u64 v[68:69], v[2:3], 1, v[198:199]
	v_permlane32_swap_b32_e32 v52, v54
	v_permlane32_swap_b32_e32 v53, v55
	v_permlane32_swap_b32_e32 v36, v38
	v_permlane32_swap_b32_e32 v37, v39
	v_permlane32_swap_b32_e32 v20, v22
	v_permlane32_swap_b32_e32 v21, v23
	v_cvt_pk_bf16_f32 v6, v6, v7
	v_cvt_pk_bf16_f32 v7, v8, v9
	global_store_dwordx4 v[68:69], v[52:55], off
	global_store_dwordx4 v[68:69], v[36:39], off offset:64
	global_store_dwordx4 v[68:69], v[20:23], off offset:128
	v_mul_f32 v52, v60, v72
	v_mul_f32 v53, v61, v72
	v_mul_f32 v54, v62, v72
	v_mul_f32 v55, v63, v72
	v_mul_f32 v36, v44, v72
	v_mul_f32 v37, v45, v72
	v_mul_f32 v38, v46, v72
	v_mul_f32 v39, v47, v72
	v_mul_f32 v20, v28, v72
	v_mul_f32 v21, v29, v72
	v_mul_f32 v22, v30, v72
	v_mul_f32 v23, v31, v72
	v_permlane32_swap_b32_e32 v4, v6
	v_permlane32_swap_b32_e32 v5, v7
	v_cvt_pk_bf16_f32 v52, v52, v53
	v_cvt_pk_bf16_f32 v53, v54, v55
	v_mul_f32 v54, v64, v72
	v_mul_f32 v55, v65, v72
	v_mul_f32 v56, v66, v72
	v_mul_f32 v57, v67, v72
	v_cvt_pk_bf16_f32 v36, v36, v37
	v_cvt_pk_bf16_f32 v37, v38, v39
	v_mul_f32 v38, v48, v72
	v_mul_f32 v39, v49, v72
	v_mul_f32 v40, v50, v72
	v_mul_f32 v41, v51, v72
	v_cvt_pk_bf16_f32 v20, v20, v21
	v_cvt_pk_bf16_f32 v21, v22, v23
	v_mul_f32 v22, v32, v72
	v_mul_f32 v23, v33, v72
	v_mul_f32 v24, v34, v72
	v_mul_f32 v25, v35, v72
	global_store_dwordx4 v[68:69], v[4:7], off offset:192
	v_cvt_pk_bf16_f32 v54, v54, v55
	v_cvt_pk_bf16_f32 v55, v56, v57
	v_mul_f32 v4, v12, v72
	v_mul_f32 v5, v13, v72
	v_mul_f32 v6, v14, v72
	v_mul_f32 v7, v15, v72
	v_cvt_pk_bf16_f32 v38, v38, v39
	v_cvt_pk_bf16_f32 v39, v40, v41
	v_cvt_pk_bf16_f32 v22, v22, v23
	v_cvt_pk_bf16_f32 v23, v24, v25
	v_cvt_pk_bf16_f32 v4, v4, v5
	v_cvt_pk_bf16_f32 v5, v6, v7
	v_mul_f32 v6, v16, v72
	v_mul_f32 v7, v17, v72
	v_mul_f32 v8, v18, v72
	v_mul_f32 v9, v19, v72
	v_permlane32_swap_b32_e32 v52, v54
	v_permlane32_swap_b32_e32 v53, v55
	v_permlane32_swap_b32_e32 v36, v38
	v_permlane32_swap_b32_e32 v37, v39
	v_permlane32_swap_b32_e32 v20, v22
	v_permlane32_swap_b32_e32 v21, v23
	v_cvt_pk_bf16_f32 v6, v6, v7
	v_cvt_pk_bf16_f32 v7, v8, v9
	global_store_dwordx4 v[68:69], v[52:55], off offset:32
	global_store_dwordx4 v[68:69], v[36:39], off offset:96
	global_store_dwordx4 v[68:69], v[20:23], off offset:160
	v_permlane32_swap_b32_e32 v4, v6
	v_permlane32_swap_b32_e32 v5, v7
	s_mov_b64 s[0:1], 0

.LBB0_1026:
	v_max_f32_e32 v112, v112, v112
	v_max_f32_e32 v113, v214, v214
	v_max_f32_e32 v113, v113, v112
	v_sub_f32_e32 v112, v214, v113
	v_exp_f32_e32 v112, v112
	v_mov_b32_e32 v214, v113
	v_mul_f32_e32 v2, v2, v112
	v_mul_f32 v80, v80, v112
	v_mul_f32 v81, v81, v112
	v_mul_f32 v78, v78, v112
	v_mul_f32 v79, v79, v112
	v_mul_f32 v76, v76, v112
	v_mul_f32 v77, v77, v112
	v_mul_f32 v74, v74, v112
	v_mul_f32 v75, v75, v112
	v_mul_f32 v72, v72, v112
	v_mul_f32 v73, v73, v112
	v_mul_f32 v70, v70, v112
	v_mul_f32 v71, v71, v112
	v_mul_f32 v68, v68, v112
	v_mul_f32 v69, v69, v112
	v_mul_f32 v66, v66, v112
	v_mul_f32 v67, v67, v112
	v_mul_f32 v64, v64, v112
	v_mul_f32 v65, v65, v112
	v_mul_f32 v62, v62, v112
	v_mul_f32 v63, v63, v112
	v_mul_f32 v60, v60, v112
	v_mul_f32 v61, v61, v112
	v_mul_f32 v58, v58, v112
	v_mul_f32 v59, v59, v112
	v_mul_f32 v56, v56, v112
	v_mul_f32 v57, v57, v112
	v_mul_f32 v54, v54, v112
	v_mul_f32 v55, v55, v112
	v_mul_f32 v52, v52, v112
	v_mul_f32 v53, v53, v112
	v_mul_f32 v50, v50, v112
	v_mul_f32 v51, v51, v112
	v_mul_f32 v48, v48, v112
	v_mul_f32 v49, v49, v112
	v_mul_f32 v46, v46, v112
	v_mul_f32 v47, v47, v112
	v_mul_f32 v44, v44, v112
	v_mul_f32 v45, v45, v112
	v_mul_f32 v42, v42, v112
	v_mul_f32 v43, v43, v112
	v_mul_f32 v40, v40, v112
	v_mul_f32 v41, v41, v112
	v_mul_f32 v38, v38, v112
	v_mul_f32 v39, v39, v112
	v_mul_f32 v36, v36, v112
	v_mul_f32 v37, v37, v112
	v_mul_f32 v34, v34, v112
	v_mul_f32 v35, v35, v112
	v_mul_f32 v32, v32, v112
	v_mul_f32 v33, v33, v112
	v_mul_f32 v30, v30, v112
	v_mul_f32 v31, v31, v112
	v_mul_f32 v28, v28, v112
	v_mul_f32 v29, v29, v112
	v_mul_f32 v26, v26, v112
	v_mul_f32 v27, v27, v112
	v_mul_f32 v24, v24, v112
	v_mul_f32 v25, v25, v112
	v_mul_f32 v22, v22, v112
	v_mul_f32 v23, v23, v112
	v_mul_f32 v20, v20, v112
	v_mul_f32 v21, v21, v112
	v_mul_f32 v18, v18, v112
	v_mul_f32 v19, v19, v112
	v_xor_b32_e32 v112, 0x80000000, v113

.LBB0_1035:
	ds_read_b128 v[4:7], v195 offset:0
	ds_read_b128 v[8:11], v195 offset:0x400
	ds_read_b128 v[12:15], v195 offset:0x800
	ds_read_b128 v[82:85], v195 offset:0xc00
	ds_read_b128 v[86:89], v195 offset:0x1000
	ds_read_b128 v[90:93], v195 offset:0x1400
	ds_read_b128 v[94:97], v195 offset:0x1800
	ds_read_b128 v[162:165], v195 offset:0x1c00
	s_nop 0
	s_waitcnt lgkmcnt(4)
	s_nop 0
	v_mfma_f32_32x32x16_bf16 v[98:113], v[4:7], v[114:117], 0
	ds_read_b128 v[4:7], v195 offset:0x2000
	v_mfma_f32_32x32x16_bf16 v[98:113], v[8:11], v[118:121], v[98:113]
	ds_read_b128 v[8:11], v195 offset:0x2400
	v_mfma_f32_32x32x16_bf16 v[98:113], v[12:15], v[122:125], v[98:113]
	ds_read_b128 v[12:15], v195 offset:0x2800
	v_mfma_f32_32x32x16_bf16 v[98:113], v[82:85], v[126:129], v[98:113]
	ds_read_b128 v[82:85], v195 offset:0x2c00
	s_waitcnt lgkmcnt(4)
	s_nop 0
	v_mfma_f32_32x32x16_bf16 v[98:113], v[86:89], v[130:133], v[98:113]
	ds_read_b128 v[86:89], v195 offset:0x3000
	v_mfma_f32_32x32x16_bf16 v[98:113], v[90:93], v[134:137], v[98:113]
	v_mfma_f32_32x32x16_bf16 v[98:113], v[94:97], v[138:141], v[98:113]
	v_mfma_f32_32x32x16_bf16 v[98:113], v[162:165], v[142:145], v[98:113]
	ds_read_b128 v[162:165], v195 offset:0x3400
	ds_read_b128 v[216:219], v195 offset:0x3800
	ds_read_b128 v[220:223], v195 offset:0x3c00
	s_waitcnt lgkmcnt(4)
	ds_read_b128 v[178:181], v195 offset:0x4000
	ds_read_b128 v[174:177], v195 offset:0x4400
	ds_read_b128 v[170:173], v195 offset:0x4800
	ds_read_b128 v[166:169], v195 offset:0x4c00
	s_nop 0
	s_waitcnt lgkmcnt(4)
	v_mfma_f32_32x32x16_bf16 v[98:113], v[4:7], v[146:149], v[98:113]
	v_mfma_f32_32x32x16_bf16 v[98:113], v[8:11], v[150:153], v[98:113]
	ds_read_b128 v[8:11], v195 offset:0x5000
	v_mfma_f32_32x32x16_bf16 v[98:113], v[12:15], v[154:157], v[98:113]
	v_mfma_f32_32x32x16_bf16 v[98:113], v[82:85], v[158:161], v[98:113]
	v_mfma_f32_32x32x16_bf16 v[82:97], v[86:89], v[114:117], 0
	s_nop 10
	v_max3_f32 v2, v98, s40, v99
	v_max3_f32 v2, v2, v100, v101
	v_max3_f32 v2, v2, v102, v103
	v_max3_f32 v2, v2, v104, v105
	v_max3_f32 v2, v2, v106, v107
	v_max3_f32 v2, v2, v108, v109
	v_max3_f32 v2, v2, v110, v111
	v_mfma_f32_32x32x16_bf16 v[82:97], v[162:165], v[118:121], v[82:97]
	v_max3_f32 v2, v2, v112, v113
	v_mul_f32_e32 v2, 0x3dd53b94, v2
	ds_bpermute_b32 v16, v206, v2
	ds_read_b128 v[162:165], v195 offset:0x5400
	ds_read_b128 v[12:15], v195 offset:0x5800
	ds_read_b128 v[4:7], v195 offset:0x5c00
	s_waitcnt lgkmcnt(0)
	v_max_f32_e32 v16, v16, v16
	v_mfma_f32_32x32x16_bf16 v[82:97], v[216:219], v[122:125], v[82:97]
	v_max_f32_e32 v2, v2, v16
	v_sub_f32_e32 v16, v2, v214
	v_cmp_ge_f32_e32 vcc, s42, v16
	s_cmp_eq_u64 vcc, exec
	v_mfma_f32_32x32x16_bf16 v[82:97], v[220:223], v[126:129], v[82:97]
	s_cbranch_scc1 .LBB0_1037
	v_max_f32_e32 v2, v2, v2
	v_max_f32_e32 v16, v214, v214
	v_max_f32_e32 v16, v16, v2
	v_sub_f32_e32 v2, v214, v16
	v_exp_f32_e32 v2, v2
	v_mov_b32_e32 v214, v16
	v_mul_f32_e32 v215, v215, v2
	v_mul_f32 v80, v80, v2
	v_mul_f32 v81, v81, v2
	v_mul_f32 v78, v78, v2
	v_mul_f32 v79, v79, v2
	v_mul_f32 v76, v76, v2
	v_mul_f32 v77, v77, v2
	v_mul_f32 v74, v74, v2
	v_mul_f32 v75, v75, v2
	v_mul_f32 v72, v72, v2
	v_mul_f32 v73, v73, v2
	v_mul_f32 v70, v70, v2
	v_mul_f32 v71, v71, v2
	v_mul_f32 v68, v68, v2
	v_mul_f32 v69, v69, v2
	v_mul_f32 v66, v66, v2
	v_mul_f32 v67, v67, v2
	v_mul_f32 v64, v64, v2
	v_mul_f32 v65, v65, v2
	v_mul_f32 v62, v62, v2
	v_mul_f32 v63, v63, v2
	v_mul_f32 v60, v60, v2
	v_mul_f32 v61, v61, v2
	v_mul_f32 v58, v58, v2
	v_mul_f32 v59, v59, v2
	v_mul_f32 v56, v56, v2
	v_mul_f32 v57, v57, v2
	v_mul_f32 v54, v54, v2
	v_mul_f32 v55, v55, v2
	v_mul_f32 v52, v52, v2
	v_mul_f32 v53, v53, v2
	v_mul_f32 v50, v50, v2
	v_mul_f32 v51, v51, v2
	v_mul_f32 v48, v48, v2
	v_mul_f32 v49, v49, v2
	v_mul_f32 v46, v46, v2
	v_mul_f32 v47, v47, v2
	v_mul_f32 v44, v44, v2
	v_mul_f32 v45, v45, v2
	v_mul_f32 v42, v42, v2
	v_mul_f32 v43, v43, v2
	v_mul_f32 v40, v40, v2
	v_mul_f32 v41, v41, v2
	v_mul_f32 v38, v38, v2
	v_mul_f32 v39, v39, v2
	v_mul_f32 v36, v36, v2
	v_mul_f32 v37, v37, v2
	v_mul_f32 v34, v34, v2
	v_mul_f32 v35, v35, v2
	v_mul_f32 v32, v32, v2
	v_mul_f32 v33, v33, v2
	v_mul_f32 v30, v30, v2
	v_mul_f32 v31, v31, v2
	v_mul_f32 v28, v28, v2
	v_mul_f32 v29, v29, v2
	v_mul_f32 v26, v26, v2
	v_mul_f32 v27, v27, v2
	v_mul_f32 v24, v24, v2
	v_mul_f32 v25, v25, v2
	v_mul_f32 v22, v22, v2
	v_mul_f32 v23, v23, v2
	v_mul_f32 v20, v20, v2
	v_mul_f32 v21, v21, v2
	v_mul_f32 v18, v18, v2
	v_mul_f32 v19, v19, v2
.LBB0_1037:
	s_waitcnt lgkmcnt(4)
	ds_read_b128 v[216:219], v195 offset:0x6000
	ds_read_b128 v[220:223], v195 offset:0x6400
	v_fma_f32 v2, v98, s43, -v214
	v_mfma_f32_32x32x16_bf16 v[82:97], v[178:181], v[130:133], v[82:97]
	ds_read_b128 v[178:181], v195 offset:0x6800
	ds_read_b128 v[224:227], v195 offset:0x6c00
	s_waitcnt lgkmcnt(4)
	v_exp_f32_e32 v2, v2
	v_fma_f32 v16, v99, s43, -v214
	v_exp_f32_e32 v16, v16
	v_fma_f32 v98, v100, s43, -v214
	v_mfma_f32_32x32x16_bf16 v[82:97], v[174:177], v[134:137], v[82:97]
	v_exp_f32_e32 v98, v98
	v_fma_f32 v99, v101, s43, -v214
	v_exp_f32_e32 v99, v99
	v_fma_f32 v100, v102, s43, -v214
	v_add_f32_e32 v17, 0, v2
	v_exp_f32_e32 v100, v100
	v_fma_f32 v101, v103, s43, -v214
	v_mfma_f32_32x32x16_bf16 v[82:97], v[170:173], v[138:141], v[82:97]
	v_add_f32_e32 v17, v16, v17
	v_exp_f32_e32 v101, v101
	v_fma_f32 v102, v104, s43, -v214
	v_exp_f32_e32 v232, v102
	v_fma_f32 v102, v105, s43, -v214
	v_cvt_pk_bf16_f32 v228, v2, v16
	v_add_f32_e32 v2, v98, v17
	v_mfma_f32_32x32x16_bf16 v[82:97], v[166:169], v[142:145], v[82:97]
	v_exp_f32_e32 v233, v102
	v_add_f32_e32 v2, v99, v2
	v_fma_f32 v16, v106, s43, -v214
	v_add_f32_e32 v2, v100, v2
	v_exp_f32_e32 v16, v16
	v_add_f32_e32 v2, v101, v2
	v_add_f32_e32 v2, v232, v2
	v_mfma_f32_32x32x16_bf16 v[82:97], v[8:11], v[146:149], v[82:97]
	v_fma_f32 v8, v107, s43, -v214
	v_exp_f32_e32 v17, v8
	v_fma_f32 v8, v108, s43, -v214
	v_exp_f32_e32 v106, v8
	v_fma_f32 v8, v109, s43, -v214
	v_exp_f32_e32 v107, v8
	v_fma_f32 v8, v110, s43, -v214
	v_mfma_f32_32x32x16_bf16 v[82:97], v[162:165], v[150:153], v[82:97]
	v_exp_f32_e32 v108, v8
	v_fma_f32 v8, v111, s43, -v214
	v_exp_f32_e32 v109, v8
	v_fma_f32 v8, v112, s43, -v214
	v_add_f32_e32 v2, v233, v2
	v_exp_f32_e32 v110, v8
	v_fma_f32 v8, v113, s43, -v214
	v_mfma_f32_32x32x16_bf16 v[82:97], v[12:15], v[154:157], v[82:97]
	v_cvt_pk_bf16_f32 v229, v98, v99
	v_cvt_pk_bf16_f32 v230, v100, v101
	v_cvt_pk_bf16_f32 v231, v232, v233
	v_add_f32_e32 v2, v16, v2
	ds_read_b128 v[174:177], v195 offset:0x7000
	ds_read_b128 v[170:173], v195 offset:0x7400
	ds_read_b128 v[166:169], v195 offset:0x7800
	v_mfma_f32_32x32x16_bf16 v[82:97], v[4:7], v[158:161], v[82:97]
	ds_read_b128 v[102:105], v195 offset:0x7c00
	s_waitcnt lgkmcnt(4)
	v_add_f32_e32 v2, v17, v2
	v_add_f32_e32 v2, v106, v2
	v_add_f32_e32 v2, v107, v2
	v_exp_f32_e32 v111, v8
	v_add_f32_e32 v2, v108, v2
	s_nop 6
	v_max3_f32 v4, v82, s40, v83
	v_max3_f32 v4, v4, v84, v85
	v_max3_f32 v4, v4, v86, v87
	v_max3_f32 v4, v4, v88, v89
	v_max3_f32 v4, v4, v90, v91
	v_max3_f32 v4, v4, v92, v93
	v_max3_f32 v4, v4, v94, v95
	v_max3_f32 v4, v4, v96, v97
	v_mul_f32_e32 v112, 0x3dd53b94, v4
	ds_bpermute_b32 v113, v206, v112
	v_mfma_f32_32x32x16_bf16 v[66:81], v[216:219], v[228:231], v[66:81]
	v_add_f32_e32 v2, v109, v2
	v_add_f32_e32 v2, v110, v2
	ds_read_b128 v[8:11], v195 offset:0x8000
	s_waitcnt lgkmcnt(0)
	v_max_f32_e32 v113, v113, v113
	v_max_f32_e32 v112, v112, v113
	ds_read_b128 v[98:101], v195 offset:0x8400
	ds_read_b128 v[12:15], v195 offset:0x8800
	v_mfma_f32_32x32x16_bf16 v[50:65], v[220:223], v[228:231], v[50:65]
	ds_read_b128 v[4:7], v195 offset:0x8c00
	v_sub_f32_e32 v113, v112, v214
	v_add_f32_e32 v2, v111, v2
	v_cmp_ge_f32_e32 vcc, s42, v113
	v_add_f32_e32 v2, v215, v2
	s_cmp_eq_u64 vcc, exec
	v_mfma_f32_32x32x16_bf16 v[34:49], v[178:181], v[228:231], v[34:49]
	v_mfma_f32_32x32x16_bf16 v[18:33], v[224:227], v[228:231], v[18:33]
	s_cbranch_scc1 .LBB0_1039
	v_max_f32_e32 v112, v112, v112
	v_max_f32_e32 v113, v214, v214
	v_max_f32_e32 v113, v113, v112
	v_sub_f32_e32 v112, v214, v113
	v_exp_f32_e32 v112, v112
	v_mov_b32_e32 v214, v113
	v_mul_f32_e32 v2, v2, v112
	v_mul_f32 v80, v80, v112
	v_mul_f32 v81, v81, v112
	v_mul_f32 v78, v78, v112
	v_mul_f32 v79, v79, v112
	v_mul_f32 v76, v76, v112
	v_mul_f32 v77, v77, v112
	v_mul_f32 v74, v74, v112
	v_mul_f32 v75, v75, v112
	v_mul_f32 v72, v72, v112
	v_mul_f32 v73, v73, v112
	v_mul_f32 v70, v70, v112
	v_mul_f32 v71, v71, v112
	v_mul_f32 v68, v68, v112
	v_mul_f32 v69, v69, v112
	v_mul_f32 v66, v66, v112
	v_mul_f32 v67, v67, v112
	v_mul_f32 v64, v64, v112
	v_mul_f32 v65, v65, v112
	v_mul_f32 v62, v62, v112
	v_mul_f32 v63, v63, v112
	v_mul_f32 v60, v60, v112
	v_mul_f32 v61, v61, v112
	v_mul_f32 v58, v58, v112
	v_mul_f32 v59, v59, v112
	v_mul_f32 v56, v56, v112
	v_mul_f32 v57, v57, v112
	v_mul_f32 v54, v54, v112
	v_mul_f32 v55, v55, v112
	v_mul_f32 v52, v52, v112
	v_mul_f32 v53, v53, v112
	v_mul_f32 v50, v50, v112
	v_mul_f32 v51, v51, v112
	v_mul_f32 v48, v48, v112
	v_mul_f32 v49, v49, v112
	v_mul_f32 v46, v46, v112
	v_mul_f32 v47, v47, v112
	v_mul_f32 v44, v44, v112
	v_mul_f32 v45, v45, v112
	v_mul_f32 v42, v42, v112
	v_mul_f32 v43, v43, v112
	v_mul_f32 v40, v40, v112
	v_mul_f32 v41, v41, v112
	v_mul_f32 v38, v38, v112
	v_mul_f32 v39, v39, v112
	v_mul_f32 v36, v36, v112
	v_mul_f32 v37, v37, v112
	v_mul_f32 v34, v34, v112
	v_mul_f32 v35, v35, v112
	v_mul_f32 v32, v32, v112
	v_mul_f32 v33, v33, v112
	v_mul_f32 v30, v30, v112
	v_mul_f32 v31, v31, v112
	v_mul_f32 v28, v28, v112
	v_mul_f32 v29, v29, v112
	v_mul_f32 v26, v26, v112
	v_mul_f32 v27, v27, v112
	v_mul_f32 v24, v24, v112
	v_mul_f32 v25, v25, v112
	v_mul_f32 v22, v22, v112
	v_mul_f32 v23, v23, v112
	v_mul_f32 v20, v20, v112
	v_mul_f32 v21, v21, v112
	v_mul_f32 v18, v18, v112
	v_mul_f32 v19, v19, v112
	v_xor_b32_e32 v112, 0x80000000, v113
	s_branch .LBB0_1040

.LBB0_1042:
	s_waitcnt vmcnt(5)
	s_mov_b32 m0, s54
	s_waitcnt lgkmcnt(0)
	s_barrier
	global_load_lds_dwordx4 v[186:187], off
	s_mov_b32 m0, s56
	s_nop 0
	global_load_lds_dwordx4 v[188:189], off
	s_mov_b32 m0, s57
	s_nop 0
	global_load_lds_dwordx4 v[190:191], off
	s_mov_b32 m0, s58
	s_nop 0
	global_load_lds_dwordx4 v[200:201], off
	s_mov_b32 m0, s59
	s_nop 0
	global_load_lds_dwordx4 v[202:203], off
	ds_read_b128 v[4:7], v197 offset:0
	ds_read_b128 v[8:11], v197 offset:0x400
	ds_read_b128 v[12:15], v197 offset:0x800
	ds_read_b128 v[82:85], v197 offset:0xc00
	ds_read_b128 v[86:89], v197 offset:0x1000
	ds_read_b128 v[90:93], v197 offset:0x1400
	ds_read_b128 v[94:97], v197 offset:0x1800
	ds_read_b128 v[162:165], v197 offset:0x1c00
	s_nop 0
	s_waitcnt lgkmcnt(4)
	s_nop 0
	v_mfma_f32_32x32x16_bf16 v[98:113], v[4:7], v[114:117], 0
	ds_read_b128 v[4:7], v197 offset:0x2000
	v_mfma_f32_32x32x16_bf16 v[98:113], v[8:11], v[118:121], v[98:113]
	ds_read_b128 v[8:11], v197 offset:0x2400
	v_mfma_f32_32x32x16_bf16 v[98:113], v[12:15], v[122:125], v[98:113]
	ds_read_b128 v[12:15], v197 offset:0x2800
	ds_read_b128 v[216:219], v197 offset:0x2c00
	s_waitcnt lgkmcnt(4)
	v_mfma_f32_32x32x16_bf16 v[98:113], v[82:85], v[126:129], v[98:113]
	ds_read_b128 v[82:85], v197 offset:0x3000
	v_mfma_f32_32x32x16_bf16 v[98:113], v[86:89], v[130:133], v[98:113]
	v_mfma_f32_32x32x16_bf16 v[98:113], v[90:93], v[134:137], v[98:113]
	v_mfma_f32_32x32x16_bf16 v[98:113], v[94:97], v[138:141], v[98:113]
	v_mfma_f32_32x32x16_bf16 v[98:113], v[162:165], v[142:145], v[98:113]
	ds_read_b128 v[162:165], v197 offset:0x3400
	ds_read_b128 v[220:223], v197 offset:0x3800
	ds_read_b128 v[224:227], v197 offset:0x3c00
	s_waitcnt lgkmcnt(4)
	ds_read_b128 v[178:181], v197 offset:0x4000
	ds_read_b128 v[174:177], v197 offset:0x4400
	ds_read_b128 v[170:173], v197 offset:0x4800
	ds_read_b128 v[166:169], v197 offset:0x4c00
	s_nop 0
	s_waitcnt lgkmcnt(4)
	v_mfma_f32_32x32x16_bf16 v[98:113], v[4:7], v[146:149], v[98:113]
	v_mfma_f32_32x32x16_bf16 v[98:113], v[8:11], v[150:153], v[98:113]
	ds_read_b128 v[8:11], v197 offset:0x5000
	v_mfma_f32_32x32x16_bf16 v[98:113], v[12:15], v[154:157], v[98:113]
	v_mfma_f32_32x32x16_bf16 v[82:97], v[82:85], v[114:117], 0
	v_mfma_f32_32x32x16_bf16 v[98:113], v[216:219], v[158:161], v[98:113]
	v_mfma_f32_32x32x16_bf16 v[82:97], v[162:165], v[118:121], v[82:97]
	s_nop 10
	v_max3_f32 v2, v98, s40, v99
	v_max3_f32 v2, v2, v100, v101
	v_max3_f32 v2, v2, v102, v103
	v_max3_f32 v2, v2, v104, v105
	v_max3_f32 v2, v2, v106, v107
	v_max3_f32 v2, v2, v108, v109
	v_max3_f32 v2, v2, v110, v111
	v_mfma_f32_32x32x16_bf16 v[82:97], v[220:223], v[122:125], v[82:97]
	v_max3_f32 v2, v2, v112, v113
	v_mul_f32_e32 v2, 0x3dd53b94, v2
	ds_bpermute_b32 v16, v206, v2
	ds_read_b128 v[162:165], v197 offset:0x5400
	ds_read_b128 v[12:15], v197 offset:0x5800
	ds_read_b128 v[4:7], v197 offset:0x5c00
	s_waitcnt lgkmcnt(0)
	v_max_f32_e32 v16, v16, v16
	v_mfma_f32_32x32x16_bf16 v[82:97], v[224:227], v[126:129], v[82:97]
	v_max_f32_e32 v2, v2, v16
	v_sub_f32_e32 v16, v2, v214
	v_cmp_ge_f32_e32 vcc, s42, v16
	s_cmp_eq_u64 vcc, exec
	s_cbranch_scc1 .LBB0_1044
	v_max_f32_e32 v2, v2, v2
	v_max_f32_e32 v16, v214, v214
	v_max_f32_e32 v16, v16, v2
	v_sub_f32_e32 v2, v214, v16
	v_exp_f32_e32 v2, v2
	v_mov_b32_e32 v214, v16
	v_mul_f32_e32 v215, v215, v2
	v_mul_f32 v80, v80, v2
	v_mul_f32 v81, v81, v2
	v_mul_f32 v78, v78, v2
	v_mul_f32 v79, v79, v2
	v_mul_f32 v76, v76, v2
	v_mul_f32 v77, v77, v2
	v_mul_f32 v74, v74, v2
	v_mul_f32 v75, v75, v2
	v_mul_f32 v72, v72, v2
	v_mul_f32 v73, v73, v2
	v_mul_f32 v70, v70, v2
	v_mul_f32 v71, v71, v2
	v_mul_f32 v68, v68, v2
	v_mul_f32 v69, v69, v2
	v_mul_f32 v66, v66, v2
	v_mul_f32 v67, v67, v2
	v_mul_f32 v64, v64, v2
	v_mul_f32 v65, v65, v2
	v_mul_f32 v62, v62, v2
	v_mul_f32 v63, v63, v2
	v_mul_f32 v60, v60, v2
	v_mul_f32 v61, v61, v2
	v_mul_f32 v58, v58, v2
	v_mul_f32 v59, v59, v2
	v_mul_f32 v56, v56, v2
	v_mul_f32 v57, v57, v2
	v_mul_f32 v54, v54, v2
	v_mul_f32 v55, v55, v2
	v_mul_f32 v52, v52, v2
	v_mul_f32 v53, v53, v2
	v_mul_f32 v50, v50, v2
	v_mul_f32 v51, v51, v2
	v_mul_f32 v48, v48, v2
	v_mul_f32 v49, v49, v2
	v_mul_f32 v46, v46, v2
	v_mul_f32 v47, v47, v2
	v_mul_f32 v44, v44, v2
	v_mul_f32 v45, v45, v2
	v_mul_f32 v42, v42, v2
	v_mul_f32 v43, v43, v2
	v_mul_f32 v40, v40, v2
	v_mul_f32 v41, v41, v2
	v_mul_f32 v38, v38, v2
	v_mul_f32 v39, v39, v2
	v_mul_f32 v36, v36, v2
	v_mul_f32 v37, v37, v2
	v_mul_f32 v34, v34, v2
	v_mul_f32 v35, v35, v2
	v_mul_f32 v32, v32, v2
	v_mul_f32 v33, v33, v2
	v_mul_f32 v30, v30, v2
	v_mul_f32 v31, v31, v2
	v_mul_f32 v28, v28, v2
	v_mul_f32 v29, v29, v2
	v_mul_f32 v26, v26, v2
	v_mul_f32 v27, v27, v2
	v_mul_f32 v24, v24, v2
	v_mul_f32 v25, v25, v2
	v_mul_f32 v22, v22, v2
	v_mul_f32 v23, v23, v2
	v_mul_f32 v20, v20, v2
	v_mul_f32 v21, v21, v2
	v_mul_f32 v18, v18, v2
	v_mul_f32 v19, v19, v2
.LBB0_1044:
	s_waitcnt lgkmcnt(4)
	ds_read_b128 v[216:219], v197 offset:0x6000
	ds_read_b128 v[220:223], v197 offset:0x6400
	v_fma_f32 v2, v98, s43, -v214
	v_mfma_f32_32x32x16_bf16 v[82:97], v[178:181], v[130:133], v[82:97]
	ds_read_b128 v[178:181], v197 offset:0x6800
	ds_read_b128 v[224:227], v197 offset:0x6c00
	s_waitcnt lgkmcnt(4)
	v_exp_f32_e32 v2, v2
	v_fma_f32 v16, v99, s43, -v214
	v_exp_f32_e32 v16, v16
	v_fma_f32 v98, v100, s43, -v214
	v_mfma_f32_32x32x16_bf16 v[82:97], v[174:177], v[134:137], v[82:97]
	v_exp_f32_e32 v98, v98
	v_fma_f32 v99, v101, s43, -v214
	v_exp_f32_e32 v99, v99
	v_fma_f32 v100, v102, s43, -v214
	v_add_f32_e32 v17, 0, v2
	v_exp_f32_e32 v100, v100
	v_fma_f32 v101, v103, s43, -v214
	v_mfma_f32_32x32x16_bf16 v[82:97], v[170:173], v[138:141], v[82:97]
	v_add_f32_e32 v17, v16, v17
	v_exp_f32_e32 v101, v101
	v_fma_f32 v102, v104, s43, -v214
	v_exp_f32_e32 v232, v102
	v_fma_f32 v102, v105, s43, -v214
	v_cvt_pk_bf16_f32 v228, v2, v16
	v_add_f32_e32 v2, v98, v17
	v_mfma_f32_32x32x16_bf16 v[82:97], v[166:169], v[142:145], v[82:97]
	v_exp_f32_e32 v233, v102
	v_add_f32_e32 v2, v99, v2
	v_fma_f32 v16, v106, s43, -v214
	v_add_f32_e32 v2, v100, v2
	v_exp_f32_e32 v16, v16
	v_add_f32_e32 v2, v101, v2
	v_add_f32_e32 v2, v232, v2
	v_mfma_f32_32x32x16_bf16 v[82:97], v[8:11], v[146:149], v[82:97]
	v_fma_f32 v8, v107, s43, -v214
	v_exp_f32_e32 v17, v8
	v_fma_f32 v8, v108, s43, -v214
	v_exp_f32_e32 v106, v8
	v_fma_f32 v8, v109, s43, -v214
	v_exp_f32_e32 v107, v8
	v_fma_f32 v8, v110, s43, -v214
	v_mfma_f32_32x32x16_bf16 v[82:97], v[162:165], v[150:153], v[82:97]
	v_exp_f32_e32 v108, v8
	v_fma_f32 v8, v111, s43, -v214
	v_exp_f32_e32 v109, v8
	v_fma_f32 v8, v112, s43, -v214
	v_add_f32_e32 v2, v233, v2
	v_exp_f32_e32 v110, v8
	v_fma_f32 v8, v113, s43, -v214
	v_mfma_f32_32x32x16_bf16 v[82:97], v[12:15], v[154:157], v[82:97]
	v_cvt_pk_bf16_f32 v229, v98, v99
	v_cvt_pk_bf16_f32 v230, v100, v101
	v_cvt_pk_bf16_f32 v231, v232, v233
	v_add_f32_e32 v2, v16, v2
	ds_read_b128 v[174:177], v197 offset:0x7000
	ds_read_b128 v[170:173], v197 offset:0x7400
	ds_read_b128 v[166:169], v197 offset:0x7800
	v_mfma_f32_32x32x16_bf16 v[82:97], v[4:7], v[158:161], v[82:97]
	ds_read_b128 v[102:105], v197 offset:0x7c00
	s_waitcnt lgkmcnt(4)
	v_add_f32_e32 v2, v17, v2
	v_add_f32_e32 v2, v106, v2
	v_add_f32_e32 v2, v107, v2
	v_exp_f32_e32 v111, v8
	v_add_f32_e32 v2, v108, v2
	s_nop 6
	v_max3_f32 v4, v82, s40, v83
	v_max3_f32 v4, v4, v84, v85
	v_max3_f32 v4, v4, v86, v87
	v_max3_f32 v4, v4, v88, v89
	v_max3_f32 v4, v4, v90, v91
	v_max3_f32 v4, v4, v92, v93
	v_max3_f32 v4, v4, v94, v95
	v_max3_f32 v4, v4, v96, v97
	v_mul_f32_e32 v112, 0x3dd53b94, v4
	ds_bpermute_b32 v113, v206, v112
	v_mfma_f32_32x32x16_bf16 v[66:81], v[216:219], v[228:231], v[66:81]
	v_add_f32_e32 v2, v109, v2
	v_add_f32_e32 v2, v110, v2
	ds_read_b128 v[8:11], v197 offset:0x8000
	s_waitcnt lgkmcnt(0)
	v_max_f32_e32 v113, v113, v113
	v_max_f32_e32 v112, v112, v113
	ds_read_b128 v[98:101], v197 offset:0x8400
	ds_read_b128 v[12:15], v197 offset:0x8800
	v_mfma_f32_32x32x16_bf16 v[50:65], v[220:223], v[228:231], v[50:65]
	ds_read_b128 v[4:7], v197 offset:0x8c00
	v_sub_f32_e32 v113, v112, v214
	v_add_f32_e32 v2, v111, v2
	v_cmp_ge_f32_e32 vcc, s42, v113
	v_add_f32_e32 v2, v215, v2
	s_cmp_eq_u64 vcc, exec
	v_mfma_f32_32x32x16_bf16 v[34:49], v[178:181], v[228:231], v[34:49]
	v_mfma_f32_32x32x16_bf16 v[18:33], v[224:227], v[228:231], v[18:33]
	s_cbranch_scc1 .LBB0_1046
	v_max_f32_e32 v112, v112, v112
	v_max_f32_e32 v113, v214, v214
	v_max_f32_e32 v113, v113, v112
	v_sub_f32_e32 v112, v214, v113
	v_exp_f32_e32 v112, v112
	v_mov_b32_e32 v214, v113
	v_mul_f32_e32 v2, v2, v112
	v_mul_f32 v80, v80, v112
	v_mul_f32 v81, v81, v112
	v_mul_f32 v78, v78, v112
	v_mul_f32 v79, v79, v112
	v_mul_f32 v76, v76, v112
	v_mul_f32 v77, v77, v112
	v_mul_f32 v74, v74, v112
	v_mul_f32 v75, v75, v112
	v_mul_f32 v72, v72, v112
	v_mul_f32 v73, v73, v112
	v_mul_f32 v70, v70, v112
	v_mul_f32 v71, v71, v112
	v_mul_f32 v68, v68, v112
	v_mul_f32 v69, v69, v112
	v_mul_f32 v66, v66, v112
	v_mul_f32 v67, v67, v112
	v_mul_f32 v64, v64, v112
	v_mul_f32 v65, v65, v112
	v_mul_f32 v62, v62, v112
	v_mul_f32 v63, v63, v112
	v_mul_f32 v60, v60, v112
	v_mul_f32 v61, v61, v112
	v_mul_f32 v58, v58, v112
	v_mul_f32 v59, v59, v112
	v_mul_f32 v56, v56, v112
	v_mul_f32 v57, v57, v112
	v_mul_f32 v54, v54, v112
	v_mul_f32 v55, v55, v112
	v_mul_f32 v52, v52, v112
	v_mul_f32 v53, v53, v112
	v_mul_f32 v50, v50, v112
	v_mul_f32 v51, v51, v112
	v_mul_f32 v48, v48, v112
	v_mul_f32 v49, v49, v112
	v_mul_f32 v46, v46, v112
	v_mul_f32 v47, v47, v112
	v_mul_f32 v44, v44, v112
	v_mul_f32 v45, v45, v112
	v_mul_f32 v42, v42, v112
	v_mul_f32 v43, v43, v112
	v_mul_f32 v40, v40, v112
	v_mul_f32 v41, v41, v112
	v_mul_f32 v38, v38, v112
	v_mul_f32 v39, v39, v112
	v_mul_f32 v36, v36, v112
	v_mul_f32 v37, v37, v112
	v_mul_f32 v34, v34, v112
	v_mul_f32 v35, v35, v112
	v_mul_f32 v32, v32, v112
	v_mul_f32 v33, v33, v112
	v_mul_f32 v30, v30, v112
	v_mul_f32 v31, v31, v112
	v_mul_f32 v28, v28, v112
	v_mul_f32 v29, v29, v112
	v_mul_f32 v26, v26, v112
	v_mul_f32 v27, v27, v112
	v_mul_f32 v24, v24, v112
	v_mul_f32 v25, v25, v112
	v_mul_f32 v22, v22, v112
	v_mul_f32 v23, v23, v112
	v_mul_f32 v20, v20, v112
	v_mul_f32 v21, v21, v112
	v_mul_f32 v18, v18, v112
	v_mul_f32 v19, v19, v112
	v_xor_b32_e32 v112, 0x80000000, v113
	s_branch .LBB0_1047

.LBB0_1048:
	s_waitcnt vmcnt(5)
	s_waitcnt lgkmcnt(0)
	s_barrier
	ds_read_b128 v[4:7], v204 offset:0
	ds_read_b128 v[8:11], v204 offset:0x400
	ds_read_b128 v[12:15], v204 offset:0x800
	ds_read_b128 v[82:85], v204 offset:0xc00
	ds_read_b128 v[86:89], v204 offset:0x1000
	ds_read_b128 v[90:93], v204 offset:0x1400
	ds_read_b128 v[94:97], v204 offset:0x1800
	ds_read_b128 v[162:165], v204 offset:0x1c00
	s_nop 0
	s_waitcnt lgkmcnt(4)
	s_nop 0
	v_mfma_f32_32x32x16_bf16 v[98:113], v[4:7], v[114:117], 0
	ds_read_b128 v[4:7], v204 offset:0x2000
	v_mfma_f32_32x32x16_bf16 v[98:113], v[8:11], v[118:121], v[98:113]
	ds_read_b128 v[8:11], v204 offset:0x2400
	v_mfma_f32_32x32x16_bf16 v[98:113], v[12:15], v[122:125], v[98:113]
	ds_read_b128 v[12:15], v204 offset:0x2800
	v_mfma_f32_32x32x16_bf16 v[98:113], v[82:85], v[126:129], v[98:113]
	ds_read_b128 v[82:85], v204 offset:0x2c00
	s_waitcnt lgkmcnt(4)
	s_nop 0
	v_mfma_f32_32x32x16_bf16 v[98:113], v[86:89], v[130:133], v[98:113]
	ds_read_b128 v[86:89], v204 offset:0x3000
	v_mfma_f32_32x32x16_bf16 v[98:113], v[90:93], v[134:137], v[98:113]
	v_mfma_f32_32x32x16_bf16 v[98:113], v[94:97], v[138:141], v[98:113]
	v_mfma_f32_32x32x16_bf16 v[98:113], v[162:165], v[142:145], v[98:113]
	ds_read_b128 v[162:165], v204 offset:0x3400
	ds_read_b128 v[216:219], v204 offset:0x3800
	ds_read_b128 v[220:223], v204 offset:0x3c00
	s_waitcnt lgkmcnt(4)
	ds_read_b128 v[178:181], v204 offset:0x4000
	ds_read_b128 v[174:177], v204 offset:0x4400
	ds_read_b128 v[170:173], v204 offset:0x4800
	ds_read_b128 v[166:169], v204 offset:0x4c00
	s_nop 0
	s_waitcnt lgkmcnt(4)
	v_mfma_f32_32x32x16_bf16 v[98:113], v[4:7], v[146:149], v[98:113]
	v_mfma_f32_32x32x16_bf16 v[98:113], v[8:11], v[150:153], v[98:113]
	ds_read_b128 v[8:11], v204 offset:0x5000
	v_mfma_f32_32x32x16_bf16 v[98:113], v[12:15], v[154:157], v[98:113]
	v_mfma_f32_32x32x16_bf16 v[98:113], v[82:85], v[158:161], v[98:113]
	v_mfma_f32_32x32x16_bf16 v[82:97], v[86:89], v[114:117], 0
	s_nop 10
	v_max3_f32 v2, v98, s40, v99
	v_max3_f32 v2, v2, v100, v101
	v_max3_f32 v2, v2, v102, v103
	v_max3_f32 v2, v2, v104, v105
	v_max3_f32 v2, v2, v106, v107
	v_max3_f32 v2, v2, v108, v109
	v_max3_f32 v2, v2, v110, v111
	v_mfma_f32_32x32x16_bf16 v[82:97], v[162:165], v[118:121], v[82:97]
	v_max3_f32 v2, v2, v112, v113
	v_mul_f32_e32 v2, 0x3dd53b94, v2
	ds_bpermute_b32 v16, v206, v2
	ds_read_b128 v[162:165], v204 offset:0x5400
	ds_read_b128 v[12:15], v204 offset:0x5800
	ds_read_b128 v[4:7], v204 offset:0x5c00
	s_waitcnt lgkmcnt(0)
	v_max_f32_e32 v16, v16, v16
	v_mfma_f32_32x32x16_bf16 v[82:97], v[216:219], v[122:125], v[82:97]
	v_max_f32_e32 v2, v2, v16
	v_sub_f32_e32 v16, v2, v214
	v_cmp_ge_f32_e32 vcc, s42, v16
	s_cmp_eq_u64 vcc, exec
	v_mfma_f32_32x32x16_bf16 v[82:97], v[220:223], v[126:129], v[82:97]
	s_cbranch_scc1 .LBB0_1050
	v_max_f32_e32 v2, v2, v2
	v_max_f32_e32 v16, v214, v214
	v_max_f32_e32 v16, v16, v2
	v_sub_f32_e32 v2, v214, v16
	v_exp_f32_e32 v2, v2
	v_mov_b32_e32 v214, v16
	v_mul_f32_e32 v215, v215, v2
	v_mul_f32 v80, v80, v2
	v_mul_f32 v81, v81, v2
	v_mul_f32 v78, v78, v2
	v_mul_f32 v79, v79, v2
	v_mul_f32 v76, v76, v2
	v_mul_f32 v77, v77, v2
	v_mul_f32 v74, v74, v2
	v_mul_f32 v75, v75, v2
	v_mul_f32 v72, v72, v2
	v_mul_f32 v73, v73, v2
	v_mul_f32 v70, v70, v2
	v_mul_f32 v71, v71, v2
	v_mul_f32 v68, v68, v2
	v_mul_f32 v69, v69, v2
	v_mul_f32 v66, v66, v2
	v_mul_f32 v67, v67, v2
	v_mul_f32 v64, v64, v2
	v_mul_f32 v65, v65, v2
	v_mul_f32 v62, v62, v2
	v_mul_f32 v63, v63, v2
	v_mul_f32 v60, v60, v2
	v_mul_f32 v61, v61, v2
	v_mul_f32 v58, v58, v2
	v_mul_f32 v59, v59, v2
	v_mul_f32 v56, v56, v2
	v_mul_f32 v57, v57, v2
	v_mul_f32 v54, v54, v2
	v_mul_f32 v55, v55, v2
	v_mul_f32 v52, v52, v2
	v_mul_f32 v53, v53, v2
	v_mul_f32 v50, v50, v2
	v_mul_f32 v51, v51, v2
	v_mul_f32 v48, v48, v2
	v_mul_f32 v49, v49, v2
	v_mul_f32 v46, v46, v2
	v_mul_f32 v47, v47, v2
	v_mul_f32 v44, v44, v2
	v_mul_f32 v45, v45, v2
	v_mul_f32 v42, v42, v2
	v_mul_f32 v43, v43, v2
	v_mul_f32 v40, v40, v2
	v_mul_f32 v41, v41, v2
	v_mul_f32 v38, v38, v2
	v_mul_f32 v39, v39, v2
	v_mul_f32 v36, v36, v2
	v_mul_f32 v37, v37, v2
	v_mul_f32 v34, v34, v2
	v_mul_f32 v35, v35, v2
	v_mul_f32 v32, v32, v2
	v_mul_f32 v33, v33, v2
	v_mul_f32 v30, v30, v2
	v_mul_f32 v31, v31, v2
	v_mul_f32 v28, v28, v2
	v_mul_f32 v29, v29, v2
	v_mul_f32 v26, v26, v2
	v_mul_f32 v27, v27, v2
	v_mul_f32 v24, v24, v2
	v_mul_f32 v25, v25, v2
	v_mul_f32 v22, v22, v2
	v_mul_f32 v23, v23, v2
	v_mul_f32 v20, v20, v2
	v_mul_f32 v21, v21, v2
	v_mul_f32 v18, v18, v2
	v_mul_f32 v19, v19, v2

.LBB0_2173:
	v_and_b32_e32 v4, 64, v220
	v_xor_b32_e32 v2, 32, v220
	v_add_u32_e32 v4, 64, v4
	v_cmp_lt_i32_e32 vcc, v2, v4
	s_mov_b32 s0, 0x3fb8aa3b
	s_waitcnt vmcnt(0)
	v_fma_f32 v4, v223, s0, -v225
	v_cndmask_b32_e32 v2, v220, v2, vcc
	v_lshlrev_b32_e32 v2, 2, v2
	ds_bpermute_b32 v2, v2, v226
	v_exp_f32_e32 v4, v4
	s_add_i32 s50, s50, s90
	s_add_i32 s49, s49, s90
	s_cmpk_gt_i32 s50, 0x1ff
	s_waitcnt lgkmcnt(0)
	v_add_f32_e32 v2, v226, v2
	v_add_f32_e32 v2, v4, v2
	v_div_scale_f32 v4, s[0:1], v2, v2, 1.0
	v_rcp_f32_e32 v5, v4
	v_div_scale_f32 v6, vcc, 1.0, v2, 1.0
	v_fma_f32 v7, -v4, v5, 1.0
	v_fmac_f32_e32 v5, v7, v5
	v_mul_f32_e32 v7, v6, v5
	v_fma_f32 v8, -v4, v7, v6
	v_fmac_f32_e32 v7, v8, v5
	v_fma_f32 v4, -v4, v7, v6
	v_div_fmas_f32 v4, v4, v5, v7
	v_div_fixup_f32 v8, v4, v2, 1.0
	v_mov_b32_e32 v2, v211
	v_mul_f32 v4, v66, v8
	v_mul_f32 v5, v67, v8
	v_mul_f32 v6, v68, v8
	v_mul_f32 v7, v69, v8
	v_add_u32_e32 v2, s51, v2
	v_cvt_pk_bf16_f32 v4, v4, v5
	v_cvt_pk_bf16_f32 v5, v6, v7
	v_mul_f32 v6, v70, v8
	v_mul_f32 v7, v71, v8
	v_mul_f32 v12, v72, v8
	v_mul_f32 v13, v73, v8
	v_lshl_add_u32 v2, v2, 11, s52
	v_cvt_pk_bf16_f32 v6, v6, v7
	v_cvt_pk_bf16_f32 v7, v12, v13
	v_lshl_add_u64 v[10:11], v[2:3], 1, v[206:207]
	v_permlane32_swap_b32_e32 v4, v6
	v_permlane32_swap_b32_e32 v5, v7
	global_store_dwordx4 v[10:11], v[4:7], off
	v_mul_f32 v12, v80, v8
	v_mul_f32 v13, v81, v8
	s_nop 0
	v_mul_f32 v4, v74, v8
	v_mul_f32 v5, v75, v8
	v_mul_f32 v6, v76, v8
	v_mul_f32 v7, v77, v8
	v_cvt_pk_bf16_f32 v4, v4, v5
	v_cvt_pk_bf16_f32 v5, v6, v7
	v_mul_f32 v6, v78, v8
	v_mul_f32 v7, v79, v8
	s_nop 0
	v_cvt_pk_bf16_f32 v6, v6, v7
	v_cvt_pk_bf16_f32 v7, v12, v13
	s_nop 0
	v_permlane32_swap_b32_e32 v4, v6
	v_permlane32_swap_b32_e32 v5, v7
	global_store_dwordx4 v[10:11], v[4:7], off offset:32
	v_mul_f32 v12, v56, v8
	v_mul_f32 v13, v57, v8
	s_nop 0
	v_mul_f32 v4, v50, v8
	v_mul_f32 v5, v51, v8
	v_mul_f32 v6, v52, v8
	v_mul_f32 v7, v53, v8
	v_cvt_pk_bf16_f32 v4, v4, v5
	v_cvt_pk_bf16_f32 v5, v6, v7
	v_mul_f32 v6, v54, v8
	v_mul_f32 v7, v55, v8
	s_nop 0
	v_cvt_pk_bf16_f32 v6, v6, v7
	v_cvt_pk_bf16_f32 v7, v12, v13
	s_nop 0
	v_permlane32_swap_b32_e32 v4, v6
	v_permlane32_swap_b32_e32 v5, v7
	global_store_dwordx4 v[10:11], v[4:7], off offset:64
	v_mul_f32 v12, v64, v8
	v_mul_f32 v13, v65, v8
	s_nop 0
	v_mul_f32 v4, v58, v8
	v_mul_f32 v5, v59, v8
	v_mul_f32 v6, v60, v8
	v_mul_f32 v7, v61, v8
	v_cvt_pk_bf16_f32 v4, v4, v5
	v_cvt_pk_bf16_f32 v5, v6, v7
	v_mul_f32 v6, v62, v8
	v_mul_f32 v7, v63, v8
	s_nop 0
	v_cvt_pk_bf16_f32 v6, v6, v7
	v_cvt_pk_bf16_f32 v7, v12, v13
	s_nop 0
	v_permlane32_swap_b32_e32 v4, v6
	v_permlane32_swap_b32_e32 v5, v7
	global_store_dwordx4 v[10:11], v[4:7], off offset:96
	v_mul_f32 v12, v40, v8
	v_mul_f32 v13, v41, v8
	s_nop 0
	v_mul_f32 v4, v34, v8
	v_mul_f32 v5, v35, v8
	v_mul_f32 v6, v36, v8
	v_mul_f32 v7, v37, v8
	v_cvt_pk_bf16_f32 v4, v4, v5
	v_cvt_pk_bf16_f32 v5, v6, v7
	v_mul_f32 v6, v38, v8
	v_mul_f32 v7, v39, v8
	s_nop 0
	v_cvt_pk_bf16_f32 v6, v6, v7
	v_cvt_pk_bf16_f32 v7, v12, v13
	s_nop 0
	v_permlane32_swap_b32_e32 v4, v6
	v_permlane32_swap_b32_e32 v5, v7
	global_store_dwordx4 v[10:11], v[4:7], off offset:128
	v_mul_f32 v12, v48, v8
	v_mul_f32 v13, v49, v8
	s_nop 0
	v_mul_f32 v4, v42, v8
	v_mul_f32 v5, v43, v8
	v_mul_f32 v6, v44, v8
	v_mul_f32 v7, v45, v8
	v_cvt_pk_bf16_f32 v4, v4, v5
	v_cvt_pk_bf16_f32 v5, v6, v7
	v_mul_f32 v6, v46, v8
	v_mul_f32 v7, v47, v8
	s_nop 0
	v_cvt_pk_bf16_f32 v6, v6, v7
	v_cvt_pk_bf16_f32 v7, v12, v13
	s_nop 0
	v_permlane32_swap_b32_e32 v4, v6
	v_permlane32_swap_b32_e32 v5, v7
	global_store_dwordx4 v[10:11], v[4:7], off offset:160
	v_mul_f32 v12, v24, v8
	v_mul_f32 v13, v25, v8
	s_nop 0
	v_mul_f32 v4, v18, v8
	v_mul_f32 v5, v19, v8
	v_mul_f32 v6, v20, v8
	v_mul_f32 v7, v21, v8
	v_cvt_pk_bf16_f32 v4, v4, v5
	v_cvt_pk_bf16_f32 v5, v6, v7
	v_mul_f32 v6, v22, v8
	v_mul_f32 v7, v23, v8
	s_nop 0
	v_cvt_pk_bf16_f32 v6, v6, v7
	v_cvt_pk_bf16_f32 v7, v12, v13
	s_nop 0
	v_permlane32_swap_b32_e32 v4, v6
	v_permlane32_swap_b32_e32 v5, v7
	global_store_dwordx4 v[10:11], v[4:7], off offset:192
	s_nop 1
	v_mul_f32 v4, v26, v8
	v_mul_f32 v5, v27, v8
	v_mul_f32 v6, v28, v8
	v_mul_f32 v7, v29, v8
	v_cvt_pk_bf16_f32 v4, v4, v5
	v_cvt_pk_bf16_f32 v5, v6, v7
	v_mul_f32 v6, v30, v8
	v_mul_f32 v7, v31, v8
	v_mul_f32 v9, v33, v8
	v_mul_f32 v8, v32, v8
	v_cvt_pk_bf16_f32 v6, v6, v7
	v_cvt_pk_bf16_f32 v7, v8, v9
	s_nop 0
	v_permlane32_swap_b32_e32 v4, v6
	v_permlane32_swap_b32_e32 v5, v7
	global_store_dwordx4 v[10:11], v[4:7], off offset:224
	s_cbranch_scc1 .LBB0_2265

.LBB0_2196:
	ds_read_b128 v[4:7], v215 offset:0
	ds_read_b128 v[8:11], v215 offset:0x400
	ds_read_b128 v[12:15], v215 offset:0x800
	ds_read_b128 v[82:85], v215 offset:0xc00
	ds_read_b128 v[86:89], v215 offset:0x1000
	ds_read_b128 v[90:93], v215 offset:0x1400
	ds_read_b128 v[94:97], v215 offset:0x1800
	ds_read_b128 v[146:149], v215 offset:0x1c00
	ds_read_b128 v[166:169], v215 offset:0x2000
	ds_read_b128 v[170:173], v215 offset:0x2400
	ds_read_b128 v[174:177], v215 offset:0x2800
	ds_read_b128 v[228:231], v215 offset:0x2c00
	ds_read_b128 v[158:161], v215 offset:0x3000
	ds_read_b128 v[154:157], v215 offset:0x3400
	ds_read_b128 v[150:153], v215 offset:0x3800
	ds_read_b128 v[162:165], v215 offset:0x3c00
	s_nop 0
	s_waitcnt lgkmcnt(8)
	ds_read_b128 v[190:193], v215 offset:0x4000
	ds_read_b128 v[186:189], v215 offset:0x4400
	ds_read_b128 v[182:185], v215 offset:0x4800
	ds_read_b128 v[178:181], v215 offset:0x4c00
	v_cndmask_b32_e64 v2, 0, 1, s[26:27]
	v_mfma_f32_32x32x16_bf16 v[98:113], v[4:7], v[114:117], 0
	v_cmp_ne_u32_e64 s[4:5], 1, v2
	s_andn2_b64 vcc, exec, s[26:27]
	v_mfma_f32_32x32x16_bf16 v[98:113], v[8:11], v[118:121], v[98:113]
	v_mfma_f32_32x32x16_bf16 v[98:113], v[12:15], v[122:125], v[98:113]
	v_mfma_f32_32x32x16_bf16 v[98:113], v[82:85], v[126:129], v[98:113]
	v_mfma_f32_32x32x16_bf16 v[98:113], v[86:89], v[130:133], v[98:113]
	v_mfma_f32_32x32x16_bf16 v[98:113], v[90:93], v[134:137], v[98:113]
	v_mfma_f32_32x32x16_bf16 v[98:113], v[94:97], v[138:141], v[98:113]
	v_mfma_f32_32x32x16_bf16 v[98:113], v[146:149], v[142:145], v[98:113]
	ds_read_b128 v[146:149], v215 offset:0x5000
	ds_read_b128 v[12:15], v215 offset:0x5400
	ds_read_b128 v[8:11], v215 offset:0x5800
	ds_read_b128 v[4:7], v215 offset:0x5c00
	s_waitcnt lgkmcnt(8)
	s_nop 0
	v_mfma_f32_32x32x16_bf16 v[82:97], v[166:169], v[114:117], 0
	v_mfma_f32_32x32x16_bf16 v[82:97], v[170:173], v[118:121], v[82:97]
	v_mfma_f32_32x32x16_bf16 v[82:97], v[174:177], v[122:125], v[82:97]
	v_mfma_f32_32x32x16_bf16 v[82:97], v[228:231], v[126:129], v[82:97]
	s_cbranch_vccnz .LBB0_2198
	s_add_i32 s76, s59, s73
	s_add_i32 s77, s76, 0x200
	s_addk_i32 s76, 0x1ff
	s_nop 2
	v_mul_f32 v16, s20, v98
	v_mul_f32 v17, s20, v99
	v_add_u32_e32 v98, s77, v208
	v_add_u32_e32 v2, s76, v201
	v_cmp_lt_u32_e32 vcc, s45, v98
	s_add_i32 s78, s77, s53
	s_add_i32 s76, s76, s70
	v_cndmask_b32_e32 v98, v221, v16, vcc
	v_cmp_lt_u32_e32 vcc, s45, v2
	v_add_u32_e32 v2, s77, v203
	s_add_i32 s79, s77, s72
	v_cndmask_b32_e32 v99, v221, v17, vcc
	v_mul_f32 v16, s20, v100
	v_mul_f32 v17, s20, v101
	v_add_u32_e32 v100, s77, v210
	v_cmp_lt_u32_e32 vcc, s45, v100
	s_add_i32 s77, s77, s71
	s_nop 0
	v_cndmask_b32_e32 v100, v221, v16, vcc
	v_cmp_lt_u32_e32 vcc, s45, v2
	v_add_u32_e32 v2, s76, v1
	s_nop 0
	v_cndmask_b32_e32 v101, v221, v17, vcc
	v_mul_f32 v16, s20, v102
	v_mul_f32 v17, s20, v103
	v_add_u32_e32 v102, s78, v200
	v_cmp_lt_u32_e32 vcc, s45, v102
	s_nop 1
	v_cndmask_b32_e32 v102, v221, v16, vcc
	v_cmp_lt_u32_e32 vcc, s45, v2
	v_add_u32_e32 v2, s77, v1
	s_nop 0
	v_cndmask_b32_e32 v103, v221, v17, vcc
	v_mul_f32 v16, s20, v104
	v_mul_f32 v17, s20, v105
	v_add_u32_e32 v104, s79, v200
	v_cmp_lt_u32_e32 vcc, s45, v104
	s_nop 1
	v_cndmask_b32_e32 v104, v221, v16, vcc
	v_cmp_lt_u32_e32 vcc, s45, v2
	v_add_u32_e32 v2, s76, v195
	s_nop 0
	v_cndmask_b32_e32 v105, v221, v17, vcc
	v_mul_f32 v16, s20, v106
	v_mul_f32 v17, s20, v107
	v_add_u32_e32 v106, s78, v202
	v_cmp_lt_u32_e32 vcc, s45, v106
	s_nop 1
	v_cndmask_b32_e32 v106, v221, v16, vcc
	v_cmp_lt_u32_e32 vcc, s45, v2
	v_add_u32_e32 v2, s77, v195
	s_nop 0
	v_cndmask_b32_e32 v107, v221, v17, vcc
	v_mul_f32 v16, s20, v108
	v_mul_f32 v17, s20, v109
	v_add_u32_e32 v108, s79, v202
	v_cmp_lt_u32_e32 vcc, s45, v108
	s_nop 1
	v_cndmask_b32_e32 v108, v221, v16, vcc
	v_cmp_lt_u32_e32 vcc, s45, v2
	v_add_u32_e32 v2, s76, v197
	s_nop 0
	v_cndmask_b32_e32 v109, v221, v17, vcc
	v_mul_f32 v16, s20, v110
	v_mul_f32 v17, s20, v111
	v_add_u32_e32 v110, s78, v204
	v_cmp_lt_u32_e32 vcc, s45, v110
	s_nop 1
	v_cndmask_b32_e32 v110, v221, v16, vcc
	v_cmp_lt_u32_e32 vcc, s45, v2
	v_add_u32_e32 v2, s77, v197
	s_nop 0
	v_cndmask_b32_e32 v111, v221, v17, vcc
	v_mul_f32 v16, s20, v112
	v_mul_f32 v17, s20, v113
	v_add_u32_e32 v112, s79, v204
	v_cmp_lt_u32_e32 vcc, s45, v112
	v_readlane_b32 s78, v249, 56
	v_readlane_b32 s79, v249, 57
	v_cndmask_b32_e32 v112, v221, v16, vcc
	v_cmp_lt_u32_e32 vcc, s45, v2
	s_nop 1
	v_cndmask_b32_e32 v113, v221, v17, vcc
.LBB0_2198:
	s_nop 5
	v_max3_f32 v2, v98, s46, v99
	v_max3_f32 v2, v2, v100, v101
	v_max3_f32 v2, v2, v102, v103
	v_max3_f32 v2, v2, v104, v105
	v_max3_f32 v2, v2, v106, v107
	v_max3_f32 v2, v2, v108, v109
	v_max3_f32 v2, v2, v110, v111
	v_max3_f32 v2, v2, v112, v113
	v_mul_f32_e32 v16, 0x3e0293ee, v2
	v_and_b32_e32 v17, 64, v220
	v_cndmask_b32_e64 v2, v2, v16, s[0:1]
	v_xor_b32_e32 v16, 32, v220
	v_add_u32_e32 v17, 64, v17
	v_cmp_lt_i32_e32 vcc, v16, v17
	s_nop 1
	v_cndmask_b32_e32 v16, v220, v16, vcc
	v_lshlrev_b32_e32 v16, 2, v16
	ds_bpermute_b32 v17, v16, v2
	s_waitcnt lgkmcnt(0)
	v_max_f32_e32 v17, v17, v17
	v_max_f32_e32 v2, v2, v17
	v_sub_f32_e32 v17, v2, v225
	v_cmp_ge_f32_e32 vcc, s47, v17
	s_cmp_eq_u64 vcc, exec
	s_cbranch_scc1 .LBB0_2200
	v_max_f32_e32 v2, v2, v2
	v_max_f32_e32 v17, v225, v225
	v_max_f32_e32 v17, v17, v2
	v_sub_f32_e32 v2, v225, v17
	v_exp_f32_e32 v2, v2
	v_mov_b32_e32 v225, v17
	v_mul_f32_e32 v226, v226, v2
	v_mul_f32 v80, v80, v2
	v_mul_f32 v81, v81, v2
	v_mul_f32 v78, v78, v2
	v_mul_f32 v79, v79, v2
	v_mul_f32 v76, v76, v2
	v_mul_f32 v77, v77, v2
	v_mul_f32 v74, v74, v2
	v_mul_f32 v75, v75, v2
	v_mul_f32 v72, v72, v2
	v_mul_f32 v73, v73, v2
	v_mul_f32 v70, v70, v2
	v_mul_f32 v71, v71, v2
	v_mul_f32 v68, v68, v2
	v_mul_f32 v69, v69, v2
	v_mul_f32 v66, v66, v2
	v_mul_f32 v67, v67, v2
	v_mul_f32 v64, v64, v2
	v_mul_f32 v65, v65, v2
	v_mul_f32 v62, v62, v2
	v_mul_f32 v63, v63, v2
	v_mul_f32 v60, v60, v2
	v_mul_f32 v61, v61, v2
	v_mul_f32 v58, v58, v2
	v_mul_f32 v59, v59, v2
	v_mul_f32 v56, v56, v2
	v_mul_f32 v57, v57, v2
	v_mul_f32 v54, v54, v2
	v_mul_f32 v55, v55, v2
	v_mul_f32 v52, v52, v2
	v_mul_f32 v53, v53, v2
	v_mul_f32 v50, v50, v2
	v_mul_f32 v51, v51, v2
	v_mul_f32 v48, v48, v2
	v_mul_f32 v49, v49, v2
	v_mul_f32 v46, v46, v2
	v_mul_f32 v47, v47, v2
	v_mul_f32 v44, v44, v2
	v_mul_f32 v45, v45, v2
	v_mul_f32 v42, v42, v2
	v_mul_f32 v43, v43, v2
	v_mul_f32 v40, v40, v2
	v_mul_f32 v41, v41, v2
	v_mul_f32 v38, v38, v2
	v_mul_f32 v39, v39, v2
	v_mul_f32 v36, v36, v2
	v_mul_f32 v37, v37, v2
	v_mul_f32 v34, v34, v2
	v_mul_f32 v35, v35, v2
	v_mul_f32 v32, v32, v2
	v_mul_f32 v33, v33, v2
	v_mul_f32 v30, v30, v2
	v_mul_f32 v31, v31, v2
	v_mul_f32 v28, v28, v2
	v_mul_f32 v29, v29, v2
	v_mul_f32 v26, v26, v2
	v_mul_f32 v27, v27, v2
	v_mul_f32 v24, v24, v2
	v_mul_f32 v25, v25, v2
	v_mul_f32 v22, v22, v2
	v_mul_f32 v23, v23, v2
	v_mul_f32 v20, v20, v2
	v_mul_f32 v21, v21, v2
	v_mul_f32 v18, v18, v2
	v_mul_f32 v19, v19, v2
.LBB0_2200:
	v_mfma_f32_32x32x16_bf16 v[82:97], v[158:161], v[130:133], v[82:97]
	v_cndmask_b32_e64 v2, 1.0, v222, s[0:1]
	v_fma_f32 v17, v98, v2, -v225
	v_fma_f32 v98, v99, v2, -v225
	v_exp_f32_e32 v227, v98
	v_fma_f32 v98, v100, v2, -v225
	v_exp_f32_e32 v228, v98
	v_fma_f32 v98, v101, v2, -v225
	v_mfma_f32_32x32x16_bf16 v[82:97], v[154:157], v[134:137], v[82:97]
	v_exp_f32_e32 v229, v98
	v_fma_f32 v98, v102, v2, -v225
	v_exp_f32_e32 v230, v98
	v_fma_f32 v98, v103, v2, -v225
	v_exp_f32_e32 v231, v98
	v_fma_f32 v98, v104, v2, -v225
	v_exp_f32_e32 v232, v98
	v_mfma_f32_32x32x16_bf16 v[82:97], v[150:153], v[138:141], v[82:97]
	v_fma_f32 v98, v105, v2, -v225
	v_exp_f32_e32 v17, v17
	v_exp_f32_e32 v233, v98
	v_cvt_pk_bf16_f32 v235, v228, v229
	v_cvt_pk_bf16_f32 v236, v230, v231
	v_cvt_pk_bf16_f32 v234, v17, v227
	v_cvt_pk_bf16_f32 v237, v232, v233
	ds_read_b128 v[174:177], v215 offset:0x6000
	ds_read_b128 v[170:173], v215 offset:0x6400
	ds_read_b128 v[166:169], v215 offset:0x6800
	ds_read_b128 v[158:161], v215 offset:0x6c00
	ds_read_b128 v[154:157], v215 offset:0x7000
	ds_read_b128 v[150:153], v215 offset:0x7400
	ds_read_b128 v[102:105], v215 offset:0x7800
	ds_read_b128 v[98:101], v215 offset:0x7c00
	s_waitcnt lgkmcnt(8)
	v_mfma_f32_32x32x16_bf16 v[82:97], v[162:165], v[142:145], v[82:97]
	s_and_b64 vcc, exec, s[4:5]
	v_mfma_f32_32x32x16_bf16 v[66:81], v[190:193], v[234:237], v[66:81]
	v_mfma_f32_32x32x16_bf16 v[50:65], v[186:189], v[234:237], v[50:65]
	v_mfma_f32_32x32x16_bf16 v[34:49], v[182:185], v[234:237], v[34:49]
	v_mfma_f32_32x32x16_bf16 v[18:33], v[178:181], v[234:237], v[18:33]
	s_cbranch_vccnz .LBB0_2202
	v_add_u32_e32 v162, s73, v224
	v_add_u32_e32 v164, 0x15e, v162
	v_add_u32_e32 v163, 0x15f, v162
	s_nop 2
	v_mul_f32 v82, s20, v82
	v_mul_f32 v83, s20, v83
	v_cmp_lt_u32_e32 vcc, s45, v164
	v_add_u32_e32 v165, 0x15d, v162
	v_add_u32_e32 v178, 0x15c, v162
	v_add_u32_e32 v179, 0x157, v162
	v_add_u32_e32 v180, 0x156, v162
	v_add_u32_e32 v181, 0x155, v162
	v_add_u32_e32 v182, 0x154, v162
	v_add_u32_e32 v183, 0x14f, v162
	v_add_u32_e32 v184, 0x14e, v162
	v_add_u32_e32 v185, 0x14d, v162
	v_add_u32_e32 v186, 0x14c, v162
	v_add_u32_e32 v187, 0x147, v162
	v_add_u32_e32 v188, 0x146, v162
	v_add_u32_e32 v189, 0x145, v162
	v_add_u32_e32 v162, 0x144, v162
	v_cndmask_b32_e32 v83, v221, v83, vcc
	v_cmp_lt_u32_e32 vcc, s45, v163
	v_mul_f32 v96, s20, v96
	v_mul_f32 v97, s20, v97
	v_mul_f32 v94, s20, v94
	v_mul_f32 v95, s20, v95
	v_cndmask_b32_e32 v82, v221, v82, vcc
	v_cmp_lt_u32_e32 vcc, s45, v162
	v_mul_f32 v92, s20, v92
	v_mul_f32 v93, s20, v93
	v_mul_f32 v90, s20, v90
	v_mul_f32 v91, s20, v91
	v_cndmask_b32_e32 v97, v221, v97, vcc
	v_cmp_lt_u32_e32 vcc, s45, v189
	v_mul_f32 v88, s20, v88
	v_mul_f32 v89, s20, v89
	v_mul_f32 v86, s20, v86
	v_mul_f32 v87, s20, v87
	v_cndmask_b32_e32 v96, v221, v96, vcc
	v_cmp_lt_u32_e32 vcc, s45, v188
	v_mul_f32 v84, s20, v84
	v_mul_f32 v85, s20, v85
	s_nop 0
	v_cndmask_b32_e32 v95, v221, v95, vcc
	v_cmp_lt_u32_e32 vcc, s45, v187
	s_nop 1
	v_cndmask_b32_e32 v94, v221, v94, vcc
	v_cmp_lt_u32_e32 vcc, s45, v186
	s_nop 1
	v_cndmask_b32_e32 v93, v221, v93, vcc
	v_cmp_lt_u32_e32 vcc, s45, v185
	s_nop 1
	v_cndmask_b32_e32 v92, v221, v92, vcc
	v_cmp_lt_u32_e32 vcc, s45, v184
	s_nop 1
	v_cndmask_b32_e32 v91, v221, v91, vcc
	v_cmp_lt_u32_e32 vcc, s45, v183
	s_nop 1
	v_cndmask_b32_e32 v90, v221, v90, vcc
	v_cmp_lt_u32_e32 vcc, s45, v182
	s_nop 1
	v_cndmask_b32_e32 v89, v221, v89, vcc
	v_cmp_lt_u32_e32 vcc, s45, v181
	s_nop 1
	v_cndmask_b32_e32 v88, v221, v88, vcc
	v_cmp_lt_u32_e32 vcc, s45, v180
	s_nop 1
	v_cndmask_b32_e32 v87, v221, v87, vcc
	v_cmp_lt_u32_e32 vcc, s45, v179
	s_nop 1
	v_cndmask_b32_e32 v86, v221, v86, vcc
	v_cmp_lt_u32_e32 vcc, s45, v178
	s_nop 1
	v_cndmask_b32_e32 v85, v221, v85, vcc
	v_cmp_lt_u32_e32 vcc, s45, v165
	s_nop 1
	v_cndmask_b32_e32 v84, v221, v84, vcc
.LBB0_2202:
	v_add_f32_e32 v17, 0, v17
	v_add_f32_e32 v17, v227, v17
	v_add_f32_e32 v17, v228, v17
	v_add_f32_e32 v17, v229, v17
	v_add_f32_e32 v17, v230, v17
	v_add_f32_e32 v17, v231, v17
	v_xor_b32_e32 v162, 0x80000000, v225
	v_add_f32_e32 v17, v232, v17
	v_add_f32_e32 v163, v233, v17
	v_fma_f32 v17, v106, v2, v162
	v_exp_f32_e32 v17, v17
	v_fma_f32 v106, v107, v2, v162
	v_exp_f32_e32 v106, v106
	v_fma_f32 v107, v108, v2, v162
	v_exp_f32_e32 v107, v107
	v_fma_f32 v108, v109, v2, v162
	v_exp_f32_e32 v108, v108
	v_add_f32_e32 v109, v17, v163
	v_add_f32_e32 v109, v106, v109
	v_add_f32_e32 v109, v107, v109
	v_add_f32_e32 v163, v108, v109
	v_fma_f32 v109, v110, v2, v162
	v_fma_f32 v110, v111, v2, v162
	v_fma_f32 v111, v112, v2, v162
	v_fma_f32 v112, v113, v2, v162
	v_max3_f32 v113, v82, s46, v83
	v_max3_f32 v113, v113, v84, v85
	v_max3_f32 v113, v113, v86, v87
	v_max3_f32 v113, v113, v88, v89
	v_max3_f32 v113, v113, v90, v91
	v_max3_f32 v113, v113, v92, v93
	v_max3_f32 v113, v113, v94, v95
	v_max3_f32 v113, v113, v96, v97
	v_mul_f32_e32 v164, 0x3e0293ee, v113
	v_cndmask_b32_e64 v113, v113, v164, s[0:1]
	ds_bpermute_b32 v16, v16, v113
	v_exp_f32_e32 v109, v109
	v_exp_f32_e32 v110, v110
	v_exp_f32_e32 v111, v111
	v_exp_f32_e32 v112, v112
	v_add_f32_e32 v163, v109, v163
	s_waitcnt lgkmcnt(0)
	v_max_f32_e32 v16, v16, v16
	v_add_f32_e32 v163, v110, v163
	v_max_f32_e32 v113, v113, v16
	v_add_f32_e32 v163, v111, v163
	v_sub_f32_e32 v16, v113, v225
	v_add_f32_e32 v163, v112, v163
	v_cmp_ge_f32_e32 vcc, s47, v16
	s_cmp_eq_u64 vcc, exec
	v_add_f32_e32 v16, v226, v163
	s_cbranch_scc1 .LBB0_2204
	v_max_f32_e32 v113, v113, v113
	v_max_f32_e32 v162, v225, v225
	v_max_f32_e32 v113, v162, v113
	v_sub_f32_e32 v162, v225, v113
	v_exp_f32_e32 v162, v162
	v_mov_b32_e32 v225, v113
	v_mul_f32_e32 v16, v16, v162
	v_mul_f32 v80, v80, v162
	v_mul_f32 v81, v81, v162
	v_mul_f32 v78, v78, v162
	v_mul_f32 v79, v79, v162
	v_mul_f32 v76, v76, v162
	v_mul_f32 v77, v77, v162
	v_mul_f32 v74, v74, v162
	v_mul_f32 v75, v75, v162
	v_mul_f32 v72, v72, v162
	v_mul_f32 v73, v73, v162
	v_mul_f32 v70, v70, v162
	v_mul_f32 v71, v71, v162
	v_mul_f32 v68, v68, v162
	v_mul_f32 v69, v69, v162
	v_mul_f32 v66, v66, v162
	v_mul_f32 v67, v67, v162
	v_mul_f32 v64, v64, v162
	v_mul_f32 v65, v65, v162
	v_mul_f32 v62, v62, v162
	v_mul_f32 v63, v63, v162
	v_mul_f32 v60, v60, v162
	v_mul_f32 v61, v61, v162
	v_mul_f32 v58, v58, v162
	v_mul_f32 v59, v59, v162
	v_mul_f32 v56, v56, v162
	v_mul_f32 v57, v57, v162
	v_mul_f32 v54, v54, v162
	v_mul_f32 v55, v55, v162
	v_mul_f32 v52, v52, v162
	v_mul_f32 v53, v53, v162
	v_mul_f32 v50, v50, v162
	v_mul_f32 v51, v51, v162
	v_mul_f32 v48, v48, v162
	v_mul_f32 v49, v49, v162
	v_mul_f32 v46, v46, v162
	v_mul_f32 v47, v47, v162
	v_mul_f32 v44, v44, v162
	v_mul_f32 v45, v45, v162
	v_mul_f32 v42, v42, v162
	v_mul_f32 v43, v43, v162
	v_mul_f32 v40, v40, v162
	v_mul_f32 v41, v41, v162
	v_mul_f32 v38, v38, v162
	v_mul_f32 v39, v39, v162
	v_mul_f32 v36, v36, v162
	v_mul_f32 v37, v37, v162
	v_mul_f32 v34, v34, v162
	v_mul_f32 v35, v35, v162
	v_mul_f32 v32, v32, v162
	v_mul_f32 v33, v33, v162
	v_mul_f32 v30, v30, v162
	v_mul_f32 v31, v31, v162
	v_mul_f32 v28, v28, v162
	v_mul_f32 v29, v29, v162
	v_mul_f32 v26, v26, v162
	v_mul_f32 v27, v27, v162
	v_mul_f32 v24, v24, v162
	v_mul_f32 v25, v25, v162
	v_mul_f32 v22, v22, v162
	v_mul_f32 v23, v23, v162
	v_mul_f32 v20, v20, v162
	v_mul_f32 v21, v21, v162
	v_mul_f32 v18, v18, v162
	v_mul_f32 v19, v19, v162
	v_xor_b32_e32 v162, 0x80000000, v113

.LBB0_2215:
	ds_read_b128 v[4:7], v216 offset:0
	ds_read_b128 v[8:11], v216 offset:0x400
	ds_read_b128 v[12:15], v216 offset:0x800
	ds_read_b128 v[82:85], v216 offset:0xc00
	ds_read_b128 v[86:89], v216 offset:0x1000
	ds_read_b128 v[90:93], v216 offset:0x1400
	ds_read_b128 v[94:97], v216 offset:0x1800
	ds_read_b128 v[146:149], v216 offset:0x1c00
	ds_read_b128 v[162:165], v216 offset:0x2000
	ds_read_b128 v[170:173], v216 offset:0x2400
	ds_read_b128 v[174:177], v216 offset:0x2800
	ds_read_b128 v[228:231], v216 offset:0x2c00
	ds_read_b128 v[158:161], v216 offset:0x3000
	ds_read_b128 v[154:157], v216 offset:0x3400
	ds_read_b128 v[150:153], v216 offset:0x3800
	ds_read_b128 v[166:169], v216 offset:0x3c00
	s_nop 0
	s_waitcnt lgkmcnt(8)
	ds_read_b128 v[190:193], v216 offset:0x4000
	ds_read_b128 v[186:189], v216 offset:0x4400
	ds_read_b128 v[182:185], v216 offset:0x4800
	ds_read_b128 v[178:181], v216 offset:0x4c00
	v_cndmask_b32_e64 v2, 0, 1, s[26:27]
	v_mfma_f32_32x32x16_bf16 v[98:113], v[4:7], v[114:117], 0
	v_cmp_ne_u32_e64 s[4:5], 1, v2
	s_andn2_b64 vcc, exec, s[26:27]
	v_mfma_f32_32x32x16_bf16 v[98:113], v[8:11], v[118:121], v[98:113]
	v_mfma_f32_32x32x16_bf16 v[98:113], v[12:15], v[122:125], v[98:113]
	v_mfma_f32_32x32x16_bf16 v[98:113], v[82:85], v[126:129], v[98:113]
	v_mfma_f32_32x32x16_bf16 v[98:113], v[86:89], v[130:133], v[98:113]
	v_mfma_f32_32x32x16_bf16 v[98:113], v[90:93], v[134:137], v[98:113]
	v_mfma_f32_32x32x16_bf16 v[98:113], v[94:97], v[138:141], v[98:113]
	v_mfma_f32_32x32x16_bf16 v[98:113], v[146:149], v[142:145], v[98:113]
	ds_read_b128 v[146:149], v216 offset:0x5000
	ds_read_b128 v[12:15], v216 offset:0x5400
	ds_read_b128 v[8:11], v216 offset:0x5800
	ds_read_b128 v[4:7], v216 offset:0x5c00
	s_waitcnt lgkmcnt(8)
	s_nop 0
	v_mfma_f32_32x32x16_bf16 v[82:97], v[162:165], v[114:117], 0
	v_mfma_f32_32x32x16_bf16 v[82:97], v[170:173], v[118:121], v[82:97]
	v_mfma_f32_32x32x16_bf16 v[82:97], v[174:177], v[122:125], v[82:97]
	v_mfma_f32_32x32x16_bf16 v[82:97], v[228:231], v[126:129], v[82:97]
	s_cbranch_vccnz .LBB0_2217
	s_add_i32 s36, s59, s73
	s_add_i32 s37, s36, 0x1c0
	s_addk_i32 s36, 0x1bf
	s_nop 2
	v_mul_f32 v16, s20, v98
	v_mul_f32 v17, s20, v99
	v_add_u32_e32 v98, s37, v208
	v_add_u32_e32 v2, s36, v201
	v_cmp_lt_u32_e32 vcc, s45, v98
	s_add_i32 s76, s37, s53
	s_add_i32 s36, s36, s70
	v_cndmask_b32_e32 v98, v221, v16, vcc
	v_cmp_lt_u32_e32 vcc, s45, v2
	v_add_u32_e32 v2, s37, v203
	s_add_i32 s77, s37, s72
	v_cndmask_b32_e32 v99, v221, v17, vcc
	v_mul_f32 v16, s20, v100
	v_mul_f32 v17, s20, v101
	v_add_u32_e32 v100, s37, v210
	v_cmp_lt_u32_e32 vcc, s45, v100
	s_add_i32 s37, s37, s71
	s_nop 0
	v_cndmask_b32_e32 v100, v221, v16, vcc
	v_cmp_lt_u32_e32 vcc, s45, v2
	v_add_u32_e32 v2, s36, v1
	s_nop 0
	v_cndmask_b32_e32 v101, v221, v17, vcc
	v_mul_f32 v16, s20, v102
	v_mul_f32 v17, s20, v103
	v_add_u32_e32 v102, s76, v200
	v_cmp_lt_u32_e32 vcc, s45, v102
	s_nop 1
	v_cndmask_b32_e32 v102, v221, v16, vcc
	v_cmp_lt_u32_e32 vcc, s45, v2
	v_add_u32_e32 v2, s37, v1
	s_nop 0
	v_cndmask_b32_e32 v103, v221, v17, vcc
	v_mul_f32 v16, s20, v104
	v_mul_f32 v17, s20, v105
	v_add_u32_e32 v104, s77, v200
	v_cmp_lt_u32_e32 vcc, s45, v104
	s_nop 1
	v_cndmask_b32_e32 v104, v221, v16, vcc
	v_cmp_lt_u32_e32 vcc, s45, v2
	v_add_u32_e32 v2, s36, v195
	s_nop 0
	v_cndmask_b32_e32 v105, v221, v17, vcc
	v_mul_f32 v16, s20, v106
	v_mul_f32 v17, s20, v107
	v_add_u32_e32 v106, s76, v202
	v_cmp_lt_u32_e32 vcc, s45, v106
	s_nop 1
	v_cndmask_b32_e32 v106, v221, v16, vcc
	v_cmp_lt_u32_e32 vcc, s45, v2
	v_add_u32_e32 v2, s37, v195
	s_nop 0
	v_cndmask_b32_e32 v107, v221, v17, vcc
	v_mul_f32 v16, s20, v108
	v_mul_f32 v17, s20, v109
	v_add_u32_e32 v108, s77, v202
	v_cmp_lt_u32_e32 vcc, s45, v108
	s_nop 1
	v_cndmask_b32_e32 v108, v221, v16, vcc
	v_cmp_lt_u32_e32 vcc, s45, v2
	v_add_u32_e32 v2, s36, v197
	s_nop 0
	v_cndmask_b32_e32 v109, v221, v17, vcc
	v_mul_f32 v16, s20, v110
	v_mul_f32 v17, s20, v111
	v_add_u32_e32 v110, s76, v204
	v_cmp_lt_u32_e32 vcc, s45, v110
	s_nop 1
	v_cndmask_b32_e32 v110, v221, v16, vcc
	v_cmp_lt_u32_e32 vcc, s45, v2
	v_add_u32_e32 v2, s37, v197
	s_nop 0
	v_cndmask_b32_e32 v111, v221, v17, vcc
	v_mul_f32 v16, s20, v112
	v_mul_f32 v17, s20, v113
	v_add_u32_e32 v112, s77, v204
	v_cmp_lt_u32_e32 vcc, s45, v112
	s_nop 1
	v_cndmask_b32_e32 v112, v221, v16, vcc
	v_cmp_lt_u32_e32 vcc, s45, v2
	s_nop 1
	v_cndmask_b32_e32 v113, v221, v17, vcc

.LBB0_2219:
	v_mfma_f32_32x32x16_bf16 v[82:97], v[158:161], v[130:133], v[82:97]
	v_cndmask_b32_e64 v2, 1.0, v222, s[0:1]
	v_fma_f32 v17, v98, v2, -v225
	v_fma_f32 v98, v99, v2, -v225
	v_exp_f32_e32 v227, v98
	v_fma_f32 v98, v100, v2, -v225
	v_exp_f32_e32 v228, v98
	v_fma_f32 v98, v101, v2, -v225
	v_mfma_f32_32x32x16_bf16 v[82:97], v[154:157], v[134:137], v[82:97]
	v_exp_f32_e32 v229, v98
	v_fma_f32 v98, v102, v2, -v225
	v_exp_f32_e32 v230, v98
	v_fma_f32 v98, v103, v2, -v225
	v_exp_f32_e32 v231, v98
	v_fma_f32 v98, v104, v2, -v225
	v_exp_f32_e32 v232, v98
	v_mfma_f32_32x32x16_bf16 v[82:97], v[150:153], v[138:141], v[82:97]
	v_fma_f32 v98, v105, v2, -v225
	v_exp_f32_e32 v17, v17
	v_exp_f32_e32 v233, v98
	v_cvt_pk_bf16_f32 v235, v228, v229
	v_cvt_pk_bf16_f32 v236, v230, v231
	v_cvt_pk_bf16_f32 v234, v17, v227
	v_cvt_pk_bf16_f32 v237, v232, v233
	ds_read_b128 v[174:177], v216 offset:0x6000
	ds_read_b128 v[170:173], v216 offset:0x6400
	ds_read_b128 v[162:165], v216 offset:0x6800
	ds_read_b128 v[158:161], v216 offset:0x6c00
	ds_read_b128 v[154:157], v216 offset:0x7000
	ds_read_b128 v[150:153], v216 offset:0x7400
	ds_read_b128 v[102:105], v216 offset:0x7800
	ds_read_b128 v[98:101], v216 offset:0x7c00
	s_waitcnt lgkmcnt(8)
	v_mfma_f32_32x32x16_bf16 v[82:97], v[166:169], v[142:145], v[82:97]
	s_and_b64 vcc, exec, s[4:5]
	v_mfma_f32_32x32x16_bf16 v[66:81], v[190:193], v[234:237], v[66:81]
	v_mfma_f32_32x32x16_bf16 v[50:65], v[186:189], v[234:237], v[50:65]
	v_mfma_f32_32x32x16_bf16 v[34:49], v[182:185], v[234:237], v[34:49]
	v_mfma_f32_32x32x16_bf16 v[18:33], v[178:181], v[234:237], v[18:33]
	s_cbranch_vccnz .LBB0_2221
	v_add_u32_e32 v166, s73, v224
	v_add_u32_e32 v168, 0x11e, v166
	v_add_u32_e32 v167, 0x11f, v166
	s_nop 2
	v_mul_f32 v82, s20, v82
	v_mul_f32 v83, s20, v83
	v_cmp_lt_u32_e32 vcc, s45, v168
	v_add_u32_e32 v169, 0x11d, v166
	v_add_u32_e32 v178, 0x11c, v166
	v_add_u32_e32 v179, 0x117, v166
	v_add_u32_e32 v180, 0x116, v166
	v_add_u32_e32 v181, 0x115, v166
	v_add_u32_e32 v182, 0x114, v166
	v_add_u32_e32 v183, 0x10f, v166
	v_add_u32_e32 v184, 0x10e, v166
	v_add_u32_e32 v185, 0x10d, v166
	v_add_u32_e32 v186, 0x10c, v166
	v_add_u32_e32 v187, 0x107, v166
	v_add_u32_e32 v188, 0x106, v166
	v_add_u32_e32 v189, 0x105, v166
	v_add_u32_e32 v166, 0x104, v166
	v_cndmask_b32_e32 v83, v221, v83, vcc
	v_cmp_lt_u32_e32 vcc, s45, v167
	v_mul_f32 v96, s20, v96
	v_mul_f32 v97, s20, v97
	v_mul_f32 v94, s20, v94
	v_mul_f32 v95, s20, v95
	v_cndmask_b32_e32 v82, v221, v82, vcc
	v_cmp_lt_u32_e32 vcc, s45, v166
	v_mul_f32 v92, s20, v92
	v_mul_f32 v93, s20, v93
	v_mul_f32 v90, s20, v90
	v_mul_f32 v91, s20, v91
	v_cndmask_b32_e32 v97, v221, v97, vcc
	v_cmp_lt_u32_e32 vcc, s45, v189
	v_mul_f32 v88, s20, v88
	v_mul_f32 v89, s20, v89
	v_mul_f32 v86, s20, v86
	v_mul_f32 v87, s20, v87
	v_cndmask_b32_e32 v96, v221, v96, vcc
	v_cmp_lt_u32_e32 vcc, s45, v188
	v_mul_f32 v84, s20, v84
	v_mul_f32 v85, s20, v85
	s_nop 0
	v_cndmask_b32_e32 v95, v221, v95, vcc
	v_cmp_lt_u32_e32 vcc, s45, v187
	s_nop 1
	v_cndmask_b32_e32 v94, v221, v94, vcc
	v_cmp_lt_u32_e32 vcc, s45, v186
	s_nop 1
	v_cndmask_b32_e32 v93, v221, v93, vcc
	v_cmp_lt_u32_e32 vcc, s45, v185
	s_nop 1
	v_cndmask_b32_e32 v92, v221, v92, vcc
	v_cmp_lt_u32_e32 vcc, s45, v184
	s_nop 1
	v_cndmask_b32_e32 v91, v221, v91, vcc
	v_cmp_lt_u32_e32 vcc, s45, v183
	s_nop 1
	v_cndmask_b32_e32 v90, v221, v90, vcc
	v_cmp_lt_u32_e32 vcc, s45, v182
	s_nop 1
	v_cndmask_b32_e32 v89, v221, v89, vcc
	v_cmp_lt_u32_e32 vcc, s45, v181
	s_nop 1
	v_cndmask_b32_e32 v88, v221, v88, vcc
	v_cmp_lt_u32_e32 vcc, s45, v180
	s_nop 1
	v_cndmask_b32_e32 v87, v221, v87, vcc
	v_cmp_lt_u32_e32 vcc, s45, v179
	s_nop 1
	v_cndmask_b32_e32 v86, v221, v86, vcc
	v_cmp_lt_u32_e32 vcc, s45, v178
	s_nop 1
	v_cndmask_b32_e32 v85, v221, v85, vcc
	v_cmp_lt_u32_e32 vcc, s45, v169
	s_nop 1
	v_cndmask_b32_e32 v84, v221, v84, vcc
.LBB0_2221:
	v_add_f32_e32 v17, 0, v17
	v_add_f32_e32 v17, v227, v17
	v_add_f32_e32 v17, v228, v17
	v_add_f32_e32 v17, v229, v17
	v_add_f32_e32 v17, v230, v17
	v_add_f32_e32 v17, v231, v17
	v_xor_b32_e32 v166, 0x80000000, v225
	v_add_f32_e32 v17, v232, v17
	v_add_f32_e32 v167, v233, v17
	v_fma_f32 v17, v106, v2, v166
	v_exp_f32_e32 v17, v17
	v_fma_f32 v106, v107, v2, v166
	v_exp_f32_e32 v106, v106
	v_fma_f32 v107, v108, v2, v166
	v_exp_f32_e32 v107, v107
	v_fma_f32 v108, v109, v2, v166
	v_exp_f32_e32 v108, v108
	v_add_f32_e32 v109, v17, v167
	v_add_f32_e32 v109, v106, v109
	v_add_f32_e32 v109, v107, v109
	v_add_f32_e32 v167, v108, v109
	v_fma_f32 v109, v110, v2, v166
	v_fma_f32 v110, v111, v2, v166
	v_fma_f32 v111, v112, v2, v166
	v_fma_f32 v112, v113, v2, v166
	v_max3_f32 v113, v82, s46, v83
	v_max3_f32 v113, v113, v84, v85
	v_max3_f32 v113, v113, v86, v87
	v_max3_f32 v113, v113, v88, v89
	v_max3_f32 v113, v113, v90, v91
	v_max3_f32 v113, v113, v92, v93
	v_max3_f32 v113, v113, v94, v95
	v_max3_f32 v113, v113, v96, v97
	v_mul_f32_e32 v168, 0x3e0293ee, v113
	v_cndmask_b32_e64 v113, v113, v168, s[0:1]
	ds_bpermute_b32 v16, v16, v113
	v_exp_f32_e32 v109, v109
	v_exp_f32_e32 v110, v110
	v_exp_f32_e32 v111, v111
	v_exp_f32_e32 v112, v112
	v_add_f32_e32 v167, v109, v167
	s_waitcnt lgkmcnt(0)
	v_max_f32_e32 v16, v16, v16
	v_add_f32_e32 v167, v110, v167
	v_max_f32_e32 v113, v113, v16
	v_add_f32_e32 v167, v111, v167
	v_sub_f32_e32 v16, v113, v225
	v_add_f32_e32 v167, v112, v167
	v_cmp_ge_f32_e32 vcc, s47, v16
	s_cmp_eq_u64 vcc, exec
	v_add_f32_e32 v16, v226, v167
	s_cbranch_scc1 .LBB0_2223
	v_max_f32_e32 v113, v113, v113
	v_max_f32_e32 v166, v225, v225
	v_max_f32_e32 v113, v166, v113
	v_sub_f32_e32 v166, v225, v113
	v_exp_f32_e32 v166, v166
	v_mov_b32_e32 v225, v113
	v_mul_f32_e32 v16, v16, v166
	v_mul_f32 v80, v80, v166
	v_mul_f32 v81, v81, v166
	v_mul_f32 v78, v78, v166
	v_mul_f32 v79, v79, v166
	v_mul_f32 v76, v76, v166
	v_mul_f32 v77, v77, v166
	v_mul_f32 v74, v74, v166
	v_mul_f32 v75, v75, v166
	v_mul_f32 v72, v72, v166
	v_mul_f32 v73, v73, v166
	v_mul_f32 v70, v70, v166
	v_mul_f32 v71, v71, v166
	v_mul_f32 v68, v68, v166
	v_mul_f32 v69, v69, v166
	v_mul_f32 v66, v66, v166
	v_mul_f32 v67, v67, v166
	v_mul_f32 v64, v64, v166
	v_mul_f32 v65, v65, v166
	v_mul_f32 v62, v62, v166
	v_mul_f32 v63, v63, v166
	v_mul_f32 v60, v60, v166
	v_mul_f32 v61, v61, v166
	v_mul_f32 v58, v58, v166
	v_mul_f32 v59, v59, v166
	v_mul_f32 v56, v56, v166
	v_mul_f32 v57, v57, v166
	v_mul_f32 v54, v54, v166
	v_mul_f32 v55, v55, v166
	v_mul_f32 v52, v52, v166
	v_mul_f32 v53, v53, v166
	v_mul_f32 v50, v50, v166
	v_mul_f32 v51, v51, v166
	v_mul_f32 v48, v48, v166
	v_mul_f32 v49, v49, v166
	v_mul_f32 v46, v46, v166
	v_mul_f32 v47, v47, v166
	v_mul_f32 v44, v44, v166
	v_mul_f32 v45, v45, v166
	v_mul_f32 v42, v42, v166
	v_mul_f32 v43, v43, v166
	v_mul_f32 v40, v40, v166
	v_mul_f32 v41, v41, v166
	v_mul_f32 v38, v38, v166
	v_mul_f32 v39, v39, v166
	v_mul_f32 v36, v36, v166
	v_mul_f32 v37, v37, v166
	v_mul_f32 v34, v34, v166
	v_mul_f32 v35, v35, v166
	v_mul_f32 v32, v32, v166
	v_mul_f32 v33, v33, v166
	v_mul_f32 v30, v30, v166
	v_mul_f32 v31, v31, v166
	v_mul_f32 v28, v28, v166
	v_mul_f32 v29, v29, v166
	v_mul_f32 v26, v26, v166
	v_mul_f32 v27, v27, v166
	v_mul_f32 v24, v24, v166
	v_mul_f32 v25, v25, v166
	v_mul_f32 v22, v22, v166
	v_mul_f32 v23, v23, v166
	v_mul_f32 v20, v20, v166
	v_mul_f32 v21, v21, v166
	v_mul_f32 v18, v18, v166
	v_mul_f32 v19, v19, v166
	v_xor_b32_e32 v166, 0x80000000, v113

.LBB0_2234:
	ds_read_b128 v[4:7], v217 offset:0
	ds_read_b128 v[8:11], v217 offset:0x400
	ds_read_b128 v[12:15], v217 offset:0x800
	ds_read_b128 v[82:85], v217 offset:0xc00
	ds_read_b128 v[86:89], v217 offset:0x1000
	ds_read_b128 v[90:93], v217 offset:0x1400
	ds_read_b128 v[94:97], v217 offset:0x1800
	ds_read_b128 v[146:149], v217 offset:0x1c00
	ds_read_b128 v[162:165], v217 offset:0x2000
	ds_read_b128 v[170:173], v217 offset:0x2400
	ds_read_b128 v[174:177], v217 offset:0x2800
	ds_read_b128 v[228:231], v217 offset:0x2c00
	ds_read_b128 v[158:161], v217 offset:0x3000
	ds_read_b128 v[154:157], v217 offset:0x3400
	ds_read_b128 v[150:153], v217 offset:0x3800
	ds_read_b128 v[166:169], v217 offset:0x3c00
	s_nop 0
	s_waitcnt lgkmcnt(8)
	ds_read_b128 v[190:193], v217 offset:0x4000
	ds_read_b128 v[186:189], v217 offset:0x4400
	ds_read_b128 v[182:185], v217 offset:0x4800
	ds_read_b128 v[178:181], v217 offset:0x4c00
	v_cndmask_b32_e64 v2, 0, 1, s[26:27]
	v_mfma_f32_32x32x16_bf16 v[98:113], v[4:7], v[114:117], 0
	v_cmp_ne_u32_e64 s[4:5], 1, v2
	s_andn2_b64 vcc, exec, s[26:27]
	v_mfma_f32_32x32x16_bf16 v[98:113], v[8:11], v[118:121], v[98:113]
	v_mfma_f32_32x32x16_bf16 v[98:113], v[12:15], v[122:125], v[98:113]
	v_mfma_f32_32x32x16_bf16 v[98:113], v[82:85], v[126:129], v[98:113]
	v_mfma_f32_32x32x16_bf16 v[98:113], v[86:89], v[130:133], v[98:113]
	v_mfma_f32_32x32x16_bf16 v[98:113], v[90:93], v[134:137], v[98:113]
	v_mfma_f32_32x32x16_bf16 v[98:113], v[94:97], v[138:141], v[98:113]
	v_mfma_f32_32x32x16_bf16 v[98:113], v[146:149], v[142:145], v[98:113]
	ds_read_b128 v[146:149], v217 offset:0x5000
	ds_read_b128 v[12:15], v217 offset:0x5400
	ds_read_b128 v[8:11], v217 offset:0x5800
	ds_read_b128 v[4:7], v217 offset:0x5c00
	s_waitcnt lgkmcnt(8)
	s_nop 0
	v_mfma_f32_32x32x16_bf16 v[82:97], v[162:165], v[114:117], 0
	v_mfma_f32_32x32x16_bf16 v[82:97], v[170:173], v[118:121], v[82:97]
	v_mfma_f32_32x32x16_bf16 v[82:97], v[174:177], v[122:125], v[82:97]
	v_mfma_f32_32x32x16_bf16 v[82:97], v[228:231], v[126:129], v[82:97]
	s_cbranch_vccnz .LBB0_2236
	s_add_i32 s30, s59, s73
	s_add_i32 s31, s30, 0x180
	s_addk_i32 s30, 0x17f
	s_nop 2
	v_mul_f32 v16, s20, v98
	v_mul_f32 v17, s20, v99
	v_add_u32_e32 v98, s31, v208
	v_add_u32_e32 v2, s30, v201
	v_cmp_lt_u32_e32 vcc, s45, v98
	s_add_i32 s34, s31, s53
	s_add_i32 s30, s30, s70
	v_cndmask_b32_e32 v98, v221, v16, vcc
	v_cmp_lt_u32_e32 vcc, s45, v2
	v_add_u32_e32 v2, s31, v203
	s_add_i32 s35, s31, s72
	v_cndmask_b32_e32 v99, v221, v17, vcc
	v_mul_f32 v16, s20, v100
	v_mul_f32 v17, s20, v101
	v_add_u32_e32 v100, s31, v210
	v_cmp_lt_u32_e32 vcc, s45, v100
	s_add_i32 s31, s31, s71
	s_nop 0
	v_cndmask_b32_e32 v100, v221, v16, vcc
	v_cmp_lt_u32_e32 vcc, s45, v2
	v_add_u32_e32 v2, s30, v1
	s_nop 0
	v_cndmask_b32_e32 v101, v221, v17, vcc
	v_mul_f32 v16, s20, v102
	v_mul_f32 v17, s20, v103
	v_add_u32_e32 v102, s34, v200
	v_cmp_lt_u32_e32 vcc, s45, v102
	s_nop 1
	v_cndmask_b32_e32 v102, v221, v16, vcc
	v_cmp_lt_u32_e32 vcc, s45, v2
	v_add_u32_e32 v2, s31, v1
	s_nop 0
	v_cndmask_b32_e32 v103, v221, v17, vcc
	v_mul_f32 v16, s20, v104
	v_mul_f32 v17, s20, v105
	v_add_u32_e32 v104, s35, v200
	v_cmp_lt_u32_e32 vcc, s45, v104
	s_nop 1
	v_cndmask_b32_e32 v104, v221, v16, vcc
	v_cmp_lt_u32_e32 vcc, s45, v2
	v_add_u32_e32 v2, s30, v195
	s_nop 0
	v_cndmask_b32_e32 v105, v221, v17, vcc
	v_mul_f32 v16, s20, v106
	v_mul_f32 v17, s20, v107
	v_add_u32_e32 v106, s34, v202
	v_cmp_lt_u32_e32 vcc, s45, v106
	s_nop 1
	v_cndmask_b32_e32 v106, v221, v16, vcc
	v_cmp_lt_u32_e32 vcc, s45, v2
	v_add_u32_e32 v2, s31, v195
	s_nop 0
	v_cndmask_b32_e32 v107, v221, v17, vcc
	v_mul_f32 v16, s20, v108
	v_mul_f32 v17, s20, v109
	v_add_u32_e32 v108, s35, v202
	v_cmp_lt_u32_e32 vcc, s45, v108
	s_nop 1
	v_cndmask_b32_e32 v108, v221, v16, vcc
	v_cmp_lt_u32_e32 vcc, s45, v2
	v_add_u32_e32 v2, s30, v197
	s_nop 0
	v_cndmask_b32_e32 v109, v221, v17, vcc
	v_mul_f32 v16, s20, v110
	v_mul_f32 v17, s20, v111
	v_add_u32_e32 v110, s34, v204
	v_cmp_lt_u32_e32 vcc, s45, v110
	s_nop 1
	v_cndmask_b32_e32 v110, v221, v16, vcc
	v_cmp_lt_u32_e32 vcc, s45, v2
	v_add_u32_e32 v2, s31, v197
	s_nop 0
	v_cndmask_b32_e32 v111, v221, v17, vcc
	v_mul_f32 v16, s20, v112
	v_mul_f32 v17, s20, v113
	v_add_u32_e32 v112, s35, v204
	v_cmp_lt_u32_e32 vcc, s45, v112
	s_nop 1
	v_cndmask_b32_e32 v112, v221, v16, vcc
	v_cmp_lt_u32_e32 vcc, s45, v2
	s_nop 1
	v_cndmask_b32_e32 v113, v221, v17, vcc

.LBB0_2238:
	v_mfma_f32_32x32x16_bf16 v[82:97], v[158:161], v[130:133], v[82:97]
	v_cndmask_b32_e64 v2, 1.0, v222, s[0:1]
	v_fma_f32 v17, v98, v2, -v225
	v_fma_f32 v98, v99, v2, -v225
	v_exp_f32_e32 v227, v98
	v_fma_f32 v98, v100, v2, -v225
	v_exp_f32_e32 v228, v98
	v_fma_f32 v98, v101, v2, -v225
	v_mfma_f32_32x32x16_bf16 v[82:97], v[154:157], v[134:137], v[82:97]
	v_exp_f32_e32 v229, v98
	v_fma_f32 v98, v102, v2, -v225
	v_exp_f32_e32 v230, v98
	v_fma_f32 v98, v103, v2, -v225
	v_exp_f32_e32 v231, v98
	v_fma_f32 v98, v104, v2, -v225
	v_exp_f32_e32 v232, v98
	v_mfma_f32_32x32x16_bf16 v[82:97], v[150:153], v[138:141], v[82:97]
	v_fma_f32 v98, v105, v2, -v225
	v_exp_f32_e32 v17, v17
	v_exp_f32_e32 v233, v98
	v_cvt_pk_bf16_f32 v235, v228, v229
	v_cvt_pk_bf16_f32 v236, v230, v231
	v_cvt_pk_bf16_f32 v234, v17, v227
	v_cvt_pk_bf16_f32 v237, v232, v233
	ds_read_b128 v[174:177], v217 offset:0x6000
	ds_read_b128 v[170:173], v217 offset:0x6400
	ds_read_b128 v[162:165], v217 offset:0x6800
	ds_read_b128 v[158:161], v217 offset:0x6c00
	ds_read_b128 v[154:157], v217 offset:0x7000
	ds_read_b128 v[150:153], v217 offset:0x7400
	ds_read_b128 v[102:105], v217 offset:0x7800
	ds_read_b128 v[98:101], v217 offset:0x7c00
	s_waitcnt lgkmcnt(8)
	v_mfma_f32_32x32x16_bf16 v[82:97], v[166:169], v[142:145], v[82:97]
	s_and_b64 vcc, exec, s[4:5]
	v_mfma_f32_32x32x16_bf16 v[66:81], v[190:193], v[234:237], v[66:81]
	v_mfma_f32_32x32x16_bf16 v[50:65], v[186:189], v[234:237], v[50:65]
	v_mfma_f32_32x32x16_bf16 v[34:49], v[182:185], v[234:237], v[34:49]
	v_mfma_f32_32x32x16_bf16 v[18:33], v[178:181], v[234:237], v[18:33]
	s_cbranch_vccnz .LBB0_2240
	v_add_u32_e32 v166, s73, v224
	v_add_u32_e32 v168, 0xde, v166
	v_add_u32_e32 v167, 0xdf, v166
	s_nop 2
	v_mul_f32 v82, s20, v82
	v_mul_f32 v83, s20, v83
	v_cmp_lt_u32_e32 vcc, s45, v168
	v_add_u32_e32 v169, 0xdd, v166
	v_add_u32_e32 v178, 0xdc, v166
	v_add_u32_e32 v179, 0xd7, v166
	v_add_u32_e32 v180, 0xd6, v166
	v_add_u32_e32 v181, 0xd5, v166
	v_add_u32_e32 v182, 0xd4, v166
	v_add_u32_e32 v183, 0xcf, v166
	v_add_u32_e32 v184, 0xce, v166
	v_add_u32_e32 v185, 0xcd, v166
	v_add_u32_e32 v186, 0xcc, v166
	v_add_u32_e32 v187, 0xc7, v166
	v_add_u32_e32 v188, 0xc6, v166
	v_add_u32_e32 v189, 0xc5, v166
	v_add_u32_e32 v166, 0xc4, v166
	v_cndmask_b32_e32 v83, v221, v83, vcc
	v_cmp_lt_u32_e32 vcc, s45, v167
	v_mul_f32 v96, s20, v96
	v_mul_f32 v97, s20, v97
	v_mul_f32 v94, s20, v94
	v_mul_f32 v95, s20, v95
	v_cndmask_b32_e32 v82, v221, v82, vcc
	v_cmp_lt_u32_e32 vcc, s45, v166
	v_mul_f32 v92, s20, v92
	v_mul_f32 v93, s20, v93
	v_mul_f32 v90, s20, v90
	v_mul_f32 v91, s20, v91
	v_cndmask_b32_e32 v97, v221, v97, vcc
	v_cmp_lt_u32_e32 vcc, s45, v189
	v_mul_f32 v88, s20, v88
	v_mul_f32 v89, s20, v89
	v_mul_f32 v86, s20, v86
	v_mul_f32 v87, s20, v87
	v_cndmask_b32_e32 v96, v221, v96, vcc
	v_cmp_lt_u32_e32 vcc, s45, v188
	v_mul_f32 v84, s20, v84
	v_mul_f32 v85, s20, v85
	s_nop 0
	v_cndmask_b32_e32 v95, v221, v95, vcc
	v_cmp_lt_u32_e32 vcc, s45, v187
	s_nop 1
	v_cndmask_b32_e32 v94, v221, v94, vcc
	v_cmp_lt_u32_e32 vcc, s45, v186
	s_nop 1
	v_cndmask_b32_e32 v93, v221, v93, vcc
	v_cmp_lt_u32_e32 vcc, s45, v185
	s_nop 1
	v_cndmask_b32_e32 v92, v221, v92, vcc
	v_cmp_lt_u32_e32 vcc, s45, v184
	s_nop 1
	v_cndmask_b32_e32 v91, v221, v91, vcc
	v_cmp_lt_u32_e32 vcc, s45, v183
	s_nop 1
	v_cndmask_b32_e32 v90, v221, v90, vcc
	v_cmp_lt_u32_e32 vcc, s45, v182
	s_nop 1
	v_cndmask_b32_e32 v89, v221, v89, vcc
	v_cmp_lt_u32_e32 vcc, s45, v181
	s_nop 1
	v_cndmask_b32_e32 v88, v221, v88, vcc
	v_cmp_lt_u32_e32 vcc, s45, v180
	s_nop 1
	v_cndmask_b32_e32 v87, v221, v87, vcc
	v_cmp_lt_u32_e32 vcc, s45, v179
	s_nop 1
	v_cndmask_b32_e32 v86, v221, v86, vcc
	v_cmp_lt_u32_e32 vcc, s45, v178
	s_nop 1
	v_cndmask_b32_e32 v85, v221, v85, vcc
	v_cmp_lt_u32_e32 vcc, s45, v169
	s_nop 1
	v_cndmask_b32_e32 v84, v221, v84, vcc

.LBB0_2253:
	s_add_i32 s75, s75, -5
	s_cmp_lt_i32 s75, s57
	s_cselect_b64 s[4:5], -1, 0
	s_or_b64 s[4:5], s[0:1], s[4:5]
	s_andn2_b64 vcc, exec, s[4:5]
	s_cbranch_vccnz .LBB0_2179
	ds_read_b128 v[4:7], v218 offset:0
	ds_read_b128 v[8:11], v218 offset:0x400
	ds_read_b128 v[12:15], v218 offset:0x800
	ds_read_b128 v[82:85], v218 offset:0xc00
	ds_read_b128 v[86:89], v218 offset:0x1000
	ds_read_b128 v[90:93], v218 offset:0x1400
	ds_read_b128 v[94:97], v218 offset:0x1800
	ds_read_b128 v[146:149], v218 offset:0x1c00
	ds_read_b128 v[166:169], v218 offset:0x2000
	ds_read_b128 v[170:173], v218 offset:0x2400
	ds_read_b128 v[174:177], v218 offset:0x2800
	ds_read_b128 v[228:231], v218 offset:0x2c00
	ds_read_b128 v[158:161], v218 offset:0x3000
	ds_read_b128 v[154:157], v218 offset:0x3400
	ds_read_b128 v[150:153], v218 offset:0x3800
	ds_read_b128 v[162:165], v218 offset:0x3c00
	s_nop 0
	s_waitcnt lgkmcnt(8)
	ds_read_b128 v[190:193], v218 offset:0x4000
	ds_read_b128 v[186:189], v218 offset:0x4400
	ds_read_b128 v[182:185], v218 offset:0x4800
	ds_read_b128 v[178:181], v218 offset:0x4c00
	v_cndmask_b32_e64 v2, 0, 1, s[26:27]
	v_mfma_f32_32x32x16_bf16 v[98:113], v[4:7], v[114:117], 0
	v_cmp_ne_u32_e64 s[4:5], 1, v2
	s_andn2_b64 vcc, exec, s[26:27]
	v_mfma_f32_32x32x16_bf16 v[98:113], v[8:11], v[118:121], v[98:113]
	v_mfma_f32_32x32x16_bf16 v[98:113], v[12:15], v[122:125], v[98:113]
	v_mfma_f32_32x32x16_bf16 v[98:113], v[82:85], v[126:129], v[98:113]
	v_mfma_f32_32x32x16_bf16 v[98:113], v[86:89], v[130:133], v[98:113]
	v_mfma_f32_32x32x16_bf16 v[98:113], v[90:93], v[134:137], v[98:113]
	v_mfma_f32_32x32x16_bf16 v[98:113], v[94:97], v[138:141], v[98:113]
	v_mfma_f32_32x32x16_bf16 v[98:113], v[146:149], v[142:145], v[98:113]
	ds_read_b128 v[146:149], v218 offset:0x5000
	ds_read_b128 v[12:15], v218 offset:0x5400
	ds_read_b128 v[8:11], v218 offset:0x5800
	ds_read_b128 v[4:7], v218 offset:0x5c00
	s_waitcnt lgkmcnt(8)
	s_nop 0
	v_mfma_f32_32x32x16_bf16 v[82:97], v[166:169], v[114:117], 0
	v_mfma_f32_32x32x16_bf16 v[82:97], v[170:173], v[118:121], v[82:97]
	v_mfma_f32_32x32x16_bf16 v[82:97], v[174:177], v[122:125], v[82:97]
	v_mfma_f32_32x32x16_bf16 v[82:97], v[228:231], v[126:129], v[82:97]
	s_cbranch_vccnz .LBB0_2256
	s_add_i32 s26, s59, s73
	s_add_i32 s27, s26, 0x140
	s_addk_i32 s26, 0x13f
	s_nop 2
	v_mul_f32 v16, s20, v98
	v_mul_f32 v17, s20, v99
	v_add_u32_e32 v98, s27, v208
	v_add_u32_e32 v2, s26, v201
	v_cmp_lt_u32_e32 vcc, s45, v98
	s_add_i32 s28, s27, s53
	s_add_i32 s26, s26, s70
	v_cndmask_b32_e32 v98, v221, v16, vcc
	v_cmp_lt_u32_e32 vcc, s45, v2
	v_add_u32_e32 v2, s27, v203
	s_add_i32 s29, s27, s72
	v_cndmask_b32_e32 v99, v221, v17, vcc
	v_mul_f32 v16, s20, v100
	v_mul_f32 v17, s20, v101
	v_add_u32_e32 v100, s27, v210
	v_cmp_lt_u32_e32 vcc, s45, v100
	s_add_i32 s27, s27, s71
	s_nop 0
	v_cndmask_b32_e32 v100, v221, v16, vcc
	v_cmp_lt_u32_e32 vcc, s45, v2
	v_add_u32_e32 v2, s26, v1
	s_nop 0
	v_cndmask_b32_e32 v101, v221, v17, vcc
	v_mul_f32 v16, s20, v102
	v_mul_f32 v17, s20, v103
	v_add_u32_e32 v102, s28, v200
	v_cmp_lt_u32_e32 vcc, s45, v102
	s_nop 1
	v_cndmask_b32_e32 v102, v221, v16, vcc
	v_cmp_lt_u32_e32 vcc, s45, v2
	v_add_u32_e32 v2, s27, v1
	s_nop 0
	v_cndmask_b32_e32 v103, v221, v17, vcc
	v_mul_f32 v16, s20, v104
	v_mul_f32 v17, s20, v105
	v_add_u32_e32 v104, s29, v200
	v_cmp_lt_u32_e32 vcc, s45, v104
	s_nop 1
	v_cndmask_b32_e32 v104, v221, v16, vcc
	v_cmp_lt_u32_e32 vcc, s45, v2
	v_add_u32_e32 v2, s26, v195
	s_nop 0
	v_cndmask_b32_e32 v105, v221, v17, vcc
	v_mul_f32 v16, s20, v106
	v_mul_f32 v17, s20, v107
	v_add_u32_e32 v106, s28, v202
	v_cmp_lt_u32_e32 vcc, s45, v106
	s_nop 1
	v_cndmask_b32_e32 v106, v221, v16, vcc
	v_cmp_lt_u32_e32 vcc, s45, v2
	v_add_u32_e32 v2, s27, v195
	s_nop 0
	v_cndmask_b32_e32 v107, v221, v17, vcc
	v_mul_f32 v16, s20, v108
	v_mul_f32 v17, s20, v109
	v_add_u32_e32 v108, s29, v202
	v_cmp_lt_u32_e32 vcc, s45, v108
	s_nop 1
	v_cndmask_b32_e32 v108, v221, v16, vcc
	v_cmp_lt_u32_e32 vcc, s45, v2
	v_add_u32_e32 v2, s26, v197
	s_nop 0
	v_cndmask_b32_e32 v109, v221, v17, vcc
	v_mul_f32 v16, s20, v110
	v_mul_f32 v17, s20, v111
	v_add_u32_e32 v110, s28, v204
	v_cmp_lt_u32_e32 vcc, s45, v110
	s_nop 1
	v_cndmask_b32_e32 v110, v221, v16, vcc
	v_cmp_lt_u32_e32 vcc, s45, v2
	v_add_u32_e32 v2, s27, v197
	s_nop 0
	v_cndmask_b32_e32 v111, v221, v17, vcc
	v_mul_f32 v16, s20, v112
	v_mul_f32 v17, s20, v113
	v_add_u32_e32 v112, s29, v204
	v_cmp_lt_u32_e32 vcc, s45, v112
	s_nop 1
	v_cndmask_b32_e32 v112, v221, v16, vcc
	v_cmp_lt_u32_e32 vcc, s45, v2
	s_nop 1
	v_cndmask_b32_e32 v113, v221, v17, vcc

.LBB0_2258:
	v_mfma_f32_32x32x16_bf16 v[82:97], v[158:161], v[130:133], v[82:97]
	v_cndmask_b32_e64 v2, 1.0, v222, s[0:1]
	v_fma_f32 v17, v98, v2, -v225
	v_fma_f32 v98, v99, v2, -v225
	v_exp_f32_e32 v227, v98
	v_fma_f32 v98, v100, v2, -v225
	v_exp_f32_e32 v228, v98
	v_fma_f32 v98, v101, v2, -v225
	v_mfma_f32_32x32x16_bf16 v[82:97], v[154:157], v[134:137], v[82:97]
	v_exp_f32_e32 v229, v98
	v_fma_f32 v98, v102, v2, -v225
	v_exp_f32_e32 v230, v98
	v_fma_f32 v98, v103, v2, -v225
	v_exp_f32_e32 v231, v98
	v_fma_f32 v98, v104, v2, -v225
	v_exp_f32_e32 v232, v98
	v_mfma_f32_32x32x16_bf16 v[82:97], v[150:153], v[138:141], v[82:97]
	v_fma_f32 v98, v105, v2, -v225
	v_exp_f32_e32 v17, v17
	v_exp_f32_e32 v233, v98
	v_cvt_pk_bf16_f32 v235, v228, v229
	v_cvt_pk_bf16_f32 v236, v230, v231
	v_cvt_pk_bf16_f32 v234, v17, v227
	v_cvt_pk_bf16_f32 v237, v232, v233
	ds_read_b128 v[174:177], v218 offset:0x6000
	ds_read_b128 v[170:173], v218 offset:0x6400
	ds_read_b128 v[166:169], v218 offset:0x6800
	ds_read_b128 v[158:161], v218 offset:0x6c00
	ds_read_b128 v[154:157], v218 offset:0x7000
	ds_read_b128 v[150:153], v218 offset:0x7400
	ds_read_b128 v[102:105], v218 offset:0x7800
	ds_read_b128 v[98:101], v218 offset:0x7c00
	s_waitcnt lgkmcnt(8)
	v_mfma_f32_32x32x16_bf16 v[82:97], v[162:165], v[142:145], v[82:97]
	s_and_b64 vcc, exec, s[4:5]
	v_mfma_f32_32x32x16_bf16 v[66:81], v[190:193], v[234:237], v[66:81]
	v_mfma_f32_32x32x16_bf16 v[50:65], v[186:189], v[234:237], v[50:65]
	v_mfma_f32_32x32x16_bf16 v[34:49], v[182:185], v[234:237], v[34:49]
	v_mfma_f32_32x32x16_bf16 v[18:33], v[178:181], v[234:237], v[18:33]
	s_cbranch_vccnz .LBB0_2260
	v_add_u32_e32 v162, s73, v224
	v_add_u32_e32 v164, 0x9e, v162
	v_add_u32_e32 v163, 0x9f, v162
	s_nop 2
	v_mul_f32 v82, s20, v82
	v_mul_f32 v83, s20, v83
	v_cmp_lt_u32_e32 vcc, s45, v164
	v_add_u32_e32 v165, 0x9d, v162
	v_add_u32_e32 v178, 0x9c, v162
	v_add_u32_e32 v179, 0x97, v162
	v_add_u32_e32 v180, 0x96, v162
	v_add_u32_e32 v181, 0x95, v162
	v_add_u32_e32 v182, 0x94, v162
	v_add_u32_e32 v183, 0x8f, v162
	v_add_u32_e32 v184, 0x8e, v162
	v_add_u32_e32 v185, 0x8d, v162
	v_add_u32_e32 v186, 0x8c, v162
	v_add_u32_e32 v187, 0x87, v162
	v_add_u32_e32 v188, 0x86, v162
	v_add_u32_e32 v189, 0x85, v162
	v_add_u32_e32 v162, 0x84, v162
	v_cndmask_b32_e32 v83, v221, v83, vcc
	v_cmp_lt_u32_e32 vcc, s45, v163
	v_mul_f32 v96, s20, v96
	v_mul_f32 v97, s20, v97
	v_mul_f32 v94, s20, v94
	v_mul_f32 v95, s20, v95
	v_cndmask_b32_e32 v82, v221, v82, vcc
	v_cmp_lt_u32_e32 vcc, s45, v162
	v_mul_f32 v92, s20, v92
	v_mul_f32 v93, s20, v93
	v_mul_f32 v90, s20, v90
	v_mul_f32 v91, s20, v91
	v_cndmask_b32_e32 v97, v221, v97, vcc
	v_cmp_lt_u32_e32 vcc, s45, v189
	v_mul_f32 v88, s20, v88
	v_mul_f32 v89, s20, v89
	v_mul_f32 v86, s20, v86
	v_mul_f32 v87, s20, v87
	v_cndmask_b32_e32 v96, v221, v96, vcc
	v_cmp_lt_u32_e32 vcc, s45, v188
	v_mul_f32 v84, s20, v84
	v_mul_f32 v85, s20, v85
	s_nop 0
	v_cndmask_b32_e32 v95, v221, v95, vcc
	v_cmp_lt_u32_e32 vcc, s45, v187
	s_nop 1
	v_cndmask_b32_e32 v94, v221, v94, vcc
	v_cmp_lt_u32_e32 vcc, s45, v186
	s_nop 1
	v_cndmask_b32_e32 v93, v221, v93, vcc
	v_cmp_lt_u32_e32 vcc, s45, v185
	s_nop 1
	v_cndmask_b32_e32 v92, v221, v92, vcc
	v_cmp_lt_u32_e32 vcc, s45, v184
	s_nop 1
	v_cndmask_b32_e32 v91, v221, v91, vcc
	v_cmp_lt_u32_e32 vcc, s45, v183
	s_nop 1
	v_cndmask_b32_e32 v90, v221, v90, vcc
	v_cmp_lt_u32_e32 vcc, s45, v182
	s_nop 1
	v_cndmask_b32_e32 v89, v221, v89, vcc
	v_cmp_lt_u32_e32 vcc, s45, v181
	s_nop 1
	v_cndmask_b32_e32 v88, v221, v88, vcc
	v_cmp_lt_u32_e32 vcc, s45, v180
	s_nop 1
	v_cndmask_b32_e32 v87, v221, v87, vcc
	v_cmp_lt_u32_e32 vcc, s45, v179
	s_nop 1
	v_cndmask_b32_e32 v86, v221, v86, vcc
	v_cmp_lt_u32_e32 vcc, s45, v178
	s_nop 1
	v_cndmask_b32_e32 v85, v221, v85, vcc
	v_cmp_lt_u32_e32 vcc, s45, v165
	s_nop 1
	v_cndmask_b32_e32 v84, v221, v84, vcc
.LBB0_2260:
	v_add_f32_e32 v17, 0, v17
	v_add_f32_e32 v17, v227, v17
	v_add_f32_e32 v17, v228, v17
	v_add_f32_e32 v17, v229, v17
	v_add_f32_e32 v17, v230, v17
	v_add_f32_e32 v17, v231, v17
	v_xor_b32_e32 v162, 0x80000000, v225
	v_add_f32_e32 v17, v232, v17
	v_add_f32_e32 v163, v233, v17
	v_fma_f32 v17, v106, v2, v162
	v_exp_f32_e32 v17, v17
	v_fma_f32 v106, v107, v2, v162
	v_exp_f32_e32 v106, v106
	v_fma_f32 v107, v108, v2, v162
	v_exp_f32_e32 v107, v107
	v_fma_f32 v108, v109, v2, v162
	v_exp_f32_e32 v108, v108
	v_add_f32_e32 v109, v17, v163
	v_add_f32_e32 v109, v106, v109
	v_add_f32_e32 v109, v107, v109
	v_add_f32_e32 v163, v108, v109
	v_fma_f32 v109, v110, v2, v162
	v_fma_f32 v110, v111, v2, v162
	v_fma_f32 v111, v112, v2, v162
	v_fma_f32 v112, v113, v2, v162
	v_max3_f32 v113, v82, s46, v83
	v_max3_f32 v113, v113, v84, v85
	v_max3_f32 v113, v113, v86, v87
	v_max3_f32 v113, v113, v88, v89
	v_max3_f32 v113, v113, v90, v91
	v_max3_f32 v113, v113, v92, v93
	v_max3_f32 v113, v113, v94, v95
	v_max3_f32 v113, v113, v96, v97
	v_mul_f32_e32 v164, 0x3e0293ee, v113
	v_cndmask_b32_e64 v113, v113, v164, s[0:1]
	ds_bpermute_b32 v16, v16, v113
	v_exp_f32_e32 v109, v109
	v_exp_f32_e32 v110, v110
	v_exp_f32_e32 v111, v111
	v_exp_f32_e32 v112, v112
	v_add_f32_e32 v163, v109, v163
	s_waitcnt lgkmcnt(0)
	v_max_f32_e32 v16, v16, v16
	v_add_f32_e32 v163, v110, v163
	v_max_f32_e32 v113, v113, v16
	v_add_f32_e32 v163, v111, v163
	v_sub_f32_e32 v16, v113, v225
	v_add_f32_e32 v163, v112, v163
	v_cmp_ge_f32_e32 vcc, s47, v16
	s_cmp_eq_u64 vcc, exec
	v_add_f32_e32 v16, v226, v163
	s_cbranch_scc1 .LBB0_2178
	v_max_f32_e32 v113, v113, v113
	v_max_f32_e32 v162, v225, v225
	v_max_f32_e32 v113, v162, v113
	v_sub_f32_e32 v162, v225, v113
	v_exp_f32_e32 v162, v162
	v_mov_b32_e32 v225, v113
	v_mul_f32_e32 v16, v16, v162
	v_mul_f32 v80, v80, v162
	v_mul_f32 v81, v81, v162
	v_mul_f32 v78, v78, v162
	v_mul_f32 v79, v79, v162
	v_mul_f32 v76, v76, v162
	v_mul_f32 v77, v77, v162
	v_mul_f32 v74, v74, v162
	v_mul_f32 v75, v75, v162
	v_mul_f32 v72, v72, v162
	v_mul_f32 v73, v73, v162
	v_mul_f32 v70, v70, v162
	v_mul_f32 v71, v71, v162
	v_mul_f32 v68, v68, v162
	v_mul_f32 v69, v69, v162
	v_mul_f32 v66, v66, v162
	v_mul_f32 v67, v67, v162
	v_mul_f32 v64, v64, v162
	v_mul_f32 v65, v65, v162
	v_mul_f32 v62, v62, v162
	v_mul_f32 v63, v63, v162
	v_mul_f32 v60, v60, v162
	v_mul_f32 v61, v61, v162
	v_mul_f32 v58, v58, v162
	v_mul_f32 v59, v59, v162
	v_mul_f32 v56, v56, v162
	v_mul_f32 v57, v57, v162
	v_mul_f32 v54, v54, v162
	v_mul_f32 v55, v55, v162
	v_mul_f32 v52, v52, v162
	v_mul_f32 v53, v53, v162
	v_mul_f32 v50, v50, v162
	v_mul_f32 v51, v51, v162
	v_mul_f32 v48, v48, v162
	v_mul_f32 v49, v49, v162
	v_mul_f32 v46, v46, v162
	v_mul_f32 v47, v47, v162
	v_mul_f32 v44, v44, v162
	v_mul_f32 v45, v45, v162
	v_mul_f32 v42, v42, v162
	v_mul_f32 v43, v43, v162
	v_mul_f32 v40, v40, v162
	v_mul_f32 v41, v41, v162
	v_mul_f32 v38, v38, v162
	v_mul_f32 v39, v39, v162
	v_mul_f32 v36, v36, v162
	v_mul_f32 v37, v37, v162
	v_mul_f32 v34, v34, v162
	v_mul_f32 v35, v35, v162
	v_mul_f32 v32, v32, v162
	v_mul_f32 v33, v33, v162
	v_mul_f32 v30, v30, v162
	v_mul_f32 v31, v31, v162
	v_mul_f32 v28, v28, v162
	v_mul_f32 v29, v29, v162
	v_mul_f32 v26, v26, v162
	v_mul_f32 v27, v27, v162
	v_mul_f32 v24, v24, v162
	v_mul_f32 v25, v25, v162
	v_mul_f32 v22, v22, v162
	v_mul_f32 v23, v23, v162
	v_mul_f32 v20, v20, v162
	v_mul_f32 v21, v21, v162
	v_mul_f32 v18, v18, v162
	v_mul_f32 v19, v19, v162
	v_xor_b32_e32 v162, 0x80000000, v113
	s_branch .LBB0_2178

.LBB0_2267:
	v_max_f32_e32 v98, v98, v98
	v_max_f32_e32 v99, v208, v208
	v_max_f32_e32 v99, v99, v98
	v_sub_f32_e32 v98, v208, v99
	v_exp_f32_e32 v98, v98
	v_mov_b32_e32 v208, v99
	v_mul_f32_e32 v90, v90, v98
	v_mul_f32 v64, v64, v98
	v_mul_f32 v65, v65, v98
	v_mul_f32 v62, v62, v98
	v_mul_f32 v63, v63, v98
	v_mul_f32 v60, v60, v98
	v_mul_f32 v61, v61, v98
	v_mul_f32 v58, v58, v98
	v_mul_f32 v59, v59, v98
	v_mul_f32 v56, v56, v98
	v_mul_f32 v57, v57, v98
	v_mul_f32 v54, v54, v98
	v_mul_f32 v55, v55, v98
	v_mul_f32 v52, v52, v98
	v_mul_f32 v53, v53, v98
	v_mul_f32 v50, v50, v98
	v_mul_f32 v51, v51, v98
	v_mul_f32 v48, v48, v98
	v_mul_f32 v49, v49, v98
	v_mul_f32 v46, v46, v98
	v_mul_f32 v47, v47, v98
	v_mul_f32 v44, v44, v98
	v_mul_f32 v45, v45, v98
	v_mul_f32 v42, v42, v98
	v_mul_f32 v43, v43, v98
	v_mul_f32 v40, v40, v98
	v_mul_f32 v41, v41, v98
	v_mul_f32 v38, v38, v98
	v_mul_f32 v39, v39, v98
	v_mul_f32 v36, v36, v98
	v_mul_f32 v37, v37, v98
	v_mul_f32 v34, v34, v98
	v_mul_f32 v35, v35, v98
	v_mul_f32 v32, v32, v98
	v_mul_f32 v33, v33, v98
	v_mul_f32 v30, v30, v98
	v_mul_f32 v31, v31, v98
	v_mul_f32 v28, v28, v98
	v_mul_f32 v29, v29, v98
	v_mul_f32 v26, v26, v98
	v_mul_f32 v27, v27, v98
	v_mul_f32 v24, v24, v98
	v_mul_f32 v25, v25, v98
	v_mul_f32 v22, v22, v98
	v_mul_f32 v23, v23, v98
	v_mul_f32 v20, v20, v98
	v_mul_f32 v21, v21, v98
	v_mul_f32 v18, v18, v98
	v_mul_f32 v19, v19, v98
	v_mul_f32 v16, v16, v98
	v_mul_f32 v17, v17, v98
	v_mul_f32 v14, v14, v98
	v_mul_f32 v15, v15, v98
	v_mul_f32 v12, v12, v98
	v_mul_f32 v13, v13, v98
	v_mul_f32 v10, v10, v98
	v_mul_f32 v11, v11, v98
	v_mul_f32 v8, v8, v98
	v_mul_f32 v9, v9, v98
	v_mul_f32 v6, v6, v98
	v_mul_f32 v7, v7, v98
	v_mul_f32 v4, v4, v98
	v_mul_f32 v5, v5, v98
	v_mul_f32 v2, v2, v98
	v_mul_f32 v3, v3, v98
	v_xor_b32_e32 v98, 0x80000000, v99
.LBB0_2268:
	v_fmamk_f32 v66, v66, 0x3e0293ee, v98
	v_exp_f32_e32 v66, v66
	v_fmamk_f32 v67, v67, 0x3e0293ee, v98
	v_exp_f32_e32 v67, v67
	v_fmamk_f32 v68, v68, 0x3e0293ee, v98
	v_exp_f32_e32 v68, v68
	v_fmamk_f32 v69, v69, 0x3e0293ee, v98
	v_exp_f32_e32 v69, v69
	v_fmamk_f32 v70, v70, 0x3e0293ee, v98
	v_cvt_pk_bf16_f32 v126, v127, v91
	v_add_f32_e32 v91, 0, v66
	v_exp_f32_e32 v70, v70
	v_fmamk_f32 v71, v71, 0x3e0293ee, v98
	v_add_f32_e32 v91, v67, v91
	v_exp_f32_e32 v71, v71
	v_fmamk_f32 v72, v72, 0x3e0293ee, v98
	v_fmamk_f32 v73, v73, 0x3e0293ee, v98
	v_add_f32_e32 v91, v68, v91
	v_exp_f32_e32 v72, v72
	v_exp_f32_e32 v73, v73
	v_add_f32_e32 v91, v69, v91
	v_add_f32_e32 v91, v70, v91
	v_fmamk_f32 v74, v74, 0x3e0293ee, v98
	v_add_f32_e32 v91, v71, v91
	v_exp_f32_e32 v74, v74
	v_cvt_pk_bf16_f32 v66, v66, v67
	v_cvt_pk_bf16_f32 v67, v68, v69
	v_cvt_pk_bf16_f32 v68, v70, v71
	v_fmamk_f32 v71, v75, 0x3e0293ee, v98
	v_cvt_pk_bf16_f32 v127, v92, v93
	v_cvt_pk_bf16_f32 v128, v94, v95
	v_cvt_pk_bf16_f32 v129, v96, v97
	v_add_f32_e32 v91, v72, v91
	v_cvt_pk_bf16_f32 v69, v72, v73
	v_exp_f32_e32 v71, v71
	v_fmamk_f32 v72, v76, 0x3e0293ee, v98
	v_mfma_f32_32x32x16_bf16 v[50:65], v[142:145], v[126:129], v[50:65]
	v_add_f32_e32 v70, v73, v91
	v_exp_f32_e32 v72, v72
	v_fmamk_f32 v73, v77, 0x3e0293ee, v98
	v_exp_f32_e32 v73, v73
	v_fmamk_f32 v75, v78, 0x3e0293ee, v98
	v_add_f32_e32 v70, v74, v70
	v_exp_f32_e32 v75, v75
	v_mfma_f32_32x32x16_bf16 v[34:49], v[138:141], v[126:129], v[34:49]
	v_fmamk_f32 v76, v79, 0x3e0293ee, v98
	v_add_f32_e32 v70, v71, v70
	v_exp_f32_e32 v76, v76
	v_fmamk_f32 v77, v80, 0x3e0293ee, v98
	v_add_f32_e32 v70, v72, v70
	v_exp_f32_e32 v77, v77
	v_fmac_f32_e32 v98, 0x3e0293ee, v81
	v_mfma_f32_32x32x16_bf16 v[18:33], v[134:137], v[126:129], v[18:33]
	v_add_f32_e32 v70, v73, v70
	v_exp_f32_e32 v78, v98
	v_add_f32_e32 v70, v75, v70
	v_add_f32_e32 v70, v76, v70
	s_waitcnt lgkmcnt(0)
	s_add_i32 s2, s2, s90
	s_add_i32 s25, s25, s26
	v_mfma_f32_32x32x16_bf16 v[2:17], v[130:133], v[126:129], v[2:17]
	s_add_i32 s27, s27, s28
	s_cmpk_lt_i32 s2, 0x100
	v_mfma_f32_32x32x16_bf16 v[50:65], v[122:125], v[66:69], v[50:65]
	v_mfma_f32_32x32x16_bf16 v[34:49], v[118:121], v[66:69], v[34:49]
	v_mfma_f32_32x32x16_bf16 v[18:33], v[114:117], v[66:69], v[18:33]
	v_mfma_f32_32x32x16_bf16 v[2:17], v[110:113], v[66:69], v[2:17]
	v_add_f32_e32 v66, v77, v70
	v_add_f32_e32 v66, v78, v66
	v_add_f32_e32 v70, v90, v66
	v_cvt_pk_bf16_f32 v66, v74, v71
	ds_bpermute_b32 v71, v192, v70
	v_cvt_pk_bf16_f32 v67, v72, v73
	v_fma_f32 v72, v207, s49, -v208
	v_exp_f32_e32 v72, v72
	v_cvt_pk_bf16_f32 v68, v75, v76
	s_waitcnt lgkmcnt(0)
	v_add_f32_e32 v70, v70, v71
	v_cvt_pk_bf16_f32 v69, v77, v78
	v_add_f32_e32 v70, v72, v70
	v_div_scale_f32 v71, s[52:53], v70, v70, 1.0
	v_rcp_f32_e32 v72, v71
	v_mfma_f32_32x32x16_bf16 v[50:65], v[106:109], v[66:69], v[50:65]
	v_fma_f32 v73, -v71, v72, 1.0
	v_fmac_f32_e32 v72, v73, v72
	v_div_scale_f32 v73, vcc, 1.0, v70, 1.0
	v_mul_f32_e32 v74, v73, v72
	v_mfma_f32_32x32x16_bf16 v[34:49], v[102:105], v[66:69], v[34:49]
	v_fma_f32 v75, -v71, v74, v73
	v_fmac_f32_e32 v74, v75, v72
	v_fma_f32 v71, -v71, v74, v73
	v_div_fmas_f32 v71, v71, v72, v74
	v_div_fixup_f32 v70, v71, v70, 1.0
	v_mov_b32_e32 v71, v211
	v_mfma_f32_32x32x16_bf16 v[18:33], v[86:89], v[66:69], v[18:33]
	v_mul_f32_e64 v50, v50, v70
	v_mul_f32_e64 v51, v51, v70
	v_mul_f32_e64 v52, v52, v70
	v_mul_f32_e64 v53, v53, v70
	s_nop 0
	v_mul_f32_e64 v34, v34, v70
	v_mul_f32_e64 v35, v35, v70
	v_mul_f32 v36, v36, v70
	v_mul_f32 v37, v37, v70
	v_cvt_pk_bf16_f32 v50, v50, v51
	v_cvt_pk_bf16_f32 v51, v52, v53
	v_mul_f32 v52, v54, v70
	v_mul_f32 v53, v55, v70
	v_mfma_f32_32x32x16_bf16 v[2:17], v[82:85], v[66:69], v[2:17]
	v_mul_f32_e64 v18, v18, v70
	v_mul_f32_e64 v19, v19, v70
	v_mul_f32_e64 v20, v20, v70
	v_mul_f32_e64 v21, v21, v70
	v_mul_f32_e64 v54, v56, v70
	v_mul_f32_e64 v55, v57, v70
	v_cvt_pk_bf16_f32 v34, v34, v35
	v_cvt_pk_bf16_f32 v35, v36, v37
	v_mul_f32 v36, v38, v70
	v_mul_f32 v37, v39, v70
	v_mul_f32 v38, v40, v70
	v_mul_f32 v39, v41, v70
	s_nop 1
	v_mul_f32 v2, v2, v70
	v_mul_f32 v3, v3, v70
	v_mul_f32 v4, v4, v70
	v_mul_f32 v5, v5, v70
	v_cvt_pk_bf16_f32 v18, v18, v19
	v_cvt_pk_bf16_f32 v19, v20, v21
	v_mul_f32 v20, v22, v70
	v_mul_f32 v21, v23, v70
	v_mul_f32 v22, v24, v70
	v_mul_f32 v23, v25, v70
	v_cvt_pk_bf16_f32 v2, v2, v3
	v_cvt_pk_bf16_f32 v3, v4, v5
	v_mul_f32 v4, v6, v70
	v_mul_f32 v5, v7, v70
	v_mul_f32 v6, v8, v70
	v_mul_f32 v7, v9, v70
	v_lshl_add_u32 v192, v71, 11, s50
	v_cvt_pk_bf16_f32 v52, v52, v53
	v_cvt_pk_bf16_f32 v53, v54, v55
	v_cvt_pk_bf16_f32 v36, v36, v37
	v_cvt_pk_bf16_f32 v37, v38, v39
	v_cvt_pk_bf16_f32 v20, v20, v21
	v_cvt_pk_bf16_f32 v21, v22, v23
	v_cvt_pk_bf16_f32 v4, v4, v5
	v_cvt_pk_bf16_f32 v5, v6, v7
	v_lshl_add_u64 v[66:67], v[192:193], 1, v[198:199]
	v_permlane32_swap_b32_e32 v50, v52
	v_permlane32_swap_b32_e32 v51, v53
	v_permlane32_swap_b32_e32 v34, v36
	v_permlane32_swap_b32_e32 v35, v37
	v_permlane32_swap_b32_e32 v18, v20
	v_permlane32_swap_b32_e32 v19, v21
	v_permlane32_swap_b32_e32 v2, v4
	v_permlane32_swap_b32_e32 v3, v5
	global_store_dwordx4 v[66:67], v[50:53], off
	global_store_dwordx4 v[66:67], v[34:37], off offset:64
	global_store_dwordx4 v[66:67], v[18:21], off offset:128
	v_mul_f32 v50, v58, v70
	v_mul_f32 v51, v59, v70
	v_mul_f32 v52, v60, v70
	v_mul_f32 v53, v61, v70
	v_mul_f32 v34, v42, v70
	v_mul_f32 v35, v43, v70
	v_mul_f32 v36, v44, v70
	v_mul_f32 v37, v45, v70
	v_mul_f32 v18, v26, v70
	v_mul_f32 v19, v27, v70
	v_mul_f32 v20, v28, v70
	v_mul_f32 v21, v29, v70
	global_store_dwordx4 v[66:67], v[2:5], off offset:192
	v_cvt_pk_bf16_f32 v50, v50, v51
	v_cvt_pk_bf16_f32 v51, v52, v53
	v_mul_f32 v2, v10, v70
	v_mul_f32 v3, v11, v70
	v_mul_f32 v4, v12, v70
	v_mul_f32 v5, v13, v70
	v_mul_f32 v52, v62, v70
	v_mul_f32 v53, v63, v70
	v_mul_f32 v54, v64, v70
	v_mul_f32 v55, v65, v70
	v_cvt_pk_bf16_f32 v34, v34, v35
	v_cvt_pk_bf16_f32 v35, v36, v37
	v_mul_f32 v36, v46, v70
	v_mul_f32 v37, v47, v70
	v_mul_f32 v38, v48, v70
	v_mul_f32 v39, v49, v70
	v_cvt_pk_bf16_f32 v18, v18, v19
	v_cvt_pk_bf16_f32 v19, v20, v21
	v_mul_f32 v20, v30, v70
	v_mul_f32 v21, v31, v70
	v_mul_f32 v22, v32, v70
	v_mul_f32 v23, v33, v70
	v_cvt_pk_bf16_f32 v2, v2, v3
	v_cvt_pk_bf16_f32 v3, v4, v5
	v_mul_f32 v4, v14, v70
	v_mul_f32 v5, v15, v70
	v_mul_f32 v6, v16, v70
	v_mul_f32 v7, v17, v70
	v_cvt_pk_bf16_f32 v52, v52, v53
	v_cvt_pk_bf16_f32 v53, v54, v55
	v_cvt_pk_bf16_f32 v36, v36, v37
	v_cvt_pk_bf16_f32 v37, v38, v39
	v_cvt_pk_bf16_f32 v20, v20, v21
	v_cvt_pk_bf16_f32 v21, v22, v23
	v_cvt_pk_bf16_f32 v4, v4, v5
	v_cvt_pk_bf16_f32 v5, v6, v7
	v_permlane32_swap_b32_e32 v50, v52
	v_permlane32_swap_b32_e32 v51, v53
	v_permlane32_swap_b32_e32 v34, v36
	v_permlane32_swap_b32_e32 v35, v37
	v_permlane32_swap_b32_e32 v18, v20
	v_permlane32_swap_b32_e32 v19, v21
	v_permlane32_swap_b32_e32 v2, v4
	v_permlane32_swap_b32_e32 v3, v5
	global_store_dwordx4 v[66:67], v[50:53], off offset:32
	global_store_dwordx4 v[66:67], v[34:37], off offset:96
	global_store_dwordx4 v[66:67], v[18:21], off offset:160
	global_store_dwordx4 v[66:67], v[2:5], off offset:224
	s_cbranch_scc0 .LBB0_2286
.LBB0_2269:
	s_and_b32 s50, s2, 12
	s_add_i32 s51, s50, s3
	s_and_b32 s50, s27, 0x60000
	s_or_b32 s50, s50, s20
	s_and_b32 s53, s25, 0xfff80000
	s_or_b32 s50, s50, s53
	s_lshl_b32 s53, s51, 7
	s_add_i32 s50, s50, s53
	s_lshl_b32 s51, s51, 2
	v_readlane_b32 s56, v249, 3
	v_mov_b32_e32 v2, s51
	v_readlane_b32 s62, v249, 9
	v_readlane_b32 s63, v249, 10
	v_add_u32_e32 v192, s50, v1
	v_or_b32_e32 v4, 16, v192
	v_mov_b32_e32 v5, v193
	v_lshl_add_u64 v[4:5], v[4:5], 1, s[8:9]
	s_ashr_i32 s52, s2, 2
	global_load_dword v207, v2, s[62:63]
	s_waitcnt lgkmcnt(0)
	s_barrier
	v_lshl_add_u64 v[2:3], v[192:193], 1, s[8:9]
	global_load_dwordx4 v[126:129], v[2:3], off
	global_load_dwordx4 v[122:125], v[4:5], off
	v_or_b32_e32 v2, 32, v192
	v_mov_b32_e32 v3, v193
	v_lshl_add_u64 v[2:3], v[2:3], 1, s[8:9]
	v_or_b32_e32 v4, 48, v192
	v_mov_b32_e32 v5, v193
	v_lshl_add_u64 v[4:5], v[4:5], 1, s[8:9]
	global_load_dwordx4 v[118:121], v[2:3], off
	global_load_dwordx4 v[114:117], v[4:5], off
	v_or_b32_e32 v2, 64, v192
	v_mov_b32_e32 v3, v193
	v_lshl_add_u64 v[2:3], v[2:3], 1, s[8:9]
	v_or_b32_e32 v4, 0x50, v192
	v_mov_b32_e32 v5, v193
	v_lshl_add_u64 v[4:5], v[4:5], 1, s[8:9]
	global_load_dwordx4 v[110:113], v[2:3], off
	global_load_dwordx4 v[102:105], v[4:5], off
	v_or_b32_e32 v2, 0x60, v192
	v_mov_b32_e32 v3, v193
	v_lshl_add_u64 v[2:3], v[2:3], 1, s[8:9]
	v_or_b32_e32 v192, 0x70, v192
	v_lshl_add_u64 v[4:5], v[192:193], 1, s[8:9]
	global_load_dwordx4 v[106:109], v[2:3], off
	global_load_dwordx4 v[98:101], v[4:5], off
	s_ashr_i32 s53, s52, 31
	s_lshl_b64 s[52:53], s[52:53], 16
	s_add_u32 s54, s21, s52
	s_addc_u32 s55, s22, s53
	s_mov_b32 m0, s29
	s_add_u32 s52, s23, s52
	v_lshl_add_u64 v[2:3], s[54:55], 0, v[190:191]
	s_addc_u32 s53, s24, s53
	global_load_lds_dwordx4 v[2:3], off
	v_lshl_add_u64 v[4:5], v[2:3], 0, s[0:1]
	s_mov_b32 m0, s30
	v_cmp_lt_i32_e32 vcc, v203, v204
	global_load_lds_dwordx4 v[4:5], off
	v_lshl_add_u64 v[4:5], s[52:53], 0, v[190:191]
	s_mov_b32 m0, s31
	v_lshl_add_u64 v[6:7], v[4:5], 0, s[0:1]
	global_load_lds_dwordx4 v[4:5], off
	s_mov_b32 m0, s33
	v_readlane_b32 s57, v249, 4
	global_load_lds_dwordx4 v[6:7], off
	v_lshl_add_u64 v[6:7], v[2:3], 0, s[4:5]
	s_mov_b32 m0, s34
	v_readlane_b32 s58, v249, 5
	global_load_lds_dwordx4 v[6:7], off
	v_lshl_add_u64 v[6:7], v[2:3], 0, s[10:11]
	s_mov_b32 m0, s35
	v_readlane_b32 s59, v249, 6
	global_load_lds_dwordx4 v[6:7], off
	v_lshl_add_u64 v[6:7], v[4:5], 0, s[4:5]
	s_mov_b32 m0, s36
	v_readlane_b32 s60, v249, 7
	global_load_lds_dwordx4 v[6:7], off
	v_lshl_add_u64 v[6:7], v[4:5], 0, s[10:11]
	s_mov_b32 m0, s37
	v_readlane_b32 s61, v249, 8
	global_load_lds_dwordx4 v[6:7], off
	v_lshl_add_u64 v[6:7], v[2:3], 0, s[12:13]
	s_mov_b32 m0, s38
	s_nop 0
	global_load_lds_dwordx4 v[6:7], off
	v_lshl_add_u64 v[6:7], v[2:3], 0, s[14:15]
	s_mov_b32 m0, s39
	s_nop 0
	global_load_lds_dwordx4 v[6:7], off
	v_lshl_add_u64 v[6:7], v[4:5], 0, s[12:13]
	s_mov_b32 m0, s40
	s_nop 0
	global_load_lds_dwordx4 v[6:7], off
	v_lshl_add_u64 v[6:7], v[4:5], 0, s[14:15]
	s_mov_b32 m0, s41
	s_nop 0
	global_load_lds_dwordx4 v[6:7], off
	s_waitcnt vmcnt(8)
	s_waitcnt lgkmcnt(0)
	s_barrier
	v_lshl_add_u64 v[6:7], v[2:3], 0, s[16:17]
	s_mov_b32 m0, s42
	v_lshl_add_u64 v[2:3], v[2:3], 0, s[18:19]
	global_load_lds_dwordx4 v[6:7], off
	s_mov_b32 m0, s43
	s_nop 0
	global_load_lds_dwordx4 v[2:3], off
	v_lshl_add_u64 v[2:3], v[4:5], 0, s[16:17]
	s_mov_b32 m0, s44
	s_nop 0
	global_load_lds_dwordx4 v[2:3], off
	v_lshl_add_u64 v[2:3], v[4:5], 0, s[18:19]
	s_mov_b32 m0, s45
	s_nop 0
	global_load_lds_dwordx4 v[2:3], off
	ds_read_b128 v[2:5], v195 offset:0
	ds_read_b128 v[6:9], v195 offset:0x400
	ds_read_b128 v[10:13], v195 offset:0x800
	ds_read_b128 v[14:17], v195 offset:0xc00
	ds_read_b128 v[34:37], v195 offset:0x1000
	ds_read_b128 v[38:41], v195 offset:0x1400
	ds_read_b128 v[42:45], v195 offset:0x1800
	ds_read_b128 v[46:49], v195 offset:0x1c00
	ds_read_b128 v[50:53], v195 offset:0x2000
	ds_read_b128 v[54:57], v195 offset:0x2400
	ds_read_b128 v[58:61], v195 offset:0x2800
	ds_read_b128 v[62:65], v195 offset:0x2c00
	ds_read_b128 v[130:133], v195 offset:0x3000
	ds_read_b128 v[134:137], v195 offset:0x3400
	ds_read_b128 v[138:141], v195 offset:0x3800
	ds_read_b128 v[170:173], v195 offset:0x3c00
	s_nop 0
	s_waitcnt lgkmcnt(8)
	s_waitcnt vmcnt(0)
	v_mfma_f32_32x32x16_bf16 v[18:33], v[2:5], v[126:129], 0
	v_cndmask_b32_e32 v3, v202, v203, vcc
	v_lshlrev_b32_e32 v192, 2, v3
	v_mfma_f32_32x32x16_bf16 v[18:33], v[6:9], v[122:125], v[18:33]
	v_mfma_f32_32x32x16_bf16 v[18:33], v[10:13], v[118:121], v[18:33]
	v_mfma_f32_32x32x16_bf16 v[18:33], v[14:17], v[114:117], v[18:33]
	v_mfma_f32_32x32x16_bf16 v[18:33], v[34:37], v[110:113], v[18:33]
	ds_read_b128 v[34:37], v195 offset:0x4000
	ds_read_b128 v[174:177], v195 offset:0x4400
	ds_read_b128 v[178:181], v195 offset:0x4800
	ds_read_b128 v[182:185], v195 offset:0x4c00
	ds_read_b128 v[94:97], v195 offset:0x5000
	ds_read_b128 v[90:93], v195 offset:0x5400
	ds_read_b128 v[86:89], v195 offset:0x5800
	ds_read_b128 v[82:85], v195 offset:0x5c00
	s_waitcnt lgkmcnt(8)
	v_mfma_f32_32x32x16_bf16 v[18:33], v[38:41], v[102:105], v[18:33]
	ds_read_b128 v[158:161], v195 offset:0x6000
	ds_read_b128 v[154:157], v195 offset:0x6400
	ds_read_b128 v[150:153], v195 offset:0x6800
	ds_read_b128 v[146:149], v195 offset:0x6c00
	ds_read_b128 v[142:145], v195 offset:0x7000
	v_mfma_f32_32x32x16_bf16 v[66:81], v[50:53], v[126:129], 0
	v_mfma_f32_32x32x16_bf16 v[66:81], v[54:57], v[122:125], v[66:81]
	v_mfma_f32_32x32x16_bf16 v[18:33], v[42:45], v[106:109], v[18:33]
	v_mfma_f32_32x32x16_bf16 v[66:81], v[58:61], v[118:121], v[66:81]
	v_mfma_f32_32x32x16_bf16 v[18:33], v[46:49], v[98:101], v[18:33]
	v_mfma_f32_32x32x16_bf16 v[66:81], v[62:65], v[114:117], v[66:81]
	s_nop 10
	v_max3_f32 v2, v18, s46, v19
	v_max3_f32 v2, v2, v20, v21
	v_max3_f32 v2, v2, v22, v23
	v_max3_f32 v2, v2, v24, v25
	v_max3_f32 v2, v2, v26, v27
	v_max3_f32 v2, v2, v28, v29
	v_max3_f32 v2, v2, v30, v31
	v_mfma_f32_32x32x16_bf16 v[66:81], v[130:133], v[110:113], v[66:81]
	v_max3_f32 v2, v2, v32, v33
	v_mul_f32_e32 v2, 0x3e0293ee, v2
	ds_bpermute_b32 v3, v192, v2
	s_waitcnt lgkmcnt(0)
	v_max_f32_e32 v3, v3, v3
	v_mfma_f32_32x32x16_bf16 v[66:81], v[134:137], v[102:105], v[66:81]
	v_max_f32_e32 v2, v2, v3
	v_max_f32_e32 v17, 0xf149f2ca, v2
	v_add_f32_e32 v2, 0x7149f2ca, v2
	v_cmp_ge_f32_e32 vcc, s48, v2
	s_cmp_eq_u64 vcc, exec
	s_cselect_b64 vcc, -1, 0
	v_cndmask_b32_e32 v208, v17, v206, vcc
	v_mfma_f32_32x32x16_bf16 v[66:81], v[138:141], v[106:109], v[66:81]
	v_sub_f32_e32 v3, 0xf149f2ca, v17
	v_fma_f32 v17, v18, s47, -v208
	v_exp_f32_e32 v18, v17
	v_fma_f32 v17, v19, s47, -v208
	v_exp_f32_e32 v19, v17
	v_fma_f32 v17, v20, s47, -v208
	v_exp_f32_e32 v20, v17
	v_mfma_f32_32x32x16_bf16 v[66:81], v[170:173], v[98:101], v[66:81]
	v_fma_f32 v21, v21, s47, -v208
	v_add_f32_e32 v38, 0, v18
	v_exp_f32_e32 v21, v21
	v_fma_f32 v22, v22, s47, -v208
	v_add_f32_e32 v38, v19, v38
	v_exp_f32_e32 v22, v22
	v_fma_f32 v23, v23, s47, -v208
	v_cvt_pk_bf16_f32 v186, v18, v19
	v_fma_f32 v19, v29, s47, -v208
	v_exp_f32_e32 v23, v23
	v_fma_f32 v24, v24, s47, -v208
	v_exp_f32_e32 v165, v19
	v_fma_f32 v19, v30, s47, -v208
	v_add_f32_e32 v38, v20, v38
	v_exp_f32_e32 v24, v24
	v_fma_f32 v25, v25, s47, -v208
	v_exp_f32_e32 v166, v19
	v_fma_f32 v19, v31, s47, -v208
	v_add_f32_e32 v38, v21, v38
	v_exp_f32_e32 v25, v25
	v_fma_f32 v26, v26, s47, -v208
	v_exp_f32_e32 v167, v19
	v_fma_f32 v19, v32, s47, -v208
	v_add_f32_e32 v38, v22, v38
	v_exp_f32_e32 v162, v26
	v_fma_f32 v26, v27, s47, -v208
	v_exp_f32_e32 v168, v19
	v_fma_f32 v19, v33, s47, -v208
	v_add_f32_e32 v38, v23, v38
	v_exp_f32_e32 v163, v26
	v_fma_f32 v27, v28, s47, -v208
	v_exp_f32_e32 v169, v19
	v_max3_f32 v19, v66, s46, v67
	v_add_f32_e32 v38, v24, v38
	v_exp_f32_e32 v164, v27
	v_max3_f32 v19, v19, v68, v69
	v_add_f32_e32 v26, v25, v38
	v_max3_f32 v19, v19, v70, v71
	v_add_f32_e32 v26, v162, v26
	v_max3_f32 v19, v19, v72, v73
	v_exp_f32_e32 v3, v3
	v_add_f32_e32 v26, v163, v26
	v_max3_f32 v19, v19, v74, v75
	v_add_f32_e32 v18, v164, v26
	v_max3_f32 v19, v19, v76, v77
	v_add_f32_e32 v18, v165, v18
	v_max3_f32 v19, v19, v78, v79
	v_add_f32_e32 v18, v166, v18
	v_max3_f32 v19, v19, v80, v81
	v_mul_f32_e32 v2, 0, v3
	v_add_f32_e32 v18, v167, v18
	v_mul_f32_e32 v171, 0x3e0293ee, v19
	v_cndmask_b32_e64 v2, v2, 0, vcc
	ds_bpermute_b32 v172, v192, v171
	v_add_f32_e32 v170, v168, v18
	v_mov_b32_e32 v3, v2
	v_mov_b32_e32 v4, v2
	v_mov_b32_e32 v5, v2
	v_mov_b32_e32 v6, v2
	v_mov_b32_e32 v7, v2
	v_mov_b32_e32 v8, v2
	v_mov_b32_e32 v9, v2
	v_mov_b32_e32 v10, v2
	v_mov_b32_e32 v11, v2
	v_mov_b32_e32 v12, v2
	v_mov_b32_e32 v13, v2
	v_mov_b32_e32 v14, v2
	v_mov_b32_e32 v15, v2
	v_mov_b32_e32 v16, v2
	v_mov_b32_e32 v17, v2
	v_cvt_pk_bf16_f32 v187, v20, v21
	v_cvt_pk_bf16_f32 v188, v22, v23
	v_cvt_pk_bf16_f32 v189, v24, v25
	ds_read_b128 v[138:141], v195 offset:0x7400
	ds_read_b128 v[134:137], v195 offset:0x7800
	ds_read_b128 v[130:133], v195 offset:0x7c00
	s_waitcnt lgkmcnt(8)
	v_add_f32_e32 v170, v169, v170
	s_nop 0
	v_mfma_f32_32x32x16_bf16 v[50:65], v[34:37], v[186:189], v[2:17]
	v_add_f32_e32 v170, v2, v170
	s_waitcnt lgkmcnt(0)
	v_max_f32_e32 v172, v172, v172
	v_max_f32_e32 v171, v171, v172
	v_sub_f32_e32 v172, v171, v208
	v_cmp_ge_f32_e32 vcc, s48, v172
	s_cmp_eq_u64 vcc, exec
	v_mfma_f32_32x32x16_bf16 v[34:49], v[174:177], v[186:189], v[2:17]
	v_mfma_f32_32x32x16_bf16 v[18:33], v[178:181], v[186:189], v[2:17]
	v_mfma_f32_32x32x16_bf16 v[2:17], v[182:185], v[186:189], v[2:17]
	s_cbranch_scc1 .LBB0_2271
	v_max_f32_e32 v171, v171, v171
	v_max_f32_e32 v172, v208, v208
	v_max_f32_e32 v173, v172, v171
	v_sub_f32_e32 v171, v208, v173
	v_exp_f32_e32 v172, v171
	v_xor_b32_e32 v171, 0x80000000, v173
	v_mov_b32_e32 v208, v173
	v_mul_f32_e32 v170, v170, v172
	v_mul_f32 v64, v64, v172
	v_mul_f32 v65, v65, v172
	v_mul_f32 v62, v62, v172
	v_mul_f32 v63, v63, v172
	v_mul_f32 v60, v60, v172
	v_mul_f32 v61, v61, v172
	v_mul_f32 v58, v58, v172
	v_mul_f32 v59, v59, v172
	v_mul_f32 v56, v56, v172
	v_mul_f32 v57, v57, v172
	v_mul_f32 v54, v54, v172
	v_mul_f32 v55, v55, v172
	v_mul_f32 v52, v52, v172
	v_mul_f32 v53, v53, v172
	v_mul_f32 v50, v50, v172
	v_mul_f32 v51, v51, v172
	v_mul_f32 v48, v48, v172
	v_mul_f32 v49, v49, v172
	v_mul_f32 v46, v46, v172
	v_mul_f32 v47, v47, v172
	v_mul_f32 v44, v44, v172
	v_mul_f32 v45, v45, v172
	v_mul_f32 v42, v42, v172
	v_mul_f32 v43, v43, v172
	v_mul_f32 v40, v40, v172
	v_mul_f32 v41, v41, v172
	v_mul_f32 v38, v38, v172
	v_mul_f32 v39, v39, v172
	v_mul_f32 v36, v36, v172
	v_mul_f32 v37, v37, v172
	v_mul_f32 v34, v34, v172
	v_mul_f32 v35, v35, v172
	v_mul_f32 v32, v32, v172
	v_mul_f32 v33, v33, v172
	v_mul_f32 v30, v30, v172
	v_mul_f32 v31, v31, v172
	v_mul_f32 v28, v28, v172
	v_mul_f32 v29, v29, v172
	v_mul_f32 v26, v26, v172
	v_mul_f32 v27, v27, v172
	v_mul_f32 v24, v24, v172
	v_mul_f32 v25, v25, v172
	v_mul_f32 v22, v22, v172
	v_mul_f32 v23, v23, v172
	v_mul_f32 v20, v20, v172
	v_mul_f32 v21, v21, v172
	v_mul_f32 v18, v18, v172
	v_mul_f32 v19, v19, v172
	v_mul_f32 v16, v16, v172
	v_mul_f32 v17, v17, v172
	v_mul_f32 v14, v14, v172
	v_mul_f32 v15, v15, v172
	v_mul_f32 v12, v12, v172
	v_mul_f32 v13, v13, v172
	v_mul_f32 v10, v10, v172
	v_mul_f32 v11, v11, v172
	v_mul_f32 v8, v8, v172
	v_mul_f32 v9, v9, v172
	v_mul_f32 v6, v6, v172
	v_mul_f32 v7, v7, v172
	v_mul_f32 v4, v4, v172
	v_mul_f32 v5, v5, v172
	v_mul_f32 v2, v2, v172
	v_mul_f32 v3, v3, v172
	s_branch .LBB0_2272

.LBB0_2272:
	v_cvt_pk_bf16_f32 v162, v162, v163
	v_cvt_pk_bf16_f32 v163, v164, v165
	v_cvt_pk_bf16_f32 v164, v166, v167
	v_cvt_pk_bf16_f32 v165, v168, v169
	v_fmamk_f32 v66, v66, 0x3e0293ee, v171
	s_waitcnt lgkmcnt(0)
	s_waitcnt vmcnt(8)
	s_waitcnt lgkmcnt(0)
	s_barrier
	v_mfma_f32_32x32x16_bf16 v[50:65], v[94:97], v[162:165], v[50:65]
	v_mfma_f32_32x32x16_bf16 v[34:49], v[90:93], v[162:165], v[34:49]
	v_mfma_f32_32x32x16_bf16 v[18:33], v[86:89], v[162:165], v[18:33]
	v_mfma_f32_32x32x16_bf16 v[2:17], v[82:85], v[162:165], v[2:17]
	v_exp_f32_e32 v162, v66
	v_fmamk_f32 v66, v67, 0x3e0293ee, v171
	v_exp_f32_e32 v163, v66
	v_fmamk_f32 v66, v68, 0x3e0293ee, v171
	v_exp_f32_e32 v164, v66
	v_fmamk_f32 v66, v69, 0x3e0293ee, v171
	v_exp_f32_e32 v165, v66
	v_fmamk_f32 v66, v70, 0x3e0293ee, v171
	v_exp_f32_e32 v180, v66
	v_fmamk_f32 v66, v71, 0x3e0293ee, v171
	v_exp_f32_e32 v181, v66
	v_fmamk_f32 v66, v72, 0x3e0293ee, v171
	v_exp_f32_e32 v182, v66
	v_fmamk_f32 v66, v73, 0x3e0293ee, v171
	v_exp_f32_e32 v183, v66
	v_fmamk_f32 v70, v74, 0x3e0293ee, v171
	v_exp_f32_e32 v184, v70
	v_fmamk_f32 v70, v75, 0x3e0293ee, v171
	v_exp_f32_e32 v185, v70
	v_fmamk_f32 v70, v76, 0x3e0293ee, v171
	v_cvt_pk_bf16_f32 v66, v162, v163
	v_cvt_pk_bf16_f32 v67, v164, v165
	v_cvt_pk_bf16_f32 v68, v180, v181
	v_cvt_pk_bf16_f32 v69, v182, v183
	v_exp_f32_e32 v186, v70
	v_fmamk_f32 v70, v77, 0x3e0293ee, v171
	v_mfma_f32_32x32x16_bf16 v[50:65], v[158:161], v[66:69], v[50:65]
	v_exp_f32_e32 v210, v70
	v_fmamk_f32 v70, v78, 0x3e0293ee, v171
	v_exp_f32_e32 v220, v70
	v_fmamk_f32 v70, v79, 0x3e0293ee, v171
	v_exp_f32_e32 v221, v70
	v_fmamk_f32 v70, v80, 0x3e0293ee, v171
	v_fmac_f32_e32 v171, 0x3e0293ee, v81
	v_mfma_f32_32x32x16_bf16 v[34:49], v[154:157], v[66:69], v[34:49]
	v_exp_f32_e32 v222, v70
	v_exp_f32_e32 v171, v171
	v_mfma_f32_32x32x16_bf16 v[18:33], v[150:153], v[66:69], v[18:33]
	v_mfma_f32_32x32x16_bf16 v[2:17], v[146:149], v[66:69], v[2:17]
	v_cvt_pk_bf16_f32 v66, v184, v185
	v_cvt_pk_bf16_f32 v67, v186, v210
	v_cvt_pk_bf16_f32 v68, v220, v221
	v_cvt_pk_bf16_f32 v69, v222, v171
	s_nop 1
	v_mfma_f32_32x32x16_bf16 v[50:65], v[142:145], v[66:69], v[50:65]
	v_mfma_f32_32x32x16_bf16 v[34:49], v[138:141], v[66:69], v[34:49]
	v_mfma_f32_32x32x16_bf16 v[18:33], v[134:137], v[66:69], v[18:33]
	v_mfma_f32_32x32x16_bf16 v[2:17], v[130:133], v[66:69], v[2:17]
	ds_read_b128 v[66:69], v197 offset:0
	ds_read_b128 v[70:73], v197 offset:0x400
	ds_read_b128 v[74:77], v197 offset:0x800
	ds_read_b128 v[78:81], v197 offset:0xc00
	ds_read_b128 v[130:133], v197 offset:0x1000
	ds_read_b128 v[134:137], v197 offset:0x1400
	ds_read_b128 v[138:141], v197 offset:0x1800
	ds_read_b128 v[142:145], v197 offset:0x1c00
	ds_read_b128 v[172:175], v197 offset:0x2000
	ds_read_b128 v[176:179], v197 offset:0x2400
	ds_read_b128 v[212:215], v197 offset:0x2800
	ds_read_b128 v[216:219], v197 offset:0x2c00
	ds_read_b128 v[166:169], v197 offset:0x3000
	ds_read_b128 v[158:161], v197 offset:0x3400
	ds_read_b128 v[154:157], v197 offset:0x3800
	ds_read_b128 v[146:149], v197 offset:0x3c00
	s_nop 0
	s_waitcnt lgkmcnt(8)
	s_nop 0
	v_mfma_f32_32x32x16_bf16 v[82:97], v[66:69], v[126:129], 0
	v_add_f32_e32 v66, 0, v162
	v_add_f32_e32 v66, v163, v66
	v_add_f32_e32 v66, v164, v66
	v_add_f32_e32 v66, v165, v66
	v_add_f32_e32 v66, v180, v66
	v_add_f32_e32 v66, v181, v66
	v_add_f32_e32 v66, v182, v66
	v_mfma_f32_32x32x16_bf16 v[82:97], v[70:73], v[122:125], v[82:97]
	v_add_f32_e32 v66, v183, v66
	v_add_f32_e32 v66, v184, v66
	v_add_f32_e32 v66, v185, v66
	v_add_f32_e32 v180, v186, v66
	ds_read_b128 v[186:189], v197 offset:0x4000
	ds_read_b128 v[182:185], v197 offset:0x4400
	ds_read_b128 v[162:165], v197 offset:0x4800
	v_mfma_f32_32x32x16_bf16 v[82:97], v[74:77], v[118:121], v[82:97]
	ds_read_b128 v[150:153], v197 offset:0x4c00
	v_mfma_f32_32x32x16_bf16 v[82:97], v[78:81], v[114:117], v[82:97]
	v_mfma_f32_32x32x16_bf16 v[82:97], v[130:133], v[110:113], v[82:97]
	v_mfma_f32_32x32x16_bf16 v[82:97], v[134:137], v[102:105], v[82:97]
	v_mfma_f32_32x32x16_bf16 v[82:97], v[138:141], v[106:109], v[82:97]
	v_mfma_f32_32x32x16_bf16 v[82:97], v[142:145], v[98:101], v[82:97]
	ds_read_b128 v[142:145], v197 offset:0x5000
	ds_read_b128 v[138:141], v197 offset:0x5400
	ds_read_b128 v[134:137], v197 offset:0x5800
	ds_read_b128 v[130:133], v197 offset:0x5c00
	s_waitcnt lgkmcnt(8)
	s_nop 0
	v_mfma_f32_32x32x16_bf16 v[66:81], v[172:175], v[126:129], 0
	s_nop 9
	v_max3_f32 v173, v82, s46, v83
	v_max3_f32 v173, v173, v84, v85
	v_max3_f32 v173, v173, v86, v87
	v_max3_f32 v173, v173, v88, v89
	v_max3_f32 v173, v173, v90, v91
	v_max3_f32 v173, v173, v92, v93
	v_max3_f32 v173, v173, v94, v95
	v_mfma_f32_32x32x16_bf16 v[66:81], v[176:179], v[122:125], v[66:81]
	v_max3_f32 v173, v173, v96, v97
	v_mul_f32_e32 v173, 0x3e0293ee, v173
	v_add_f32_e32 v172, v210, v180
	ds_bpermute_b32 v174, v192, v173
	v_add_f32_e32 v172, v220, v172
	v_add_f32_e32 v172, v221, v172
	v_add_f32_e32 v172, v222, v172
	v_mfma_f32_32x32x16_bf16 v[66:81], v[212:215], v[118:121], v[66:81]
	v_add_f32_e32 v171, v171, v172
	v_add_f32_e32 v210, v170, v171
	s_waitcnt lgkmcnt(0)
	v_max_f32_e32 v170, v174, v174
	v_max_f32_e32 v170, v173, v170
	v_sub_f32_e32 v171, v170, v208
	v_cmp_ge_f32_e32 vcc, s48, v171
	s_cmp_eq_u64 vcc, exec
	v_mfma_f32_32x32x16_bf16 v[66:81], v[216:219], v[114:117], v[66:81]
	s_cbranch_scc1 .LBB0_2274
	v_max_f32_e32 v170, v170, v170
	v_max_f32_e32 v171, v208, v208
	v_max_f32_e32 v171, v171, v170
	v_sub_f32_e32 v170, v208, v171
	v_exp_f32_e32 v170, v170
	v_mov_b32_e32 v208, v171
	v_mul_f32_e32 v210, v210, v170
	v_mul_f32 v64, v64, v170
	v_mul_f32 v65, v65, v170
	v_mul_f32 v62, v62, v170
	v_mul_f32 v63, v63, v170
	v_mul_f32 v60, v60, v170
	v_mul_f32 v61, v61, v170
	v_mul_f32 v58, v58, v170
	v_mul_f32 v59, v59, v170
	v_mul_f32 v56, v56, v170
	v_mul_f32 v57, v57, v170
	v_mul_f32 v54, v54, v170
	v_mul_f32 v55, v55, v170
	v_mul_f32 v52, v52, v170
	v_mul_f32 v53, v53, v170
	v_mul_f32 v50, v50, v170
	v_mul_f32 v51, v51, v170
	v_mul_f32 v48, v48, v170
	v_mul_f32 v49, v49, v170
	v_mul_f32 v46, v46, v170
	v_mul_f32 v47, v47, v170
	v_mul_f32 v44, v44, v170
	v_mul_f32 v45, v45, v170
	v_mul_f32 v42, v42, v170
	v_mul_f32 v43, v43, v170
	v_mul_f32 v40, v40, v170
	v_mul_f32 v41, v41, v170
	v_mul_f32 v38, v38, v170
	v_mul_f32 v39, v39, v170
	v_mul_f32 v36, v36, v170
	v_mul_f32 v37, v37, v170
	v_mul_f32 v34, v34, v170
	v_mul_f32 v35, v35, v170
	v_mul_f32 v32, v32, v170
	v_mul_f32 v33, v33, v170
	v_mul_f32 v30, v30, v170
	v_mul_f32 v31, v31, v170
	v_mul_f32 v28, v28, v170
	v_mul_f32 v29, v29, v170
	v_mul_f32 v26, v26, v170
	v_mul_f32 v27, v27, v170
	v_mul_f32 v24, v24, v170
	v_mul_f32 v25, v25, v170
	v_mul_f32 v22, v22, v170
	v_mul_f32 v23, v23, v170
	v_mul_f32 v20, v20, v170
	v_mul_f32 v21, v21, v170
	v_mul_f32 v18, v18, v170
	v_mul_f32 v19, v19, v170
	v_mul_f32 v16, v16, v170
	v_mul_f32 v17, v17, v170
	v_mul_f32 v14, v14, v170
	v_mul_f32 v15, v15, v170
	v_mul_f32 v12, v12, v170
	v_mul_f32 v13, v13, v170
	v_mul_f32 v10, v10, v170
	v_mul_f32 v11, v11, v170
	v_mul_f32 v8, v8, v170
	v_mul_f32 v9, v9, v170
	v_mul_f32 v6, v6, v170
	v_mul_f32 v7, v7, v170
	v_mul_f32 v4, v4, v170
	v_mul_f32 v5, v5, v170
	v_mul_f32 v2, v2, v170
	v_mul_f32 v3, v3, v170
.LBB0_2274:
	v_mfma_f32_32x32x16_bf16 v[66:81], v[166:169], v[110:113], v[66:81]
	v_fma_f32 v82, v82, s47, -v208
	v_exp_f32_e32 v82, v82
	v_fma_f32 v83, v83, s47, -v208
	v_exp_f32_e32 v83, v83
	v_fma_f32 v84, v84, s47, -v208
	v_exp_f32_e32 v84, v84
	v_fma_f32 v85, v85, s47, -v208
	v_mfma_f32_32x32x16_bf16 v[66:81], v[158:161], v[102:105], v[66:81]
	v_exp_f32_e32 v85, v85
	v_fma_f32 v86, v86, s47, -v208
	v_add_f32_e32 v170, 0, v82
	v_exp_f32_e32 v86, v86
	v_fma_f32 v87, v87, s47, -v208
	v_add_f32_e32 v170, v83, v170
	v_exp_f32_e32 v87, v87
	v_mfma_f32_32x32x16_bf16 v[66:81], v[154:157], v[106:109], v[66:81]
	v_fma_f32 v88, v88, s47, -v208
	v_add_f32_e32 v170, v84, v170
	v_exp_f32_e32 v88, v88
	v_fma_f32 v89, v89, s47, -v208
	v_add_f32_e32 v170, v85, v170
	v_exp_f32_e32 v89, v89
	v_fma_f32 v90, v90, s47, -v208
	v_mfma_f32_32x32x16_bf16 v[66:81], v[146:149], v[98:101], v[66:81]
	v_add_f32_e32 v170, v86, v170
	v_exp_f32_e32 v90, v90
	v_fma_f32 v91, v91, s47, -v208
	v_add_f32_e32 v170, v87, v170
	v_exp_f32_e32 v91, v91
	v_fma_f32 v92, v92, s47, -v208
	v_add_f32_e32 v170, v88, v170
	s_nop 4
	v_max3_f32 v146, v66, s46, v67
	v_max3_f32 v146, v146, v68, v69
	v_max3_f32 v146, v146, v70, v71
	v_max3_f32 v146, v146, v72, v73
	v_max3_f32 v146, v146, v74, v75
	v_max3_f32 v146, v146, v76, v77
	v_max3_f32 v146, v146, v78, v79
	v_max3_f32 v146, v146, v80, v81
	v_exp_f32_e32 v92, v92
	v_fma_f32 v93, v93, s47, -v208
	v_mul_f32_e32 v146, 0x3e0293ee, v146
	v_add_f32_e32 v166, v89, v170
	v_exp_f32_e32 v93, v93
	v_fma_f32 v94, v94, s47, -v208
	ds_bpermute_b32 v147, v192, v146
	v_add_f32_e32 v166, v90, v166
	v_cvt_pk_bf16_f32 v212, v82, v83
	v_cvt_pk_bf16_f32 v213, v84, v85
	v_cvt_pk_bf16_f32 v214, v86, v87
	v_cvt_pk_bf16_f32 v215, v88, v89
	v_exp_f32_e32 v94, v94
	v_fma_f32 v95, v95, s47, -v208
	v_add_f32_e32 v216, v91, v166
	ds_read_b128 v[178:181], v197 offset:0x6000
	ds_read_b128 v[174:177], v197 offset:0x6400
	ds_read_b128 v[170:173], v197 offset:0x6800
	ds_read_b128 v[166:169], v197 offset:0x6c00
	ds_read_b128 v[158:161], v197 offset:0x7000
	ds_read_b128 v[154:157], v197 offset:0x7400
	ds_read_b128 v[86:89], v197 offset:0x7800
	ds_read_b128 v[82:85], v197 offset:0x7c00
	s_waitcnt lgkmcnt(8)
	v_exp_f32_e32 v95, v95
	v_mfma_f32_32x32x16_bf16 v[50:65], v[186:189], v[212:215], v[50:65]
	v_fma_f32 v96, v96, s47, -v208
	v_add_f32_e32 v186, v92, v216
	v_exp_f32_e32 v96, v96
	v_fma_f32 v97, v97, s47, -v208
	v_exp_f32_e32 v97, v97
	s_waitcnt lgkmcnt(0)
	v_max_f32_e32 v147, v147, v147
	v_max_f32_e32 v146, v146, v147
	v_mfma_f32_32x32x16_bf16 v[34:49], v[182:185], v[212:215], v[34:49]
	v_add_f32_e32 v182, v93, v186
	v_add_f32_e32 v182, v94, v182
	v_add_f32_e32 v182, v95, v182
	v_add_f32_e32 v148, v96, v182
	v_sub_f32_e32 v147, v146, v208
	v_add_f32_e32 v148, v97, v148
	v_cmp_ge_f32_e32 vcc, s48, v147
	v_mfma_f32_32x32x16_bf16 v[18:33], v[162:165], v[212:215], v[18:33]
	v_add_f32_e32 v210, v210, v148
	s_cmp_eq_u64 vcc, exec
	v_mfma_f32_32x32x16_bf16 v[2:17], v[150:153], v[212:215], v[2:17]
	s_cbranch_scc1 .LBB0_2276
	v_max_f32_e32 v146, v146, v146
	v_max_f32_e32 v147, v208, v208
	v_max_f32_e32 v147, v147, v146
	v_sub_f32_e32 v146, v208, v147
	v_exp_f32_e32 v146, v146
	v_mov_b32_e32 v208, v147
	v_mul_f32_e32 v210, v210, v146
	v_mul_f32 v64, v64, v146
	v_mul_f32 v65, v65, v146
	v_mul_f32 v62, v62, v146
	v_mul_f32 v63, v63, v146
	v_mul_f32 v60, v60, v146
	v_mul_f32 v61, v61, v146
	v_mul_f32 v58, v58, v146
	v_mul_f32 v59, v59, v146
	v_mul_f32 v56, v56, v146
	v_mul_f32 v57, v57, v146
	v_mul_f32 v54, v54, v146
	v_mul_f32 v55, v55, v146
	v_mul_f32 v52, v52, v146
	v_mul_f32 v53, v53, v146
	v_mul_f32 v50, v50, v146
	v_mul_f32 v51, v51, v146
	v_mul_f32 v48, v48, v146
	v_mul_f32 v49, v49, v146
	v_mul_f32 v46, v46, v146
	v_mul_f32 v47, v47, v146
	v_mul_f32 v44, v44, v146
	v_mul_f32 v45, v45, v146
	v_mul_f32 v42, v42, v146
	v_mul_f32 v43, v43, v146
	v_mul_f32 v40, v40, v146
	v_mul_f32 v41, v41, v146
	v_mul_f32 v38, v38, v146
	v_mul_f32 v39, v39, v146
	v_mul_f32 v36, v36, v146
	v_mul_f32 v37, v37, v146
	v_mul_f32 v34, v34, v146
	v_mul_f32 v35, v35, v146
	v_mul_f32 v32, v32, v146
	v_mul_f32 v33, v33, v146
	v_mul_f32 v30, v30, v146
	v_mul_f32 v31, v31, v146
	v_mul_f32 v28, v28, v146
	v_mul_f32 v29, v29, v146
	v_mul_f32 v26, v26, v146
	v_mul_f32 v27, v27, v146
	v_mul_f32 v24, v24, v146
	v_mul_f32 v25, v25, v146
	v_mul_f32 v22, v22, v146
	v_mul_f32 v23, v23, v146
	v_mul_f32 v20, v20, v146
	v_mul_f32 v21, v21, v146
	v_mul_f32 v18, v18, v146
	v_mul_f32 v19, v19, v146
	v_mul_f32 v16, v16, v146
	v_mul_f32 v17, v17, v146
	v_mul_f32 v14, v14, v146
	v_mul_f32 v15, v15, v146
	v_mul_f32 v12, v12, v146
	v_mul_f32 v13, v13, v146
	v_mul_f32 v10, v10, v146
	v_mul_f32 v11, v11, v146
	v_mul_f32 v8, v8, v146
	v_mul_f32 v9, v9, v146
	v_mul_f32 v6, v6, v146
	v_mul_f32 v7, v7, v146
	v_mul_f32 v4, v4, v146
	v_mul_f32 v5, v5, v146
	v_mul_f32 v2, v2, v146
	v_mul_f32 v3, v3, v146
	v_xor_b32_e32 v146, 0x80000000, v147
	s_branch .LBB0_2277

.LBB0_2277:
	v_fmamk_f32 v66, v66, 0x3e0293ee, v146
	v_exp_f32_e32 v150, v66
	v_fmamk_f32 v66, v67, 0x3e0293ee, v146
	v_exp_f32_e32 v151, v66
	v_fmamk_f32 v66, v68, 0x3e0293ee, v146
	v_exp_f32_e32 v152, v66
	v_fmamk_f32 v66, v69, 0x3e0293ee, v146
	v_cvt_pk_bf16_f32 v90, v90, v91
	v_cvt_pk_bf16_f32 v91, v92, v93
	v_cvt_pk_bf16_f32 v92, v94, v95
	v_cvt_pk_bf16_f32 v93, v96, v97
	v_exp_f32_e32 v153, v66
	v_fmamk_f32 v66, v70, 0x3e0293ee, v146
	v_mfma_f32_32x32x16_bf16 v[50:65], v[142:145], v[90:93], v[50:65]
	v_exp_f32_e32 v162, v66
	v_fmamk_f32 v66, v71, 0x3e0293ee, v146
	v_exp_f32_e32 v163, v66
	v_fmamk_f32 v66, v72, 0x3e0293ee, v146
	v_exp_f32_e32 v164, v66
	v_fmamk_f32 v66, v73, 0x3e0293ee, v146
	v_exp_f32_e32 v165, v66
	v_mfma_f32_32x32x16_bf16 v[34:49], v[138:141], v[90:93], v[34:49]
	v_fmamk_f32 v70, v74, 0x3e0293ee, v146
	v_exp_f32_e32 v182, v70
	v_fmamk_f32 v70, v75, 0x3e0293ee, v146
	v_exp_f32_e32 v183, v70
	v_fmamk_f32 v70, v76, 0x3e0293ee, v146
	v_cvt_pk_bf16_f32 v66, v150, v151
	v_cvt_pk_bf16_f32 v67, v152, v153
	v_mfma_f32_32x32x16_bf16 v[18:33], v[134:137], v[90:93], v[18:33]
	v_cvt_pk_bf16_f32 v68, v162, v163
	v_cvt_pk_bf16_f32 v69, v164, v165
	v_exp_f32_e32 v184, v70
	v_fmamk_f32 v70, v77, 0x3e0293ee, v146
	s_waitcnt lgkmcnt(0)
	v_exp_f32_e32 v216, v70
	v_fmamk_f32 v70, v78, 0x3e0293ee, v146
	v_mfma_f32_32x32x16_bf16 v[2:17], v[130:133], v[90:93], v[2:17]
	v_exp_f32_e32 v217, v70
	v_fmamk_f32 v70, v79, 0x3e0293ee, v146
	v_exp_f32_e32 v218, v70
	v_fmamk_f32 v70, v80, 0x3e0293ee, v146
	v_fmac_f32_e32 v146, 0x3e0293ee, v81
	v_exp_f32_e32 v219, v70
	v_exp_f32_e32 v220, v146
	v_mfma_f32_32x32x16_bf16 v[50:65], v[178:181], v[66:69], v[50:65]
	s_waitcnt vmcnt(4)
	s_waitcnt lgkmcnt(0)
	s_barrier
	v_mfma_f32_32x32x16_bf16 v[34:49], v[174:177], v[66:69], v[34:49]
	v_mfma_f32_32x32x16_bf16 v[18:33], v[170:173], v[66:69], v[18:33]
	v_mfma_f32_32x32x16_bf16 v[2:17], v[166:169], v[66:69], v[2:17]
	v_cvt_pk_bf16_f32 v66, v182, v183
	v_cvt_pk_bf16_f32 v67, v184, v216
	v_cvt_pk_bf16_f32 v68, v217, v218
	v_cvt_pk_bf16_f32 v69, v219, v220
	s_nop 1
	v_mfma_f32_32x32x16_bf16 v[50:65], v[158:161], v[66:69], v[50:65]
	v_mfma_f32_32x32x16_bf16 v[34:49], v[154:157], v[66:69], v[34:49]
	v_mfma_f32_32x32x16_bf16 v[18:33], v[86:89], v[66:69], v[18:33]
	v_mfma_f32_32x32x16_bf16 v[2:17], v[82:85], v[66:69], v[2:17]
	ds_read_b128 v[66:69], v200 offset:0
	ds_read_b128 v[70:73], v200 offset:0x400
	ds_read_b128 v[74:77], v200 offset:0x800
	ds_read_b128 v[78:81], v200 offset:0xc00
	ds_read_b128 v[130:133], v200 offset:0x1000
	ds_read_b128 v[134:137], v200 offset:0x1400
	ds_read_b128 v[138:141], v200 offset:0x1800
	ds_read_b128 v[142:145], v200 offset:0x1c00
	ds_read_b128 v[170:173], v200 offset:0x2000
	ds_read_b128 v[174:177], v200 offset:0x2400
	ds_read_b128 v[178:181], v200 offset:0x2800
	ds_read_b128 v[212:215], v200 offset:0x2c00
	ds_read_b128 v[166:169], v200 offset:0x3000
	ds_read_b128 v[158:161], v200 offset:0x3400
	ds_read_b128 v[154:157], v200 offset:0x3800
	ds_read_b128 v[146:149], v200 offset:0x3c00
	s_nop 0
	s_waitcnt lgkmcnt(8)
	ds_read_b128 v[186:189], v200 offset:0x4000
	s_nop 0
	v_mfma_f32_32x32x16_bf16 v[82:97], v[66:69], v[126:129], 0
	v_add_f32_e32 v66, 0, v150
	v_add_f32_e32 v66, v151, v66
	v_add_f32_e32 v66, v152, v66
	v_add_f32_e32 v66, v153, v66
	v_add_f32_e32 v66, v162, v66
	v_add_f32_e32 v66, v163, v66
	v_add_f32_e32 v66, v164, v66
	v_mfma_f32_32x32x16_bf16 v[82:97], v[70:73], v[122:125], v[82:97]
	v_add_f32_e32 v66, v165, v66
	v_add_f32_e32 v66, v182, v66
	v_add_f32_e32 v66, v183, v66
	v_add_f32_e32 v221, v184, v66
	ds_read_b128 v[182:185], v200 offset:0x4400
	ds_read_b128 v[162:165], v200 offset:0x4800
	ds_read_b128 v[150:153], v200 offset:0x4c00
	v_mfma_f32_32x32x16_bf16 v[82:97], v[74:77], v[118:121], v[82:97]
	v_mfma_f32_32x32x16_bf16 v[82:97], v[78:81], v[114:117], v[82:97]
	v_mfma_f32_32x32x16_bf16 v[82:97], v[130:133], v[110:113], v[82:97]
	v_mfma_f32_32x32x16_bf16 v[82:97], v[134:137], v[102:105], v[82:97]
	v_mfma_f32_32x32x16_bf16 v[82:97], v[138:141], v[106:109], v[82:97]
	v_mfma_f32_32x32x16_bf16 v[82:97], v[142:145], v[98:101], v[82:97]
	ds_read_b128 v[142:145], v200 offset:0x5000
	ds_read_b128 v[138:141], v200 offset:0x5400
	ds_read_b128 v[134:137], v200 offset:0x5800
	ds_read_b128 v[130:133], v200 offset:0x5c00
	s_waitcnt lgkmcnt(8)
	s_nop 0
	v_mfma_f32_32x32x16_bf16 v[66:81], v[170:173], v[126:129], 0
	s_nop 9
	v_max3_f32 v171, v82, s46, v83
	v_max3_f32 v171, v171, v84, v85
	v_max3_f32 v171, v171, v86, v87
	v_max3_f32 v171, v171, v88, v89
	v_max3_f32 v171, v171, v90, v91
	v_max3_f32 v171, v171, v92, v93
	v_max3_f32 v171, v171, v94, v95
	v_mfma_f32_32x32x16_bf16 v[66:81], v[174:177], v[122:125], v[66:81]
	v_max3_f32 v171, v171, v96, v97
	v_mul_f32_e32 v171, 0x3e0293ee, v171
	v_add_f32_e32 v170, v216, v221
	ds_bpermute_b32 v172, v192, v171
	v_add_f32_e32 v170, v217, v170
	v_add_f32_e32 v170, v218, v170
	v_add_f32_e32 v170, v219, v170
	v_mfma_f32_32x32x16_bf16 v[66:81], v[178:181], v[118:121], v[66:81]
	v_add_f32_e32 v170, v220, v170
	v_add_f32_e32 v210, v210, v170
	s_waitcnt lgkmcnt(0)
	v_max_f32_e32 v170, v172, v172
	v_max_f32_e32 v170, v171, v170
	v_sub_f32_e32 v171, v170, v208
	v_cmp_ge_f32_e32 vcc, s48, v171
	s_cmp_eq_u64 vcc, exec
	v_mfma_f32_32x32x16_bf16 v[66:81], v[212:215], v[114:117], v[66:81]
	s_cbranch_scc1 .LBB0_2279
	v_max_f32_e32 v170, v170, v170
	v_max_f32_e32 v171, v208, v208
	v_max_f32_e32 v171, v171, v170
	v_sub_f32_e32 v170, v208, v171
	v_exp_f32_e32 v170, v170
	v_mov_b32_e32 v208, v171
	v_mul_f32_e32 v210, v210, v170
	v_mul_f32 v64, v64, v170
	v_mul_f32 v65, v65, v170
	v_mul_f32 v62, v62, v170
	v_mul_f32 v63, v63, v170
	v_mul_f32 v60, v60, v170
	v_mul_f32 v61, v61, v170
	v_mul_f32 v58, v58, v170
	v_mul_f32 v59, v59, v170
	v_mul_f32 v56, v56, v170
	v_mul_f32 v57, v57, v170
	v_mul_f32 v54, v54, v170
	v_mul_f32 v55, v55, v170
	v_mul_f32 v52, v52, v170
	v_mul_f32 v53, v53, v170
	v_mul_f32 v50, v50, v170
	v_mul_f32 v51, v51, v170
	v_mul_f32 v48, v48, v170
	v_mul_f32 v49, v49, v170
	v_mul_f32 v46, v46, v170
	v_mul_f32 v47, v47, v170
	v_mul_f32 v44, v44, v170
	v_mul_f32 v45, v45, v170
	v_mul_f32 v42, v42, v170
	v_mul_f32 v43, v43, v170
	v_mul_f32 v40, v40, v170
	v_mul_f32 v41, v41, v170
	v_mul_f32 v38, v38, v170
	v_mul_f32 v39, v39, v170
	v_mul_f32 v36, v36, v170
	v_mul_f32 v37, v37, v170
	v_mul_f32 v34, v34, v170
	v_mul_f32 v35, v35, v170
	v_mul_f32 v32, v32, v170
	v_mul_f32 v33, v33, v170
	v_mul_f32 v30, v30, v170
	v_mul_f32 v31, v31, v170
	v_mul_f32 v28, v28, v170
	v_mul_f32 v29, v29, v170
	v_mul_f32 v26, v26, v170
	v_mul_f32 v27, v27, v170
	v_mul_f32 v24, v24, v170
	v_mul_f32 v25, v25, v170
	v_mul_f32 v22, v22, v170
	v_mul_f32 v23, v23, v170
	v_mul_f32 v20, v20, v170
	v_mul_f32 v21, v21, v170
	v_mul_f32 v18, v18, v170
	v_mul_f32 v19, v19, v170
	v_mul_f32 v16, v16, v170
	v_mul_f32 v17, v17, v170
	v_mul_f32 v14, v14, v170
	v_mul_f32 v15, v15, v170
	v_mul_f32 v12, v12, v170
	v_mul_f32 v13, v13, v170
	v_mul_f32 v10, v10, v170
	v_mul_f32 v11, v11, v170
	v_mul_f32 v8, v8, v170
	v_mul_f32 v9, v9, v170
	v_mul_f32 v6, v6, v170
	v_mul_f32 v7, v7, v170
	v_mul_f32 v4, v4, v170
	v_mul_f32 v5, v5, v170
	v_mul_f32 v2, v2, v170
	v_mul_f32 v3, v3, v170
.LBB0_2279:
	v_mfma_f32_32x32x16_bf16 v[66:81], v[166:169], v[110:113], v[66:81]
	v_fma_f32 v82, v82, s47, -v208
	v_exp_f32_e32 v82, v82
	v_fma_f32 v83, v83, s47, -v208
	v_exp_f32_e32 v83, v83
	v_fma_f32 v84, v84, s47, -v208
	v_exp_f32_e32 v84, v84
	v_fma_f32 v85, v85, s47, -v208
	v_mfma_f32_32x32x16_bf16 v[66:81], v[158:161], v[102:105], v[66:81]
	v_exp_f32_e32 v85, v85
	v_fma_f32 v86, v86, s47, -v208
	v_add_f32_e32 v170, 0, v82
	v_exp_f32_e32 v86, v86
	v_fma_f32 v87, v87, s47, -v208
	v_add_f32_e32 v170, v83, v170
	v_exp_f32_e32 v87, v87
	v_mfma_f32_32x32x16_bf16 v[66:81], v[154:157], v[106:109], v[66:81]
	v_fma_f32 v88, v88, s47, -v208
	v_add_f32_e32 v170, v84, v170
	v_exp_f32_e32 v88, v88
	v_fma_f32 v89, v89, s47, -v208
	v_add_f32_e32 v170, v85, v170
	v_exp_f32_e32 v89, v89
	v_fma_f32 v90, v90, s47, -v208
	v_mfma_f32_32x32x16_bf16 v[66:81], v[146:149], v[98:101], v[66:81]
	v_add_f32_e32 v170, v86, v170
	v_exp_f32_e32 v90, v90
	v_fma_f32 v91, v91, s47, -v208
	v_add_f32_e32 v170, v87, v170
	v_exp_f32_e32 v91, v91
	v_fma_f32 v92, v92, s47, -v208
	v_add_f32_e32 v170, v88, v170
	s_nop 4
	v_max3_f32 v146, v66, s46, v67
	v_max3_f32 v146, v146, v68, v69
	v_max3_f32 v146, v146, v70, v71
	v_max3_f32 v146, v146, v72, v73
	v_max3_f32 v146, v146, v74, v75
	v_max3_f32 v146, v146, v76, v77
	v_max3_f32 v146, v146, v78, v79
	v_max3_f32 v146, v146, v80, v81
	v_exp_f32_e32 v92, v92
	v_fma_f32 v93, v93, s47, -v208
	v_mul_f32_e32 v146, 0x3e0293ee, v146
	v_add_f32_e32 v166, v89, v170
	v_exp_f32_e32 v93, v93
	v_fma_f32 v94, v94, s47, -v208
	ds_bpermute_b32 v147, v192, v146
	v_add_f32_e32 v166, v90, v166
	v_cvt_pk_bf16_f32 v212, v82, v83
	v_cvt_pk_bf16_f32 v213, v84, v85
	v_cvt_pk_bf16_f32 v214, v86, v87
	v_cvt_pk_bf16_f32 v215, v88, v89
	v_exp_f32_e32 v94, v94
	v_fma_f32 v95, v95, s47, -v208
	v_add_f32_e32 v216, v91, v166
	ds_read_b128 v[178:181], v200 offset:0x6000
	ds_read_b128 v[174:177], v200 offset:0x6400
	ds_read_b128 v[170:173], v200 offset:0x6800
	ds_read_b128 v[166:169], v200 offset:0x6c00
	ds_read_b128 v[158:161], v200 offset:0x7000
	ds_read_b128 v[154:157], v200 offset:0x7400
	ds_read_b128 v[86:89], v200 offset:0x7800
	ds_read_b128 v[82:85], v200 offset:0x7c00
	s_waitcnt lgkmcnt(8)
	v_exp_f32_e32 v95, v95
	v_mfma_f32_32x32x16_bf16 v[50:65], v[186:189], v[212:215], v[50:65]
	v_fma_f32 v96, v96, s47, -v208
	v_add_f32_e32 v186, v92, v216
	v_exp_f32_e32 v96, v96
	v_fma_f32 v97, v97, s47, -v208
	v_exp_f32_e32 v97, v97
	s_waitcnt lgkmcnt(0)
	v_max_f32_e32 v147, v147, v147
	v_max_f32_e32 v146, v146, v147
	v_mfma_f32_32x32x16_bf16 v[34:49], v[182:185], v[212:215], v[34:49]
	v_add_f32_e32 v182, v93, v186
	v_add_f32_e32 v182, v94, v182
	v_add_f32_e32 v182, v95, v182
	v_add_f32_e32 v148, v96, v182
	v_sub_f32_e32 v147, v146, v208
	v_add_f32_e32 v148, v97, v148
	v_cmp_ge_f32_e32 vcc, s48, v147
	v_mfma_f32_32x32x16_bf16 v[18:33], v[162:165], v[212:215], v[18:33]
	v_add_f32_e32 v182, v210, v148
	s_cmp_eq_u64 vcc, exec
	v_mfma_f32_32x32x16_bf16 v[2:17], v[150:153], v[212:215], v[2:17]
	s_cbranch_scc1 .LBB0_2281
	v_max_f32_e32 v146, v146, v146
	v_max_f32_e32 v147, v208, v208
	v_max_f32_e32 v147, v147, v146
	v_sub_f32_e32 v146, v208, v147
	v_exp_f32_e32 v146, v146
	v_mov_b32_e32 v208, v147
	v_mul_f32_e32 v182, v182, v146
	v_mul_f32 v64, v64, v146
	v_mul_f32 v65, v65, v146
	v_mul_f32 v62, v62, v146
	v_mul_f32 v63, v63, v146
	v_mul_f32 v60, v60, v146
	v_mul_f32 v61, v61, v146
	v_mul_f32 v58, v58, v146
	v_mul_f32 v59, v59, v146
	v_mul_f32 v56, v56, v146
	v_mul_f32 v57, v57, v146
	v_mul_f32 v54, v54, v146
	v_mul_f32 v55, v55, v146
	v_mul_f32 v52, v52, v146
	v_mul_f32 v53, v53, v146
	v_mul_f32 v50, v50, v146
	v_mul_f32 v51, v51, v146
	v_mul_f32 v48, v48, v146
	v_mul_f32 v49, v49, v146
	v_mul_f32 v46, v46, v146
	v_mul_f32 v47, v47, v146
	v_mul_f32 v44, v44, v146
	v_mul_f32 v45, v45, v146
	v_mul_f32 v42, v42, v146
	v_mul_f32 v43, v43, v146
	v_mul_f32 v40, v40, v146
	v_mul_f32 v41, v41, v146
	v_mul_f32 v38, v38, v146
	v_mul_f32 v39, v39, v146
	v_mul_f32 v36, v36, v146
	v_mul_f32 v37, v37, v146
	v_mul_f32 v34, v34, v146
	v_mul_f32 v35, v35, v146
	v_mul_f32 v32, v32, v146
	v_mul_f32 v33, v33, v146
	v_mul_f32 v30, v30, v146
	v_mul_f32 v31, v31, v146
	v_mul_f32 v28, v28, v146
	v_mul_f32 v29, v29, v146
	v_mul_f32 v26, v26, v146
	v_mul_f32 v27, v27, v146
	v_mul_f32 v24, v24, v146
	v_mul_f32 v25, v25, v146
	v_mul_f32 v22, v22, v146
	v_mul_f32 v23, v23, v146
	v_mul_f32 v20, v20, v146
	v_mul_f32 v21, v21, v146
	v_mul_f32 v18, v18, v146
	v_mul_f32 v19, v19, v146
	v_mul_f32 v16, v16, v146
	v_mul_f32 v17, v17, v146
	v_mul_f32 v14, v14, v146
	v_mul_f32 v15, v15, v146
	v_mul_f32 v12, v12, v146
	v_mul_f32 v13, v13, v146
	v_mul_f32 v10, v10, v146
	v_mul_f32 v11, v11, v146
	v_mul_f32 v8, v8, v146
	v_mul_f32 v9, v9, v146
	v_mul_f32 v6, v6, v146
	v_mul_f32 v7, v7, v146
	v_mul_f32 v4, v4, v146
	v_mul_f32 v5, v5, v146
	v_mul_f32 v2, v2, v146
	v_mul_f32 v3, v3, v146
	v_xor_b32_e32 v146, 0x80000000, v147
	s_branch .LBB0_2282

.LBB0_2282:
	v_fmamk_f32 v66, v66, 0x3e0293ee, v146
	v_exp_f32_e32 v150, v66
	v_fmamk_f32 v66, v67, 0x3e0293ee, v146
	v_exp_f32_e32 v151, v66
	v_fmamk_f32 v66, v68, 0x3e0293ee, v146
	v_exp_f32_e32 v152, v66
	v_fmamk_f32 v66, v69, 0x3e0293ee, v146
	v_cvt_pk_bf16_f32 v90, v90, v91
	v_cvt_pk_bf16_f32 v91, v92, v93
	v_cvt_pk_bf16_f32 v92, v94, v95
	v_cvt_pk_bf16_f32 v93, v96, v97
	v_exp_f32_e32 v153, v66
	v_fmamk_f32 v66, v70, 0x3e0293ee, v146
	v_mfma_f32_32x32x16_bf16 v[34:49], v[138:141], v[90:93], v[34:49]
	v_exp_f32_e32 v183, v66
	v_fmamk_f32 v66, v71, 0x3e0293ee, v146
	v_exp_f32_e32 v188, v66
	v_fmamk_f32 v66, v72, 0x3e0293ee, v146
	v_exp_f32_e32 v189, v66
	v_fmamk_f32 v66, v73, 0x3e0293ee, v146
	v_exp_f32_e32 v210, v66
	v_mfma_f32_32x32x16_bf16 v[50:65], v[142:145], v[90:93], v[50:65]
	v_cvt_pk_bf16_f32 v66, v150, v151
	v_cvt_pk_bf16_f32 v67, v152, v153
	v_cvt_pk_bf16_f32 v68, v183, v188
	v_cvt_pk_bf16_f32 v69, v189, v210
	s_waitcnt lgkmcnt(0)
	v_fmamk_f32 v70, v74, 0x3e0293ee, v146
	s_waitcnt vmcnt(0)
	v_mfma_f32_32x32x16_bf16 v[18:33], v[134:137], v[90:93], v[18:33]
	s_waitcnt lgkmcnt(0)
	s_barrier
	v_mfma_f32_32x32x16_bf16 v[2:17], v[130:133], v[90:93], v[2:17]
	v_mfma_f32_32x32x16_bf16 v[34:49], v[174:177], v[66:69], v[34:49]
	v_exp_f32_e32 v174, v70
	v_fmamk_f32 v70, v75, 0x3e0293ee, v146
	v_exp_f32_e32 v175, v70
	v_fmamk_f32 v70, v76, 0x3e0293ee, v146
	v_exp_f32_e32 v176, v70
	v_fmamk_f32 v70, v77, 0x3e0293ee, v146
	v_exp_f32_e32 v220, v70
	v_mfma_f32_32x32x16_bf16 v[50:65], v[178:181], v[66:69], v[50:65]
	v_fmamk_f32 v70, v78, 0x3e0293ee, v146
	v_exp_f32_e32 v221, v70
	v_fmamk_f32 v70, v79, 0x3e0293ee, v146
	v_exp_f32_e32 v222, v70
	v_fmamk_f32 v70, v80, 0x3e0293ee, v146
	v_fmac_f32_e32 v146, 0x3e0293ee, v81
	v_exp_f32_e32 v223, v70
	v_mfma_f32_32x32x16_bf16 v[18:33], v[170:173], v[66:69], v[18:33]
	v_exp_f32_e32 v224, v146
	v_mfma_f32_32x32x16_bf16 v[2:17], v[166:169], v[66:69], v[2:17]
	v_cvt_pk_bf16_f32 v66, v174, v175
	v_cvt_pk_bf16_f32 v67, v176, v220
	v_cvt_pk_bf16_f32 v68, v221, v222
	v_cvt_pk_bf16_f32 v69, v223, v224
	s_nop 1
	v_mfma_f32_32x32x16_bf16 v[50:65], v[158:161], v[66:69], v[50:65]
	v_mfma_f32_32x32x16_bf16 v[34:49], v[154:157], v[66:69], v[34:49]
	v_mfma_f32_32x32x16_bf16 v[18:33], v[86:89], v[66:69], v[18:33]
	v_mfma_f32_32x32x16_bf16 v[2:17], v[82:85], v[66:69], v[2:17]
	ds_read_b128 v[66:69], v201 offset:0
	ds_read_b128 v[70:73], v201 offset:0x400
	ds_read_b128 v[74:77], v201 offset:0x800
	ds_read_b128 v[78:81], v201 offset:0xc00
	ds_read_b128 v[130:133], v201 offset:0x1000
	ds_read_b128 v[134:137], v201 offset:0x1400
	ds_read_b128 v[138:141], v201 offset:0x1800
	ds_read_b128 v[142:145], v201 offset:0x1c00
	ds_read_b128 v[178:181], v201 offset:0x2000
	ds_read_b128 v[184:187], v201 offset:0x2400
	ds_read_b128 v[212:215], v201 offset:0x2800
	ds_read_b128 v[216:219], v201 offset:0x2c00
	ds_read_b128 v[166:169], v201 offset:0x3000
	ds_read_b128 v[162:165], v201 offset:0x3400
	ds_read_b128 v[154:157], v201 offset:0x3800
	ds_read_b128 v[146:149], v201 offset:0x3c00
	s_nop 0
	s_waitcnt lgkmcnt(8)
	s_nop 0
	v_mfma_f32_32x32x16_bf16 v[82:97], v[66:69], v[126:129], 0
	v_add_f32_e32 v66, 0, v150
	v_add_f32_e32 v66, v151, v66
	v_add_f32_e32 v66, v152, v66
	v_add_f32_e32 v66, v153, v66
	v_add_f32_e32 v66, v183, v66
	v_add_f32_e32 v66, v188, v66
	v_add_f32_e32 v66, v189, v66
	v_mfma_f32_32x32x16_bf16 v[82:97], v[70:73], v[122:125], v[82:97]
	v_add_f32_e32 v66, v210, v66
	v_add_f32_e32 v66, v174, v66
	v_add_f32_e32 v66, v175, v66
	v_add_f32_e32 v183, v176, v66
	ds_read_b128 v[174:177], v201 offset:0x4000
	ds_read_b128 v[170:173], v201 offset:0x4400
	ds_read_b128 v[158:161], v201 offset:0x4800
	v_mfma_f32_32x32x16_bf16 v[82:97], v[74:77], v[118:121], v[82:97]
	ds_read_b128 v[150:153], v201 offset:0x4c00
	v_mfma_f32_32x32x16_bf16 v[82:97], v[78:81], v[114:117], v[82:97]
	v_mfma_f32_32x32x16_bf16 v[82:97], v[130:133], v[110:113], v[82:97]
	v_mfma_f32_32x32x16_bf16 v[82:97], v[134:137], v[102:105], v[82:97]
	v_mfma_f32_32x32x16_bf16 v[82:97], v[138:141], v[106:109], v[82:97]
	v_mfma_f32_32x32x16_bf16 v[82:97], v[142:145], v[98:101], v[82:97]
	ds_read_b128 v[142:145], v201 offset:0x5000
	ds_read_b128 v[138:141], v201 offset:0x5400
	ds_read_b128 v[134:137], v201 offset:0x5800
	ds_read_b128 v[130:133], v201 offset:0x5c00
	s_waitcnt lgkmcnt(8)
	s_nop 0
	v_mfma_f32_32x32x16_bf16 v[66:81], v[178:181], v[126:129], 0
	s_nop 9
	v_max3_f32 v127, v82, s46, v83
	v_max3_f32 v127, v127, v84, v85
	v_max3_f32 v127, v127, v86, v87
	v_max3_f32 v127, v127, v88, v89
	v_add_f32_e32 v126, v220, v183
	v_add_f32_e32 v126, v221, v126
	v_add_f32_e32 v126, v222, v126
	v_mfma_f32_32x32x16_bf16 v[66:81], v[184:187], v[122:125], v[66:81]
	v_max3_f32 v122, v127, v90, v91
	v_max3_f32 v122, v122, v92, v93
	v_max3_f32 v122, v122, v94, v95
	v_max3_f32 v122, v122, v96, v97
	v_mul_f32_e32 v122, 0x3e0293ee, v122
	ds_bpermute_b32 v123, v192, v122
	v_add_f32_e32 v124, v223, v126
	v_mfma_f32_32x32x16_bf16 v[66:81], v[212:215], v[118:121], v[66:81]
	v_add_f32_e32 v118, v224, v124
	v_add_f32_e32 v126, v182, v118
	s_waitcnt lgkmcnt(0)
	v_max_f32_e32 v118, v123, v123
	v_max_f32_e32 v118, v122, v118
	v_sub_f32_e32 v119, v118, v208
	v_cmp_ge_f32_e32 vcc, s48, v119
	s_cmp_eq_u64 vcc, exec
	v_mfma_f32_32x32x16_bf16 v[66:81], v[216:219], v[114:117], v[66:81]
	s_cbranch_scc1 .LBB0_2284
	v_max_f32_e32 v114, v118, v118
	v_max_f32_e32 v115, v208, v208
	v_max_f32_e32 v115, v115, v114
	v_sub_f32_e32 v114, v208, v115
	v_exp_f32_e32 v114, v114
	v_mov_b32_e32 v208, v115
	v_mul_f32_e32 v126, v126, v114
	v_mul_f32 v64, v64, v114
	v_mul_f32 v65, v65, v114
	v_mul_f32 v62, v62, v114
	v_mul_f32 v63, v63, v114
	v_mul_f32 v60, v60, v114
	v_mul_f32 v61, v61, v114
	v_mul_f32 v58, v58, v114
	v_mul_f32 v59, v59, v114
	v_mul_f32 v56, v56, v114
	v_mul_f32 v57, v57, v114
	v_mul_f32 v54, v54, v114
	v_mul_f32 v55, v55, v114
	v_mul_f32 v52, v52, v114
	v_mul_f32 v53, v53, v114
	v_mul_f32 v50, v50, v114
	v_mul_f32 v51, v51, v114
	v_mul_f32 v48, v48, v114
	v_mul_f32 v49, v49, v114
	v_mul_f32 v46, v46, v114
	v_mul_f32 v47, v47, v114
	v_mul_f32 v44, v44, v114
	v_mul_f32 v45, v45, v114
	v_mul_f32 v42, v42, v114
	v_mul_f32 v43, v43, v114
	v_mul_f32 v40, v40, v114
	v_mul_f32 v41, v41, v114
	v_mul_f32 v38, v38, v114
	v_mul_f32 v39, v39, v114
	v_mul_f32 v36, v36, v114
	v_mul_f32 v37, v37, v114
	v_mul_f32 v34, v34, v114
	v_mul_f32 v35, v35, v114
	v_mul_f32 v32, v32, v114
	v_mul_f32 v33, v33, v114
	v_mul_f32 v30, v30, v114
	v_mul_f32 v31, v31, v114
	v_mul_f32 v28, v28, v114
	v_mul_f32 v29, v29, v114
	v_mul_f32 v26, v26, v114
	v_mul_f32 v27, v27, v114
	v_mul_f32 v24, v24, v114
	v_mul_f32 v25, v25, v114
	v_mul_f32 v22, v22, v114
	v_mul_f32 v23, v23, v114
	v_mul_f32 v20, v20, v114
	v_mul_f32 v21, v21, v114
	v_mul_f32 v18, v18, v114
	v_mul_f32 v19, v19, v114
	v_mul_f32 v16, v16, v114
	v_mul_f32 v17, v17, v114
	v_mul_f32 v14, v14, v114
	v_mul_f32 v15, v15, v114
	v_mul_f32 v12, v12, v114
	v_mul_f32 v13, v13, v114
	v_mul_f32 v10, v10, v114
	v_mul_f32 v11, v11, v114
	v_mul_f32 v8, v8, v114
	v_mul_f32 v9, v9, v114
	v_mul_f32 v6, v6, v114
	v_mul_f32 v7, v7, v114
	v_mul_f32 v4, v4, v114
	v_mul_f32 v5, v5, v114
	v_mul_f32 v2, v2, v114
	v_mul_f32 v3, v3, v114
